# prep phase: s5pre coefficient loads batched (8 dwordx4 instead of 32 serialized dwords), Hyena filter output loop with 16-deep LDS read pipeline and no per-store waits; S5 items with internal item loo
# speedup vs baseline: 1.1137x; 1.0243x over previous
.LBB0_58:
	s_or_b64 exec, exec, s[0:1]
	s_waitcnt vmcnt(0)
	v_mul_f32_e32 v16, v12, v16
	v_mul_f32_e32 v19, 0x3fb8aa3b, v16
	s_mov_b32 s5, 0x3fb8aa3b
	v_fma_f32 v20, v16, s5, -v19
	v_rndne_f32_e32 v21, v19
	v_fmac_f32_e32 v20, 0x32a5705f, v16
	v_sub_f32_e32 v19, v19, v21
	v_add_f32_e32 v19, v19, v20
	v_cvt_i32_f32_e32 v20, v21
	v_exp_f32_e32 v19, v19
	s_mov_b32 s6, 0xc2ce8ed0
	v_cmp_ngt_f32_e32 vcc, s6, v16
	s_mov_b32 s4, 0x42b17218
	v_ldexp_f32 v19, v19, v20
	v_cndmask_b32_e32 v19, 0, v19, vcc
	v_cmp_nlt_f32_e32 vcc, s4, v16
	v_mul_f32_e32 v16, v0, v0
	v_fmamk_f32 v20, v16, 0xb94c1982, v199
	v_fmaak_f32 v20, v16, v20, 0xbe2aaa9d
	v_mul_f32_e32 v20, v16, v20
	v_fmac_f32_e32 v0, v0, v20
	v_fmamk_f32 v20, v16, 0x37d75334, v200
	v_fmaak_f32 v20, v16, v20, 0x3d2aabf7
	v_fmaak_f32 v20, v16, v20, 0xbf000004
	v_fma_f32 v16, v16, v20, 1.0
	v_lshlrev_b32_e32 v20, 30, v17
	v_and_b32_e32 v17, 1, v17
	v_cndmask_b32_e32 v19, v210, v19, vcc
	v_cmp_eq_u32_e32 vcc, 0, v17
	v_xor_b32_e32 v15, v15, v14
	v_and_b32_e32 v21, 0x80000000, v20
	v_cndmask_b32_e32 v17, v16, v0, vcc
	v_xor_b32_e32 v0, 0x80000000, v0
	v_xor_b32_e32 v15, v15, v17
	v_cndmask_b32_e32 v0, v0, v16, vcc
	v_xor_b32_e32 v15, v15, v21
	v_bitop3_b32 v0, v0, v20, s27 bitop3:0x78
	v_cmp_class_f32_e64 vcc, v14, s2
	v_lshl_add_u64 v[16:17], s[40:41], 0, v[8:9]
	v_mov_b32_e32 v28, v13
	v_cndmask_b32_e32 v23, v207, v0, vcc
	v_cndmask_b32_e32 v0, v207, v15, vcc
	v_mul_f32_e32 v20, v19, v23
	v_mul_f32_e32 v21, v19, v0
	global_store_dwordx2 v[4:5], v[20:21], off
	v_lshl_add_u64 v[14:15], s[24:25], 0, v[8:9]
	global_load_dwordx4 v[140:143], v[16:17], off offset:0
	global_load_dwordx4 v[144:147], v[16:17], off offset:16
	global_load_dwordx4 v[148:151], v[16:17], off offset:32
	global_load_dwordx4 v[152:155], v[16:17], off offset:48
	global_load_dwordx4 v[168:171], v[14:15], off offset:0
	global_load_dwordx4 v[172:175], v[14:15], off offset:16
	global_load_dwordx4 v[176:179], v[14:15], off offset:32
	global_load_dwordx4 v[180:183], v[14:15], off offset:48
	v_fma_f32 v20, v19, v23, -1.0
	v_pk_mul_f32 v[24:25], v[12:13], v[12:13]
	v_lshl_or_b32 v26, v3, 10, v18
	v_readlane_b32 s0, v251, 11
	v_pk_mul_f32 v[28:29], v[28:29], v[20:21] op_sel:[0,1] op_sel_hi:[0,0]
	v_ashrrev_i32_e32 v27, 31, v26
	v_pk_add_f32 v[24:25], v[24:25], v[24:25] op_sel:[0,1] op_sel_hi:[0,1]
	v_readlane_b32 s1, v251, 12
	v_pk_fma_f32 v[30:31], v[12:13], v[20:21], v[28:29]
	v_pk_fma_f32 v[12:13], v[12:13], v[20:21], v[28:29] op_sel_hi:[0,1,1] neg_lo:[0,0,1] neg_hi:[0,0,1]
	v_lshl_add_u64 v[26:27], v[26:27], 3, s[0:1]
	v_div_scale_f32 v3, s[0:1], v25, v25, v13
	v_div_scale_f32 v19, s[0:1], v24, v24, v30
	v_rcp_f32_e32 v20, v3
	v_rcp_f32_e32 v21, v19
	v_div_scale_f32 v12, vcc, v13, v25, v13
	v_fma_f32 v28, -v3, v20, 1.0
	v_fma_f32 v29, -v19, v21, 1.0
	v_fmac_f32_e32 v20, v28, v20
	v_div_scale_f32 v23, s[0:1], v30, v24, v30
	v_fmac_f32_e32 v21, v29, v21
	v_mul_f32_e32 v28, v12, v20
	v_mul_f32_e32 v29, v23, v21
	v_fma_f32 v31, -v3, v28, v12
	v_fma_f32 v32, -v19, v29, v23
	v_fmac_f32_e32 v28, v31, v20
	v_fmac_f32_e32 v29, v32, v21
	v_fma_f32 v3, -v3, v28, v12
	v_fma_f32 v12, -v19, v29, v23
	v_div_fmas_f32 v3, v3, v20, v28
	s_mov_b64 vcc, s[0:1]
	v_div_fixup_f32 v13, v3, v25, v13
	v_div_fmas_f32 v3, v12, v21, v29
	v_div_fixup_f32 v12, v3, v24, v30
	s_movk_i32 s0, 0x1000
	s_add_u32 s24, s24, 0x8000
	s_addc_u32 s25, s25, 0
	s_add_u32 s40, s40, 0x8000
	s_addc_u32 s41, s41, 0
	s_waitcnt vmcnt(0)
	v_mov_b32_e32 v0, v140
	v_mov_b32_e32 v22, v168
	v_pk_mul_f32 v[20:21], v[0:1], v[12:13] op_sel:[0,1] op_sel_hi:[0,0]
	v_pk_fma_f32 v[24:25], v[22:23], v[12:13], v[20:21] neg_lo:[0,0,1] neg_hi:[0,0,1]
	v_pk_fma_f32 v[20:21], v[22:23], v[12:13], v[20:21] op_sel_hi:[0,1,1]
	v_mov_b32_e32 v25, v21
	global_store_dwordx2 v[26:27], v[24:25], off
	v_mov_b32_e32 v0, v141
	v_mov_b32_e32 v20, v169
	v_pk_mul_f32 v[22:23], v[0:1], v[12:13] op_sel:[0,1] op_sel_hi:[0,0]
	v_pk_fma_f32 v[24:25], v[20:21], v[12:13], v[22:23] neg_lo:[0,0,1] neg_hi:[0,0,1]
	v_pk_fma_f32 v[20:21], v[20:21], v[12:13], v[22:23] op_sel_hi:[0,1,1]
	v_mov_b32_e32 v25, v21
	global_store_dwordx2 v[26:27], v[24:25], off offset:8
	v_mov_b32_e32 v0, v142
	v_mov_b32_e32 v20, v170
	v_pk_mul_f32 v[22:23], v[0:1], v[12:13] op_sel:[0,1] op_sel_hi:[0,0]
	v_pk_fma_f32 v[24:25], v[20:21], v[12:13], v[22:23] neg_lo:[0,0,1] neg_hi:[0,0,1]
	v_pk_fma_f32 v[20:21], v[20:21], v[12:13], v[22:23] op_sel_hi:[0,1,1]
	v_mov_b32_e32 v25, v21
	global_store_dwordx2 v[26:27], v[24:25], off offset:1024
	v_mov_b32_e32 v0, v143
	v_mov_b32_e32 v20, v171
	v_pk_mul_f32 v[22:23], v[12:13], v[0:1] op_sel:[1,0] op_sel_hi:[0,0]
	v_pk_fma_f32 v[24:25], v[12:13], v[20:21], v[22:23] neg_lo:[0,0,1] neg_hi:[0,0,1]
	v_pk_fma_f32 v[20:21], v[12:13], v[20:21], v[22:23] op_sel_hi:[1,0,1]
	s_nop 0
	v_mov_b32_e32 v25, v21
	global_store_dwordx2 v[26:27], v[24:25], off offset:1032
	v_mov_b32_e32 v0, v144
	v_mov_b32_e32 v20, v172
	v_pk_mul_f32 v[22:23], v[12:13], v[0:1] op_sel:[1,0] op_sel_hi:[0,0]
	v_pk_fma_f32 v[24:25], v[12:13], v[20:21], v[22:23] neg_lo:[0,0,1] neg_hi:[0,0,1]
	v_pk_fma_f32 v[20:21], v[12:13], v[20:21], v[22:23] op_sel_hi:[1,0,1]
	s_nop 0
	v_mov_b32_e32 v25, v21
	global_store_dwordx2 v[26:27], v[24:25], off offset:2048
	v_mov_b32_e32 v0, v145
	v_mov_b32_e32 v20, v173
	v_pk_mul_f32 v[22:23], v[12:13], v[0:1] op_sel:[1,0] op_sel_hi:[0,0]
	v_pk_fma_f32 v[24:25], v[12:13], v[20:21], v[22:23] neg_lo:[0,0,1] neg_hi:[0,0,1]
	v_pk_fma_f32 v[20:21], v[12:13], v[20:21], v[22:23] op_sel_hi:[1,0,1]
	s_nop 0
	v_mov_b32_e32 v25, v21
	global_store_dwordx2 v[26:27], v[24:25], off offset:2056
	v_mov_b32_e32 v0, v146
	v_mov_b32_e32 v20, v174
	v_pk_mul_f32 v[22:23], v[12:13], v[0:1] op_sel:[1,0] op_sel_hi:[0,0]
	v_pk_fma_f32 v[24:25], v[12:13], v[20:21], v[22:23] neg_lo:[0,0,1] neg_hi:[0,0,1]
	v_pk_fma_f32 v[20:21], v[12:13], v[20:21], v[22:23] op_sel_hi:[1,0,1]
	s_nop 0
	v_mov_b32_e32 v25, v21
	global_store_dwordx2 v[26:27], v[24:25], off offset:3072
	v_mov_b32_e32 v0, v147
	v_mov_b32_e32 v20, v175
	v_pk_mul_f32 v[22:23], v[12:13], v[0:1] op_sel:[1,0] op_sel_hi:[0,0]
	v_pk_fma_f32 v[24:25], v[12:13], v[20:21], v[22:23] neg_lo:[0,0,1] neg_hi:[0,0,1]
	v_pk_fma_f32 v[20:21], v[12:13], v[20:21], v[22:23] op_sel_hi:[1,0,1]
	v_add_co_u32_e32 v22, vcc, s0, v26
	v_mov_b32_e32 v25, v21
	global_store_dwordx2 v[26:27], v[24:25], off offset:3080
	v_mov_b32_e32 v0, v148
	v_mov_b32_e32 v20, v176
	v_addc_co_u32_e32 v23, vcc, 0, v27, vcc
	s_mov_b64 s[0:1], 0x800
	v_cmp_lt_i32_e32 vcc, s22, v2
	v_lshl_add_u64 v[6:7], v[6:7], 0, s[0:1]
	v_lshl_add_u64 v[10:11], v[10:11], 0, s[0:1]
	s_mov_b64 s[0:1], 0x1000
	s_or_b64 s[42:43], vcc, s[42:43]
	v_lshl_add_u64 v[4:5], v[4:5], 0, s[0:1]
	v_pk_mul_f32 v[24:25], v[12:13], v[0:1] op_sel:[1,0] op_sel_hi:[0,0]
	v_pk_fma_f32 v[26:27], v[12:13], v[20:21], v[24:25] neg_lo:[0,0,1] neg_hi:[0,0,1]
	v_pk_fma_f32 v[20:21], v[12:13], v[20:21], v[24:25] op_sel_hi:[1,0,1]
	s_nop 0
	v_mov_b32_e32 v27, v21
	global_store_dwordx2 v[22:23], v[26:27], off
	v_mov_b32_e32 v0, v149
	v_mov_b32_e32 v20, v177
	v_pk_mul_f32 v[24:25], v[12:13], v[0:1] op_sel:[1,0] op_sel_hi:[0,0]
	v_pk_fma_f32 v[26:27], v[12:13], v[20:21], v[24:25] neg_lo:[0,0,1] neg_hi:[0,0,1]
	v_pk_fma_f32 v[20:21], v[12:13], v[20:21], v[24:25] op_sel_hi:[1,0,1]
	s_nop 0
	v_mov_b32_e32 v27, v21
	global_store_dwordx2 v[22:23], v[26:27], off offset:8
	v_mov_b32_e32 v0, v150
	v_mov_b32_e32 v20, v178
	v_pk_mul_f32 v[24:25], v[12:13], v[0:1] op_sel:[1,0] op_sel_hi:[0,0]
	v_pk_fma_f32 v[26:27], v[12:13], v[20:21], v[24:25] neg_lo:[0,0,1] neg_hi:[0,0,1]
	v_pk_fma_f32 v[20:21], v[12:13], v[20:21], v[24:25] op_sel_hi:[1,0,1]
	s_nop 0
	v_mov_b32_e32 v27, v21
	global_store_dwordx2 v[22:23], v[26:27], off offset:1024
	v_mov_b32_e32 v0, v151
	v_mov_b32_e32 v20, v179
	v_pk_mul_f32 v[24:25], v[12:13], v[0:1] op_sel:[1,0] op_sel_hi:[0,0]
	v_pk_fma_f32 v[26:27], v[12:13], v[20:21], v[24:25] neg_lo:[0,0,1] neg_hi:[0,0,1]
	v_pk_fma_f32 v[20:21], v[12:13], v[20:21], v[24:25] op_sel_hi:[1,0,1]
	s_nop 0
	v_mov_b32_e32 v27, v21
	global_store_dwordx2 v[22:23], v[26:27], off offset:1032
	v_mov_b32_e32 v0, v152
	v_mov_b32_e32 v20, v180
	v_pk_mul_f32 v[24:25], v[12:13], v[0:1] op_sel:[1,0] op_sel_hi:[0,0]
	v_pk_fma_f32 v[26:27], v[12:13], v[20:21], v[24:25] neg_lo:[0,0,1] neg_hi:[0,0,1]
	v_pk_fma_f32 v[20:21], v[12:13], v[20:21], v[24:25] op_sel_hi:[1,0,1]
	s_nop 0
	v_mov_b32_e32 v27, v21
	global_store_dwordx2 v[22:23], v[26:27], off offset:2048
	v_mov_b32_e32 v0, v153
	v_mov_b32_e32 v20, v181
	v_pk_mul_f32 v[24:25], v[12:13], v[0:1] op_sel:[1,0] op_sel_hi:[0,0]
	v_pk_fma_f32 v[26:27], v[12:13], v[20:21], v[24:25] neg_lo:[0,0,1] neg_hi:[0,0,1]
	v_pk_fma_f32 v[20:21], v[12:13], v[20:21], v[24:25] op_sel_hi:[1,0,1]
	s_nop 0
	v_mov_b32_e32 v27, v21
	global_store_dwordx2 v[22:23], v[26:27], off offset:2056
	v_mov_b32_e32 v0, v154
	v_mov_b32_e32 v20, v182
	v_pk_mul_f32 v[24:25], v[12:13], v[0:1] op_sel:[1,0] op_sel_hi:[0,0]
	v_pk_fma_f32 v[26:27], v[12:13], v[20:21], v[24:25] neg_lo:[0,0,1] neg_hi:[0,0,1]
	v_pk_fma_f32 v[20:21], v[12:13], v[20:21], v[24:25] op_sel_hi:[1,0,1]
	s_nop 0
	v_mov_b32_e32 v27, v21
	global_store_dwordx2 v[22:23], v[26:27], off offset:3072
	v_mov_b32_e32 v0, v155
	s_nop 0
	v_mov_b32_e32 v14, v183
	v_add_u32_e32 v15, 0x200, v2
	v_pk_mul_f32 v[2:3], v[12:13], v[0:1] op_sel:[1,0] op_sel_hi:[0,0]
	v_pk_fma_f32 v[16:17], v[12:13], v[14:15], v[2:3] neg_lo:[0,0,1] neg_hi:[0,0,1]
	v_pk_fma_f32 v[2:3], v[12:13], v[14:15], v[2:3] op_sel_hi:[1,0,1]
	s_nop 0
	v_mov_b32_e32 v17, v3
	v_mov_b32_e32 v2, v15
	global_store_dwordx2 v[22:23], v[16:17], off offset:3080
	s_andn2_b64 exec, exec, s[42:43]
	s_cbranch_execz .LBB0_63

.LBB0_349:
	v_lshl_add_u32 v68, s0, 2, v73
	v_lshl_add_u32 v69, v68, 2, v205
	v_add_u32_e32 v70, 0xa300, v69
	v_add_u32_e32 v68, s74, v68
	v_mov_b32_e32 v110, v68
	v_ashrrev_i32_e32 v111, 31, v68
	v_lshl_add_u64 v[112:113], v[110:111], 2, s[20:21]
	global_load_dwordx4 v[116:119], v[112:113], off
	ds_read_b128 v[138:141], v69 offset:41728
	ds_read_b128 v[142:145], v69 offset:42240
	ds_read_b128 v[146:149], v69 offset:42752
	ds_read_b128 v[150:153], v69 offset:43264
	ds_read_b128 v[154:157], v69 offset:43776
	ds_read_b128 v[158:161], v69 offset:44288
	ds_read_b128 v[168:171], v69 offset:44800
	ds_read_b128 v[172:175], v69 offset:45312
	ds_read_b128 v[176:179], v69 offset:45824
	ds_read_b128 v[180:183], v69 offset:46336
	ds_read_b128 v[184:187], v69 offset:46848
	ds_read_b128 v[188:191], v69 offset:47360
	ds_read_b128 v[192:195], v69 offset:47872
	ds_read_b128 v[224:227], v69 offset:48384
	ds_read_b128 v[228:231], v69 offset:48896
	ds_read_b128 v[232:235], v69 offset:49408
	s_waitcnt lgkmcnt(15)
	v_mul_f32_e32 v120, v2, v138
	v_mul_f32_e32 v121, v2, v139
	v_mul_f32_e32 v122, v2, v140
	v_mul_f32_e32 v123, v2, v141
	ds_read_b128 v[138:141], v69 offset:49920
	s_waitcnt lgkmcnt(15)
	v_fmac_f32_e32 v120, v3, v142
	v_fmac_f32_e32 v121, v3, v143
	v_fmac_f32_e32 v122, v3, v144
	v_fmac_f32_e32 v123, v3, v145
	ds_read_b128 v[142:145], v69 offset:50432
	s_waitcnt lgkmcnt(15)
	v_fmac_f32_e32 v120, v4, v146
	v_fmac_f32_e32 v121, v4, v147
	v_fmac_f32_e32 v122, v4, v148
	v_fmac_f32_e32 v123, v4, v149
	ds_read_b128 v[146:149], v69 offset:50944
	s_waitcnt lgkmcnt(15)
	v_fmac_f32_e32 v120, v5, v150
	v_fmac_f32_e32 v121, v5, v151
	v_fmac_f32_e32 v122, v5, v152
	v_fmac_f32_e32 v123, v5, v153
	ds_read_b128 v[150:153], v69 offset:51456
	s_waitcnt lgkmcnt(15)
	v_fmac_f32_e32 v120, v6, v154
	v_fmac_f32_e32 v121, v6, v155
	v_fmac_f32_e32 v122, v6, v156
	v_fmac_f32_e32 v123, v6, v157
	ds_read_b128 v[154:157], v69 offset:51968
	s_waitcnt lgkmcnt(15)
	v_fmac_f32_e32 v120, v7, v158
	v_fmac_f32_e32 v121, v7, v159
	v_fmac_f32_e32 v122, v7, v160
	v_fmac_f32_e32 v123, v7, v161
	ds_read_b128 v[158:161], v69 offset:52480
	s_waitcnt lgkmcnt(15)
	v_fmac_f32_e32 v120, v8, v168
	v_fmac_f32_e32 v121, v8, v169
	v_fmac_f32_e32 v122, v8, v170
	v_fmac_f32_e32 v123, v8, v171
	ds_read_b128 v[168:171], v69 offset:52992
	s_waitcnt lgkmcnt(15)
	v_fmac_f32_e32 v120, v9, v172
	v_fmac_f32_e32 v121, v9, v173
	v_fmac_f32_e32 v122, v9, v174
	v_fmac_f32_e32 v123, v9, v175
	ds_read_b128 v[172:175], v69 offset:53504
	s_waitcnt lgkmcnt(15)
	v_fmac_f32_e32 v120, v10, v176
	v_fmac_f32_e32 v121, v10, v177
	v_fmac_f32_e32 v122, v10, v178
	v_fmac_f32_e32 v123, v10, v179
	ds_read_b128 v[176:179], v69 offset:54016
	s_waitcnt lgkmcnt(15)
	v_fmac_f32_e32 v120, v11, v180
	v_fmac_f32_e32 v121, v11, v181
	v_fmac_f32_e32 v122, v11, v182
	v_fmac_f32_e32 v123, v11, v183
	ds_read_b128 v[180:183], v69 offset:54528
	s_waitcnt lgkmcnt(15)
	v_fmac_f32_e32 v120, v12, v184
	v_fmac_f32_e32 v121, v12, v185
	v_fmac_f32_e32 v122, v12, v186
	v_fmac_f32_e32 v123, v12, v187
	ds_read_b128 v[184:187], v69 offset:55040
	s_waitcnt lgkmcnt(15)
	v_fmac_f32_e32 v120, v13, v188
	v_fmac_f32_e32 v121, v13, v189
	v_fmac_f32_e32 v122, v13, v190
	v_fmac_f32_e32 v123, v13, v191
	ds_read_b128 v[188:191], v69 offset:55552
	s_waitcnt lgkmcnt(15)
	v_fmac_f32_e32 v120, v14, v192
	v_fmac_f32_e32 v121, v14, v193
	v_fmac_f32_e32 v122, v14, v194
	v_fmac_f32_e32 v123, v14, v195
	ds_read_b128 v[192:195], v69 offset:56064
	s_waitcnt lgkmcnt(15)
	v_fmac_f32_e32 v120, v15, v224
	v_fmac_f32_e32 v121, v15, v225
	v_fmac_f32_e32 v122, v15, v226
	v_fmac_f32_e32 v123, v15, v227
	ds_read_b128 v[224:227], v69 offset:56576
	s_waitcnt lgkmcnt(15)
	v_fmac_f32_e32 v120, v16, v228
	v_fmac_f32_e32 v121, v16, v229
	v_fmac_f32_e32 v122, v16, v230
	v_fmac_f32_e32 v123, v16, v231
	ds_read_b128 v[228:231], v69 offset:57088
	s_waitcnt lgkmcnt(15)
	v_fmac_f32_e32 v120, v17, v232
	v_fmac_f32_e32 v121, v17, v233
	v_fmac_f32_e32 v122, v17, v234
	v_fmac_f32_e32 v123, v17, v235
	ds_read_b128 v[232:235], v69 offset:57600
	s_waitcnt lgkmcnt(15)
	v_fmac_f32_e32 v120, v18, v138
	v_fmac_f32_e32 v121, v18, v139
	v_fmac_f32_e32 v122, v18, v140
	v_fmac_f32_e32 v123, v18, v141
	ds_read_b128 v[138:141], v69 offset:58112
	s_waitcnt lgkmcnt(15)
	v_fmac_f32_e32 v120, v19, v142
	v_fmac_f32_e32 v121, v19, v143
	v_fmac_f32_e32 v122, v19, v144
	v_fmac_f32_e32 v123, v19, v145
	ds_read_b128 v[142:145], v69 offset:58624
	s_waitcnt lgkmcnt(15)
	v_fmac_f32_e32 v120, v20, v146
	v_fmac_f32_e32 v121, v20, v147
	v_fmac_f32_e32 v122, v20, v148
	v_fmac_f32_e32 v123, v20, v149
	ds_read_b128 v[146:149], v69 offset:59136
	s_waitcnt lgkmcnt(15)
	v_fmac_f32_e32 v120, v21, v150
	v_fmac_f32_e32 v121, v21, v151
	v_fmac_f32_e32 v122, v21, v152
	v_fmac_f32_e32 v123, v21, v153
	ds_read_b128 v[150:153], v69 offset:59648
	s_waitcnt lgkmcnt(15)
	v_fmac_f32_e32 v120, v22, v154
	v_fmac_f32_e32 v121, v22, v155
	v_fmac_f32_e32 v122, v22, v156
	v_fmac_f32_e32 v123, v22, v157
	ds_read_b128 v[154:157], v69 offset:60160
	s_waitcnt lgkmcnt(15)
	v_fmac_f32_e32 v120, v23, v158
	v_fmac_f32_e32 v121, v23, v159
	v_fmac_f32_e32 v122, v23, v160
	v_fmac_f32_e32 v123, v23, v161
	ds_read_b128 v[158:161], v69 offset:60672
	s_waitcnt lgkmcnt(15)
	v_fmac_f32_e32 v120, v24, v168
	v_fmac_f32_e32 v121, v24, v169
	v_fmac_f32_e32 v122, v24, v170
	v_fmac_f32_e32 v123, v24, v171
	ds_read_b128 v[168:171], v69 offset:61184
	s_waitcnt lgkmcnt(15)
	v_fmac_f32_e32 v120, v25, v172
	v_fmac_f32_e32 v121, v25, v173
	v_fmac_f32_e32 v122, v25, v174
	v_fmac_f32_e32 v123, v25, v175
	ds_read_b128 v[172:175], v69 offset:61696
	s_waitcnt lgkmcnt(15)
	v_fmac_f32_e32 v120, v26, v176
	v_fmac_f32_e32 v121, v26, v177
	v_fmac_f32_e32 v122, v26, v178
	v_fmac_f32_e32 v123, v26, v179
	ds_read_b128 v[176:179], v69 offset:62208
	s_waitcnt lgkmcnt(15)
	v_fmac_f32_e32 v120, v27, v180
	v_fmac_f32_e32 v121, v27, v181
	v_fmac_f32_e32 v122, v27, v182
	v_fmac_f32_e32 v123, v27, v183
	ds_read_b128 v[180:183], v69 offset:62720
	s_waitcnt lgkmcnt(15)
	v_fmac_f32_e32 v120, v28, v184
	v_fmac_f32_e32 v121, v28, v185
	v_fmac_f32_e32 v122, v28, v186
	v_fmac_f32_e32 v123, v28, v187
	ds_read_b128 v[184:187], v69 offset:63232
	s_waitcnt lgkmcnt(15)
	v_fmac_f32_e32 v120, v29, v188
	v_fmac_f32_e32 v121, v29, v189
	v_fmac_f32_e32 v122, v29, v190
	v_fmac_f32_e32 v123, v29, v191
	ds_read_b128 v[188:191], v69 offset:63744
	s_waitcnt lgkmcnt(15)
	v_fmac_f32_e32 v120, v30, v192
	v_fmac_f32_e32 v121, v30, v193
	v_fmac_f32_e32 v122, v30, v194
	v_fmac_f32_e32 v123, v30, v195
	ds_read_b128 v[192:195], v69 offset:64256
	s_waitcnt lgkmcnt(15)
	v_fmac_f32_e32 v120, v31, v224
	v_fmac_f32_e32 v121, v31, v225
	v_fmac_f32_e32 v122, v31, v226
	v_fmac_f32_e32 v123, v31, v227
	ds_read_b128 v[224:227], v69 offset:64768
	s_waitcnt lgkmcnt(15)
	v_fmac_f32_e32 v120, v32, v228
	v_fmac_f32_e32 v121, v32, v229
	v_fmac_f32_e32 v122, v32, v230
	v_fmac_f32_e32 v123, v32, v231
	ds_read_b128 v[228:231], v69 offset:65280
	s_waitcnt lgkmcnt(15)
	v_fmac_f32_e32 v120, v33, v232
	v_fmac_f32_e32 v121, v33, v233
	v_fmac_f32_e32 v122, v33, v234
	v_fmac_f32_e32 v123, v33, v235
	ds_read_b128 v[232:235], v70 offset:24064
	s_waitcnt lgkmcnt(15)
	v_fmac_f32_e32 v120, v34, v138
	v_fmac_f32_e32 v121, v34, v139
	v_fmac_f32_e32 v122, v34, v140
	v_fmac_f32_e32 v123, v34, v141
	ds_read_b128 v[138:141], v70 offset:24576
	s_waitcnt lgkmcnt(15)
	v_fmac_f32_e32 v120, v35, v142
	v_fmac_f32_e32 v121, v35, v143
	v_fmac_f32_e32 v122, v35, v144
	v_fmac_f32_e32 v123, v35, v145
	ds_read_b128 v[142:145], v70 offset:25088
	s_waitcnt lgkmcnt(15)
	v_fmac_f32_e32 v120, v36, v146
	v_fmac_f32_e32 v121, v36, v147
	v_fmac_f32_e32 v122, v36, v148
	v_fmac_f32_e32 v123, v36, v149
	ds_read_b128 v[146:149], v70 offset:25600
	s_waitcnt lgkmcnt(15)
	v_fmac_f32_e32 v120, v37, v150
	v_fmac_f32_e32 v121, v37, v151
	v_fmac_f32_e32 v122, v37, v152
	v_fmac_f32_e32 v123, v37, v153
	ds_read_b128 v[150:153], v70 offset:26112
	s_waitcnt lgkmcnt(15)
	v_fmac_f32_e32 v120, v38, v154
	v_fmac_f32_e32 v121, v38, v155
	v_fmac_f32_e32 v122, v38, v156
	v_fmac_f32_e32 v123, v38, v157
	ds_read_b128 v[154:157], v70 offset:26624
	s_waitcnt lgkmcnt(15)
	v_fmac_f32_e32 v120, v39, v158
	v_fmac_f32_e32 v121, v39, v159
	v_fmac_f32_e32 v122, v39, v160
	v_fmac_f32_e32 v123, v39, v161
	ds_read_b128 v[158:161], v70 offset:27136
	s_waitcnt lgkmcnt(15)
	v_fmac_f32_e32 v120, v40, v168
	v_fmac_f32_e32 v121, v40, v169
	v_fmac_f32_e32 v122, v40, v170
	v_fmac_f32_e32 v123, v40, v171
	ds_read_b128 v[168:171], v70 offset:27648
	s_waitcnt lgkmcnt(15)
	v_fmac_f32_e32 v120, v41, v172
	v_fmac_f32_e32 v121, v41, v173
	v_fmac_f32_e32 v122, v41, v174
	v_fmac_f32_e32 v123, v41, v175
	ds_read_b128 v[172:175], v70 offset:28160
	s_waitcnt lgkmcnt(15)
	v_fmac_f32_e32 v120, v42, v176
	v_fmac_f32_e32 v121, v42, v177
	v_fmac_f32_e32 v122, v42, v178
	v_fmac_f32_e32 v123, v42, v179
	ds_read_b128 v[176:179], v70 offset:28672
	s_waitcnt lgkmcnt(15)
	v_fmac_f32_e32 v120, v43, v180
	v_fmac_f32_e32 v121, v43, v181
	v_fmac_f32_e32 v122, v43, v182
	v_fmac_f32_e32 v123, v43, v183
	ds_read_b128 v[180:183], v70 offset:29184
	s_waitcnt lgkmcnt(15)
	v_fmac_f32_e32 v120, v44, v184
	v_fmac_f32_e32 v121, v44, v185
	v_fmac_f32_e32 v122, v44, v186
	v_fmac_f32_e32 v123, v44, v187
	ds_read_b128 v[184:187], v70 offset:29696
	s_waitcnt lgkmcnt(15)
	v_fmac_f32_e32 v120, v45, v188
	v_fmac_f32_e32 v121, v45, v189
	v_fmac_f32_e32 v122, v45, v190
	v_fmac_f32_e32 v123, v45, v191
	ds_read_b128 v[188:191], v70 offset:30208
	s_waitcnt lgkmcnt(15)
	v_fmac_f32_e32 v120, v46, v192
	v_fmac_f32_e32 v121, v46, v193
	v_fmac_f32_e32 v122, v46, v194
	v_fmac_f32_e32 v123, v46, v195
	ds_read_b128 v[192:195], v70 offset:30720
	s_waitcnt lgkmcnt(15)
	v_fmac_f32_e32 v120, v47, v224
	v_fmac_f32_e32 v121, v47, v225
	v_fmac_f32_e32 v122, v47, v226
	v_fmac_f32_e32 v123, v47, v227
	ds_read_b128 v[224:227], v70 offset:31232
	s_waitcnt lgkmcnt(15)
	v_fmac_f32_e32 v120, v48, v228
	v_fmac_f32_e32 v121, v48, v229
	v_fmac_f32_e32 v122, v48, v230
	v_fmac_f32_e32 v123, v48, v231
	ds_read_b128 v[228:231], v70 offset:31744
	s_waitcnt lgkmcnt(15)
	v_fmac_f32_e32 v120, v49, v232
	v_fmac_f32_e32 v121, v49, v233
	v_fmac_f32_e32 v122, v49, v234
	v_fmac_f32_e32 v123, v49, v235
	ds_read_b128 v[232:235], v70 offset:32256
	s_waitcnt lgkmcnt(15)
	v_fmac_f32_e32 v120, v50, v138
	v_fmac_f32_e32 v121, v50, v139
	v_fmac_f32_e32 v122, v50, v140
	v_fmac_f32_e32 v123, v50, v141
	s_waitcnt lgkmcnt(14)
	v_fmac_f32_e32 v120, v51, v142
	v_fmac_f32_e32 v121, v51, v143
	v_fmac_f32_e32 v122, v51, v144
	v_fmac_f32_e32 v123, v51, v145
	s_waitcnt lgkmcnt(13)
	v_fmac_f32_e32 v120, v52, v146
	v_fmac_f32_e32 v121, v52, v147
	v_fmac_f32_e32 v122, v52, v148
	v_fmac_f32_e32 v123, v52, v149
	s_waitcnt lgkmcnt(12)
	v_fmac_f32_e32 v120, v53, v150
	v_fmac_f32_e32 v121, v53, v151
	v_fmac_f32_e32 v122, v53, v152
	v_fmac_f32_e32 v123, v53, v153
	s_waitcnt lgkmcnt(11)
	v_fmac_f32_e32 v120, v54, v154
	v_fmac_f32_e32 v121, v54, v155
	v_fmac_f32_e32 v122, v54, v156
	v_fmac_f32_e32 v123, v54, v157
	s_waitcnt lgkmcnt(10)
	v_fmac_f32_e32 v120, v55, v158
	v_fmac_f32_e32 v121, v55, v159
	v_fmac_f32_e32 v122, v55, v160
	v_fmac_f32_e32 v123, v55, v161
	s_waitcnt lgkmcnt(9)
	v_fmac_f32_e32 v120, v56, v168
	v_fmac_f32_e32 v121, v56, v169
	v_fmac_f32_e32 v122, v56, v170
	v_fmac_f32_e32 v123, v56, v171
	s_waitcnt lgkmcnt(8)
	v_fmac_f32_e32 v120, v57, v172
	v_fmac_f32_e32 v121, v57, v173
	v_fmac_f32_e32 v122, v57, v174
	v_fmac_f32_e32 v123, v57, v175
	s_waitcnt lgkmcnt(7)
	v_fmac_f32_e32 v120, v58, v176
	v_fmac_f32_e32 v121, v58, v177
	v_fmac_f32_e32 v122, v58, v178
	v_fmac_f32_e32 v123, v58, v179
	s_waitcnt lgkmcnt(6)
	v_fmac_f32_e32 v120, v59, v180
	v_fmac_f32_e32 v121, v59, v181
	v_fmac_f32_e32 v122, v59, v182
	v_fmac_f32_e32 v123, v59, v183
	s_waitcnt lgkmcnt(5)
	v_fmac_f32_e32 v120, v60, v184
	v_fmac_f32_e32 v121, v60, v185
	v_fmac_f32_e32 v122, v60, v186
	v_fmac_f32_e32 v123, v60, v187
	s_waitcnt lgkmcnt(4)
	v_fmac_f32_e32 v120, v61, v188
	v_fmac_f32_e32 v121, v61, v189
	v_fmac_f32_e32 v122, v61, v190
	v_fmac_f32_e32 v123, v61, v191
	s_waitcnt lgkmcnt(3)
	v_fmac_f32_e32 v120, v62, v192
	v_fmac_f32_e32 v121, v62, v193
	v_fmac_f32_e32 v122, v62, v194
	v_fmac_f32_e32 v123, v62, v195
	s_waitcnt lgkmcnt(2)
	v_fmac_f32_e32 v120, v63, v224
	v_fmac_f32_e32 v121, v63, v225
	v_fmac_f32_e32 v122, v63, v226
	v_fmac_f32_e32 v123, v63, v227
	s_waitcnt lgkmcnt(1)
	v_fmac_f32_e32 v120, v64, v228
	v_fmac_f32_e32 v121, v64, v229
	v_fmac_f32_e32 v122, v64, v230
	v_fmac_f32_e32 v123, v64, v231
	s_waitcnt lgkmcnt(0)
	v_fmac_f32_e32 v120, v65, v232
	v_fmac_f32_e32 v121, v65, v233
	v_fmac_f32_e32 v122, v65, v234
	v_fmac_f32_e32 v123, v65, v235
	s_waitcnt vmcnt(0)
	v_mul_f32_e64 v132, v74, |v116|
	v_mul_f32_e64 v133, v74, |v117|
	v_mul_f32_e64 v84, v74, |v118|
	v_mul_f32_e64 v85, v74, |v119|
	v_mul_f32_e32 v132, 0x3fb8aa3b, v132
	v_mul_f32_e32 v133, 0x3fb8aa3b, v133
	v_mul_f32_e32 v84, 0x3fb8aa3b, v84
	v_mul_f32_e32 v85, 0x3fb8aa3b, v85
	v_exp_f32_e32 v132, v132
	v_exp_f32_e32 v133, v133
	v_exp_f32_e32 v84, v84
	v_exp_f32_e32 v85, v85
	v_mov_b32_e32 v124, v110
	v_mov_b32_e32 v125, v111
	v_or_b32_e32 v126, 1, v110
	v_mov_b32_e32 v127, v111
	v_or_b32_e32 v128, 2, v110
	v_mov_b32_e32 v129, v111
	v_or_b32_e32 v130, 3, v110
	v_mov_b32_e32 v131, v111
	v_lshlrev_b64 v[124:125], s30, v[124:125]
	v_lshlrev_b64 v[126:127], s30, v[126:127]
	v_lshlrev_b64 v[128:129], s30, v[128:129]
	v_lshlrev_b64 v[130:131], s30, v[130:131]
	v_lshl_add_u64 v[124:125], v[124:125], 2, v[66:67]
	v_lshl_add_u64 v[126:127], v[126:127], 2, v[66:67]
	v_lshl_add_u64 v[128:129], v[128:129], 2, v[66:67]
	v_lshl_add_u64 v[130:131], v[130:131], 2, v[66:67]
	v_mul_f32_e32 v120, v120, v132
	v_mul_f32_e32 v121, v121, v133
	v_mul_f32_e32 v122, v122, v84
	v_mul_f32_e32 v123, v123, v85
	global_store_dword v[124:125], v120, off
	global_store_dword v[126:127], v121, off
	global_store_dword v[128:129], v122, off
	global_store_dword v[130:131], v123, off
	s_add_i32 s0, s0, 1
	s_cmp_eq_u32 s0, 4
	s_cbranch_scc0 .LBB0_349
	s_add_i32 s0, s29, 1
	s_cmp_eq_u32 s29, s31
	s_mov_b32 s29, s0
	s_cbranch_scc0 .LBB0_345
	s_barrier

.LBB0_524:
	s_and_b64 vcc, exec, s[0:1]
	s_cbranch_vccz .LBB0_408
	s_lshr_b32 s0, s23, 1
	s_and_b32 s1, s23, 1
	v_lshrrev_b32_e32 v0, 6, v135
	v_readlane_b32 s32, v249, 47
	v_readlane_b32 s10, v251, 1
	v_readlane_b32 s11, v251, 2
	v_readfirstlane_b32 s4, v0
	s_nop 3
	s_sub_u32 s10, s10, 0x168
	s_subb_u32 s11, s11, 0
	s_load_dwordx4 s[16:19], s[10:11], 0xd8
	s_load_dwordx2 s[20:21], s[10:11], 0xe8
	s_lshl_b32 s6, s1, 3
	s_add_i32 s6, s6, s4
	v_and_b32_e32 v2, 63, v135
	v_lshrrev_b32_e32 v3, 4, v2
	v_and_b32_e32 v4, 15, v2
	v_lshlrev_b32_e32 v5, 11, v4
	v_lshl_add_u32 v5, v3, 4, v5
	v_lshlrev_b32_e32 v6, 4, v4
	v_lshl_add_u32 v6, v3, 11, v6
	v_lshlrev_b32_e32 v7, 3, v2
	v_lshlrev_b32_e32 v11, 2, v4
	v_lshl_add_u32 v11, v3, 13, v11
	v_add_u32_e32 v12, 0x1000, v11
	v_lshlrev_b32_e32 v13, 1, v4
	v_lshl_add_u32 v13, v3, 12, v13
	v_lshlrev_b32_e32 v14, 8, v4
	v_lshl_add_u32 v14, v3, 4, v14
	v_lshlrev_b32_e32 v15, 5, v3
	v_lshlrev_b32_e32 v16, 2, v4
	v_lshlrev_b32_e32 v10, 4, v3
	s_mul_i32 s54, s4, 0x1400
	s_add_i32 s54, s54, 0xc000
	v_lshl_add_u32 v8, v2, 2, s54
	v_lshl_add_u32 v9, v3, 4, s54
	s_mov_b32 s52, 0x00010001
	s_mov_b32 s53, 0x00010001
	s_add_i32 s55, s6, 0
	s_lshl_b32 s56, s55, 13
	s_add_u32 s12, s94, 0x12d96000
	s_addc_u32 s13, s95, 0
	s_add_u32 s12, s12, s56
	s_addc_u32 s13, s13, 0
	s_lshl_b32 s56, s55, 9
	s_add_u32 s50, s94, 0x12d92000
	s_addc_u32 s51, s95, 0
	s_add_u32 s50, s50, s56
	s_addc_u32 s51, s51, 0
	global_load_dwordx2 v[2:3], v7, s[50:51]
	s_add_i32 s55, s6, 16
	s_lshl_b32 s56, s55, 13
	s_add_u32 s14, s94, 0x12d96000
	s_addc_u32 s15, s95, 0
	s_add_u32 s14, s14, s56
	s_addc_u32 s15, s15, 0
	s_lshl_b32 s56, s55, 9
	s_add_u32 s50, s94, 0x12d92000
	s_addc_u32 s51, s95, 0
	s_add_u32 s50, s50, s56
	s_addc_u32 s51, s51, 0
	global_load_dwordx2 v[18:19], v7, s[50:51]
	s_waitcnt vmcnt(1)
	ds_write_b32 v8, v2 offset:0
	ds_write_b32 v8, v3 offset:256
	v_mul_f32_e32 v180, v3, v3
	v_mul_f32_e32 v181, v2, v3
	v_fma_f32 v2, v2, v2, -v180
	v_add_f32_e32 v3, v181, v181
	ds_write_b32 v8, v2 offset:512
	ds_write_b32 v8, v3 offset:768
	v_mul_f32_e32 v180, v3, v3
	v_mul_f32_e32 v181, v2, v3
	v_fma_f32 v2, v2, v2, -v180
	v_add_f32_e32 v3, v181, v181
	ds_write_b32 v8, v2 offset:1024
	ds_write_b32 v8, v3 offset:1280
	v_mul_f32_e32 v180, v3, v3
	v_mul_f32_e32 v181, v2, v3
	v_fma_f32 v2, v2, v2, -v180
	v_add_f32_e32 v3, v181, v181
	ds_write_b32 v8, v2 offset:1536
	ds_write_b32 v8, v3 offset:1792
	v_mul_f32_e32 v180, v3, v3
	v_mul_f32_e32 v181, v2, v3
	v_fma_f32 v2, v2, v2, -v180
	v_add_f32_e32 v3, v181, v181
	ds_write_b32 v8, v2 offset:2048
	ds_write_b32 v8, v3 offset:2304
	s_waitcnt vmcnt(0)
	ds_write_b32 v8, v18 offset:2560
	ds_write_b32 v8, v19 offset:2816
	v_mul_f32_e32 v180, v19, v19
	v_mul_f32_e32 v181, v18, v19
	v_fma_f32 v18, v18, v18, -v180
	v_add_f32_e32 v19, v181, v181
	ds_write_b32 v8, v18 offset:3072
	ds_write_b32 v8, v19 offset:3328
	v_mul_f32_e32 v180, v19, v19
	v_mul_f32_e32 v181, v18, v19
	v_fma_f32 v18, v18, v18, -v180
	v_add_f32_e32 v19, v181, v181
	ds_write_b32 v8, v18 offset:3584
	ds_write_b32 v8, v19 offset:3840
	v_mul_f32_e32 v180, v19, v19
	v_mul_f32_e32 v181, v18, v19
	v_fma_f32 v18, v18, v18, -v180
	v_add_f32_e32 v19, v181, v181
	ds_write_b32 v8, v18 offset:4096
	ds_write_b32 v8, v19 offset:4352
	v_mul_f32_e32 v180, v19, v19
	v_mul_f32_e32 v181, v18, v19
	v_fma_f32 v18, v18, v18, -v180
	v_add_f32_e32 v19, v181, v181
	ds_write_b32 v8, v18 offset:4608
	ds_write_b32 v8, v19 offset:4864
	s_waitcnt lgkmcnt(0)
	s_mov_b32 s10, 0x80008000
	s_mov_b32 s11, 0x80008000
	s_lshl_b32 s55, s32, 10
	s_lshl_b32 s56, s6, 6
	s_add_u32 s55, s55, s56
	s_add_u32 s20, s20, s55
	s_addc_u32 s21, s21, 0
	global_load_dword v0, v16, s[20:21]
	s_lshl_b32 s56, s32, 1
	s_add_i32 s56, s56, 1
	s_lshl_b32 s56, s56, 4
	s_add_i32 s56, s56, s6
	s_lshl_b32 s56, s56, 12
	s_add_u32 s24, s16, s56
	s_addc_u32 s25, s17, 0
	s_add_u32 s38, s18, s56
	s_addc_u32 s39, s19, 0
	s_lshl_b32 s56, s32, 1
	s_add_i32 s56, s56, 0
	s_lshl_b32 s56, s56, 4
	s_add_i32 s56, s56, s6
	s_lshl_b32 s56, s56, 12
	s_add_u32 s16, s16, s56
	s_addc_u32 s17, s17, 0
	s_add_u32 s18, s18, s56
	s_addc_u32 s19, s19, 0
	s_lshl_b32 s55, s0, 15
	s_add_i32 s56, s6, 0
	s_lshl_b32 s56, s56, 6
	s_add_u32 s55, s55, s56
	s_add_u32 s8, s94, 0x8a40000
	s_addc_u32 s9, s95, 0
	s_add_u32 s8, s8, s55
	s_addc_u32 s9, s9, 0
	global_load_dwordx4 v[184:187], v5, s[8:9] offset:0
	global_load_dwordx4 v[188:191], v5, s[8:9] offset:1024
	global_load_dwordx4 v[20:23], v6, s[12:13] offset:0
	global_load_dwordx4 v[24:27], v6, s[12:13] offset:1024
	global_load_dwordx4 v[28:31], v6, s[12:13] offset:256
	global_load_dwordx4 v[32:35], v6, s[12:13] offset:1280
	global_load_dwordx4 v[36:39], v6, s[12:13] offset:512
	global_load_dwordx4 v[40:43], v6, s[12:13] offset:1536
	global_load_dwordx4 v[44:47], v6, s[12:13] offset:768
	global_load_dwordx4 v[48:51], v6, s[12:13] offset:1792
	s_lshl_b32 s56, s0, 5
	s_add_i32 s55, s6, 0
	s_lshl_b32 s55, s55, 1
	s_add_i32 s56, s56, s55
	s_add_i32 s56, s56, 0
	s_lshl_b32 s56, s56, 9
	s_add_u32 s48, s94, 0x133d6000
	s_addc_u32 s49, s95, 0
	s_add_u32 s48, s48, s56
	s_addc_u32 s49, s49, 0
	global_load_dwordx4 v[52:55], v15, s[48:49] offset:0
	global_load_dwordx4 v[56:59], v15, s[48:49] offset:16
	global_load_dwordx4 v[60:63], v15, s[48:49] offset:128
	global_load_dwordx4 v[64:67], v15, s[48:49] offset:144
	global_load_dwordx4 v[68:71], v15, s[48:49] offset:256
	global_load_dwordx4 v[72:75], v15, s[48:49] offset:272
	global_load_dwordx4 v[76:79], v15, s[48:49] offset:384
	global_load_dwordx4 v[80:83], v15, s[48:49] offset:400
	s_waitcnt vmcnt(0)
	s_branch .Ls5b_body2
.Ls5b_head1:
	s_waitcnt vmcnt(8)
.Ls5b_body2:
	s_add_i32 s46, s23, s84
	s_cmp_lt_i32 s46, 768
	s_cselect_b32 s46, s46, s23
	s_lshr_b32 s1, s46, 1
	s_lshl_b32 s55, s0, 15
	s_add_i32 s56, s6, 0
	s_lshl_b32 s56, s56, 6
	s_add_u32 s55, s55, s56
	s_add_u32 s8, s94, 0x8a40000
	s_addc_u32 s9, s95, 0
	s_add_u32 s8, s8, s55
	s_addc_u32 s9, s9, 0
	s_lshl_b32 s55, s0, 14
	s_lshl_b32 s56, s6, 5
	s_add_u32 s55, s55, s56
	s_add_u32 s44, s94, 0x11640000
	s_addc_u32 s45, s95, 0
	s_add_u32 s44, s44, s55
	s_addc_u32 s45, s45, 0
	v_mfma_f32_16x16x4_f32 v[84:87], v20, v184, 0
	v_mfma_f32_16x16x4_f32 v[88:91], v21, v184, 0
	v_mfma_f32_16x16x4_f32 v[116:119], v20, v188, 0
	v_mfma_f32_16x16x4_f32 v[120:123], v21, v188, 0
	v_mfma_f32_16x16x4_f32 v[92:95], v28, v184, 0
	v_mfma_f32_16x16x4_f32 v[96:99], v29, v184, 0
	v_mfma_f32_16x16x4_f32 v[124:127], v28, v188, 0
	v_mfma_f32_16x16x4_f32 v[128:131], v29, v188, 0
	v_mfma_f32_16x16x4_f32 v[100:103], v36, v184, 0
	v_mfma_f32_16x16x4_f32 v[104:107], v37, v184, 0
	v_mfma_f32_16x16x4_f32 v[140:143], v36, v188, 0
	v_mfma_f32_16x16x4_f32 v[144:147], v37, v188, 0
	v_mfma_f32_16x16x4_f32 v[108:111], v44, v184, 0
	v_mfma_f32_16x16x4_f32 v[112:115], v45, v184, 0
	v_mfma_f32_16x16x4_f32 v[148:151], v44, v188, 0
	v_mfma_f32_16x16x4_f32 v[152:155], v45, v188, 0
	v_mfma_f32_16x16x4_f32 v[84:87], v22, v185, v[84:87]
	v_mfma_f32_16x16x4_f32 v[88:91], v23, v185, v[88:91]
	v_mfma_f32_16x16x4_f32 v[116:119], v22, v189, v[116:119]
	v_mfma_f32_16x16x4_f32 v[120:123], v23, v189, v[120:123]
	v_mfma_f32_16x16x4_f32 v[92:95], v30, v185, v[92:95]
	v_mfma_f32_16x16x4_f32 v[96:99], v31, v185, v[96:99]
	v_mfma_f32_16x16x4_f32 v[124:127], v30, v189, v[124:127]
	v_mfma_f32_16x16x4_f32 v[128:131], v31, v189, v[128:131]
	v_mfma_f32_16x16x4_f32 v[100:103], v38, v185, v[100:103]
	v_mfma_f32_16x16x4_f32 v[104:107], v39, v185, v[104:107]
	v_mfma_f32_16x16x4_f32 v[140:143], v38, v189, v[140:143]
	v_mfma_f32_16x16x4_f32 v[144:147], v39, v189, v[144:147]
	v_mfma_f32_16x16x4_f32 v[108:111], v46, v185, v[108:111]
	v_mfma_f32_16x16x4_f32 v[112:115], v47, v185, v[112:115]
	v_mfma_f32_16x16x4_f32 v[148:151], v46, v189, v[148:151]
	v_mfma_f32_16x16x4_f32 v[152:155], v47, v189, v[152:155]
	v_mfma_f32_16x16x4_f32 v[84:87], v24, v186, v[84:87]
	v_mfma_f32_16x16x4_f32 v[88:91], v25, v186, v[88:91]
	v_mfma_f32_16x16x4_f32 v[116:119], v24, v190, v[116:119]
	v_mfma_f32_16x16x4_f32 v[120:123], v25, v190, v[120:123]
	v_mfma_f32_16x16x4_f32 v[92:95], v32, v186, v[92:95]
	v_mfma_f32_16x16x4_f32 v[96:99], v33, v186, v[96:99]
	v_mfma_f32_16x16x4_f32 v[124:127], v32, v190, v[124:127]
	v_mfma_f32_16x16x4_f32 v[128:131], v33, v190, v[128:131]
	v_mfma_f32_16x16x4_f32 v[100:103], v40, v186, v[100:103]
	v_mfma_f32_16x16x4_f32 v[104:107], v41, v186, v[104:107]
	v_mfma_f32_16x16x4_f32 v[140:143], v40, v190, v[140:143]
	v_mfma_f32_16x16x4_f32 v[144:147], v41, v190, v[144:147]
	v_mfma_f32_16x16x4_f32 v[108:111], v48, v186, v[108:111]
	v_mfma_f32_16x16x4_f32 v[112:115], v49, v186, v[112:115]
	v_mfma_f32_16x16x4_f32 v[148:151], v48, v190, v[148:151]
	v_mfma_f32_16x16x4_f32 v[152:155], v49, v190, v[152:155]
	v_mfma_f32_16x16x4_f32 v[84:87], v26, v187, v[84:87]
	v_mfma_f32_16x16x4_f32 v[88:91], v27, v187, v[88:91]
	v_mfma_f32_16x16x4_f32 v[116:119], v26, v191, v[116:119]
	v_mfma_f32_16x16x4_f32 v[120:123], v27, v191, v[120:123]
	v_mfma_f32_16x16x4_f32 v[92:95], v34, v187, v[92:95]
	v_mfma_f32_16x16x4_f32 v[96:99], v35, v187, v[96:99]
	v_mfma_f32_16x16x4_f32 v[124:127], v34, v191, v[124:127]
	v_mfma_f32_16x16x4_f32 v[128:131], v35, v191, v[128:131]
	v_mfma_f32_16x16x4_f32 v[100:103], v42, v187, v[100:103]
	v_mfma_f32_16x16x4_f32 v[104:107], v43, v187, v[104:107]
	v_mfma_f32_16x16x4_f32 v[140:143], v42, v191, v[140:143]
	v_mfma_f32_16x16x4_f32 v[144:147], v43, v191, v[144:147]
	v_mfma_f32_16x16x4_f32 v[108:111], v50, v187, v[108:111]
	v_mfma_f32_16x16x4_f32 v[112:115], v51, v187, v[112:115]
	v_mfma_f32_16x16x4_f32 v[148:151], v50, v191, v[148:151]
	v_mfma_f32_16x16x4_f32 v[152:155], v51, v191, v[152:155]
	global_load_dwordx4 v[20:23], v14, s[16:17] offset:0
	global_load_dwordx4 v[24:27], v14, s[18:19] offset:0
	global_load_dwordx4 v[28:31], v14, s[16:17] offset:64
	global_load_dwordx4 v[32:35], v14, s[18:19] offset:64
	global_load_dwordx4 v[36:39], v14, s[16:17] offset:128
	global_load_dwordx4 v[40:43], v14, s[18:19] offset:128
	global_load_dwordx4 v[44:47], v14, s[16:17] offset:192
	global_load_dwordx4 v[48:51], v14, s[18:19] offset:192
	s_nop 9
	ds_read_b128 v[156:159], v9 offset:0
	ds_read_b128 v[168:171], v9 offset:256
	ds_read_b128 v[172:175], v9 offset:64
	ds_read_b128 v[176:179], v9 offset:320
	s_waitcnt lgkmcnt(2)
	s_mov_b64 exec, s[52:53]
	v_fmac_f32_e32 v84, v156, v52
	v_fmac_f32_e32 v85, v157, v54
	v_fmac_f32_e32 v86, v158, v56
	v_fmac_f32_e32 v87, v159, v58
	v_fma_f32 v84, -v168, v53, v84
	v_fma_f32 v85, -v169, v55, v85
	v_fma_f32 v86, -v170, v57, v86
	v_fma_f32 v87, -v171, v59, v87
	v_fmac_f32_e32 v88, v156, v53
	v_fmac_f32_e32 v89, v157, v55
	v_fmac_f32_e32 v90, v158, v57
	v_fmac_f32_e32 v91, v159, v59
	v_fmac_f32_e32 v88, v168, v52
	v_fmac_f32_e32 v89, v169, v54
	v_fmac_f32_e32 v90, v170, v56
	v_fmac_f32_e32 v91, v171, v58
	s_mov_b64 exec, -1
	v_fmac_f32_e32 v116, v156, v84
	v_fmac_f32_e32 v117, v157, v85
	v_fmac_f32_e32 v118, v158, v86
	v_fmac_f32_e32 v119, v159, v87
	v_fma_f32 v116, -v168, v88, v116
	v_fma_f32 v117, -v169, v89, v117
	v_fma_f32 v118, -v170, v90, v118
	v_fma_f32 v119, -v171, v91, v119
	v_fmac_f32_e32 v120, v156, v88
	v_fmac_f32_e32 v121, v157, v89
	v_fmac_f32_e32 v122, v158, v90
	v_fmac_f32_e32 v123, v159, v91
	v_fmac_f32_e32 v120, v168, v84
	v_fmac_f32_e32 v121, v169, v85
	v_fmac_f32_e32 v122, v170, v86
	v_fmac_f32_e32 v123, v171, v87
	ds_read_b128 v[156:159], v9 offset:128
	ds_read_b128 v[168:171], v9 offset:384
	s_waitcnt lgkmcnt(2)
	s_mov_b64 exec, s[52:53]
	v_fmac_f32_e32 v92, v172, v60
	v_fmac_f32_e32 v93, v173, v62
	v_fmac_f32_e32 v94, v174, v64
	v_fmac_f32_e32 v95, v175, v66
	v_fma_f32 v92, -v176, v61, v92
	v_fma_f32 v93, -v177, v63, v93
	v_fma_f32 v94, -v178, v65, v94
	v_fma_f32 v95, -v179, v67, v95
	v_fmac_f32_e32 v96, v172, v61
	v_fmac_f32_e32 v97, v173, v63
	v_fmac_f32_e32 v98, v174, v65
	v_fmac_f32_e32 v99, v175, v67
	v_fmac_f32_e32 v96, v176, v60
	v_fmac_f32_e32 v97, v177, v62
	v_fmac_f32_e32 v98, v178, v64
	v_fmac_f32_e32 v99, v179, v66
	s_mov_b64 exec, -1
	v_fmac_f32_e32 v124, v172, v92
	v_fmac_f32_e32 v125, v173, v93
	v_fmac_f32_e32 v126, v174, v94
	v_fmac_f32_e32 v127, v175, v95
	v_fma_f32 v124, -v176, v96, v124
	v_fma_f32 v125, -v177, v97, v125
	v_fma_f32 v126, -v178, v98, v126
	v_fma_f32 v127, -v179, v99, v127
	v_fmac_f32_e32 v128, v172, v96
	v_fmac_f32_e32 v129, v173, v97
	v_fmac_f32_e32 v130, v174, v98
	v_fmac_f32_e32 v131, v175, v99
	v_fmac_f32_e32 v128, v176, v92
	v_fmac_f32_e32 v129, v177, v93
	v_fmac_f32_e32 v130, v178, v94
	v_fmac_f32_e32 v131, v179, v95
	ds_read_b128 v[172:175], v9 offset:192
	ds_read_b128 v[176:179], v9 offset:448
	s_waitcnt lgkmcnt(2)
	s_mov_b64 exec, s[52:53]
	v_fmac_f32_e32 v100, v156, v68
	v_fmac_f32_e32 v101, v157, v70
	v_fmac_f32_e32 v102, v158, v72
	v_fmac_f32_e32 v103, v159, v74
	v_fma_f32 v100, -v168, v69, v100
	v_fma_f32 v101, -v169, v71, v101
	v_fma_f32 v102, -v170, v73, v102
	v_fma_f32 v103, -v171, v75, v103
	v_fmac_f32_e32 v104, v156, v69
	v_fmac_f32_e32 v105, v157, v71
	v_fmac_f32_e32 v106, v158, v73
	v_fmac_f32_e32 v107, v159, v75
	v_fmac_f32_e32 v104, v168, v68
	v_fmac_f32_e32 v105, v169, v70
	v_fmac_f32_e32 v106, v170, v72
	v_fmac_f32_e32 v107, v171, v74
	s_mov_b64 exec, -1
	v_fmac_f32_e32 v140, v156, v100
	v_fmac_f32_e32 v141, v157, v101
	v_fmac_f32_e32 v142, v158, v102
	v_fmac_f32_e32 v143, v159, v103
	v_fma_f32 v140, -v168, v104, v140
	v_fma_f32 v141, -v169, v105, v141
	v_fma_f32 v142, -v170, v106, v142
	v_fma_f32 v143, -v171, v107, v143
	v_fmac_f32_e32 v144, v156, v104
	v_fmac_f32_e32 v145, v157, v105
	v_fmac_f32_e32 v146, v158, v106
	v_fmac_f32_e32 v147, v159, v107
	v_fmac_f32_e32 v144, v168, v100
	v_fmac_f32_e32 v145, v169, v101
	v_fmac_f32_e32 v146, v170, v102
	v_fmac_f32_e32 v147, v171, v103
	s_waitcnt lgkmcnt(0)
	s_mov_b64 exec, s[52:53]
	v_fmac_f32_e32 v108, v172, v76
	v_fmac_f32_e32 v109, v173, v78
	v_fmac_f32_e32 v110, v174, v80
	v_fmac_f32_e32 v111, v175, v82
	v_fma_f32 v108, -v176, v77, v108
	v_fma_f32 v109, -v177, v79, v109
	v_fma_f32 v110, -v178, v81, v110
	v_fma_f32 v111, -v179, v83, v111
	v_fmac_f32_e32 v112, v172, v77
	v_fmac_f32_e32 v113, v173, v79
	v_fmac_f32_e32 v114, v174, v81
	v_fmac_f32_e32 v115, v175, v83
	v_fmac_f32_e32 v112, v176, v76
	v_fmac_f32_e32 v113, v177, v78
	v_fmac_f32_e32 v114, v178, v80
	v_fmac_f32_e32 v115, v179, v82
	s_mov_b64 exec, -1
	v_fmac_f32_e32 v148, v172, v108
	v_fmac_f32_e32 v149, v173, v109
	v_fmac_f32_e32 v150, v174, v110
	v_fmac_f32_e32 v151, v175, v111
	v_fma_f32 v148, -v176, v112, v148
	v_fma_f32 v149, -v177, v113, v149
	v_fma_f32 v150, -v178, v114, v150
	v_fma_f32 v151, -v179, v115, v151
	v_fmac_f32_e32 v152, v172, v112
	v_fmac_f32_e32 v153, v173, v113
	v_fmac_f32_e32 v154, v174, v114
	v_fmac_f32_e32 v155, v175, v115
	v_fmac_f32_e32 v152, v176, v108
	v_fmac_f32_e32 v153, v177, v109
	v_fmac_f32_e32 v154, v178, v110
	v_fmac_f32_e32 v155, v179, v111
	global_load_dwordx4 v[52:55], v6, s[14:15] offset:0
	global_load_dwordx4 v[56:59], v6, s[14:15] offset:1024
	global_load_dwordx4 v[60:63], v6, s[14:15] offset:256
	global_load_dwordx4 v[64:67], v6, s[14:15] offset:1280
	global_load_dwordx4 v[68:71], v6, s[14:15] offset:512
	global_load_dwordx4 v[72:75], v6, s[14:15] offset:1536
	global_load_dwordx4 v[76:79], v6, s[14:15] offset:768
	global_load_dwordx4 v[80:83], v6, s[14:15] offset:1792
	ds_read_b128 v[156:159], v9 offset:512
	ds_read_b128 v[168:171], v9 offset:768
	ds_read_b128 v[172:175], v9 offset:576
	ds_read_b128 v[176:179], v9 offset:832
	s_waitcnt lgkmcnt(2)
	v_mov_b32_e32 v180, v116
	v_mov_b32_e32 v181, v117
	v_mov_b32_e32 v182, v118
	v_mov_b32_e32 v183, v119
	s_nop 1
	v_fmac_f32_dpp v116, v116, v156 row_shr:1 row_mask:0xf bank_mask:0xf bound_ctrl:0
	v_fmac_f32_dpp v117, v117, v157 row_shr:1 row_mask:0xf bank_mask:0xf bound_ctrl:0
	v_fmac_f32_dpp v118, v118, v158 row_shr:1 row_mask:0xf bank_mask:0xf bound_ctrl:0
	v_fmac_f32_dpp v119, v119, v159 row_shr:1 row_mask:0xf bank_mask:0xf bound_ctrl:0
	v_fmac_f32_dpp v116, v120, -v168 row_shr:1 row_mask:0xf bank_mask:0xf bound_ctrl:0
	v_fmac_f32_dpp v117, v121, -v169 row_shr:1 row_mask:0xf bank_mask:0xf bound_ctrl:0
	v_fmac_f32_dpp v118, v122, -v170 row_shr:1 row_mask:0xf bank_mask:0xf bound_ctrl:0
	v_fmac_f32_dpp v119, v123, -v171 row_shr:1 row_mask:0xf bank_mask:0xf bound_ctrl:0
	v_fmac_f32_dpp v120, v120, v156 row_shr:1 row_mask:0xf bank_mask:0xf bound_ctrl:0
	v_fmac_f32_dpp v121, v121, v157 row_shr:1 row_mask:0xf bank_mask:0xf bound_ctrl:0
	v_fmac_f32_dpp v122, v122, v158 row_shr:1 row_mask:0xf bank_mask:0xf bound_ctrl:0
	v_fmac_f32_dpp v123, v123, v159 row_shr:1 row_mask:0xf bank_mask:0xf bound_ctrl:0
	v_fmac_f32_dpp v120, v180, v168 row_shr:1 row_mask:0xf bank_mask:0xf bound_ctrl:0
	v_fmac_f32_dpp v121, v181, v169 row_shr:1 row_mask:0xf bank_mask:0xf bound_ctrl:0
	v_fmac_f32_dpp v122, v182, v170 row_shr:1 row_mask:0xf bank_mask:0xf bound_ctrl:0
	v_fmac_f32_dpp v123, v183, v171 row_shr:1 row_mask:0xf bank_mask:0xf bound_ctrl:0
	ds_read_b128 v[156:159], v9 offset:640
	ds_read_b128 v[168:171], v9 offset:896
	s_waitcnt lgkmcnt(2)
	v_mov_b32_e32 v180, v124
	v_mov_b32_e32 v181, v125
	v_mov_b32_e32 v182, v126
	v_mov_b32_e32 v183, v127
	v_fmac_f32_dpp v124, v124, v172 row_shr:1 row_mask:0xf bank_mask:0xf bound_ctrl:0
	v_fmac_f32_dpp v125, v125, v173 row_shr:1 row_mask:0xf bank_mask:0xf bound_ctrl:0
	v_fmac_f32_dpp v126, v126, v174 row_shr:1 row_mask:0xf bank_mask:0xf bound_ctrl:0
	v_fmac_f32_dpp v127, v127, v175 row_shr:1 row_mask:0xf bank_mask:0xf bound_ctrl:0
	v_fmac_f32_dpp v124, v128, -v176 row_shr:1 row_mask:0xf bank_mask:0xf bound_ctrl:0
	v_fmac_f32_dpp v125, v129, -v177 row_shr:1 row_mask:0xf bank_mask:0xf bound_ctrl:0
	v_fmac_f32_dpp v126, v130, -v178 row_shr:1 row_mask:0xf bank_mask:0xf bound_ctrl:0
	v_fmac_f32_dpp v127, v131, -v179 row_shr:1 row_mask:0xf bank_mask:0xf bound_ctrl:0
	v_fmac_f32_dpp v128, v128, v172 row_shr:1 row_mask:0xf bank_mask:0xf bound_ctrl:0
	v_fmac_f32_dpp v129, v129, v173 row_shr:1 row_mask:0xf bank_mask:0xf bound_ctrl:0
	v_fmac_f32_dpp v130, v130, v174 row_shr:1 row_mask:0xf bank_mask:0xf bound_ctrl:0
	v_fmac_f32_dpp v131, v131, v175 row_shr:1 row_mask:0xf bank_mask:0xf bound_ctrl:0
	v_fmac_f32_dpp v128, v180, v176 row_shr:1 row_mask:0xf bank_mask:0xf bound_ctrl:0
	v_fmac_f32_dpp v129, v181, v177 row_shr:1 row_mask:0xf bank_mask:0xf bound_ctrl:0
	v_fmac_f32_dpp v130, v182, v178 row_shr:1 row_mask:0xf bank_mask:0xf bound_ctrl:0
	v_fmac_f32_dpp v131, v183, v179 row_shr:1 row_mask:0xf bank_mask:0xf bound_ctrl:0
	ds_read_b128 v[172:175], v9 offset:704
	ds_read_b128 v[176:179], v9 offset:960
	s_waitcnt lgkmcnt(2)
	v_mov_b32_e32 v180, v140
	v_mov_b32_e32 v181, v141
	v_mov_b32_e32 v182, v142
	v_mov_b32_e32 v183, v143
	v_fmac_f32_dpp v140, v140, v156 row_shr:1 row_mask:0xf bank_mask:0xf bound_ctrl:0
	v_fmac_f32_dpp v141, v141, v157 row_shr:1 row_mask:0xf bank_mask:0xf bound_ctrl:0
	v_fmac_f32_dpp v142, v142, v158 row_shr:1 row_mask:0xf bank_mask:0xf bound_ctrl:0
	v_fmac_f32_dpp v143, v143, v159 row_shr:1 row_mask:0xf bank_mask:0xf bound_ctrl:0
	v_fmac_f32_dpp v140, v144, -v168 row_shr:1 row_mask:0xf bank_mask:0xf bound_ctrl:0
	v_fmac_f32_dpp v141, v145, -v169 row_shr:1 row_mask:0xf bank_mask:0xf bound_ctrl:0
	v_fmac_f32_dpp v142, v146, -v170 row_shr:1 row_mask:0xf bank_mask:0xf bound_ctrl:0
	v_fmac_f32_dpp v143, v147, -v171 row_shr:1 row_mask:0xf bank_mask:0xf bound_ctrl:0
	v_fmac_f32_dpp v144, v144, v156 row_shr:1 row_mask:0xf bank_mask:0xf bound_ctrl:0
	v_fmac_f32_dpp v145, v145, v157 row_shr:1 row_mask:0xf bank_mask:0xf bound_ctrl:0
	v_fmac_f32_dpp v146, v146, v158 row_shr:1 row_mask:0xf bank_mask:0xf bound_ctrl:0
	v_fmac_f32_dpp v147, v147, v159 row_shr:1 row_mask:0xf bank_mask:0xf bound_ctrl:0
	v_fmac_f32_dpp v144, v180, v168 row_shr:1 row_mask:0xf bank_mask:0xf bound_ctrl:0
	v_fmac_f32_dpp v145, v181, v169 row_shr:1 row_mask:0xf bank_mask:0xf bound_ctrl:0
	v_fmac_f32_dpp v146, v182, v170 row_shr:1 row_mask:0xf bank_mask:0xf bound_ctrl:0
	v_fmac_f32_dpp v147, v183, v171 row_shr:1 row_mask:0xf bank_mask:0xf bound_ctrl:0
	ds_read_b128 v[156:159], v9 offset:1024
	ds_read_b128 v[168:171], v9 offset:1280
	s_waitcnt lgkmcnt(2)
	v_mov_b32_e32 v180, v148
	v_mov_b32_e32 v181, v149
	v_mov_b32_e32 v182, v150
	v_mov_b32_e32 v183, v151
	v_fmac_f32_dpp v148, v148, v172 row_shr:1 row_mask:0xf bank_mask:0xf bound_ctrl:0
	v_fmac_f32_dpp v149, v149, v173 row_shr:1 row_mask:0xf bank_mask:0xf bound_ctrl:0
	v_fmac_f32_dpp v150, v150, v174 row_shr:1 row_mask:0xf bank_mask:0xf bound_ctrl:0
	v_fmac_f32_dpp v151, v151, v175 row_shr:1 row_mask:0xf bank_mask:0xf bound_ctrl:0
	v_fmac_f32_dpp v148, v152, -v176 row_shr:1 row_mask:0xf bank_mask:0xf bound_ctrl:0
	v_fmac_f32_dpp v149, v153, -v177 row_shr:1 row_mask:0xf bank_mask:0xf bound_ctrl:0
	v_fmac_f32_dpp v150, v154, -v178 row_shr:1 row_mask:0xf bank_mask:0xf bound_ctrl:0
	v_fmac_f32_dpp v151, v155, -v179 row_shr:1 row_mask:0xf bank_mask:0xf bound_ctrl:0
	v_fmac_f32_dpp v152, v152, v172 row_shr:1 row_mask:0xf bank_mask:0xf bound_ctrl:0
	v_fmac_f32_dpp v153, v153, v173 row_shr:1 row_mask:0xf bank_mask:0xf bound_ctrl:0
	v_fmac_f32_dpp v154, v154, v174 row_shr:1 row_mask:0xf bank_mask:0xf bound_ctrl:0
	v_fmac_f32_dpp v155, v155, v175 row_shr:1 row_mask:0xf bank_mask:0xf bound_ctrl:0
	v_fmac_f32_dpp v152, v180, v176 row_shr:1 row_mask:0xf bank_mask:0xf bound_ctrl:0
	v_fmac_f32_dpp v153, v181, v177 row_shr:1 row_mask:0xf bank_mask:0xf bound_ctrl:0
	v_fmac_f32_dpp v154, v182, v178 row_shr:1 row_mask:0xf bank_mask:0xf bound_ctrl:0
	v_fmac_f32_dpp v155, v183, v179 row_shr:1 row_mask:0xf bank_mask:0xf bound_ctrl:0
	ds_read_b128 v[172:175], v9 offset:1088
	ds_read_b128 v[176:179], v9 offset:1344
	s_waitcnt lgkmcnt(2)
	v_mov_b32_e32 v180, v116
	v_mov_b32_e32 v181, v117
	v_mov_b32_e32 v182, v118
	v_mov_b32_e32 v183, v119
	v_fmac_f32_dpp v116, v116, v156 row_shr:2 row_mask:0xf bank_mask:0xf bound_ctrl:0
	v_fmac_f32_dpp v117, v117, v157 row_shr:2 row_mask:0xf bank_mask:0xf bound_ctrl:0
	v_fmac_f32_dpp v118, v118, v158 row_shr:2 row_mask:0xf bank_mask:0xf bound_ctrl:0
	v_fmac_f32_dpp v119, v119, v159 row_shr:2 row_mask:0xf bank_mask:0xf bound_ctrl:0
	v_fmac_f32_dpp v116, v120, -v168 row_shr:2 row_mask:0xf bank_mask:0xf bound_ctrl:0
	v_fmac_f32_dpp v117, v121, -v169 row_shr:2 row_mask:0xf bank_mask:0xf bound_ctrl:0
	v_fmac_f32_dpp v118, v122, -v170 row_shr:2 row_mask:0xf bank_mask:0xf bound_ctrl:0
	v_fmac_f32_dpp v119, v123, -v171 row_shr:2 row_mask:0xf bank_mask:0xf bound_ctrl:0
	v_fmac_f32_dpp v120, v120, v156 row_shr:2 row_mask:0xf bank_mask:0xf bound_ctrl:0
	v_fmac_f32_dpp v121, v121, v157 row_shr:2 row_mask:0xf bank_mask:0xf bound_ctrl:0
	v_fmac_f32_dpp v122, v122, v158 row_shr:2 row_mask:0xf bank_mask:0xf bound_ctrl:0
	v_fmac_f32_dpp v123, v123, v159 row_shr:2 row_mask:0xf bank_mask:0xf bound_ctrl:0
	v_fmac_f32_dpp v120, v180, v168 row_shr:2 row_mask:0xf bank_mask:0xf bound_ctrl:0
	v_fmac_f32_dpp v121, v181, v169 row_shr:2 row_mask:0xf bank_mask:0xf bound_ctrl:0
	v_fmac_f32_dpp v122, v182, v170 row_shr:2 row_mask:0xf bank_mask:0xf bound_ctrl:0
	v_fmac_f32_dpp v123, v183, v171 row_shr:2 row_mask:0xf bank_mask:0xf bound_ctrl:0
	ds_read_b128 v[156:159], v9 offset:1152
	ds_read_b128 v[168:171], v9 offset:1408
	s_waitcnt lgkmcnt(2)
	v_mov_b32_e32 v180, v124
	v_mov_b32_e32 v181, v125
	v_mov_b32_e32 v182, v126
	v_mov_b32_e32 v183, v127
	v_fmac_f32_dpp v124, v124, v172 row_shr:2 row_mask:0xf bank_mask:0xf bound_ctrl:0
	v_fmac_f32_dpp v125, v125, v173 row_shr:2 row_mask:0xf bank_mask:0xf bound_ctrl:0
	v_fmac_f32_dpp v126, v126, v174 row_shr:2 row_mask:0xf bank_mask:0xf bound_ctrl:0
	v_fmac_f32_dpp v127, v127, v175 row_shr:2 row_mask:0xf bank_mask:0xf bound_ctrl:0
	v_fmac_f32_dpp v124, v128, -v176 row_shr:2 row_mask:0xf bank_mask:0xf bound_ctrl:0
	v_fmac_f32_dpp v125, v129, -v177 row_shr:2 row_mask:0xf bank_mask:0xf bound_ctrl:0
	v_fmac_f32_dpp v126, v130, -v178 row_shr:2 row_mask:0xf bank_mask:0xf bound_ctrl:0
	v_fmac_f32_dpp v127, v131, -v179 row_shr:2 row_mask:0xf bank_mask:0xf bound_ctrl:0
	v_fmac_f32_dpp v128, v128, v172 row_shr:2 row_mask:0xf bank_mask:0xf bound_ctrl:0
	v_fmac_f32_dpp v129, v129, v173 row_shr:2 row_mask:0xf bank_mask:0xf bound_ctrl:0
	v_fmac_f32_dpp v130, v130, v174 row_shr:2 row_mask:0xf bank_mask:0xf bound_ctrl:0
	v_fmac_f32_dpp v131, v131, v175 row_shr:2 row_mask:0xf bank_mask:0xf bound_ctrl:0
	v_fmac_f32_dpp v128, v180, v176 row_shr:2 row_mask:0xf bank_mask:0xf bound_ctrl:0
	v_fmac_f32_dpp v129, v181, v177 row_shr:2 row_mask:0xf bank_mask:0xf bound_ctrl:0
	v_fmac_f32_dpp v130, v182, v178 row_shr:2 row_mask:0xf bank_mask:0xf bound_ctrl:0
	v_fmac_f32_dpp v131, v183, v179 row_shr:2 row_mask:0xf bank_mask:0xf bound_ctrl:0
	ds_read_b128 v[172:175], v9 offset:1216
	ds_read_b128 v[176:179], v9 offset:1472
	s_waitcnt lgkmcnt(2)
	v_mov_b32_e32 v180, v140
	v_mov_b32_e32 v181, v141
	v_mov_b32_e32 v182, v142
	v_mov_b32_e32 v183, v143
	v_fmac_f32_dpp v140, v140, v156 row_shr:2 row_mask:0xf bank_mask:0xf bound_ctrl:0
	v_fmac_f32_dpp v141, v141, v157 row_shr:2 row_mask:0xf bank_mask:0xf bound_ctrl:0
	v_fmac_f32_dpp v142, v142, v158 row_shr:2 row_mask:0xf bank_mask:0xf bound_ctrl:0
	v_fmac_f32_dpp v143, v143, v159 row_shr:2 row_mask:0xf bank_mask:0xf bound_ctrl:0
	v_fmac_f32_dpp v140, v144, -v168 row_shr:2 row_mask:0xf bank_mask:0xf bound_ctrl:0
	v_fmac_f32_dpp v141, v145, -v169 row_shr:2 row_mask:0xf bank_mask:0xf bound_ctrl:0
	v_fmac_f32_dpp v142, v146, -v170 row_shr:2 row_mask:0xf bank_mask:0xf bound_ctrl:0
	v_fmac_f32_dpp v143, v147, -v171 row_shr:2 row_mask:0xf bank_mask:0xf bound_ctrl:0
	v_fmac_f32_dpp v144, v144, v156 row_shr:2 row_mask:0xf bank_mask:0xf bound_ctrl:0
	v_fmac_f32_dpp v145, v145, v157 row_shr:2 row_mask:0xf bank_mask:0xf bound_ctrl:0
	v_fmac_f32_dpp v146, v146, v158 row_shr:2 row_mask:0xf bank_mask:0xf bound_ctrl:0
	v_fmac_f32_dpp v147, v147, v159 row_shr:2 row_mask:0xf bank_mask:0xf bound_ctrl:0
	v_fmac_f32_dpp v144, v180, v168 row_shr:2 row_mask:0xf bank_mask:0xf bound_ctrl:0
	v_fmac_f32_dpp v145, v181, v169 row_shr:2 row_mask:0xf bank_mask:0xf bound_ctrl:0
	v_fmac_f32_dpp v146, v182, v170 row_shr:2 row_mask:0xf bank_mask:0xf bound_ctrl:0
	v_fmac_f32_dpp v147, v183, v171 row_shr:2 row_mask:0xf bank_mask:0xf bound_ctrl:0
	ds_read_b128 v[156:159], v9 offset:1536
	ds_read_b128 v[168:171], v9 offset:1792
	s_waitcnt lgkmcnt(2)
	v_mov_b32_e32 v180, v148
	v_mov_b32_e32 v181, v149
	v_mov_b32_e32 v182, v150
	v_mov_b32_e32 v183, v151
	v_fmac_f32_dpp v148, v148, v172 row_shr:2 row_mask:0xf bank_mask:0xf bound_ctrl:0
	v_fmac_f32_dpp v149, v149, v173 row_shr:2 row_mask:0xf bank_mask:0xf bound_ctrl:0
	v_fmac_f32_dpp v150, v150, v174 row_shr:2 row_mask:0xf bank_mask:0xf bound_ctrl:0
	v_fmac_f32_dpp v151, v151, v175 row_shr:2 row_mask:0xf bank_mask:0xf bound_ctrl:0
	v_fmac_f32_dpp v148, v152, -v176 row_shr:2 row_mask:0xf bank_mask:0xf bound_ctrl:0
	v_fmac_f32_dpp v149, v153, -v177 row_shr:2 row_mask:0xf bank_mask:0xf bound_ctrl:0
	v_fmac_f32_dpp v150, v154, -v178 row_shr:2 row_mask:0xf bank_mask:0xf bound_ctrl:0
	v_fmac_f32_dpp v151, v155, -v179 row_shr:2 row_mask:0xf bank_mask:0xf bound_ctrl:0
	v_fmac_f32_dpp v152, v152, v172 row_shr:2 row_mask:0xf bank_mask:0xf bound_ctrl:0
	v_fmac_f32_dpp v153, v153, v173 row_shr:2 row_mask:0xf bank_mask:0xf bound_ctrl:0
	v_fmac_f32_dpp v154, v154, v174 row_shr:2 row_mask:0xf bank_mask:0xf bound_ctrl:0
	v_fmac_f32_dpp v155, v155, v175 row_shr:2 row_mask:0xf bank_mask:0xf bound_ctrl:0
	v_fmac_f32_dpp v152, v180, v176 row_shr:2 row_mask:0xf bank_mask:0xf bound_ctrl:0
	v_fmac_f32_dpp v153, v181, v177 row_shr:2 row_mask:0xf bank_mask:0xf bound_ctrl:0
	v_fmac_f32_dpp v154, v182, v178 row_shr:2 row_mask:0xf bank_mask:0xf bound_ctrl:0
	v_fmac_f32_dpp v155, v183, v179 row_shr:2 row_mask:0xf bank_mask:0xf bound_ctrl:0
	ds_read_b128 v[172:175], v9 offset:1600
	ds_read_b128 v[176:179], v9 offset:1856
	s_waitcnt lgkmcnt(2)
	v_mov_b32_e32 v180, v116
	v_mov_b32_e32 v181, v117
	v_mov_b32_e32 v182, v118
	v_mov_b32_e32 v183, v119
	v_fmac_f32_dpp v116, v116, v156 row_shr:4 row_mask:0xf bank_mask:0xf bound_ctrl:0
	v_fmac_f32_dpp v117, v117, v157 row_shr:4 row_mask:0xf bank_mask:0xf bound_ctrl:0
	v_fmac_f32_dpp v118, v118, v158 row_shr:4 row_mask:0xf bank_mask:0xf bound_ctrl:0
	v_fmac_f32_dpp v119, v119, v159 row_shr:4 row_mask:0xf bank_mask:0xf bound_ctrl:0
	v_fmac_f32_dpp v116, v120, -v168 row_shr:4 row_mask:0xf bank_mask:0xf bound_ctrl:0
	v_fmac_f32_dpp v117, v121, -v169 row_shr:4 row_mask:0xf bank_mask:0xf bound_ctrl:0
	v_fmac_f32_dpp v118, v122, -v170 row_shr:4 row_mask:0xf bank_mask:0xf bound_ctrl:0
	v_fmac_f32_dpp v119, v123, -v171 row_shr:4 row_mask:0xf bank_mask:0xf bound_ctrl:0
	v_fmac_f32_dpp v120, v120, v156 row_shr:4 row_mask:0xf bank_mask:0xf bound_ctrl:0
	v_fmac_f32_dpp v121, v121, v157 row_shr:4 row_mask:0xf bank_mask:0xf bound_ctrl:0
	v_fmac_f32_dpp v122, v122, v158 row_shr:4 row_mask:0xf bank_mask:0xf bound_ctrl:0
	v_fmac_f32_dpp v123, v123, v159 row_shr:4 row_mask:0xf bank_mask:0xf bound_ctrl:0
	v_fmac_f32_dpp v120, v180, v168 row_shr:4 row_mask:0xf bank_mask:0xf bound_ctrl:0
	v_fmac_f32_dpp v121, v181, v169 row_shr:4 row_mask:0xf bank_mask:0xf bound_ctrl:0
	v_fmac_f32_dpp v122, v182, v170 row_shr:4 row_mask:0xf bank_mask:0xf bound_ctrl:0
	v_fmac_f32_dpp v123, v183, v171 row_shr:4 row_mask:0xf bank_mask:0xf bound_ctrl:0
	ds_read_b128 v[156:159], v9 offset:1664
	ds_read_b128 v[168:171], v9 offset:1920
	s_waitcnt lgkmcnt(2)
	v_mov_b32_e32 v180, v124
	v_mov_b32_e32 v181, v125
	v_mov_b32_e32 v182, v126
	v_mov_b32_e32 v183, v127
	v_fmac_f32_dpp v124, v124, v172 row_shr:4 row_mask:0xf bank_mask:0xf bound_ctrl:0
	v_fmac_f32_dpp v125, v125, v173 row_shr:4 row_mask:0xf bank_mask:0xf bound_ctrl:0
	v_fmac_f32_dpp v126, v126, v174 row_shr:4 row_mask:0xf bank_mask:0xf bound_ctrl:0
	v_fmac_f32_dpp v127, v127, v175 row_shr:4 row_mask:0xf bank_mask:0xf bound_ctrl:0
	v_fmac_f32_dpp v124, v128, -v176 row_shr:4 row_mask:0xf bank_mask:0xf bound_ctrl:0
	v_fmac_f32_dpp v125, v129, -v177 row_shr:4 row_mask:0xf bank_mask:0xf bound_ctrl:0
	v_fmac_f32_dpp v126, v130, -v178 row_shr:4 row_mask:0xf bank_mask:0xf bound_ctrl:0
	v_fmac_f32_dpp v127, v131, -v179 row_shr:4 row_mask:0xf bank_mask:0xf bound_ctrl:0
	v_fmac_f32_dpp v128, v128, v172 row_shr:4 row_mask:0xf bank_mask:0xf bound_ctrl:0
	v_fmac_f32_dpp v129, v129, v173 row_shr:4 row_mask:0xf bank_mask:0xf bound_ctrl:0
	v_fmac_f32_dpp v130, v130, v174 row_shr:4 row_mask:0xf bank_mask:0xf bound_ctrl:0
	v_fmac_f32_dpp v131, v131, v175 row_shr:4 row_mask:0xf bank_mask:0xf bound_ctrl:0
	v_fmac_f32_dpp v128, v180, v176 row_shr:4 row_mask:0xf bank_mask:0xf bound_ctrl:0
	v_fmac_f32_dpp v129, v181, v177 row_shr:4 row_mask:0xf bank_mask:0xf bound_ctrl:0
	v_fmac_f32_dpp v130, v182, v178 row_shr:4 row_mask:0xf bank_mask:0xf bound_ctrl:0
	v_fmac_f32_dpp v131, v183, v179 row_shr:4 row_mask:0xf bank_mask:0xf bound_ctrl:0
	ds_read_b128 v[172:175], v9 offset:1728
	ds_read_b128 v[176:179], v9 offset:1984
	s_waitcnt lgkmcnt(2)
	v_mov_b32_e32 v180, v140
	v_mov_b32_e32 v181, v141
	v_mov_b32_e32 v182, v142
	v_mov_b32_e32 v183, v143
	v_fmac_f32_dpp v140, v140, v156 row_shr:4 row_mask:0xf bank_mask:0xf bound_ctrl:0
	v_fmac_f32_dpp v141, v141, v157 row_shr:4 row_mask:0xf bank_mask:0xf bound_ctrl:0
	v_fmac_f32_dpp v142, v142, v158 row_shr:4 row_mask:0xf bank_mask:0xf bound_ctrl:0
	v_fmac_f32_dpp v143, v143, v159 row_shr:4 row_mask:0xf bank_mask:0xf bound_ctrl:0
	v_fmac_f32_dpp v140, v144, -v168 row_shr:4 row_mask:0xf bank_mask:0xf bound_ctrl:0
	v_fmac_f32_dpp v141, v145, -v169 row_shr:4 row_mask:0xf bank_mask:0xf bound_ctrl:0
	v_fmac_f32_dpp v142, v146, -v170 row_shr:4 row_mask:0xf bank_mask:0xf bound_ctrl:0
	v_fmac_f32_dpp v143, v147, -v171 row_shr:4 row_mask:0xf bank_mask:0xf bound_ctrl:0
	v_fmac_f32_dpp v144, v144, v156 row_shr:4 row_mask:0xf bank_mask:0xf bound_ctrl:0
	v_fmac_f32_dpp v145, v145, v157 row_shr:4 row_mask:0xf bank_mask:0xf bound_ctrl:0
	v_fmac_f32_dpp v146, v146, v158 row_shr:4 row_mask:0xf bank_mask:0xf bound_ctrl:0
	v_fmac_f32_dpp v147, v147, v159 row_shr:4 row_mask:0xf bank_mask:0xf bound_ctrl:0
	v_fmac_f32_dpp v144, v180, v168 row_shr:4 row_mask:0xf bank_mask:0xf bound_ctrl:0
	v_fmac_f32_dpp v145, v181, v169 row_shr:4 row_mask:0xf bank_mask:0xf bound_ctrl:0
	v_fmac_f32_dpp v146, v182, v170 row_shr:4 row_mask:0xf bank_mask:0xf bound_ctrl:0
	v_fmac_f32_dpp v147, v183, v171 row_shr:4 row_mask:0xf bank_mask:0xf bound_ctrl:0
	ds_read_b128 v[156:159], v9 offset:2048
	ds_read_b128 v[168:171], v9 offset:2304
	s_waitcnt lgkmcnt(2)
	v_mov_b32_e32 v180, v148
	v_mov_b32_e32 v181, v149
	v_mov_b32_e32 v182, v150
	v_mov_b32_e32 v183, v151
	v_fmac_f32_dpp v148, v148, v172 row_shr:4 row_mask:0xf bank_mask:0xf bound_ctrl:0
	v_fmac_f32_dpp v149, v149, v173 row_shr:4 row_mask:0xf bank_mask:0xf bound_ctrl:0
	v_fmac_f32_dpp v150, v150, v174 row_shr:4 row_mask:0xf bank_mask:0xf bound_ctrl:0
	v_fmac_f32_dpp v151, v151, v175 row_shr:4 row_mask:0xf bank_mask:0xf bound_ctrl:0
	v_fmac_f32_dpp v148, v152, -v176 row_shr:4 row_mask:0xf bank_mask:0xf bound_ctrl:0
	v_fmac_f32_dpp v149, v153, -v177 row_shr:4 row_mask:0xf bank_mask:0xf bound_ctrl:0
	v_fmac_f32_dpp v150, v154, -v178 row_shr:4 row_mask:0xf bank_mask:0xf bound_ctrl:0
	v_fmac_f32_dpp v151, v155, -v179 row_shr:4 row_mask:0xf bank_mask:0xf bound_ctrl:0
	v_fmac_f32_dpp v152, v152, v172 row_shr:4 row_mask:0xf bank_mask:0xf bound_ctrl:0
	v_fmac_f32_dpp v153, v153, v173 row_shr:4 row_mask:0xf bank_mask:0xf bound_ctrl:0
	v_fmac_f32_dpp v154, v154, v174 row_shr:4 row_mask:0xf bank_mask:0xf bound_ctrl:0
	v_fmac_f32_dpp v155, v155, v175 row_shr:4 row_mask:0xf bank_mask:0xf bound_ctrl:0
	v_fmac_f32_dpp v152, v180, v176 row_shr:4 row_mask:0xf bank_mask:0xf bound_ctrl:0
	v_fmac_f32_dpp v153, v181, v177 row_shr:4 row_mask:0xf bank_mask:0xf bound_ctrl:0
	v_fmac_f32_dpp v154, v182, v178 row_shr:4 row_mask:0xf bank_mask:0xf bound_ctrl:0
	v_fmac_f32_dpp v155, v183, v179 row_shr:4 row_mask:0xf bank_mask:0xf bound_ctrl:0
	ds_read_b128 v[172:175], v9 offset:2112
	ds_read_b128 v[176:179], v9 offset:2368
	s_waitcnt lgkmcnt(2)
	v_mov_b32_e32 v180, v116
	v_mov_b32_e32 v181, v117
	v_mov_b32_e32 v182, v118
	v_mov_b32_e32 v183, v119
	v_fmac_f32_dpp v116, v116, v156 row_shr:8 row_mask:0xf bank_mask:0xf bound_ctrl:0
	v_fmac_f32_dpp v117, v117, v157 row_shr:8 row_mask:0xf bank_mask:0xf bound_ctrl:0
	v_fmac_f32_dpp v118, v118, v158 row_shr:8 row_mask:0xf bank_mask:0xf bound_ctrl:0
	v_fmac_f32_dpp v119, v119, v159 row_shr:8 row_mask:0xf bank_mask:0xf bound_ctrl:0
	v_fmac_f32_dpp v116, v120, -v168 row_shr:8 row_mask:0xf bank_mask:0xf bound_ctrl:0
	v_fmac_f32_dpp v117, v121, -v169 row_shr:8 row_mask:0xf bank_mask:0xf bound_ctrl:0
	v_fmac_f32_dpp v118, v122, -v170 row_shr:8 row_mask:0xf bank_mask:0xf bound_ctrl:0
	v_fmac_f32_dpp v119, v123, -v171 row_shr:8 row_mask:0xf bank_mask:0xf bound_ctrl:0
	v_fmac_f32_dpp v120, v120, v156 row_shr:8 row_mask:0xf bank_mask:0xf bound_ctrl:0
	v_fmac_f32_dpp v121, v121, v157 row_shr:8 row_mask:0xf bank_mask:0xf bound_ctrl:0
	v_fmac_f32_dpp v122, v122, v158 row_shr:8 row_mask:0xf bank_mask:0xf bound_ctrl:0
	v_fmac_f32_dpp v123, v123, v159 row_shr:8 row_mask:0xf bank_mask:0xf bound_ctrl:0
	v_fmac_f32_dpp v120, v180, v168 row_shr:8 row_mask:0xf bank_mask:0xf bound_ctrl:0
	v_fmac_f32_dpp v121, v181, v169 row_shr:8 row_mask:0xf bank_mask:0xf bound_ctrl:0
	v_fmac_f32_dpp v122, v182, v170 row_shr:8 row_mask:0xf bank_mask:0xf bound_ctrl:0
	v_fmac_f32_dpp v123, v183, v171 row_shr:8 row_mask:0xf bank_mask:0xf bound_ctrl:0
	ds_read_b128 v[156:159], v9 offset:2176
	ds_read_b128 v[168:171], v9 offset:2432
	s_waitcnt lgkmcnt(2)
	v_mov_b32_e32 v180, v124
	v_mov_b32_e32 v181, v125
	v_mov_b32_e32 v182, v126
	v_mov_b32_e32 v183, v127
	v_fmac_f32_dpp v124, v124, v172 row_shr:8 row_mask:0xf bank_mask:0xf bound_ctrl:0
	v_fmac_f32_dpp v125, v125, v173 row_shr:8 row_mask:0xf bank_mask:0xf bound_ctrl:0
	v_fmac_f32_dpp v126, v126, v174 row_shr:8 row_mask:0xf bank_mask:0xf bound_ctrl:0
	v_fmac_f32_dpp v127, v127, v175 row_shr:8 row_mask:0xf bank_mask:0xf bound_ctrl:0
	v_fmac_f32_dpp v124, v128, -v176 row_shr:8 row_mask:0xf bank_mask:0xf bound_ctrl:0
	v_fmac_f32_dpp v125, v129, -v177 row_shr:8 row_mask:0xf bank_mask:0xf bound_ctrl:0
	v_fmac_f32_dpp v126, v130, -v178 row_shr:8 row_mask:0xf bank_mask:0xf bound_ctrl:0
	v_fmac_f32_dpp v127, v131, -v179 row_shr:8 row_mask:0xf bank_mask:0xf bound_ctrl:0
	v_fmac_f32_dpp v128, v128, v172 row_shr:8 row_mask:0xf bank_mask:0xf bound_ctrl:0
	v_fmac_f32_dpp v129, v129, v173 row_shr:8 row_mask:0xf bank_mask:0xf bound_ctrl:0
	v_fmac_f32_dpp v130, v130, v174 row_shr:8 row_mask:0xf bank_mask:0xf bound_ctrl:0
	v_fmac_f32_dpp v131, v131, v175 row_shr:8 row_mask:0xf bank_mask:0xf bound_ctrl:0
	v_fmac_f32_dpp v128, v180, v176 row_shr:8 row_mask:0xf bank_mask:0xf bound_ctrl:0
	v_fmac_f32_dpp v129, v181, v177 row_shr:8 row_mask:0xf bank_mask:0xf bound_ctrl:0
	v_fmac_f32_dpp v130, v182, v178 row_shr:8 row_mask:0xf bank_mask:0xf bound_ctrl:0
	v_fmac_f32_dpp v131, v183, v179 row_shr:8 row_mask:0xf bank_mask:0xf bound_ctrl:0
	ds_read_b128 v[172:175], v9 offset:2240
	ds_read_b128 v[176:179], v9 offset:2496
	s_waitcnt lgkmcnt(2)
	v_mov_b32_e32 v180, v140
	v_mov_b32_e32 v181, v141
	v_mov_b32_e32 v182, v142
	v_mov_b32_e32 v183, v143
	v_fmac_f32_dpp v140, v140, v156 row_shr:8 row_mask:0xf bank_mask:0xf bound_ctrl:0
	v_fmac_f32_dpp v141, v141, v157 row_shr:8 row_mask:0xf bank_mask:0xf bound_ctrl:0
	v_fmac_f32_dpp v142, v142, v158 row_shr:8 row_mask:0xf bank_mask:0xf bound_ctrl:0
	v_fmac_f32_dpp v143, v143, v159 row_shr:8 row_mask:0xf bank_mask:0xf bound_ctrl:0
	v_fmac_f32_dpp v140, v144, -v168 row_shr:8 row_mask:0xf bank_mask:0xf bound_ctrl:0
	v_fmac_f32_dpp v141, v145, -v169 row_shr:8 row_mask:0xf bank_mask:0xf bound_ctrl:0
	v_fmac_f32_dpp v142, v146, -v170 row_shr:8 row_mask:0xf bank_mask:0xf bound_ctrl:0
	v_fmac_f32_dpp v143, v147, -v171 row_shr:8 row_mask:0xf bank_mask:0xf bound_ctrl:0
	v_fmac_f32_dpp v144, v144, v156 row_shr:8 row_mask:0xf bank_mask:0xf bound_ctrl:0
	v_fmac_f32_dpp v145, v145, v157 row_shr:8 row_mask:0xf bank_mask:0xf bound_ctrl:0
	v_fmac_f32_dpp v146, v146, v158 row_shr:8 row_mask:0xf bank_mask:0xf bound_ctrl:0
	v_fmac_f32_dpp v147, v147, v159 row_shr:8 row_mask:0xf bank_mask:0xf bound_ctrl:0
	v_fmac_f32_dpp v144, v180, v168 row_shr:8 row_mask:0xf bank_mask:0xf bound_ctrl:0
	v_fmac_f32_dpp v145, v181, v169 row_shr:8 row_mask:0xf bank_mask:0xf bound_ctrl:0
	v_fmac_f32_dpp v146, v182, v170 row_shr:8 row_mask:0xf bank_mask:0xf bound_ctrl:0
	v_fmac_f32_dpp v147, v183, v171 row_shr:8 row_mask:0xf bank_mask:0xf bound_ctrl:0
	s_waitcnt lgkmcnt(0)
	v_mov_b32_e32 v180, v148
	v_mov_b32_e32 v181, v149
	v_mov_b32_e32 v182, v150
	v_mov_b32_e32 v183, v151
	v_fmac_f32_dpp v148, v148, v172 row_shr:8 row_mask:0xf bank_mask:0xf bound_ctrl:0
	v_fmac_f32_dpp v149, v149, v173 row_shr:8 row_mask:0xf bank_mask:0xf bound_ctrl:0
	v_fmac_f32_dpp v150, v150, v174 row_shr:8 row_mask:0xf bank_mask:0xf bound_ctrl:0
	v_fmac_f32_dpp v151, v151, v175 row_shr:8 row_mask:0xf bank_mask:0xf bound_ctrl:0
	v_fmac_f32_dpp v148, v152, -v176 row_shr:8 row_mask:0xf bank_mask:0xf bound_ctrl:0
	v_fmac_f32_dpp v149, v153, -v177 row_shr:8 row_mask:0xf bank_mask:0xf bound_ctrl:0
	v_fmac_f32_dpp v150, v154, -v178 row_shr:8 row_mask:0xf bank_mask:0xf bound_ctrl:0
	v_fmac_f32_dpp v151, v155, -v179 row_shr:8 row_mask:0xf bank_mask:0xf bound_ctrl:0
	v_fmac_f32_dpp v152, v152, v172 row_shr:8 row_mask:0xf bank_mask:0xf bound_ctrl:0
	v_fmac_f32_dpp v153, v153, v173 row_shr:8 row_mask:0xf bank_mask:0xf bound_ctrl:0
	v_fmac_f32_dpp v154, v154, v174 row_shr:8 row_mask:0xf bank_mask:0xf bound_ctrl:0
	v_fmac_f32_dpp v155, v155, v175 row_shr:8 row_mask:0xf bank_mask:0xf bound_ctrl:0
	v_fmac_f32_dpp v152, v180, v176 row_shr:8 row_mask:0xf bank_mask:0xf bound_ctrl:0
	v_fmac_f32_dpp v153, v181, v177 row_shr:8 row_mask:0xf bank_mask:0xf bound_ctrl:0
	v_fmac_f32_dpp v154, v182, v178 row_shr:8 row_mask:0xf bank_mask:0xf bound_ctrl:0
	v_fmac_f32_dpp v155, v183, v179 row_shr:8 row_mask:0xf bank_mask:0xf bound_ctrl:0
	ds_read_b128 v[156:159], v9 offset:0
	ds_read_b128 v[168:171], v9 offset:256
	ds_read_b128 v[172:175], v9 offset:64
	ds_read_b128 v[176:179], v9 offset:320
	s_waitcnt lgkmcnt(2)
	s_nop 1
	v_fmac_f32_dpp v84, v116, v156 row_shr:1 row_mask:0xf bank_mask:0xf bound_ctrl:0
	v_fmac_f32_dpp v85, v117, v157 row_shr:1 row_mask:0xf bank_mask:0xf bound_ctrl:0
	v_fmac_f32_dpp v86, v118, v158 row_shr:1 row_mask:0xf bank_mask:0xf bound_ctrl:0
	v_fmac_f32_dpp v87, v119, v159 row_shr:1 row_mask:0xf bank_mask:0xf bound_ctrl:0
	v_fmac_f32_dpp v84, v120, -v168 row_shr:1 row_mask:0xf bank_mask:0xf bound_ctrl:0
	v_fmac_f32_dpp v85, v121, -v169 row_shr:1 row_mask:0xf bank_mask:0xf bound_ctrl:0
	v_fmac_f32_dpp v86, v122, -v170 row_shr:1 row_mask:0xf bank_mask:0xf bound_ctrl:0
	v_fmac_f32_dpp v87, v123, -v171 row_shr:1 row_mask:0xf bank_mask:0xf bound_ctrl:0
	v_fmac_f32_dpp v88, v120, v156 row_shr:1 row_mask:0xf bank_mask:0xf bound_ctrl:0
	v_fmac_f32_dpp v89, v121, v157 row_shr:1 row_mask:0xf bank_mask:0xf bound_ctrl:0
	v_fmac_f32_dpp v90, v122, v158 row_shr:1 row_mask:0xf bank_mask:0xf bound_ctrl:0
	v_fmac_f32_dpp v91, v123, v159 row_shr:1 row_mask:0xf bank_mask:0xf bound_ctrl:0
	v_fmac_f32_dpp v88, v116, v168 row_shr:1 row_mask:0xf bank_mask:0xf bound_ctrl:0
	v_fmac_f32_dpp v89, v117, v169 row_shr:1 row_mask:0xf bank_mask:0xf bound_ctrl:0
	v_fmac_f32_dpp v90, v118, v170 row_shr:1 row_mask:0xf bank_mask:0xf bound_ctrl:0
	v_fmac_f32_dpp v91, v119, v171 row_shr:1 row_mask:0xf bank_mask:0xf bound_ctrl:0
	ds_read_b128 v[156:159], v9 offset:128
	ds_read_b128 v[168:171], v9 offset:384
	s_waitcnt lgkmcnt(2)
	v_fmac_f32_dpp v92, v124, v172 row_shr:1 row_mask:0xf bank_mask:0xf bound_ctrl:0
	v_fmac_f32_dpp v93, v125, v173 row_shr:1 row_mask:0xf bank_mask:0xf bound_ctrl:0
	v_fmac_f32_dpp v94, v126, v174 row_shr:1 row_mask:0xf bank_mask:0xf bound_ctrl:0
	v_fmac_f32_dpp v95, v127, v175 row_shr:1 row_mask:0xf bank_mask:0xf bound_ctrl:0
	v_fmac_f32_dpp v92, v128, -v176 row_shr:1 row_mask:0xf bank_mask:0xf bound_ctrl:0
	v_fmac_f32_dpp v93, v129, -v177 row_shr:1 row_mask:0xf bank_mask:0xf bound_ctrl:0
	v_fmac_f32_dpp v94, v130, -v178 row_shr:1 row_mask:0xf bank_mask:0xf bound_ctrl:0
	v_fmac_f32_dpp v95, v131, -v179 row_shr:1 row_mask:0xf bank_mask:0xf bound_ctrl:0
	v_fmac_f32_dpp v96, v128, v172 row_shr:1 row_mask:0xf bank_mask:0xf bound_ctrl:0
	v_fmac_f32_dpp v97, v129, v173 row_shr:1 row_mask:0xf bank_mask:0xf bound_ctrl:0
	v_fmac_f32_dpp v98, v130, v174 row_shr:1 row_mask:0xf bank_mask:0xf bound_ctrl:0
	v_fmac_f32_dpp v99, v131, v175 row_shr:1 row_mask:0xf bank_mask:0xf bound_ctrl:0
	v_fmac_f32_dpp v96, v124, v176 row_shr:1 row_mask:0xf bank_mask:0xf bound_ctrl:0
	v_fmac_f32_dpp v97, v125, v177 row_shr:1 row_mask:0xf bank_mask:0xf bound_ctrl:0
	v_fmac_f32_dpp v98, v126, v178 row_shr:1 row_mask:0xf bank_mask:0xf bound_ctrl:0
	v_fmac_f32_dpp v99, v127, v179 row_shr:1 row_mask:0xf bank_mask:0xf bound_ctrl:0
	ds_read_b128 v[172:175], v9 offset:192
	ds_read_b128 v[176:179], v9 offset:448
	s_waitcnt lgkmcnt(2)
	v_fmac_f32_dpp v100, v140, v156 row_shr:1 row_mask:0xf bank_mask:0xf bound_ctrl:0
	v_fmac_f32_dpp v101, v141, v157 row_shr:1 row_mask:0xf bank_mask:0xf bound_ctrl:0
	v_fmac_f32_dpp v102, v142, v158 row_shr:1 row_mask:0xf bank_mask:0xf bound_ctrl:0
	v_fmac_f32_dpp v103, v143, v159 row_shr:1 row_mask:0xf bank_mask:0xf bound_ctrl:0
	v_fmac_f32_dpp v100, v144, -v168 row_shr:1 row_mask:0xf bank_mask:0xf bound_ctrl:0
	v_fmac_f32_dpp v101, v145, -v169 row_shr:1 row_mask:0xf bank_mask:0xf bound_ctrl:0
	v_fmac_f32_dpp v102, v146, -v170 row_shr:1 row_mask:0xf bank_mask:0xf bound_ctrl:0
	v_fmac_f32_dpp v103, v147, -v171 row_shr:1 row_mask:0xf bank_mask:0xf bound_ctrl:0
	v_fmac_f32_dpp v104, v144, v156 row_shr:1 row_mask:0xf bank_mask:0xf bound_ctrl:0
	v_fmac_f32_dpp v105, v145, v157 row_shr:1 row_mask:0xf bank_mask:0xf bound_ctrl:0
	v_fmac_f32_dpp v106, v146, v158 row_shr:1 row_mask:0xf bank_mask:0xf bound_ctrl:0
	v_fmac_f32_dpp v107, v147, v159 row_shr:1 row_mask:0xf bank_mask:0xf bound_ctrl:0
	v_fmac_f32_dpp v104, v140, v168 row_shr:1 row_mask:0xf bank_mask:0xf bound_ctrl:0
	v_fmac_f32_dpp v105, v141, v169 row_shr:1 row_mask:0xf bank_mask:0xf bound_ctrl:0
	v_fmac_f32_dpp v106, v142, v170 row_shr:1 row_mask:0xf bank_mask:0xf bound_ctrl:0
	v_fmac_f32_dpp v107, v143, v171 row_shr:1 row_mask:0xf bank_mask:0xf bound_ctrl:0
	s_waitcnt lgkmcnt(0)
	v_fmac_f32_dpp v108, v148, v172 row_shr:1 row_mask:0xf bank_mask:0xf bound_ctrl:0
	v_fmac_f32_dpp v109, v149, v173 row_shr:1 row_mask:0xf bank_mask:0xf bound_ctrl:0
	v_fmac_f32_dpp v110, v150, v174 row_shr:1 row_mask:0xf bank_mask:0xf bound_ctrl:0
	v_fmac_f32_dpp v111, v151, v175 row_shr:1 row_mask:0xf bank_mask:0xf bound_ctrl:0
	v_fmac_f32_dpp v108, v152, -v176 row_shr:1 row_mask:0xf bank_mask:0xf bound_ctrl:0
	v_fmac_f32_dpp v109, v153, -v177 row_shr:1 row_mask:0xf bank_mask:0xf bound_ctrl:0
	v_fmac_f32_dpp v110, v154, -v178 row_shr:1 row_mask:0xf bank_mask:0xf bound_ctrl:0
	v_fmac_f32_dpp v111, v155, -v179 row_shr:1 row_mask:0xf bank_mask:0xf bound_ctrl:0
	v_fmac_f32_dpp v112, v152, v172 row_shr:1 row_mask:0xf bank_mask:0xf bound_ctrl:0
	v_fmac_f32_dpp v113, v153, v173 row_shr:1 row_mask:0xf bank_mask:0xf bound_ctrl:0
	v_fmac_f32_dpp v114, v154, v174 row_shr:1 row_mask:0xf bank_mask:0xf bound_ctrl:0
	v_fmac_f32_dpp v115, v155, v175 row_shr:1 row_mask:0xf bank_mask:0xf bound_ctrl:0
	v_fmac_f32_dpp v112, v148, v176 row_shr:1 row_mask:0xf bank_mask:0xf bound_ctrl:0
	v_fmac_f32_dpp v113, v149, v177 row_shr:1 row_mask:0xf bank_mask:0xf bound_ctrl:0
	v_fmac_f32_dpp v114, v150, v178 row_shr:1 row_mask:0xf bank_mask:0xf bound_ctrl:0
	v_fmac_f32_dpp v115, v151, v179 row_shr:1 row_mask:0xf bank_mask:0xf bound_ctrl:0
	s_waitcnt vmcnt(8)
	v_xor_b32_e32 v24, 0x80000000, v24
	v_xor_b32_e32 v25, 0x80000000, v25
	v_xor_b32_e32 v26, 0x80000000, v26
	v_xor_b32_e32 v27, 0x80000000, v27
	v_xor_b32_e32 v32, 0x80000000, v32
	v_xor_b32_e32 v33, 0x80000000, v33
	v_xor_b32_e32 v34, 0x80000000, v34
	v_xor_b32_e32 v35, 0x80000000, v35
	v_xor_b32_e32 v40, 0x80000000, v40
	v_xor_b32_e32 v41, 0x80000000, v41
	v_xor_b32_e32 v42, 0x80000000, v42
	v_xor_b32_e32 v43, 0x80000000, v43
	v_xor_b32_e32 v48, 0x80000000, v48
	v_xor_b32_e32 v49, 0x80000000, v49
	v_xor_b32_e32 v50, 0x80000000, v50
	v_xor_b32_e32 v51, 0x80000000, v51
	s_nop 1
	v_mfma_f32_16x16x4_f32 v[192:195], v84, v20, 0
	v_mfma_f32_16x16x4_f32 v[228:231], v88, v24, 0
	v_mfma_f32_16x16x4_f32 v[224:227], v116, v20, 0
	v_mfma_f32_16x16x4_f32 v[232:235], v120, v24, 0
	v_mfma_f32_16x16x4_f32 v[192:195], v85, v21, v[192:195]
	v_mfma_f32_16x16x4_f32 v[228:231], v89, v25, v[228:231]
	v_mfma_f32_16x16x4_f32 v[224:227], v117, v21, v[224:227]
	v_mfma_f32_16x16x4_f32 v[232:235], v121, v25, v[232:235]
	v_mfma_f32_16x16x4_f32 v[192:195], v86, v22, v[192:195]
	v_mfma_f32_16x16x4_f32 v[228:231], v90, v26, v[228:231]
	v_mfma_f32_16x16x4_f32 v[224:227], v118, v22, v[224:227]
	v_mfma_f32_16x16x4_f32 v[232:235], v122, v26, v[232:235]
	v_mfma_f32_16x16x4_f32 v[192:195], v87, v23, v[192:195]
	v_mfma_f32_16x16x4_f32 v[228:231], v91, v27, v[228:231]
	v_mfma_f32_16x16x4_f32 v[224:227], v119, v23, v[224:227]
	v_mfma_f32_16x16x4_f32 v[232:235], v123, v27, v[232:235]
	v_mfma_f32_16x16x4_f32 v[192:195], v92, v28, v[192:195]
	v_mfma_f32_16x16x4_f32 v[228:231], v96, v32, v[228:231]
	v_mfma_f32_16x16x4_f32 v[224:227], v124, v28, v[224:227]
	v_mfma_f32_16x16x4_f32 v[232:235], v128, v32, v[232:235]
	v_mfma_f32_16x16x4_f32 v[192:195], v93, v29, v[192:195]
	v_mfma_f32_16x16x4_f32 v[228:231], v97, v33, v[228:231]
	v_mfma_f32_16x16x4_f32 v[224:227], v125, v29, v[224:227]
	v_mfma_f32_16x16x4_f32 v[232:235], v129, v33, v[232:235]
	v_mfma_f32_16x16x4_f32 v[192:195], v94, v30, v[192:195]
	v_mfma_f32_16x16x4_f32 v[228:231], v98, v34, v[228:231]
	v_mfma_f32_16x16x4_f32 v[224:227], v126, v30, v[224:227]
	v_mfma_f32_16x16x4_f32 v[232:235], v130, v34, v[232:235]
	v_mfma_f32_16x16x4_f32 v[192:195], v95, v31, v[192:195]
	v_mfma_f32_16x16x4_f32 v[228:231], v99, v35, v[228:231]
	v_mfma_f32_16x16x4_f32 v[224:227], v127, v31, v[224:227]
	v_mfma_f32_16x16x4_f32 v[232:235], v131, v35, v[232:235]
	v_mfma_f32_16x16x4_f32 v[192:195], v100, v36, v[192:195]
	v_mfma_f32_16x16x4_f32 v[228:231], v104, v40, v[228:231]
	v_mfma_f32_16x16x4_f32 v[224:227], v140, v36, v[224:227]
	v_mfma_f32_16x16x4_f32 v[232:235], v144, v40, v[232:235]
	v_mfma_f32_16x16x4_f32 v[192:195], v101, v37, v[192:195]
	v_mfma_f32_16x16x4_f32 v[228:231], v105, v41, v[228:231]
	v_mfma_f32_16x16x4_f32 v[224:227], v141, v37, v[224:227]
	v_mfma_f32_16x16x4_f32 v[232:235], v145, v41, v[232:235]
	v_mfma_f32_16x16x4_f32 v[192:195], v102, v38, v[192:195]
	v_mfma_f32_16x16x4_f32 v[228:231], v106, v42, v[228:231]
	v_mfma_f32_16x16x4_f32 v[224:227], v142, v38, v[224:227]
	v_mfma_f32_16x16x4_f32 v[232:235], v146, v42, v[232:235]
	v_mfma_f32_16x16x4_f32 v[192:195], v103, v39, v[192:195]
	v_mfma_f32_16x16x4_f32 v[228:231], v107, v43, v[228:231]
	v_mfma_f32_16x16x4_f32 v[224:227], v143, v39, v[224:227]
	v_mfma_f32_16x16x4_f32 v[232:235], v147, v43, v[232:235]
	v_mfma_f32_16x16x4_f32 v[192:195], v108, v44, v[192:195]
	v_mfma_f32_16x16x4_f32 v[228:231], v112, v48, v[228:231]
	v_mfma_f32_16x16x4_f32 v[224:227], v148, v44, v[224:227]
	v_mfma_f32_16x16x4_f32 v[232:235], v152, v48, v[232:235]
	v_mfma_f32_16x16x4_f32 v[192:195], v109, v45, v[192:195]
	v_mfma_f32_16x16x4_f32 v[228:231], v113, v49, v[228:231]
	v_mfma_f32_16x16x4_f32 v[224:227], v149, v45, v[224:227]
	v_mfma_f32_16x16x4_f32 v[232:235], v153, v49, v[232:235]
	v_mfma_f32_16x16x4_f32 v[192:195], v110, v46, v[192:195]
	v_mfma_f32_16x16x4_f32 v[228:231], v114, v50, v[228:231]
	v_mfma_f32_16x16x4_f32 v[224:227], v150, v46, v[224:227]
	v_mfma_f32_16x16x4_f32 v[232:235], v154, v50, v[232:235]
	v_mfma_f32_16x16x4_f32 v[192:195], v111, v47, v[192:195]
	v_mfma_f32_16x16x4_f32 v[228:231], v115, v51, v[228:231]
	v_mfma_f32_16x16x4_f32 v[224:227], v151, v47, v[224:227]
	v_mfma_f32_16x16x4_f32 v[232:235], v155, v51, v[232:235]
	s_lshl_b32 s56, s0, 5
	s_add_i32 s55, s6, 0
	s_lshl_b32 s55, s55, 1
	s_add_i32 s56, s56, s55
	s_add_i32 s56, s56, 1
	s_lshl_b32 s56, s56, 9
	s_add_u32 s48, s94, 0x133d6000
	s_addc_u32 s49, s95, 0
	s_add_u32 s48, s48, s56
	s_addc_u32 s49, s49, 0
	global_load_dwordx4 v[20:23], v15, s[48:49] offset:0
	global_load_dwordx4 v[24:27], v15, s[48:49] offset:16
	global_load_dwordx4 v[28:31], v15, s[48:49] offset:128
	global_load_dwordx4 v[32:35], v15, s[48:49] offset:144
	global_load_dwordx4 v[36:39], v15, s[48:49] offset:256
	global_load_dwordx4 v[40:43], v15, s[48:49] offset:272
	global_load_dwordx4 v[44:47], v15, s[48:49] offset:384
	global_load_dwordx4 v[48:51], v15, s[48:49] offset:400
	s_cmp_ge_u32 s0, 128
	s_cbranch_scc1 .Ls5b_nofin4
	s_and_b32 s55, s0, 7
	s_cmp_lg_u32 s55, 7
	s_cbranch_scc1 .Ls5b_nofin4
	s_lshr_b32 s55, s0, 3
	s_lshl_b32 s55, s55, 2
	s_add_i32 s55, s55, s32
	s_lshl_b32 s55, s55, 1
	s_add_i32 s55, s55, 0
	s_lshl_b32 s55, s55, 4
	s_add_i32 s55, s55, s6
	s_lshl_b32 s55, s55, 8
	s_add_u32 s48, s92, 0x4000000
	s_addc_u32 s49, s93, 0
	s_add_u32 s48, s48, s55
	s_addc_u32 s49, s49, 0
	s_add_u32 s50, s48, 0x80000
	s_addc_u32 s51, s49, 0
	s_mov_b64 exec, s[10:11]
	global_store_dwordx4 v10, v[116:119], s[48:49] offset:0
	global_store_dwordx4 v10, v[120:123], s[50:51] offset:0
	global_store_dwordx4 v10, v[124:127], s[48:49] offset:64
	global_store_dwordx4 v10, v[128:131], s[50:51] offset:64
	global_store_dwordx4 v10, v[140:143], s[48:49] offset:128
	global_store_dwordx4 v10, v[144:147], s[50:51] offset:128
	global_store_dwordx4 v10, v[148:151], s[48:49] offset:192
	global_store_dwordx4 v10, v[152:155], s[50:51] offset:192
	s_mov_b64 exec, -1
	s_waitcnt vmcnt(0)
.Ls5b_nofin4:
	s_waitcnt vmcnt(8)
	v_mfma_f32_16x16x4_f32 v[84:87], v52, v184, 0
	v_mfma_f32_16x16x4_f32 v[88:91], v53, v184, 0
	v_mfma_f32_16x16x4_f32 v[116:119], v52, v188, 0
	v_mfma_f32_16x16x4_f32 v[120:123], v53, v188, 0
	v_mfma_f32_16x16x4_f32 v[92:95], v60, v184, 0
	v_mfma_f32_16x16x4_f32 v[96:99], v61, v184, 0
	v_mfma_f32_16x16x4_f32 v[124:127], v60, v188, 0
	v_mfma_f32_16x16x4_f32 v[128:131], v61, v188, 0
	v_mfma_f32_16x16x4_f32 v[100:103], v68, v184, 0
	v_mfma_f32_16x16x4_f32 v[104:107], v69, v184, 0
	v_mfma_f32_16x16x4_f32 v[140:143], v68, v188, 0
	v_mfma_f32_16x16x4_f32 v[144:147], v69, v188, 0
	v_mfma_f32_16x16x4_f32 v[108:111], v76, v184, 0
	v_mfma_f32_16x16x4_f32 v[112:115], v77, v184, 0
	v_mfma_f32_16x16x4_f32 v[148:151], v76, v188, 0
	v_mfma_f32_16x16x4_f32 v[152:155], v77, v188, 0
	v_mfma_f32_16x16x4_f32 v[84:87], v54, v185, v[84:87]
	v_mfma_f32_16x16x4_f32 v[88:91], v55, v185, v[88:91]
	v_mfma_f32_16x16x4_f32 v[116:119], v54, v189, v[116:119]
	v_mfma_f32_16x16x4_f32 v[120:123], v55, v189, v[120:123]
	v_mfma_f32_16x16x4_f32 v[92:95], v62, v185, v[92:95]
	v_mfma_f32_16x16x4_f32 v[96:99], v63, v185, v[96:99]
	v_mfma_f32_16x16x4_f32 v[124:127], v62, v189, v[124:127]
	v_mfma_f32_16x16x4_f32 v[128:131], v63, v189, v[128:131]
	v_mfma_f32_16x16x4_f32 v[100:103], v70, v185, v[100:103]
	v_mfma_f32_16x16x4_f32 v[104:107], v71, v185, v[104:107]
	v_mfma_f32_16x16x4_f32 v[140:143], v70, v189, v[140:143]
	v_mfma_f32_16x16x4_f32 v[144:147], v71, v189, v[144:147]
	v_mfma_f32_16x16x4_f32 v[108:111], v78, v185, v[108:111]
	v_mfma_f32_16x16x4_f32 v[112:115], v79, v185, v[112:115]
	v_mfma_f32_16x16x4_f32 v[148:151], v78, v189, v[148:151]
	v_mfma_f32_16x16x4_f32 v[152:155], v79, v189, v[152:155]
	v_mfma_f32_16x16x4_f32 v[84:87], v56, v186, v[84:87]
	v_mfma_f32_16x16x4_f32 v[88:91], v57, v186, v[88:91]
	v_mfma_f32_16x16x4_f32 v[116:119], v56, v190, v[116:119]
	v_mfma_f32_16x16x4_f32 v[120:123], v57, v190, v[120:123]
	v_mfma_f32_16x16x4_f32 v[92:95], v64, v186, v[92:95]
	v_mfma_f32_16x16x4_f32 v[96:99], v65, v186, v[96:99]
	v_mfma_f32_16x16x4_f32 v[124:127], v64, v190, v[124:127]
	v_mfma_f32_16x16x4_f32 v[128:131], v65, v190, v[128:131]
	v_mfma_f32_16x16x4_f32 v[100:103], v72, v186, v[100:103]
	v_mfma_f32_16x16x4_f32 v[104:107], v73, v186, v[104:107]
	v_mfma_f32_16x16x4_f32 v[140:143], v72, v190, v[140:143]
	v_mfma_f32_16x16x4_f32 v[144:147], v73, v190, v[144:147]
	v_mfma_f32_16x16x4_f32 v[108:111], v80, v186, v[108:111]
	v_mfma_f32_16x16x4_f32 v[112:115], v81, v186, v[112:115]
	v_mfma_f32_16x16x4_f32 v[148:151], v80, v190, v[148:151]
	v_mfma_f32_16x16x4_f32 v[152:155], v81, v190, v[152:155]
	v_mfma_f32_16x16x4_f32 v[84:87], v58, v187, v[84:87]
	v_mfma_f32_16x16x4_f32 v[88:91], v59, v187, v[88:91]
	v_mfma_f32_16x16x4_f32 v[116:119], v58, v191, v[116:119]
	v_mfma_f32_16x16x4_f32 v[120:123], v59, v191, v[120:123]
	v_mfma_f32_16x16x4_f32 v[92:95], v66, v187, v[92:95]
	v_mfma_f32_16x16x4_f32 v[96:99], v67, v187, v[96:99]
	v_mfma_f32_16x16x4_f32 v[124:127], v66, v191, v[124:127]
	v_mfma_f32_16x16x4_f32 v[128:131], v67, v191, v[128:131]
	v_mfma_f32_16x16x4_f32 v[100:103], v74, v187, v[100:103]
	v_mfma_f32_16x16x4_f32 v[104:107], v75, v187, v[104:107]
	v_mfma_f32_16x16x4_f32 v[140:143], v74, v191, v[140:143]
	v_mfma_f32_16x16x4_f32 v[144:147], v75, v191, v[144:147]
	v_mfma_f32_16x16x4_f32 v[108:111], v82, v187, v[108:111]
	v_mfma_f32_16x16x4_f32 v[112:115], v83, v187, v[112:115]
	v_mfma_f32_16x16x4_f32 v[148:151], v82, v191, v[148:151]
	v_mfma_f32_16x16x4_f32 v[152:155], v83, v191, v[152:155]
	global_load_dwordx4 v[52:55], v14, s[24:25] offset:0
	global_load_dwordx4 v[56:59], v14, s[38:39] offset:0
	global_load_dwordx4 v[60:63], v14, s[24:25] offset:64
	global_load_dwordx4 v[64:67], v14, s[38:39] offset:64
	global_load_dwordx4 v[68:71], v14, s[24:25] offset:128
	global_load_dwordx4 v[72:75], v14, s[38:39] offset:128
	global_load_dwordx4 v[76:79], v14, s[24:25] offset:192
	global_load_dwordx4 v[80:83], v14, s[38:39] offset:192
	global_load_dword v236, v11, s[8:9] offset:0
	global_load_dword v237, v11, s[8:9] offset:2048
	global_load_dword v238, v12, s[8:9] offset:0
	global_load_dword v239, v12, s[8:9] offset:2048
	global_load_dword v240, v11, s[8:9] offset:1024
	global_load_dword v241, v11, s[8:9] offset:3072
	global_load_dword v242, v12, s[8:9] offset:1024
	global_load_dword v243, v12, s[8:9] offset:3072
	s_waitcnt vmcnt(16)
	s_nop 9
	ds_read_b128 v[156:159], v9 offset:2560
	ds_read_b128 v[168:171], v9 offset:2816
	ds_read_b128 v[172:175], v9 offset:2624
	ds_read_b128 v[176:179], v9 offset:2880
	s_waitcnt lgkmcnt(2)
	s_mov_b64 exec, s[10:11]
	v_fmac_f32_e32 v116, v156, v20
	v_fmac_f32_e32 v117, v157, v22
	v_fmac_f32_e32 v118, v158, v24
	v_fmac_f32_e32 v119, v159, v26
	v_fma_f32 v116, -v168, v21, v116
	v_fma_f32 v117, -v169, v23, v117
	v_fma_f32 v118, -v170, v25, v118
	v_fma_f32 v119, -v171, v27, v119
	v_fmac_f32_e32 v120, v156, v21
	v_fmac_f32_e32 v121, v157, v23
	v_fmac_f32_e32 v122, v158, v25
	v_fmac_f32_e32 v123, v159, v27
	v_fmac_f32_e32 v120, v168, v20
	v_fmac_f32_e32 v121, v169, v22
	v_fmac_f32_e32 v122, v170, v24
	v_fmac_f32_e32 v123, v171, v26
	s_mov_b64 exec, -1
	v_fmac_f32_e32 v84, v156, v116
	v_fmac_f32_e32 v85, v157, v117
	v_fmac_f32_e32 v86, v158, v118
	v_fmac_f32_e32 v87, v159, v119
	v_fma_f32 v84, -v168, v120, v84
	v_fma_f32 v85, -v169, v121, v85
	v_fma_f32 v86, -v170, v122, v86
	v_fma_f32 v87, -v171, v123, v87
	v_fmac_f32_e32 v88, v156, v120
	v_fmac_f32_e32 v89, v157, v121
	v_fmac_f32_e32 v90, v158, v122
	v_fmac_f32_e32 v91, v159, v123
	v_fmac_f32_e32 v88, v168, v116
	v_fmac_f32_e32 v89, v169, v117
	v_fmac_f32_e32 v90, v170, v118
	v_fmac_f32_e32 v91, v171, v119
	ds_read_b128 v[156:159], v9 offset:2688
	ds_read_b128 v[168:171], v9 offset:2944
	s_waitcnt lgkmcnt(2)
	s_mov_b64 exec, s[10:11]
	v_fmac_f32_e32 v124, v172, v28
	v_fmac_f32_e32 v125, v173, v30
	v_fmac_f32_e32 v126, v174, v32
	v_fmac_f32_e32 v127, v175, v34
	v_fma_f32 v124, -v176, v29, v124
	v_fma_f32 v125, -v177, v31, v125
	v_fma_f32 v126, -v178, v33, v126
	v_fma_f32 v127, -v179, v35, v127
	v_fmac_f32_e32 v128, v172, v29
	v_fmac_f32_e32 v129, v173, v31
	v_fmac_f32_e32 v130, v174, v33
	v_fmac_f32_e32 v131, v175, v35
	v_fmac_f32_e32 v128, v176, v28
	v_fmac_f32_e32 v129, v177, v30
	v_fmac_f32_e32 v130, v178, v32
	v_fmac_f32_e32 v131, v179, v34
	s_mov_b64 exec, -1
	v_fmac_f32_e32 v92, v172, v124
	v_fmac_f32_e32 v93, v173, v125
	v_fmac_f32_e32 v94, v174, v126
	v_fmac_f32_e32 v95, v175, v127
	v_fma_f32 v92, -v176, v128, v92
	v_fma_f32 v93, -v177, v129, v93
	v_fma_f32 v94, -v178, v130, v94
	v_fma_f32 v95, -v179, v131, v95
	v_fmac_f32_e32 v96, v172, v128
	v_fmac_f32_e32 v97, v173, v129
	v_fmac_f32_e32 v98, v174, v130
	v_fmac_f32_e32 v99, v175, v131
	v_fmac_f32_e32 v96, v176, v124
	v_fmac_f32_e32 v97, v177, v125
	v_fmac_f32_e32 v98, v178, v126
	v_fmac_f32_e32 v99, v179, v127
	ds_read_b128 v[172:175], v9 offset:2752
	ds_read_b128 v[176:179], v9 offset:3008
	s_waitcnt lgkmcnt(2)
	s_mov_b64 exec, s[10:11]
	v_fmac_f32_e32 v140, v156, v36
	v_fmac_f32_e32 v141, v157, v38
	v_fmac_f32_e32 v142, v158, v40
	v_fmac_f32_e32 v143, v159, v42
	v_fma_f32 v140, -v168, v37, v140
	v_fma_f32 v141, -v169, v39, v141
	v_fma_f32 v142, -v170, v41, v142
	v_fma_f32 v143, -v171, v43, v143
	v_fmac_f32_e32 v144, v156, v37
	v_fmac_f32_e32 v145, v157, v39
	v_fmac_f32_e32 v146, v158, v41
	v_fmac_f32_e32 v147, v159, v43
	v_fmac_f32_e32 v144, v168, v36
	v_fmac_f32_e32 v145, v169, v38
	v_fmac_f32_e32 v146, v170, v40
	v_fmac_f32_e32 v147, v171, v42
	s_mov_b64 exec, -1
	v_fmac_f32_e32 v100, v156, v140
	v_fmac_f32_e32 v101, v157, v141
	v_fmac_f32_e32 v102, v158, v142
	v_fmac_f32_e32 v103, v159, v143
	v_fma_f32 v100, -v168, v144, v100
	v_fma_f32 v101, -v169, v145, v101
	v_fma_f32 v102, -v170, v146, v102
	v_fma_f32 v103, -v171, v147, v103
	v_fmac_f32_e32 v104, v156, v144
	v_fmac_f32_e32 v105, v157, v145
	v_fmac_f32_e32 v106, v158, v146
	v_fmac_f32_e32 v107, v159, v147
	v_fmac_f32_e32 v104, v168, v140
	v_fmac_f32_e32 v105, v169, v141
	v_fmac_f32_e32 v106, v170, v142
	v_fmac_f32_e32 v107, v171, v143
	s_waitcnt lgkmcnt(0)
	s_mov_b64 exec, s[10:11]
	v_fmac_f32_e32 v148, v172, v44
	v_fmac_f32_e32 v149, v173, v46
	v_fmac_f32_e32 v150, v174, v48
	v_fmac_f32_e32 v151, v175, v50
	v_fma_f32 v148, -v176, v45, v148
	v_fma_f32 v149, -v177, v47, v149
	v_fma_f32 v150, -v178, v49, v150
	v_fma_f32 v151, -v179, v51, v151
	v_fmac_f32_e32 v152, v172, v45
	v_fmac_f32_e32 v153, v173, v47
	v_fmac_f32_e32 v154, v174, v49
	v_fmac_f32_e32 v155, v175, v51
	v_fmac_f32_e32 v152, v176, v44
	v_fmac_f32_e32 v153, v177, v46
	v_fmac_f32_e32 v154, v178, v48
	v_fmac_f32_e32 v155, v179, v50
	s_mov_b64 exec, -1
	v_fmac_f32_e32 v108, v172, v148
	v_fmac_f32_e32 v109, v173, v149
	v_fmac_f32_e32 v110, v174, v150
	v_fmac_f32_e32 v111, v175, v151
	v_fma_f32 v108, -v176, v152, v108
	v_fma_f32 v109, -v177, v153, v109
	v_fma_f32 v110, -v178, v154, v110
	v_fma_f32 v111, -v179, v155, v111
	v_fmac_f32_e32 v112, v172, v152
	v_fmac_f32_e32 v113, v173, v153
	v_fmac_f32_e32 v114, v174, v154
	v_fmac_f32_e32 v115, v175, v155
	v_fmac_f32_e32 v112, v176, v148
	v_fmac_f32_e32 v113, v177, v149
	v_fmac_f32_e32 v114, v178, v150
	v_fmac_f32_e32 v115, v179, v151
	global_load_dwordx4 v[20:23], v6, s[12:13] offset:0
	global_load_dwordx4 v[24:27], v6, s[12:13] offset:1024
	global_load_dwordx4 v[28:31], v6, s[12:13] offset:256
	global_load_dwordx4 v[32:35], v6, s[12:13] offset:1280
	global_load_dwordx4 v[36:39], v6, s[12:13] offset:512
	global_load_dwordx4 v[40:43], v6, s[12:13] offset:1536
	global_load_dwordx4 v[44:47], v6, s[12:13] offset:768
	global_load_dwordx4 v[48:51], v6, s[12:13] offset:1792
	s_lshl_b32 s55, s1, 15
	s_add_i32 s56, s6, 0
	s_lshl_b32 s56, s56, 6
	s_add_u32 s55, s55, s56
	s_add_u32 s50, s94, 0x8a40000
	s_addc_u32 s51, s95, 0
	s_add_u32 s50, s50, s55
	s_addc_u32 s51, s51, 0
	global_load_dwordx4 v[184:187], v5, s[50:51] offset:0
	global_load_dwordx4 v[188:191], v5, s[50:51] offset:1024
	ds_read_b128 v[156:159], v9 offset:3072
	ds_read_b128 v[168:171], v9 offset:3328
	ds_read_b128 v[172:175], v9 offset:3136
	ds_read_b128 v[176:179], v9 offset:3392
	s_waitcnt lgkmcnt(2)
	v_mov_b32_e32 v180, v84
	v_mov_b32_e32 v181, v85
	v_mov_b32_e32 v182, v86
	v_mov_b32_e32 v183, v87
	s_nop 1
	v_fmac_f32_dpp v84, v84, v156 row_shl:1 row_mask:0xf bank_mask:0xf bound_ctrl:0
	v_fmac_f32_dpp v85, v85, v157 row_shl:1 row_mask:0xf bank_mask:0xf bound_ctrl:0
	v_fmac_f32_dpp v86, v86, v158 row_shl:1 row_mask:0xf bank_mask:0xf bound_ctrl:0
	v_fmac_f32_dpp v87, v87, v159 row_shl:1 row_mask:0xf bank_mask:0xf bound_ctrl:0
	v_fmac_f32_dpp v84, v88, -v168 row_shl:1 row_mask:0xf bank_mask:0xf bound_ctrl:0
	v_fmac_f32_dpp v85, v89, -v169 row_shl:1 row_mask:0xf bank_mask:0xf bound_ctrl:0
	v_fmac_f32_dpp v86, v90, -v170 row_shl:1 row_mask:0xf bank_mask:0xf bound_ctrl:0
	v_fmac_f32_dpp v87, v91, -v171 row_shl:1 row_mask:0xf bank_mask:0xf bound_ctrl:0
	v_fmac_f32_dpp v88, v88, v156 row_shl:1 row_mask:0xf bank_mask:0xf bound_ctrl:0
	v_fmac_f32_dpp v89, v89, v157 row_shl:1 row_mask:0xf bank_mask:0xf bound_ctrl:0
	v_fmac_f32_dpp v90, v90, v158 row_shl:1 row_mask:0xf bank_mask:0xf bound_ctrl:0
	v_fmac_f32_dpp v91, v91, v159 row_shl:1 row_mask:0xf bank_mask:0xf bound_ctrl:0
	v_fmac_f32_dpp v88, v180, v168 row_shl:1 row_mask:0xf bank_mask:0xf bound_ctrl:0
	v_fmac_f32_dpp v89, v181, v169 row_shl:1 row_mask:0xf bank_mask:0xf bound_ctrl:0
	v_fmac_f32_dpp v90, v182, v170 row_shl:1 row_mask:0xf bank_mask:0xf bound_ctrl:0
	v_fmac_f32_dpp v91, v183, v171 row_shl:1 row_mask:0xf bank_mask:0xf bound_ctrl:0
	ds_read_b128 v[156:159], v9 offset:3200
	ds_read_b128 v[168:171], v9 offset:3456
	s_waitcnt lgkmcnt(2)
	v_mov_b32_e32 v180, v92
	v_mov_b32_e32 v181, v93
	v_mov_b32_e32 v182, v94
	v_mov_b32_e32 v183, v95
	v_fmac_f32_dpp v92, v92, v172 row_shl:1 row_mask:0xf bank_mask:0xf bound_ctrl:0
	v_fmac_f32_dpp v93, v93, v173 row_shl:1 row_mask:0xf bank_mask:0xf bound_ctrl:0
	v_fmac_f32_dpp v94, v94, v174 row_shl:1 row_mask:0xf bank_mask:0xf bound_ctrl:0
	v_fmac_f32_dpp v95, v95, v175 row_shl:1 row_mask:0xf bank_mask:0xf bound_ctrl:0
	v_fmac_f32_dpp v92, v96, -v176 row_shl:1 row_mask:0xf bank_mask:0xf bound_ctrl:0
	v_fmac_f32_dpp v93, v97, -v177 row_shl:1 row_mask:0xf bank_mask:0xf bound_ctrl:0
	v_fmac_f32_dpp v94, v98, -v178 row_shl:1 row_mask:0xf bank_mask:0xf bound_ctrl:0
	v_fmac_f32_dpp v95, v99, -v179 row_shl:1 row_mask:0xf bank_mask:0xf bound_ctrl:0
	v_fmac_f32_dpp v96, v96, v172 row_shl:1 row_mask:0xf bank_mask:0xf bound_ctrl:0
	v_fmac_f32_dpp v97, v97, v173 row_shl:1 row_mask:0xf bank_mask:0xf bound_ctrl:0
	v_fmac_f32_dpp v98, v98, v174 row_shl:1 row_mask:0xf bank_mask:0xf bound_ctrl:0
	v_fmac_f32_dpp v99, v99, v175 row_shl:1 row_mask:0xf bank_mask:0xf bound_ctrl:0
	v_fmac_f32_dpp v96, v180, v176 row_shl:1 row_mask:0xf bank_mask:0xf bound_ctrl:0
	v_fmac_f32_dpp v97, v181, v177 row_shl:1 row_mask:0xf bank_mask:0xf bound_ctrl:0
	v_fmac_f32_dpp v98, v182, v178 row_shl:1 row_mask:0xf bank_mask:0xf bound_ctrl:0
	v_fmac_f32_dpp v99, v183, v179 row_shl:1 row_mask:0xf bank_mask:0xf bound_ctrl:0
	ds_read_b128 v[172:175], v9 offset:3264
	ds_read_b128 v[176:179], v9 offset:3520
	s_waitcnt lgkmcnt(2)
	v_mov_b32_e32 v180, v100
	v_mov_b32_e32 v181, v101
	v_mov_b32_e32 v182, v102
	v_mov_b32_e32 v183, v103
	v_fmac_f32_dpp v100, v100, v156 row_shl:1 row_mask:0xf bank_mask:0xf bound_ctrl:0
	v_fmac_f32_dpp v101, v101, v157 row_shl:1 row_mask:0xf bank_mask:0xf bound_ctrl:0
	v_fmac_f32_dpp v102, v102, v158 row_shl:1 row_mask:0xf bank_mask:0xf bound_ctrl:0
	v_fmac_f32_dpp v103, v103, v159 row_shl:1 row_mask:0xf bank_mask:0xf bound_ctrl:0
	v_fmac_f32_dpp v100, v104, -v168 row_shl:1 row_mask:0xf bank_mask:0xf bound_ctrl:0
	v_fmac_f32_dpp v101, v105, -v169 row_shl:1 row_mask:0xf bank_mask:0xf bound_ctrl:0
	v_fmac_f32_dpp v102, v106, -v170 row_shl:1 row_mask:0xf bank_mask:0xf bound_ctrl:0
	v_fmac_f32_dpp v103, v107, -v171 row_shl:1 row_mask:0xf bank_mask:0xf bound_ctrl:0
	v_fmac_f32_dpp v104, v104, v156 row_shl:1 row_mask:0xf bank_mask:0xf bound_ctrl:0
	v_fmac_f32_dpp v105, v105, v157 row_shl:1 row_mask:0xf bank_mask:0xf bound_ctrl:0
	v_fmac_f32_dpp v106, v106, v158 row_shl:1 row_mask:0xf bank_mask:0xf bound_ctrl:0
	v_fmac_f32_dpp v107, v107, v159 row_shl:1 row_mask:0xf bank_mask:0xf bound_ctrl:0
	v_fmac_f32_dpp v104, v180, v168 row_shl:1 row_mask:0xf bank_mask:0xf bound_ctrl:0
	v_fmac_f32_dpp v105, v181, v169 row_shl:1 row_mask:0xf bank_mask:0xf bound_ctrl:0
	v_fmac_f32_dpp v106, v182, v170 row_shl:1 row_mask:0xf bank_mask:0xf bound_ctrl:0
	v_fmac_f32_dpp v107, v183, v171 row_shl:1 row_mask:0xf bank_mask:0xf bound_ctrl:0
	ds_read_b128 v[156:159], v9 offset:3584
	ds_read_b128 v[168:171], v9 offset:3840
	s_waitcnt lgkmcnt(2)
	v_mov_b32_e32 v180, v108
	v_mov_b32_e32 v181, v109
	v_mov_b32_e32 v182, v110
	v_mov_b32_e32 v183, v111
	v_fmac_f32_dpp v108, v108, v172 row_shl:1 row_mask:0xf bank_mask:0xf bound_ctrl:0
	v_fmac_f32_dpp v109, v109, v173 row_shl:1 row_mask:0xf bank_mask:0xf bound_ctrl:0
	v_fmac_f32_dpp v110, v110, v174 row_shl:1 row_mask:0xf bank_mask:0xf bound_ctrl:0
	v_fmac_f32_dpp v111, v111, v175 row_shl:1 row_mask:0xf bank_mask:0xf bound_ctrl:0
	v_fmac_f32_dpp v108, v112, -v176 row_shl:1 row_mask:0xf bank_mask:0xf bound_ctrl:0
	v_fmac_f32_dpp v109, v113, -v177 row_shl:1 row_mask:0xf bank_mask:0xf bound_ctrl:0
	v_fmac_f32_dpp v110, v114, -v178 row_shl:1 row_mask:0xf bank_mask:0xf bound_ctrl:0
	v_fmac_f32_dpp v111, v115, -v179 row_shl:1 row_mask:0xf bank_mask:0xf bound_ctrl:0
	v_fmac_f32_dpp v112, v112, v172 row_shl:1 row_mask:0xf bank_mask:0xf bound_ctrl:0
	v_fmac_f32_dpp v113, v113, v173 row_shl:1 row_mask:0xf bank_mask:0xf bound_ctrl:0
	v_fmac_f32_dpp v114, v114, v174 row_shl:1 row_mask:0xf bank_mask:0xf bound_ctrl:0
	v_fmac_f32_dpp v115, v115, v175 row_shl:1 row_mask:0xf bank_mask:0xf bound_ctrl:0
	v_fmac_f32_dpp v112, v180, v176 row_shl:1 row_mask:0xf bank_mask:0xf bound_ctrl:0
	v_fmac_f32_dpp v113, v181, v177 row_shl:1 row_mask:0xf bank_mask:0xf bound_ctrl:0
	v_fmac_f32_dpp v114, v182, v178 row_shl:1 row_mask:0xf bank_mask:0xf bound_ctrl:0
	v_fmac_f32_dpp v115, v183, v179 row_shl:1 row_mask:0xf bank_mask:0xf bound_ctrl:0
	ds_read_b128 v[172:175], v9 offset:3648
	ds_read_b128 v[176:179], v9 offset:3904
	s_waitcnt lgkmcnt(2)
	v_mov_b32_e32 v180, v84
	v_mov_b32_e32 v181, v85
	v_mov_b32_e32 v182, v86
	v_mov_b32_e32 v183, v87
	v_fmac_f32_dpp v84, v84, v156 row_shl:2 row_mask:0xf bank_mask:0xf bound_ctrl:0
	v_fmac_f32_dpp v85, v85, v157 row_shl:2 row_mask:0xf bank_mask:0xf bound_ctrl:0
	v_fmac_f32_dpp v86, v86, v158 row_shl:2 row_mask:0xf bank_mask:0xf bound_ctrl:0
	v_fmac_f32_dpp v87, v87, v159 row_shl:2 row_mask:0xf bank_mask:0xf bound_ctrl:0
	v_fmac_f32_dpp v84, v88, -v168 row_shl:2 row_mask:0xf bank_mask:0xf bound_ctrl:0
	v_fmac_f32_dpp v85, v89, -v169 row_shl:2 row_mask:0xf bank_mask:0xf bound_ctrl:0
	v_fmac_f32_dpp v86, v90, -v170 row_shl:2 row_mask:0xf bank_mask:0xf bound_ctrl:0
	v_fmac_f32_dpp v87, v91, -v171 row_shl:2 row_mask:0xf bank_mask:0xf bound_ctrl:0
	v_fmac_f32_dpp v88, v88, v156 row_shl:2 row_mask:0xf bank_mask:0xf bound_ctrl:0
	v_fmac_f32_dpp v89, v89, v157 row_shl:2 row_mask:0xf bank_mask:0xf bound_ctrl:0
	v_fmac_f32_dpp v90, v90, v158 row_shl:2 row_mask:0xf bank_mask:0xf bound_ctrl:0
	v_fmac_f32_dpp v91, v91, v159 row_shl:2 row_mask:0xf bank_mask:0xf bound_ctrl:0
	v_fmac_f32_dpp v88, v180, v168 row_shl:2 row_mask:0xf bank_mask:0xf bound_ctrl:0
	v_fmac_f32_dpp v89, v181, v169 row_shl:2 row_mask:0xf bank_mask:0xf bound_ctrl:0
	v_fmac_f32_dpp v90, v182, v170 row_shl:2 row_mask:0xf bank_mask:0xf bound_ctrl:0
	v_fmac_f32_dpp v91, v183, v171 row_shl:2 row_mask:0xf bank_mask:0xf bound_ctrl:0
	ds_read_b128 v[156:159], v9 offset:3712
	ds_read_b128 v[168:171], v9 offset:3968
	s_waitcnt lgkmcnt(2)
	v_mov_b32_e32 v180, v92
	v_mov_b32_e32 v181, v93
	v_mov_b32_e32 v182, v94
	v_mov_b32_e32 v183, v95
	v_fmac_f32_dpp v92, v92, v172 row_shl:2 row_mask:0xf bank_mask:0xf bound_ctrl:0
	v_fmac_f32_dpp v93, v93, v173 row_shl:2 row_mask:0xf bank_mask:0xf bound_ctrl:0
	v_fmac_f32_dpp v94, v94, v174 row_shl:2 row_mask:0xf bank_mask:0xf bound_ctrl:0
	v_fmac_f32_dpp v95, v95, v175 row_shl:2 row_mask:0xf bank_mask:0xf bound_ctrl:0
	v_fmac_f32_dpp v92, v96, -v176 row_shl:2 row_mask:0xf bank_mask:0xf bound_ctrl:0
	v_fmac_f32_dpp v93, v97, -v177 row_shl:2 row_mask:0xf bank_mask:0xf bound_ctrl:0
	v_fmac_f32_dpp v94, v98, -v178 row_shl:2 row_mask:0xf bank_mask:0xf bound_ctrl:0
	v_fmac_f32_dpp v95, v99, -v179 row_shl:2 row_mask:0xf bank_mask:0xf bound_ctrl:0
	v_fmac_f32_dpp v96, v96, v172 row_shl:2 row_mask:0xf bank_mask:0xf bound_ctrl:0
	v_fmac_f32_dpp v97, v97, v173 row_shl:2 row_mask:0xf bank_mask:0xf bound_ctrl:0
	v_fmac_f32_dpp v98, v98, v174 row_shl:2 row_mask:0xf bank_mask:0xf bound_ctrl:0
	v_fmac_f32_dpp v99, v99, v175 row_shl:2 row_mask:0xf bank_mask:0xf bound_ctrl:0
	v_fmac_f32_dpp v96, v180, v176 row_shl:2 row_mask:0xf bank_mask:0xf bound_ctrl:0
	v_fmac_f32_dpp v97, v181, v177 row_shl:2 row_mask:0xf bank_mask:0xf bound_ctrl:0
	v_fmac_f32_dpp v98, v182, v178 row_shl:2 row_mask:0xf bank_mask:0xf bound_ctrl:0
	v_fmac_f32_dpp v99, v183, v179 row_shl:2 row_mask:0xf bank_mask:0xf bound_ctrl:0
	ds_read_b128 v[172:175], v9 offset:3776
	ds_read_b128 v[176:179], v9 offset:4032
	s_waitcnt lgkmcnt(2)
	v_mov_b32_e32 v180, v100
	v_mov_b32_e32 v181, v101
	v_mov_b32_e32 v182, v102
	v_mov_b32_e32 v183, v103
	v_fmac_f32_dpp v100, v100, v156 row_shl:2 row_mask:0xf bank_mask:0xf bound_ctrl:0
	v_fmac_f32_dpp v101, v101, v157 row_shl:2 row_mask:0xf bank_mask:0xf bound_ctrl:0
	v_fmac_f32_dpp v102, v102, v158 row_shl:2 row_mask:0xf bank_mask:0xf bound_ctrl:0
	v_fmac_f32_dpp v103, v103, v159 row_shl:2 row_mask:0xf bank_mask:0xf bound_ctrl:0
	v_fmac_f32_dpp v100, v104, -v168 row_shl:2 row_mask:0xf bank_mask:0xf bound_ctrl:0
	v_fmac_f32_dpp v101, v105, -v169 row_shl:2 row_mask:0xf bank_mask:0xf bound_ctrl:0
	v_fmac_f32_dpp v102, v106, -v170 row_shl:2 row_mask:0xf bank_mask:0xf bound_ctrl:0
	v_fmac_f32_dpp v103, v107, -v171 row_shl:2 row_mask:0xf bank_mask:0xf bound_ctrl:0
	v_fmac_f32_dpp v104, v104, v156 row_shl:2 row_mask:0xf bank_mask:0xf bound_ctrl:0
	v_fmac_f32_dpp v105, v105, v157 row_shl:2 row_mask:0xf bank_mask:0xf bound_ctrl:0
	v_fmac_f32_dpp v106, v106, v158 row_shl:2 row_mask:0xf bank_mask:0xf bound_ctrl:0
	v_fmac_f32_dpp v107, v107, v159 row_shl:2 row_mask:0xf bank_mask:0xf bound_ctrl:0
	v_fmac_f32_dpp v104, v180, v168 row_shl:2 row_mask:0xf bank_mask:0xf bound_ctrl:0
	v_fmac_f32_dpp v105, v181, v169 row_shl:2 row_mask:0xf bank_mask:0xf bound_ctrl:0
	v_fmac_f32_dpp v106, v182, v170 row_shl:2 row_mask:0xf bank_mask:0xf bound_ctrl:0
	v_fmac_f32_dpp v107, v183, v171 row_shl:2 row_mask:0xf bank_mask:0xf bound_ctrl:0
	ds_read_b128 v[156:159], v9 offset:4096
	ds_read_b128 v[168:171], v9 offset:4352
	s_waitcnt lgkmcnt(2)
	v_mov_b32_e32 v180, v108
	v_mov_b32_e32 v181, v109
	v_mov_b32_e32 v182, v110
	v_mov_b32_e32 v183, v111
	v_fmac_f32_dpp v108, v108, v172 row_shl:2 row_mask:0xf bank_mask:0xf bound_ctrl:0
	v_fmac_f32_dpp v109, v109, v173 row_shl:2 row_mask:0xf bank_mask:0xf bound_ctrl:0
	v_fmac_f32_dpp v110, v110, v174 row_shl:2 row_mask:0xf bank_mask:0xf bound_ctrl:0
	v_fmac_f32_dpp v111, v111, v175 row_shl:2 row_mask:0xf bank_mask:0xf bound_ctrl:0
	v_fmac_f32_dpp v108, v112, -v176 row_shl:2 row_mask:0xf bank_mask:0xf bound_ctrl:0
	v_fmac_f32_dpp v109, v113, -v177 row_shl:2 row_mask:0xf bank_mask:0xf bound_ctrl:0
	v_fmac_f32_dpp v110, v114, -v178 row_shl:2 row_mask:0xf bank_mask:0xf bound_ctrl:0
	v_fmac_f32_dpp v111, v115, -v179 row_shl:2 row_mask:0xf bank_mask:0xf bound_ctrl:0
	v_fmac_f32_dpp v112, v112, v172 row_shl:2 row_mask:0xf bank_mask:0xf bound_ctrl:0
	v_fmac_f32_dpp v113, v113, v173 row_shl:2 row_mask:0xf bank_mask:0xf bound_ctrl:0
	v_fmac_f32_dpp v114, v114, v174 row_shl:2 row_mask:0xf bank_mask:0xf bound_ctrl:0
	v_fmac_f32_dpp v115, v115, v175 row_shl:2 row_mask:0xf bank_mask:0xf bound_ctrl:0
	v_fmac_f32_dpp v112, v180, v176 row_shl:2 row_mask:0xf bank_mask:0xf bound_ctrl:0
	v_fmac_f32_dpp v113, v181, v177 row_shl:2 row_mask:0xf bank_mask:0xf bound_ctrl:0
	v_fmac_f32_dpp v114, v182, v178 row_shl:2 row_mask:0xf bank_mask:0xf bound_ctrl:0
	v_fmac_f32_dpp v115, v183, v179 row_shl:2 row_mask:0xf bank_mask:0xf bound_ctrl:0
	ds_read_b128 v[172:175], v9 offset:4160
	ds_read_b128 v[176:179], v9 offset:4416
	s_waitcnt lgkmcnt(2)
	v_mov_b32_e32 v180, v84
	v_mov_b32_e32 v181, v85
	v_mov_b32_e32 v182, v86
	v_mov_b32_e32 v183, v87
	v_fmac_f32_dpp v84, v84, v156 row_shl:4 row_mask:0xf bank_mask:0xf bound_ctrl:0
	v_fmac_f32_dpp v85, v85, v157 row_shl:4 row_mask:0xf bank_mask:0xf bound_ctrl:0
	v_fmac_f32_dpp v86, v86, v158 row_shl:4 row_mask:0xf bank_mask:0xf bound_ctrl:0
	v_fmac_f32_dpp v87, v87, v159 row_shl:4 row_mask:0xf bank_mask:0xf bound_ctrl:0
	v_fmac_f32_dpp v84, v88, -v168 row_shl:4 row_mask:0xf bank_mask:0xf bound_ctrl:0
	v_fmac_f32_dpp v85, v89, -v169 row_shl:4 row_mask:0xf bank_mask:0xf bound_ctrl:0
	v_fmac_f32_dpp v86, v90, -v170 row_shl:4 row_mask:0xf bank_mask:0xf bound_ctrl:0
	v_fmac_f32_dpp v87, v91, -v171 row_shl:4 row_mask:0xf bank_mask:0xf bound_ctrl:0
	v_fmac_f32_dpp v88, v88, v156 row_shl:4 row_mask:0xf bank_mask:0xf bound_ctrl:0
	v_fmac_f32_dpp v89, v89, v157 row_shl:4 row_mask:0xf bank_mask:0xf bound_ctrl:0
	v_fmac_f32_dpp v90, v90, v158 row_shl:4 row_mask:0xf bank_mask:0xf bound_ctrl:0
	v_fmac_f32_dpp v91, v91, v159 row_shl:4 row_mask:0xf bank_mask:0xf bound_ctrl:0
	v_fmac_f32_dpp v88, v180, v168 row_shl:4 row_mask:0xf bank_mask:0xf bound_ctrl:0
	v_fmac_f32_dpp v89, v181, v169 row_shl:4 row_mask:0xf bank_mask:0xf bound_ctrl:0
	v_fmac_f32_dpp v90, v182, v170 row_shl:4 row_mask:0xf bank_mask:0xf bound_ctrl:0
	v_fmac_f32_dpp v91, v183, v171 row_shl:4 row_mask:0xf bank_mask:0xf bound_ctrl:0
	ds_read_b128 v[156:159], v9 offset:4224
	ds_read_b128 v[168:171], v9 offset:4480
	s_waitcnt lgkmcnt(2)
	v_mov_b32_e32 v180, v92
	v_mov_b32_e32 v181, v93
	v_mov_b32_e32 v182, v94
	v_mov_b32_e32 v183, v95
	v_fmac_f32_dpp v92, v92, v172 row_shl:4 row_mask:0xf bank_mask:0xf bound_ctrl:0
	v_fmac_f32_dpp v93, v93, v173 row_shl:4 row_mask:0xf bank_mask:0xf bound_ctrl:0
	v_fmac_f32_dpp v94, v94, v174 row_shl:4 row_mask:0xf bank_mask:0xf bound_ctrl:0
	v_fmac_f32_dpp v95, v95, v175 row_shl:4 row_mask:0xf bank_mask:0xf bound_ctrl:0
	v_fmac_f32_dpp v92, v96, -v176 row_shl:4 row_mask:0xf bank_mask:0xf bound_ctrl:0
	v_fmac_f32_dpp v93, v97, -v177 row_shl:4 row_mask:0xf bank_mask:0xf bound_ctrl:0
	v_fmac_f32_dpp v94, v98, -v178 row_shl:4 row_mask:0xf bank_mask:0xf bound_ctrl:0
	v_fmac_f32_dpp v95, v99, -v179 row_shl:4 row_mask:0xf bank_mask:0xf bound_ctrl:0
	v_fmac_f32_dpp v96, v96, v172 row_shl:4 row_mask:0xf bank_mask:0xf bound_ctrl:0
	v_fmac_f32_dpp v97, v97, v173 row_shl:4 row_mask:0xf bank_mask:0xf bound_ctrl:0
	v_fmac_f32_dpp v98, v98, v174 row_shl:4 row_mask:0xf bank_mask:0xf bound_ctrl:0
	v_fmac_f32_dpp v99, v99, v175 row_shl:4 row_mask:0xf bank_mask:0xf bound_ctrl:0
	v_fmac_f32_dpp v96, v180, v176 row_shl:4 row_mask:0xf bank_mask:0xf bound_ctrl:0
	v_fmac_f32_dpp v97, v181, v177 row_shl:4 row_mask:0xf bank_mask:0xf bound_ctrl:0
	v_fmac_f32_dpp v98, v182, v178 row_shl:4 row_mask:0xf bank_mask:0xf bound_ctrl:0
	v_fmac_f32_dpp v99, v183, v179 row_shl:4 row_mask:0xf bank_mask:0xf bound_ctrl:0
	ds_read_b128 v[172:175], v9 offset:4288
	ds_read_b128 v[176:179], v9 offset:4544
	s_waitcnt lgkmcnt(2)
	v_mov_b32_e32 v180, v100
	v_mov_b32_e32 v181, v101
	v_mov_b32_e32 v182, v102
	v_mov_b32_e32 v183, v103
	v_fmac_f32_dpp v100, v100, v156 row_shl:4 row_mask:0xf bank_mask:0xf bound_ctrl:0
	v_fmac_f32_dpp v101, v101, v157 row_shl:4 row_mask:0xf bank_mask:0xf bound_ctrl:0
	v_fmac_f32_dpp v102, v102, v158 row_shl:4 row_mask:0xf bank_mask:0xf bound_ctrl:0
	v_fmac_f32_dpp v103, v103, v159 row_shl:4 row_mask:0xf bank_mask:0xf bound_ctrl:0
	v_fmac_f32_dpp v100, v104, -v168 row_shl:4 row_mask:0xf bank_mask:0xf bound_ctrl:0
	v_fmac_f32_dpp v101, v105, -v169 row_shl:4 row_mask:0xf bank_mask:0xf bound_ctrl:0
	v_fmac_f32_dpp v102, v106, -v170 row_shl:4 row_mask:0xf bank_mask:0xf bound_ctrl:0
	v_fmac_f32_dpp v103, v107, -v171 row_shl:4 row_mask:0xf bank_mask:0xf bound_ctrl:0
	v_fmac_f32_dpp v104, v104, v156 row_shl:4 row_mask:0xf bank_mask:0xf bound_ctrl:0
	v_fmac_f32_dpp v105, v105, v157 row_shl:4 row_mask:0xf bank_mask:0xf bound_ctrl:0
	v_fmac_f32_dpp v106, v106, v158 row_shl:4 row_mask:0xf bank_mask:0xf bound_ctrl:0
	v_fmac_f32_dpp v107, v107, v159 row_shl:4 row_mask:0xf bank_mask:0xf bound_ctrl:0
	v_fmac_f32_dpp v104, v180, v168 row_shl:4 row_mask:0xf bank_mask:0xf bound_ctrl:0
	v_fmac_f32_dpp v105, v181, v169 row_shl:4 row_mask:0xf bank_mask:0xf bound_ctrl:0
	v_fmac_f32_dpp v106, v182, v170 row_shl:4 row_mask:0xf bank_mask:0xf bound_ctrl:0
	v_fmac_f32_dpp v107, v183, v171 row_shl:4 row_mask:0xf bank_mask:0xf bound_ctrl:0
	ds_read_b128 v[156:159], v9 offset:4608
	ds_read_b128 v[168:171], v9 offset:4864
	s_waitcnt lgkmcnt(2)
	v_mov_b32_e32 v180, v108
	v_mov_b32_e32 v181, v109
	v_mov_b32_e32 v182, v110
	v_mov_b32_e32 v183, v111
	v_fmac_f32_dpp v108, v108, v172 row_shl:4 row_mask:0xf bank_mask:0xf bound_ctrl:0
	v_fmac_f32_dpp v109, v109, v173 row_shl:4 row_mask:0xf bank_mask:0xf bound_ctrl:0
	v_fmac_f32_dpp v110, v110, v174 row_shl:4 row_mask:0xf bank_mask:0xf bound_ctrl:0
	v_fmac_f32_dpp v111, v111, v175 row_shl:4 row_mask:0xf bank_mask:0xf bound_ctrl:0
	v_fmac_f32_dpp v108, v112, -v176 row_shl:4 row_mask:0xf bank_mask:0xf bound_ctrl:0
	v_fmac_f32_dpp v109, v113, -v177 row_shl:4 row_mask:0xf bank_mask:0xf bound_ctrl:0
	v_fmac_f32_dpp v110, v114, -v178 row_shl:4 row_mask:0xf bank_mask:0xf bound_ctrl:0
	v_fmac_f32_dpp v111, v115, -v179 row_shl:4 row_mask:0xf bank_mask:0xf bound_ctrl:0
	v_fmac_f32_dpp v112, v112, v172 row_shl:4 row_mask:0xf bank_mask:0xf bound_ctrl:0
	v_fmac_f32_dpp v113, v113, v173 row_shl:4 row_mask:0xf bank_mask:0xf bound_ctrl:0
	v_fmac_f32_dpp v114, v114, v174 row_shl:4 row_mask:0xf bank_mask:0xf bound_ctrl:0
	v_fmac_f32_dpp v115, v115, v175 row_shl:4 row_mask:0xf bank_mask:0xf bound_ctrl:0
	v_fmac_f32_dpp v112, v180, v176 row_shl:4 row_mask:0xf bank_mask:0xf bound_ctrl:0
	v_fmac_f32_dpp v113, v181, v177 row_shl:4 row_mask:0xf bank_mask:0xf bound_ctrl:0
	v_fmac_f32_dpp v114, v182, v178 row_shl:4 row_mask:0xf bank_mask:0xf bound_ctrl:0
	v_fmac_f32_dpp v115, v183, v179 row_shl:4 row_mask:0xf bank_mask:0xf bound_ctrl:0
	ds_read_b128 v[172:175], v9 offset:4672
	ds_read_b128 v[176:179], v9 offset:4928
	s_waitcnt lgkmcnt(2)
	v_mov_b32_e32 v180, v84
	v_mov_b32_e32 v181, v85
	v_mov_b32_e32 v182, v86
	v_mov_b32_e32 v183, v87
	v_fmac_f32_dpp v84, v84, v156 row_shl:8 row_mask:0xf bank_mask:0xf bound_ctrl:0
	v_fmac_f32_dpp v85, v85, v157 row_shl:8 row_mask:0xf bank_mask:0xf bound_ctrl:0
	v_fmac_f32_dpp v86, v86, v158 row_shl:8 row_mask:0xf bank_mask:0xf bound_ctrl:0
	v_fmac_f32_dpp v87, v87, v159 row_shl:8 row_mask:0xf bank_mask:0xf bound_ctrl:0
	v_fmac_f32_dpp v84, v88, -v168 row_shl:8 row_mask:0xf bank_mask:0xf bound_ctrl:0
	v_fmac_f32_dpp v85, v89, -v169 row_shl:8 row_mask:0xf bank_mask:0xf bound_ctrl:0
	v_fmac_f32_dpp v86, v90, -v170 row_shl:8 row_mask:0xf bank_mask:0xf bound_ctrl:0
	v_fmac_f32_dpp v87, v91, -v171 row_shl:8 row_mask:0xf bank_mask:0xf bound_ctrl:0
	v_fmac_f32_dpp v88, v88, v156 row_shl:8 row_mask:0xf bank_mask:0xf bound_ctrl:0
	v_fmac_f32_dpp v89, v89, v157 row_shl:8 row_mask:0xf bank_mask:0xf bound_ctrl:0
	v_fmac_f32_dpp v90, v90, v158 row_shl:8 row_mask:0xf bank_mask:0xf bound_ctrl:0
	v_fmac_f32_dpp v91, v91, v159 row_shl:8 row_mask:0xf bank_mask:0xf bound_ctrl:0
	v_fmac_f32_dpp v88, v180, v168 row_shl:8 row_mask:0xf bank_mask:0xf bound_ctrl:0
	v_fmac_f32_dpp v89, v181, v169 row_shl:8 row_mask:0xf bank_mask:0xf bound_ctrl:0
	v_fmac_f32_dpp v90, v182, v170 row_shl:8 row_mask:0xf bank_mask:0xf bound_ctrl:0
	v_fmac_f32_dpp v91, v183, v171 row_shl:8 row_mask:0xf bank_mask:0xf bound_ctrl:0
	ds_read_b128 v[156:159], v9 offset:4736
	ds_read_b128 v[168:171], v9 offset:4992
	s_waitcnt lgkmcnt(2)
	v_mov_b32_e32 v180, v92
	v_mov_b32_e32 v181, v93
	v_mov_b32_e32 v182, v94
	v_mov_b32_e32 v183, v95
	v_fmac_f32_dpp v92, v92, v172 row_shl:8 row_mask:0xf bank_mask:0xf bound_ctrl:0
	v_fmac_f32_dpp v93, v93, v173 row_shl:8 row_mask:0xf bank_mask:0xf bound_ctrl:0
	v_fmac_f32_dpp v94, v94, v174 row_shl:8 row_mask:0xf bank_mask:0xf bound_ctrl:0
	v_fmac_f32_dpp v95, v95, v175 row_shl:8 row_mask:0xf bank_mask:0xf bound_ctrl:0
	v_fmac_f32_dpp v92, v96, -v176 row_shl:8 row_mask:0xf bank_mask:0xf bound_ctrl:0
	v_fmac_f32_dpp v93, v97, -v177 row_shl:8 row_mask:0xf bank_mask:0xf bound_ctrl:0
	v_fmac_f32_dpp v94, v98, -v178 row_shl:8 row_mask:0xf bank_mask:0xf bound_ctrl:0
	v_fmac_f32_dpp v95, v99, -v179 row_shl:8 row_mask:0xf bank_mask:0xf bound_ctrl:0
	v_fmac_f32_dpp v96, v96, v172 row_shl:8 row_mask:0xf bank_mask:0xf bound_ctrl:0
	v_fmac_f32_dpp v97, v97, v173 row_shl:8 row_mask:0xf bank_mask:0xf bound_ctrl:0
	v_fmac_f32_dpp v98, v98, v174 row_shl:8 row_mask:0xf bank_mask:0xf bound_ctrl:0
	v_fmac_f32_dpp v99, v99, v175 row_shl:8 row_mask:0xf bank_mask:0xf bound_ctrl:0
	v_fmac_f32_dpp v96, v180, v176 row_shl:8 row_mask:0xf bank_mask:0xf bound_ctrl:0
	v_fmac_f32_dpp v97, v181, v177 row_shl:8 row_mask:0xf bank_mask:0xf bound_ctrl:0
	v_fmac_f32_dpp v98, v182, v178 row_shl:8 row_mask:0xf bank_mask:0xf bound_ctrl:0
	v_fmac_f32_dpp v99, v183, v179 row_shl:8 row_mask:0xf bank_mask:0xf bound_ctrl:0
	ds_read_b128 v[172:175], v9 offset:4800
	ds_read_b128 v[176:179], v9 offset:5056
	s_waitcnt lgkmcnt(2)
	v_mov_b32_e32 v180, v100
	v_mov_b32_e32 v181, v101
	v_mov_b32_e32 v182, v102
	v_mov_b32_e32 v183, v103
	v_fmac_f32_dpp v100, v100, v156 row_shl:8 row_mask:0xf bank_mask:0xf bound_ctrl:0
	v_fmac_f32_dpp v101, v101, v157 row_shl:8 row_mask:0xf bank_mask:0xf bound_ctrl:0
	v_fmac_f32_dpp v102, v102, v158 row_shl:8 row_mask:0xf bank_mask:0xf bound_ctrl:0
	v_fmac_f32_dpp v103, v103, v159 row_shl:8 row_mask:0xf bank_mask:0xf bound_ctrl:0
	v_fmac_f32_dpp v100, v104, -v168 row_shl:8 row_mask:0xf bank_mask:0xf bound_ctrl:0
	v_fmac_f32_dpp v101, v105, -v169 row_shl:8 row_mask:0xf bank_mask:0xf bound_ctrl:0
	v_fmac_f32_dpp v102, v106, -v170 row_shl:8 row_mask:0xf bank_mask:0xf bound_ctrl:0
	v_fmac_f32_dpp v103, v107, -v171 row_shl:8 row_mask:0xf bank_mask:0xf bound_ctrl:0
	v_fmac_f32_dpp v104, v104, v156 row_shl:8 row_mask:0xf bank_mask:0xf bound_ctrl:0
	v_fmac_f32_dpp v105, v105, v157 row_shl:8 row_mask:0xf bank_mask:0xf bound_ctrl:0
	v_fmac_f32_dpp v106, v106, v158 row_shl:8 row_mask:0xf bank_mask:0xf bound_ctrl:0
	v_fmac_f32_dpp v107, v107, v159 row_shl:8 row_mask:0xf bank_mask:0xf bound_ctrl:0
	v_fmac_f32_dpp v104, v180, v168 row_shl:8 row_mask:0xf bank_mask:0xf bound_ctrl:0
	v_fmac_f32_dpp v105, v181, v169 row_shl:8 row_mask:0xf bank_mask:0xf bound_ctrl:0
	v_fmac_f32_dpp v106, v182, v170 row_shl:8 row_mask:0xf bank_mask:0xf bound_ctrl:0
	v_fmac_f32_dpp v107, v183, v171 row_shl:8 row_mask:0xf bank_mask:0xf bound_ctrl:0
	s_waitcnt lgkmcnt(0)
	v_mov_b32_e32 v180, v108
	v_mov_b32_e32 v181, v109
	v_mov_b32_e32 v182, v110
	v_mov_b32_e32 v183, v111
	v_fmac_f32_dpp v108, v108, v172 row_shl:8 row_mask:0xf bank_mask:0xf bound_ctrl:0
	v_fmac_f32_dpp v109, v109, v173 row_shl:8 row_mask:0xf bank_mask:0xf bound_ctrl:0
	v_fmac_f32_dpp v110, v110, v174 row_shl:8 row_mask:0xf bank_mask:0xf bound_ctrl:0
	v_fmac_f32_dpp v111, v111, v175 row_shl:8 row_mask:0xf bank_mask:0xf bound_ctrl:0
	v_fmac_f32_dpp v108, v112, -v176 row_shl:8 row_mask:0xf bank_mask:0xf bound_ctrl:0
	v_fmac_f32_dpp v109, v113, -v177 row_shl:8 row_mask:0xf bank_mask:0xf bound_ctrl:0
	v_fmac_f32_dpp v110, v114, -v178 row_shl:8 row_mask:0xf bank_mask:0xf bound_ctrl:0
	v_fmac_f32_dpp v111, v115, -v179 row_shl:8 row_mask:0xf bank_mask:0xf bound_ctrl:0
	v_fmac_f32_dpp v112, v112, v172 row_shl:8 row_mask:0xf bank_mask:0xf bound_ctrl:0
	v_fmac_f32_dpp v113, v113, v173 row_shl:8 row_mask:0xf bank_mask:0xf bound_ctrl:0
	v_fmac_f32_dpp v114, v114, v174 row_shl:8 row_mask:0xf bank_mask:0xf bound_ctrl:0
	v_fmac_f32_dpp v115, v115, v175 row_shl:8 row_mask:0xf bank_mask:0xf bound_ctrl:0
	v_fmac_f32_dpp v112, v180, v176 row_shl:8 row_mask:0xf bank_mask:0xf bound_ctrl:0
	v_fmac_f32_dpp v113, v181, v177 row_shl:8 row_mask:0xf bank_mask:0xf bound_ctrl:0
	v_fmac_f32_dpp v114, v182, v178 row_shl:8 row_mask:0xf bank_mask:0xf bound_ctrl:0
	v_fmac_f32_dpp v115, v183, v179 row_shl:8 row_mask:0xf bank_mask:0xf bound_ctrl:0
	ds_read_b128 v[156:159], v9 offset:2560
	ds_read_b128 v[168:171], v9 offset:2816
	ds_read_b128 v[172:175], v9 offset:2624
	ds_read_b128 v[176:179], v9 offset:2880
	s_waitcnt lgkmcnt(2)
	s_nop 1
	v_fmac_f32_dpp v116, v84, v156 row_shl:1 row_mask:0xf bank_mask:0xf bound_ctrl:0
	v_fmac_f32_dpp v117, v85, v157 row_shl:1 row_mask:0xf bank_mask:0xf bound_ctrl:0
	v_fmac_f32_dpp v118, v86, v158 row_shl:1 row_mask:0xf bank_mask:0xf bound_ctrl:0
	v_fmac_f32_dpp v119, v87, v159 row_shl:1 row_mask:0xf bank_mask:0xf bound_ctrl:0
	v_fmac_f32_dpp v116, v88, -v168 row_shl:1 row_mask:0xf bank_mask:0xf bound_ctrl:0
	v_fmac_f32_dpp v117, v89, -v169 row_shl:1 row_mask:0xf bank_mask:0xf bound_ctrl:0
	v_fmac_f32_dpp v118, v90, -v170 row_shl:1 row_mask:0xf bank_mask:0xf bound_ctrl:0
	v_fmac_f32_dpp v119, v91, -v171 row_shl:1 row_mask:0xf bank_mask:0xf bound_ctrl:0
	v_fmac_f32_dpp v120, v88, v156 row_shl:1 row_mask:0xf bank_mask:0xf bound_ctrl:0
	v_fmac_f32_dpp v121, v89, v157 row_shl:1 row_mask:0xf bank_mask:0xf bound_ctrl:0
	v_fmac_f32_dpp v122, v90, v158 row_shl:1 row_mask:0xf bank_mask:0xf bound_ctrl:0
	v_fmac_f32_dpp v123, v91, v159 row_shl:1 row_mask:0xf bank_mask:0xf bound_ctrl:0
	v_fmac_f32_dpp v120, v84, v168 row_shl:1 row_mask:0xf bank_mask:0xf bound_ctrl:0
	v_fmac_f32_dpp v121, v85, v169 row_shl:1 row_mask:0xf bank_mask:0xf bound_ctrl:0
	v_fmac_f32_dpp v122, v86, v170 row_shl:1 row_mask:0xf bank_mask:0xf bound_ctrl:0
	v_fmac_f32_dpp v123, v87, v171 row_shl:1 row_mask:0xf bank_mask:0xf bound_ctrl:0
	ds_read_b128 v[156:159], v9 offset:2688
	ds_read_b128 v[168:171], v9 offset:2944
	s_waitcnt lgkmcnt(2)
	v_fmac_f32_dpp v124, v92, v172 row_shl:1 row_mask:0xf bank_mask:0xf bound_ctrl:0
	v_fmac_f32_dpp v125, v93, v173 row_shl:1 row_mask:0xf bank_mask:0xf bound_ctrl:0
	v_fmac_f32_dpp v126, v94, v174 row_shl:1 row_mask:0xf bank_mask:0xf bound_ctrl:0
	v_fmac_f32_dpp v127, v95, v175 row_shl:1 row_mask:0xf bank_mask:0xf bound_ctrl:0
	v_fmac_f32_dpp v124, v96, -v176 row_shl:1 row_mask:0xf bank_mask:0xf bound_ctrl:0
	v_fmac_f32_dpp v125, v97, -v177 row_shl:1 row_mask:0xf bank_mask:0xf bound_ctrl:0
	v_fmac_f32_dpp v126, v98, -v178 row_shl:1 row_mask:0xf bank_mask:0xf bound_ctrl:0
	v_fmac_f32_dpp v127, v99, -v179 row_shl:1 row_mask:0xf bank_mask:0xf bound_ctrl:0
	v_fmac_f32_dpp v128, v96, v172 row_shl:1 row_mask:0xf bank_mask:0xf bound_ctrl:0
	v_fmac_f32_dpp v129, v97, v173 row_shl:1 row_mask:0xf bank_mask:0xf bound_ctrl:0
	v_fmac_f32_dpp v130, v98, v174 row_shl:1 row_mask:0xf bank_mask:0xf bound_ctrl:0
	v_fmac_f32_dpp v131, v99, v175 row_shl:1 row_mask:0xf bank_mask:0xf bound_ctrl:0
	v_fmac_f32_dpp v128, v92, v176 row_shl:1 row_mask:0xf bank_mask:0xf bound_ctrl:0
	v_fmac_f32_dpp v129, v93, v177 row_shl:1 row_mask:0xf bank_mask:0xf bound_ctrl:0
	v_fmac_f32_dpp v130, v94, v178 row_shl:1 row_mask:0xf bank_mask:0xf bound_ctrl:0
	v_fmac_f32_dpp v131, v95, v179 row_shl:1 row_mask:0xf bank_mask:0xf bound_ctrl:0
	ds_read_b128 v[172:175], v9 offset:2752
	ds_read_b128 v[176:179], v9 offset:3008
	s_waitcnt lgkmcnt(2)
	v_fmac_f32_dpp v140, v100, v156 row_shl:1 row_mask:0xf bank_mask:0xf bound_ctrl:0
	v_fmac_f32_dpp v141, v101, v157 row_shl:1 row_mask:0xf bank_mask:0xf bound_ctrl:0
	v_fmac_f32_dpp v142, v102, v158 row_shl:1 row_mask:0xf bank_mask:0xf bound_ctrl:0
	v_fmac_f32_dpp v143, v103, v159 row_shl:1 row_mask:0xf bank_mask:0xf bound_ctrl:0
	v_fmac_f32_dpp v140, v104, -v168 row_shl:1 row_mask:0xf bank_mask:0xf bound_ctrl:0
	v_fmac_f32_dpp v141, v105, -v169 row_shl:1 row_mask:0xf bank_mask:0xf bound_ctrl:0
	v_fmac_f32_dpp v142, v106, -v170 row_shl:1 row_mask:0xf bank_mask:0xf bound_ctrl:0
	v_fmac_f32_dpp v143, v107, -v171 row_shl:1 row_mask:0xf bank_mask:0xf bound_ctrl:0
	v_fmac_f32_dpp v144, v104, v156 row_shl:1 row_mask:0xf bank_mask:0xf bound_ctrl:0
	v_fmac_f32_dpp v145, v105, v157 row_shl:1 row_mask:0xf bank_mask:0xf bound_ctrl:0
	v_fmac_f32_dpp v146, v106, v158 row_shl:1 row_mask:0xf bank_mask:0xf bound_ctrl:0
	v_fmac_f32_dpp v147, v107, v159 row_shl:1 row_mask:0xf bank_mask:0xf bound_ctrl:0
	v_fmac_f32_dpp v144, v100, v168 row_shl:1 row_mask:0xf bank_mask:0xf bound_ctrl:0
	v_fmac_f32_dpp v145, v101, v169 row_shl:1 row_mask:0xf bank_mask:0xf bound_ctrl:0
	v_fmac_f32_dpp v146, v102, v170 row_shl:1 row_mask:0xf bank_mask:0xf bound_ctrl:0
	v_fmac_f32_dpp v147, v103, v171 row_shl:1 row_mask:0xf bank_mask:0xf bound_ctrl:0
	s_waitcnt lgkmcnt(0)
	v_fmac_f32_dpp v148, v108, v172 row_shl:1 row_mask:0xf bank_mask:0xf bound_ctrl:0
	v_fmac_f32_dpp v149, v109, v173 row_shl:1 row_mask:0xf bank_mask:0xf bound_ctrl:0
	v_fmac_f32_dpp v150, v110, v174 row_shl:1 row_mask:0xf bank_mask:0xf bound_ctrl:0
	v_fmac_f32_dpp v151, v111, v175 row_shl:1 row_mask:0xf bank_mask:0xf bound_ctrl:0
	v_fmac_f32_dpp v148, v112, -v176 row_shl:1 row_mask:0xf bank_mask:0xf bound_ctrl:0
	v_fmac_f32_dpp v149, v113, -v177 row_shl:1 row_mask:0xf bank_mask:0xf bound_ctrl:0
	v_fmac_f32_dpp v150, v114, -v178 row_shl:1 row_mask:0xf bank_mask:0xf bound_ctrl:0
	v_fmac_f32_dpp v151, v115, -v179 row_shl:1 row_mask:0xf bank_mask:0xf bound_ctrl:0
	v_fmac_f32_dpp v152, v112, v172 row_shl:1 row_mask:0xf bank_mask:0xf bound_ctrl:0
	v_fmac_f32_dpp v153, v113, v173 row_shl:1 row_mask:0xf bank_mask:0xf bound_ctrl:0
	v_fmac_f32_dpp v154, v114, v174 row_shl:1 row_mask:0xf bank_mask:0xf bound_ctrl:0
	v_fmac_f32_dpp v155, v115, v175 row_shl:1 row_mask:0xf bank_mask:0xf bound_ctrl:0
	v_fmac_f32_dpp v152, v108, v176 row_shl:1 row_mask:0xf bank_mask:0xf bound_ctrl:0
	v_fmac_f32_dpp v153, v109, v177 row_shl:1 row_mask:0xf bank_mask:0xf bound_ctrl:0
	v_fmac_f32_dpp v154, v110, v178 row_shl:1 row_mask:0xf bank_mask:0xf bound_ctrl:0
	v_fmac_f32_dpp v155, v111, v179 row_shl:1 row_mask:0xf bank_mask:0xf bound_ctrl:0
	s_waitcnt vmcnt(18)
	v_xor_b32_e32 v56, 0x80000000, v56
	v_xor_b32_e32 v57, 0x80000000, v57
	v_xor_b32_e32 v58, 0x80000000, v58
	v_xor_b32_e32 v59, 0x80000000, v59
	v_xor_b32_e32 v64, 0x80000000, v64
	v_xor_b32_e32 v65, 0x80000000, v65
	v_xor_b32_e32 v66, 0x80000000, v66
	v_xor_b32_e32 v67, 0x80000000, v67
	v_xor_b32_e32 v72, 0x80000000, v72
	v_xor_b32_e32 v73, 0x80000000, v73
	v_xor_b32_e32 v74, 0x80000000, v74
	v_xor_b32_e32 v75, 0x80000000, v75
	v_xor_b32_e32 v80, 0x80000000, v80
	v_xor_b32_e32 v81, 0x80000000, v81
	v_xor_b32_e32 v82, 0x80000000, v82
	v_xor_b32_e32 v83, 0x80000000, v83
	s_nop 1
	v_mfma_f32_16x16x4_f32 v[192:195], v84, v52, v[192:195]
	v_mfma_f32_16x16x4_f32 v[228:231], v88, v56, v[228:231]
	v_mfma_f32_16x16x4_f32 v[224:227], v116, v52, v[224:227]
	v_mfma_f32_16x16x4_f32 v[232:235], v120, v56, v[232:235]
	v_mfma_f32_16x16x4_f32 v[192:195], v85, v53, v[192:195]
	v_mfma_f32_16x16x4_f32 v[228:231], v89, v57, v[228:231]
	v_mfma_f32_16x16x4_f32 v[224:227], v117, v53, v[224:227]
	v_mfma_f32_16x16x4_f32 v[232:235], v121, v57, v[232:235]
	v_mfma_f32_16x16x4_f32 v[192:195], v86, v54, v[192:195]
	v_mfma_f32_16x16x4_f32 v[228:231], v90, v58, v[228:231]
	v_mfma_f32_16x16x4_f32 v[224:227], v118, v54, v[224:227]
	v_mfma_f32_16x16x4_f32 v[232:235], v122, v58, v[232:235]
	v_mfma_f32_16x16x4_f32 v[192:195], v87, v55, v[192:195]
	v_mfma_f32_16x16x4_f32 v[228:231], v91, v59, v[228:231]
	v_mfma_f32_16x16x4_f32 v[224:227], v119, v55, v[224:227]
	v_mfma_f32_16x16x4_f32 v[232:235], v123, v59, v[232:235]
	v_mfma_f32_16x16x4_f32 v[192:195], v92, v60, v[192:195]
	v_mfma_f32_16x16x4_f32 v[228:231], v96, v64, v[228:231]
	v_mfma_f32_16x16x4_f32 v[224:227], v124, v60, v[224:227]
	v_mfma_f32_16x16x4_f32 v[232:235], v128, v64, v[232:235]
	v_mfma_f32_16x16x4_f32 v[192:195], v93, v61, v[192:195]
	v_mfma_f32_16x16x4_f32 v[228:231], v97, v65, v[228:231]
	v_mfma_f32_16x16x4_f32 v[224:227], v125, v61, v[224:227]
	v_mfma_f32_16x16x4_f32 v[232:235], v129, v65, v[232:235]
	v_mfma_f32_16x16x4_f32 v[192:195], v94, v62, v[192:195]
	v_mfma_f32_16x16x4_f32 v[228:231], v98, v66, v[228:231]
	v_mfma_f32_16x16x4_f32 v[224:227], v126, v62, v[224:227]
	v_mfma_f32_16x16x4_f32 v[232:235], v130, v66, v[232:235]
	v_mfma_f32_16x16x4_f32 v[192:195], v95, v63, v[192:195]
	v_mfma_f32_16x16x4_f32 v[228:231], v99, v67, v[228:231]
	v_mfma_f32_16x16x4_f32 v[224:227], v127, v63, v[224:227]
	v_mfma_f32_16x16x4_f32 v[232:235], v131, v67, v[232:235]
	v_mfma_f32_16x16x4_f32 v[192:195], v100, v68, v[192:195]
	v_mfma_f32_16x16x4_f32 v[228:231], v104, v72, v[228:231]
	v_mfma_f32_16x16x4_f32 v[224:227], v140, v68, v[224:227]
	v_mfma_f32_16x16x4_f32 v[232:235], v144, v72, v[232:235]
	v_mfma_f32_16x16x4_f32 v[192:195], v101, v69, v[192:195]
	v_mfma_f32_16x16x4_f32 v[228:231], v105, v73, v[228:231]
	v_mfma_f32_16x16x4_f32 v[224:227], v141, v69, v[224:227]
	v_mfma_f32_16x16x4_f32 v[232:235], v145, v73, v[232:235]
	v_mfma_f32_16x16x4_f32 v[192:195], v102, v70, v[192:195]
	v_mfma_f32_16x16x4_f32 v[228:231], v106, v74, v[228:231]
	v_mfma_f32_16x16x4_f32 v[224:227], v142, v70, v[224:227]
	v_mfma_f32_16x16x4_f32 v[232:235], v146, v74, v[232:235]
	v_mfma_f32_16x16x4_f32 v[192:195], v103, v71, v[192:195]
	v_mfma_f32_16x16x4_f32 v[228:231], v107, v75, v[228:231]
	v_mfma_f32_16x16x4_f32 v[224:227], v143, v71, v[224:227]
	v_mfma_f32_16x16x4_f32 v[232:235], v147, v75, v[232:235]
	v_mfma_f32_16x16x4_f32 v[192:195], v108, v76, v[192:195]
	v_mfma_f32_16x16x4_f32 v[228:231], v112, v80, v[228:231]
	v_mfma_f32_16x16x4_f32 v[224:227], v148, v76, v[224:227]
	v_mfma_f32_16x16x4_f32 v[232:235], v152, v80, v[232:235]
	v_mfma_f32_16x16x4_f32 v[192:195], v109, v77, v[192:195]
	v_mfma_f32_16x16x4_f32 v[228:231], v113, v81, v[228:231]
	v_mfma_f32_16x16x4_f32 v[224:227], v149, v77, v[224:227]
	v_mfma_f32_16x16x4_f32 v[232:235], v153, v81, v[232:235]
	v_mfma_f32_16x16x4_f32 v[192:195], v110, v78, v[192:195]
	v_mfma_f32_16x16x4_f32 v[228:231], v114, v82, v[228:231]
	v_mfma_f32_16x16x4_f32 v[224:227], v150, v78, v[224:227]
	v_mfma_f32_16x16x4_f32 v[232:235], v154, v82, v[232:235]
	v_mfma_f32_16x16x4_f32 v[192:195], v111, v79, v[192:195]
	v_mfma_f32_16x16x4_f32 v[228:231], v115, v83, v[228:231]
	v_mfma_f32_16x16x4_f32 v[224:227], v151, v79, v[224:227]
	v_mfma_f32_16x16x4_f32 v[232:235], v155, v83, v[232:235]
	s_lshl_b32 s56, s1, 5
	s_add_i32 s55, s6, 0
	s_lshl_b32 s55, s55, 1
	s_add_i32 s56, s56, s55
	s_add_i32 s56, s56, 0
	s_lshl_b32 s56, s56, 9
	s_add_u32 s48, s94, 0x133d6000
	s_addc_u32 s49, s95, 0
	s_add_u32 s48, s48, s56
	s_addc_u32 s49, s49, 0
	global_load_dwordx4 v[52:55], v15, s[48:49] offset:0
	global_load_dwordx4 v[56:59], v15, s[48:49] offset:16
	global_load_dwordx4 v[60:63], v15, s[48:49] offset:128
	global_load_dwordx4 v[64:67], v15, s[48:49] offset:144
	global_load_dwordx4 v[68:71], v15, s[48:49] offset:256
	global_load_dwordx4 v[72:75], v15, s[48:49] offset:272
	global_load_dwordx4 v[76:79], v15, s[48:49] offset:384
	global_load_dwordx4 v[80:83], v15, s[48:49] offset:400
	s_cmp_ge_u32 s0, 128
	s_cbranch_scc1 .Ls5b_nofin5
	s_and_b32 s55, s0, 7
	s_cmp_lg_u32 s55, 0
	s_cbranch_scc1 .Ls5b_nofin5
	s_lshr_b32 s55, s0, 3
	s_lshl_b32 s55, s55, 2
	s_add_i32 s55, s55, s32
	s_lshl_b32 s55, s55, 1
	s_add_i32 s55, s55, 1
	s_lshl_b32 s55, s55, 4
	s_add_i32 s55, s55, s6
	s_lshl_b32 s55, s55, 8
	s_add_u32 s48, s92, 0x4000000
	s_addc_u32 s49, s93, 0
	s_add_u32 s48, s48, s55
	s_addc_u32 s49, s49, 0
	s_add_u32 s50, s48, 0x80000
	s_addc_u32 s51, s49, 0
	s_mov_b64 exec, s[52:53]
	global_store_dwordx4 v10, v[84:87], s[48:49] offset:0
	global_store_dwordx4 v10, v[88:91], s[50:51] offset:0
	global_store_dwordx4 v10, v[92:95], s[48:49] offset:64
	global_store_dwordx4 v10, v[96:99], s[50:51] offset:64
	global_store_dwordx4 v10, v[100:103], s[48:49] offset:128
	global_store_dwordx4 v10, v[104:107], s[50:51] offset:128
	global_store_dwordx4 v10, v[108:111], s[48:49] offset:192
	global_store_dwordx4 v10, v[112:115], s[50:51] offset:192
	s_mov_b64 exec, -1
	s_waitcnt vmcnt(0)
.Ls5b_nofin5:
	s_waitcnt vmcnt(8)
	s_nop 9
	v_add_f32_e32 v192, v192, v228
	v_add_f32_e32 v193, v193, v229
	v_add_f32_e32 v194, v194, v230
	v_add_f32_e32 v195, v195, v231
	v_add_f32_e32 v224, v224, v232
	v_add_f32_e32 v225, v225, v233
	v_add_f32_e32 v226, v226, v234
	v_add_f32_e32 v227, v227, v235
	v_fmac_f32_e32 v192, v236, v0
	v_fmac_f32_e32 v193, v237, v0
	v_fmac_f32_e32 v194, v238, v0
	v_fmac_f32_e32 v195, v239, v0
	v_fmac_f32_e32 v224, v240, v0
	v_fmac_f32_e32 v225, v241, v0
	v_fmac_f32_e32 v226, v242, v0
	v_fmac_f32_e32 v227, v243, v0
	v_cvt_pk_bf16_f32 v228, v192, v192
	v_cvt_pk_bf16_f32 v229, v193, v193
	v_cvt_pk_bf16_f32 v230, v194, v194
	v_cvt_pk_bf16_f32 v231, v195, v195
	v_cvt_pk_bf16_f32 v232, v224, v224
	v_cvt_pk_bf16_f32 v233, v225, v225
	v_cvt_pk_bf16_f32 v234, v226, v226
	v_cvt_pk_bf16_f32 v235, v227, v227
	s_waitcnt vmcnt(0)
	global_store_short v13, v228, s[44:45] offset:0
	global_store_short v13, v229, s[44:45] offset:1024
	global_store_short v13, v230, s[44:45] offset:2048
	global_store_short v13, v231, s[44:45] offset:3072
	global_store_short v13, v232, s[44:45] offset:512
	global_store_short v13, v233, s[44:45] offset:1536
	global_store_short v13, v234, s[44:45] offset:2560
	global_store_short v13, v235, s[44:45] offset:3584
	s_add_i32 s55, s23, s84
	s_cmp_lt_i32 s55, 768
	s_cbranch_scc0 .Ls5b_exit3
	s_mov_b32 s23, s55
	s_mov_b32 s0, s1
	s_branch .Ls5b_head1
.Ls5b_exit3:
	s_waitcnt vmcnt(0)
	s_movk_i32 s33, 0x1ff
	v_readlane_b32 s4, v249, 11
	v_readlane_b32 s5, v249, 12
	v_readlane_b32 s6, v249, 13
	v_readlane_b32 s7, v249, 14
	v_readlane_b32 s8, v249, 15
	v_readlane_b32 s9, v249, 16
	v_readlane_b32 s10, v249, 17
	v_readlane_b32 s11, v249, 18
	v_readlane_b32 s12, v249, 19
	v_readlane_b32 s13, v249, 20
	v_readlane_b32 s14, v249, 21
	v_readlane_b32 s15, v249, 22
	v_readlane_b32 s16, v249, 23
	v_readlane_b32 s17, v249, 24
	v_readlane_b32 s18, v249, 25
	v_readlane_b32 s19, v249, 26
	s_branch .LBB0_408

.LBB0_608:
	s_and_b64 vcc, exec, s[0:1]
	s_cbranch_vccz .LBB0_618
	s_add_i32 s0, s86, 0xffffff00
	v_lshrrev_b32_e32 v0, 6, v135
	v_readlane_b32 s32, v249, 47
	v_readfirstlane_b32 s4, v0
	s_nop 3
	s_lshl_b32 s6, s4, 1
	v_and_b32_e32 v2, 63, v135
	v_lshrrev_b32_e32 v3, 4, v2
	v_and_b32_e32 v4, 15, v2
	v_lshlrev_b32_e32 v5, 11, v4
	v_lshl_add_u32 v5, v3, 4, v5
	v_lshlrev_b32_e32 v6, 4, v4
	v_lshl_add_u32 v6, v3, 11, v6
	v_lshlrev_b32_e32 v7, 3, v2
	v_lshlrev_b32_e32 v10, 5, v3
	s_mul_i32 s54, s4, 0x2800
	s_add_i32 s54, s54, 0x8000
	v_lshl_add_u32 v8, v2, 2, s54
	v_lshl_add_u32 v9, v3, 4, s54
	s_mov_b32 s52, 0x00010001
	s_mov_b32 s53, 0x00010001
	s_add_i32 s55, s6, 0
	s_lshl_b32 s56, s55, 13
	s_add_u32 s12, s94, 0x12d96000
	s_addc_u32 s13, s95, 0
	s_add_u32 s12, s12, s56
	s_addc_u32 s13, s13, 0
	s_lshl_b32 s56, s55, 9
	s_add_u32 s50, s94, 0x12d92000
	s_addc_u32 s51, s95, 0
	s_add_u32 s50, s50, s56
	s_addc_u32 s51, s51, 0
	global_load_dwordx2 v[2:3], v7, s[50:51]
	s_add_i32 s55, s6, 16
	s_lshl_b32 s56, s55, 13
	s_add_u32 s14, s94, 0x12d96000
	s_addc_u32 s15, s95, 0
	s_add_u32 s14, s14, s56
	s_addc_u32 s15, s15, 0
	s_lshl_b32 s56, s55, 9
	s_add_u32 s50, s94, 0x12d92000
	s_addc_u32 s51, s95, 0
	s_add_u32 s50, s50, s56
	s_addc_u32 s51, s51, 0
	global_load_dwordx2 v[50:51], v7, s[50:51]
	s_add_i32 s55, s6, 1
	s_lshl_b32 s56, s55, 13
	s_add_u32 s36, s94, 0x12d96000
	s_addc_u32 s37, s95, 0
	s_add_u32 s36, s36, s56
	s_addc_u32 s37, s37, 0
	s_lshl_b32 s56, s55, 9
	s_add_u32 s50, s94, 0x12d92000
	s_addc_u32 s51, s95, 0
	s_add_u32 s50, s50, s56
	s_addc_u32 s51, s51, 0
	global_load_dwordx2 v[90:91], v7, s[50:51]
	s_add_i32 s55, s6, 17
	s_lshl_b32 s56, s55, 13
	s_add_u32 s38, s94, 0x12d96000
	s_addc_u32 s39, s95, 0
	s_add_u32 s38, s38, s56
	s_addc_u32 s39, s39, 0
	s_lshl_b32 s56, s55, 9
	s_add_u32 s50, s94, 0x12d92000
	s_addc_u32 s51, s95, 0
	s_add_u32 s50, s50, s56
	s_addc_u32 s51, s51, 0
	global_load_dwordx2 v[94:95], v7, s[50:51]
	s_waitcnt vmcnt(3)
	ds_write_b32 v8, v2 offset:0
	ds_write_b32 v8, v3 offset:256
	v_mul_f32_e32 v228, v3, v3
	v_mul_f32_e32 v229, v2, v3
	v_fma_f32 v2, v2, v2, -v228
	v_add_f32_e32 v3, v229, v229
	ds_write_b32 v8, v2 offset:512
	ds_write_b32 v8, v3 offset:768
	v_mul_f32_e32 v228, v3, v3
	v_mul_f32_e32 v229, v2, v3
	v_fma_f32 v2, v2, v2, -v228
	v_add_f32_e32 v3, v229, v229
	ds_write_b32 v8, v2 offset:1024
	ds_write_b32 v8, v3 offset:1280
	v_mul_f32_e32 v228, v3, v3
	v_mul_f32_e32 v229, v2, v3
	v_fma_f32 v2, v2, v2, -v228
	v_add_f32_e32 v3, v229, v229
	ds_write_b32 v8, v2 offset:1536
	ds_write_b32 v8, v3 offset:1792
	v_mul_f32_e32 v228, v3, v3
	v_mul_f32_e32 v229, v2, v3
	v_fma_f32 v2, v2, v2, -v228
	v_add_f32_e32 v3, v229, v229
	ds_write_b32 v8, v2 offset:2048
	ds_write_b32 v8, v3 offset:2304
	s_waitcnt vmcnt(2)
	ds_write_b32 v8, v50 offset:2560
	ds_write_b32 v8, v51 offset:2816
	v_mul_f32_e32 v228, v51, v51
	v_mul_f32_e32 v229, v50, v51
	v_fma_f32 v50, v50, v50, -v228
	v_add_f32_e32 v51, v229, v229
	ds_write_b32 v8, v50 offset:3072
	ds_write_b32 v8, v51 offset:3328
	v_mul_f32_e32 v228, v51, v51
	v_mul_f32_e32 v229, v50, v51
	v_fma_f32 v50, v50, v50, -v228
	v_add_f32_e32 v51, v229, v229
	ds_write_b32 v8, v50 offset:3584
	ds_write_b32 v8, v51 offset:3840
	v_mul_f32_e32 v228, v51, v51
	v_mul_f32_e32 v229, v50, v51
	v_fma_f32 v50, v50, v50, -v228
	v_add_f32_e32 v51, v229, v229
	ds_write_b32 v8, v50 offset:4096
	ds_write_b32 v8, v51 offset:4352
	v_mul_f32_e32 v228, v51, v51
	v_mul_f32_e32 v229, v50, v51
	v_fma_f32 v50, v50, v50, -v228
	v_add_f32_e32 v51, v229, v229
	ds_write_b32 v8, v50 offset:4608
	ds_write_b32 v8, v51 offset:4864
	s_waitcnt vmcnt(1)
	ds_write_b32 v8, v90 offset:5120
	ds_write_b32 v8, v91 offset:5376
	v_mul_f32_e32 v228, v91, v91
	v_mul_f32_e32 v229, v90, v91
	v_fma_f32 v90, v90, v90, -v228
	v_add_f32_e32 v91, v229, v229
	ds_write_b32 v8, v90 offset:5632
	ds_write_b32 v8, v91 offset:5888
	v_mul_f32_e32 v228, v91, v91
	v_mul_f32_e32 v229, v90, v91
	v_fma_f32 v90, v90, v90, -v228
	v_add_f32_e32 v91, v229, v229
	ds_write_b32 v8, v90 offset:6144
	ds_write_b32 v8, v91 offset:6400
	v_mul_f32_e32 v228, v91, v91
	v_mul_f32_e32 v229, v90, v91
	v_fma_f32 v90, v90, v90, -v228
	v_add_f32_e32 v91, v229, v229
	ds_write_b32 v8, v90 offset:6656
	ds_write_b32 v8, v91 offset:6912
	v_mul_f32_e32 v228, v91, v91
	v_mul_f32_e32 v229, v90, v91
	v_fma_f32 v90, v90, v90, -v228
	v_add_f32_e32 v91, v229, v229
	ds_write_b32 v8, v90 offset:7168
	ds_write_b32 v8, v91 offset:7424
	s_waitcnt vmcnt(0)
	ds_write_b32 v8, v94 offset:7680
	ds_write_b32 v8, v95 offset:7936
	v_mul_f32_e32 v228, v95, v95
	v_mul_f32_e32 v229, v94, v95
	v_fma_f32 v94, v94, v94, -v228
	v_add_f32_e32 v95, v229, v229
	ds_write_b32 v8, v94 offset:8192
	ds_write_b32 v8, v95 offset:8448
	v_mul_f32_e32 v228, v95, v95
	v_mul_f32_e32 v229, v94, v95
	v_fma_f32 v94, v94, v94, -v228
	v_add_f32_e32 v95, v229, v229
	ds_write_b32 v8, v94 offset:8704
	ds_write_b32 v8, v95 offset:8960
	v_mul_f32_e32 v228, v95, v95
	v_mul_f32_e32 v229, v94, v95
	v_fma_f32 v94, v94, v94, -v228
	v_add_f32_e32 v95, v229, v229
	ds_write_b32 v8, v94 offset:9216
	ds_write_b32 v8, v95 offset:9472
	v_mul_f32_e32 v228, v95, v95
	v_mul_f32_e32 v229, v94, v95
	v_fma_f32 v94, v94, v94, -v228
	v_add_f32_e32 v95, v229, v229
	ds_write_b32 v8, v94 offset:9728
	ds_write_b32 v8, v95 offset:9984
	s_waitcnt lgkmcnt(0)
	s_mov_b32 s10, 0x80008000
	s_mov_b32 s11, 0x80008000
	s_lshl_b32 s55, s0, 15
	s_add_i32 s56, s6, 0
	s_lshl_b32 s56, s56, 6
	s_add_u32 s55, s55, s56
	s_add_u32 s8, s94, 0x8a40000
	s_addc_u32 s9, s95, 0
	s_add_u32 s8, s8, s55
	s_addc_u32 s9, s9, 0
	global_load_dwordx4 v[232:235], v5, s[8:9] offset:0
	global_load_dwordx4 v[236:239], v5, s[8:9] offset:1024
	global_load_dwordx4 v[12:15], v6, s[12:13] offset:0
	global_load_dwordx4 v[16:19], v6, s[12:13] offset:1024
	global_load_dwordx4 v[20:23], v6, s[12:13] offset:256
	global_load_dwordx4 v[24:27], v6, s[12:13] offset:1280
	global_load_dwordx4 v[28:31], v6, s[12:13] offset:512
	global_load_dwordx4 v[32:35], v6, s[12:13] offset:1536
	global_load_dwordx4 v[36:39], v6, s[12:13] offset:768
	global_load_dwordx4 v[40:43], v6, s[12:13] offset:1792
	s_lshl_b32 s55, s0, 15
	s_add_i32 s56, s6, 1
	s_lshl_b32 s56, s56, 6
	s_add_u32 s55, s55, s56
	s_add_u32 s48, s94, 0x8a40000
	s_addc_u32 s49, s95, 0
	s_add_u32 s48, s48, s55
	s_addc_u32 s49, s49, 0
	global_load_dwordx4 v[240:243], v5, s[48:49] offset:0
	global_load_dwordx4 v[244:247], v5, s[48:49] offset:1024
	s_waitcnt vmcnt(0)
	s_branch .Ls5a_body2
.Ls5a_head1:
	s_waitcnt vmcnt(32)
.Ls5a_body2:
	s_add_i32 s46, s86, s84
	s_cmp_lt_i32 s46, 640
	s_cselect_b32 s46, s46, s86
	s_add_i32 s1, s46, 0xffffff00
	v_mfma_f32_16x16x4_f32 v[80:83], v12, v232, 0
	v_mfma_f32_16x16x4_f32 v[84:87], v13, v232, 0
	v_mfma_f32_16x16x4_f32 v[144:147], v12, v236, 0
	v_mfma_f32_16x16x4_f32 v[148:151], v13, v236, 0
	v_mfma_f32_16x16x4_f32 v[112:115], v20, v232, 0
	v_mfma_f32_16x16x4_f32 v[116:119], v21, v232, 0
	v_mfma_f32_16x16x4_f32 v[152:155], v20, v236, 0
	v_mfma_f32_16x16x4_f32 v[156:159], v21, v236, 0
	v_mfma_f32_16x16x4_f32 v[120:123], v28, v232, 0
	v_mfma_f32_16x16x4_f32 v[124:127], v29, v232, 0
	v_mfma_f32_16x16x4_f32 v[168:171], v28, v236, 0
	v_mfma_f32_16x16x4_f32 v[172:175], v29, v236, 0
	v_mfma_f32_16x16x4_f32 v[128:131], v36, v232, 0
	v_mfma_f32_16x16x4_f32 v[140:143], v37, v232, 0
	v_mfma_f32_16x16x4_f32 v[176:179], v36, v236, 0
	v_mfma_f32_16x16x4_f32 v[180:183], v37, v236, 0
	v_mfma_f32_16x16x4_f32 v[80:83], v14, v233, v[80:83]
	v_mfma_f32_16x16x4_f32 v[84:87], v15, v233, v[84:87]
	v_mfma_f32_16x16x4_f32 v[144:147], v14, v237, v[144:147]
	v_mfma_f32_16x16x4_f32 v[148:151], v15, v237, v[148:151]
	v_mfma_f32_16x16x4_f32 v[112:115], v22, v233, v[112:115]
	v_mfma_f32_16x16x4_f32 v[116:119], v23, v233, v[116:119]
	v_mfma_f32_16x16x4_f32 v[152:155], v22, v237, v[152:155]
	v_mfma_f32_16x16x4_f32 v[156:159], v23, v237, v[156:159]
	v_mfma_f32_16x16x4_f32 v[120:123], v30, v233, v[120:123]
	v_mfma_f32_16x16x4_f32 v[124:127], v31, v233, v[124:127]
	v_mfma_f32_16x16x4_f32 v[168:171], v30, v237, v[168:171]
	v_mfma_f32_16x16x4_f32 v[172:175], v31, v237, v[172:175]
	v_mfma_f32_16x16x4_f32 v[128:131], v38, v233, v[128:131]
	v_mfma_f32_16x16x4_f32 v[140:143], v39, v233, v[140:143]
	v_mfma_f32_16x16x4_f32 v[176:179], v38, v237, v[176:179]
	v_mfma_f32_16x16x4_f32 v[180:183], v39, v237, v[180:183]
	v_mfma_f32_16x16x4_f32 v[80:83], v16, v234, v[80:83]
	v_mfma_f32_16x16x4_f32 v[84:87], v17, v234, v[84:87]
	v_mfma_f32_16x16x4_f32 v[144:147], v16, v238, v[144:147]
	v_mfma_f32_16x16x4_f32 v[148:151], v17, v238, v[148:151]
	v_mfma_f32_16x16x4_f32 v[112:115], v24, v234, v[112:115]
	v_mfma_f32_16x16x4_f32 v[116:119], v25, v234, v[116:119]
	v_mfma_f32_16x16x4_f32 v[152:155], v24, v238, v[152:155]
	v_mfma_f32_16x16x4_f32 v[156:159], v25, v238, v[156:159]
	v_mfma_f32_16x16x4_f32 v[120:123], v32, v234, v[120:123]
	v_mfma_f32_16x16x4_f32 v[124:127], v33, v234, v[124:127]
	v_mfma_f32_16x16x4_f32 v[168:171], v32, v238, v[168:171]
	v_mfma_f32_16x16x4_f32 v[172:175], v33, v238, v[172:175]
	v_mfma_f32_16x16x4_f32 v[128:131], v40, v234, v[128:131]
	v_mfma_f32_16x16x4_f32 v[140:143], v41, v234, v[140:143]
	v_mfma_f32_16x16x4_f32 v[176:179], v40, v238, v[176:179]
	v_mfma_f32_16x16x4_f32 v[180:183], v41, v238, v[180:183]
	v_mfma_f32_16x16x4_f32 v[80:83], v18, v235, v[80:83]
	v_mfma_f32_16x16x4_f32 v[84:87], v19, v235, v[84:87]
	v_mfma_f32_16x16x4_f32 v[144:147], v18, v239, v[144:147]
	v_mfma_f32_16x16x4_f32 v[148:151], v19, v239, v[148:151]
	v_mfma_f32_16x16x4_f32 v[112:115], v26, v235, v[112:115]
	v_mfma_f32_16x16x4_f32 v[116:119], v27, v235, v[116:119]
	v_mfma_f32_16x16x4_f32 v[152:155], v26, v239, v[152:155]
	v_mfma_f32_16x16x4_f32 v[156:159], v27, v239, v[156:159]
	v_mfma_f32_16x16x4_f32 v[120:123], v34, v235, v[120:123]
	v_mfma_f32_16x16x4_f32 v[124:127], v35, v235, v[124:127]
	v_mfma_f32_16x16x4_f32 v[168:171], v34, v239, v[168:171]
	v_mfma_f32_16x16x4_f32 v[172:175], v35, v239, v[172:175]
	v_mfma_f32_16x16x4_f32 v[128:131], v42, v235, v[128:131]
	v_mfma_f32_16x16x4_f32 v[140:143], v43, v235, v[140:143]
	v_mfma_f32_16x16x4_f32 v[176:179], v42, v239, v[176:179]
	v_mfma_f32_16x16x4_f32 v[180:183], v43, v239, v[180:183]
	s_nop 9
	ds_read_b128 v[184:187], v9 offset:0
	ds_read_b128 v[188:191], v9 offset:256
	ds_read_b128 v[192:195], v9 offset:64
	ds_read_b128 v[224:227], v9 offset:320
	s_waitcnt lgkmcnt(2)
	v_fmac_f32_e32 v144, v184, v80
	v_fmac_f32_e32 v145, v185, v81
	v_fmac_f32_e32 v146, v186, v82
	v_fmac_f32_e32 v147, v187, v83
	v_fma_f32 v144, -v188, v84, v144
	v_fma_f32 v145, -v189, v85, v145
	v_fma_f32 v146, -v190, v86, v146
	v_fma_f32 v147, -v191, v87, v147
	v_fmac_f32_e32 v148, v184, v84
	v_fmac_f32_e32 v149, v185, v85
	v_fmac_f32_e32 v150, v186, v86
	v_fmac_f32_e32 v151, v187, v87
	v_fmac_f32_e32 v148, v188, v80
	v_fmac_f32_e32 v149, v189, v81
	v_fmac_f32_e32 v150, v190, v82
	v_fmac_f32_e32 v151, v191, v83
	ds_read_b128 v[184:187], v9 offset:128
	ds_read_b128 v[188:191], v9 offset:384
	s_waitcnt lgkmcnt(2)
	v_fmac_f32_e32 v152, v192, v112
	v_fmac_f32_e32 v153, v193, v113
	v_fmac_f32_e32 v154, v194, v114
	v_fmac_f32_e32 v155, v195, v115
	v_fma_f32 v152, -v224, v116, v152
	v_fma_f32 v153, -v225, v117, v153
	v_fma_f32 v154, -v226, v118, v154
	v_fma_f32 v155, -v227, v119, v155
	v_fmac_f32_e32 v156, v192, v116
	v_fmac_f32_e32 v157, v193, v117
	v_fmac_f32_e32 v158, v194, v118
	v_fmac_f32_e32 v159, v195, v119
	v_fmac_f32_e32 v156, v224, v112
	v_fmac_f32_e32 v157, v225, v113
	v_fmac_f32_e32 v158, v226, v114
	v_fmac_f32_e32 v159, v227, v115
	ds_read_b128 v[192:195], v9 offset:192
	ds_read_b128 v[224:227], v9 offset:448
	s_waitcnt lgkmcnt(2)
	v_fmac_f32_e32 v168, v184, v120
	v_fmac_f32_e32 v169, v185, v121
	v_fmac_f32_e32 v170, v186, v122
	v_fmac_f32_e32 v171, v187, v123
	v_fma_f32 v168, -v188, v124, v168
	v_fma_f32 v169, -v189, v125, v169
	v_fma_f32 v170, -v190, v126, v170
	v_fma_f32 v171, -v191, v127, v171
	v_fmac_f32_e32 v172, v184, v124
	v_fmac_f32_e32 v173, v185, v125
	v_fmac_f32_e32 v174, v186, v126
	v_fmac_f32_e32 v175, v187, v127
	v_fmac_f32_e32 v172, v188, v120
	v_fmac_f32_e32 v173, v189, v121
	v_fmac_f32_e32 v174, v190, v122
	v_fmac_f32_e32 v175, v191, v123
	s_waitcnt lgkmcnt(0)
	v_fmac_f32_e32 v176, v192, v128
	v_fmac_f32_e32 v177, v193, v129
	v_fmac_f32_e32 v178, v194, v130
	v_fmac_f32_e32 v179, v195, v131
	v_fma_f32 v176, -v224, v140, v176
	v_fma_f32 v177, -v225, v141, v177
	v_fma_f32 v178, -v226, v142, v178
	v_fma_f32 v179, -v227, v143, v179
	v_fmac_f32_e32 v180, v192, v140
	v_fmac_f32_e32 v181, v193, v141
	v_fmac_f32_e32 v182, v194, v142
	v_fmac_f32_e32 v183, v195, v143
	v_fmac_f32_e32 v180, v224, v128
	v_fmac_f32_e32 v181, v225, v129
	v_fmac_f32_e32 v182, v226, v130
	v_fmac_f32_e32 v183, v227, v131
	global_load_dwordx4 v[44:47], v6, s[14:15] offset:0
	global_load_dwordx4 v[52:55], v6, s[14:15] offset:1024
	global_load_dwordx4 v[56:59], v6, s[14:15] offset:256
	global_load_dwordx4 v[60:63], v6, s[14:15] offset:1280
	global_load_dwordx4 v[64:67], v6, s[14:15] offset:512
	global_load_dwordx4 v[68:71], v6, s[14:15] offset:1536
	global_load_dwordx4 v[72:75], v6, s[14:15] offset:768
	global_load_dwordx4 v[76:79], v6, s[14:15] offset:1792
	ds_read_b128 v[184:187], v9 offset:512
	ds_read_b128 v[188:191], v9 offset:768
	ds_read_b128 v[192:195], v9 offset:576
	ds_read_b128 v[224:227], v9 offset:832
	s_waitcnt lgkmcnt(2)
	v_mov_b32_e32 v228, v144
	v_mov_b32_e32 v229, v145
	v_mov_b32_e32 v230, v146
	v_mov_b32_e32 v231, v147
	s_nop 1
	v_fmac_f32_dpp v144, v144, v184 row_shr:1 row_mask:0xf bank_mask:0xf bound_ctrl:0
	v_fmac_f32_dpp v145, v145, v185 row_shr:1 row_mask:0xf bank_mask:0xf bound_ctrl:0
	v_fmac_f32_dpp v146, v146, v186 row_shr:1 row_mask:0xf bank_mask:0xf bound_ctrl:0
	v_fmac_f32_dpp v147, v147, v187 row_shr:1 row_mask:0xf bank_mask:0xf bound_ctrl:0
	v_fmac_f32_dpp v144, v148, -v188 row_shr:1 row_mask:0xf bank_mask:0xf bound_ctrl:0
	v_fmac_f32_dpp v145, v149, -v189 row_shr:1 row_mask:0xf bank_mask:0xf bound_ctrl:0
	v_fmac_f32_dpp v146, v150, -v190 row_shr:1 row_mask:0xf bank_mask:0xf bound_ctrl:0
	v_fmac_f32_dpp v147, v151, -v191 row_shr:1 row_mask:0xf bank_mask:0xf bound_ctrl:0
	v_fmac_f32_dpp v148, v148, v184 row_shr:1 row_mask:0xf bank_mask:0xf bound_ctrl:0
	v_fmac_f32_dpp v149, v149, v185 row_shr:1 row_mask:0xf bank_mask:0xf bound_ctrl:0
	v_fmac_f32_dpp v150, v150, v186 row_shr:1 row_mask:0xf bank_mask:0xf bound_ctrl:0
	v_fmac_f32_dpp v151, v151, v187 row_shr:1 row_mask:0xf bank_mask:0xf bound_ctrl:0
	v_fmac_f32_dpp v148, v228, v188 row_shr:1 row_mask:0xf bank_mask:0xf bound_ctrl:0
	v_fmac_f32_dpp v149, v229, v189 row_shr:1 row_mask:0xf bank_mask:0xf bound_ctrl:0
	v_fmac_f32_dpp v150, v230, v190 row_shr:1 row_mask:0xf bank_mask:0xf bound_ctrl:0
	v_fmac_f32_dpp v151, v231, v191 row_shr:1 row_mask:0xf bank_mask:0xf bound_ctrl:0
	ds_read_b128 v[184:187], v9 offset:640
	ds_read_b128 v[188:191], v9 offset:896
	s_waitcnt lgkmcnt(2)
	v_mov_b32_e32 v228, v152
	v_mov_b32_e32 v229, v153
	v_mov_b32_e32 v230, v154
	v_mov_b32_e32 v231, v155
	v_fmac_f32_dpp v152, v152, v192 row_shr:1 row_mask:0xf bank_mask:0xf bound_ctrl:0
	v_fmac_f32_dpp v153, v153, v193 row_shr:1 row_mask:0xf bank_mask:0xf bound_ctrl:0
	v_fmac_f32_dpp v154, v154, v194 row_shr:1 row_mask:0xf bank_mask:0xf bound_ctrl:0
	v_fmac_f32_dpp v155, v155, v195 row_shr:1 row_mask:0xf bank_mask:0xf bound_ctrl:0
	v_fmac_f32_dpp v152, v156, -v224 row_shr:1 row_mask:0xf bank_mask:0xf bound_ctrl:0
	v_fmac_f32_dpp v153, v157, -v225 row_shr:1 row_mask:0xf bank_mask:0xf bound_ctrl:0
	v_fmac_f32_dpp v154, v158, -v226 row_shr:1 row_mask:0xf bank_mask:0xf bound_ctrl:0
	v_fmac_f32_dpp v155, v159, -v227 row_shr:1 row_mask:0xf bank_mask:0xf bound_ctrl:0
	v_fmac_f32_dpp v156, v156, v192 row_shr:1 row_mask:0xf bank_mask:0xf bound_ctrl:0
	v_fmac_f32_dpp v157, v157, v193 row_shr:1 row_mask:0xf bank_mask:0xf bound_ctrl:0
	v_fmac_f32_dpp v158, v158, v194 row_shr:1 row_mask:0xf bank_mask:0xf bound_ctrl:0
	v_fmac_f32_dpp v159, v159, v195 row_shr:1 row_mask:0xf bank_mask:0xf bound_ctrl:0
	v_fmac_f32_dpp v156, v228, v224 row_shr:1 row_mask:0xf bank_mask:0xf bound_ctrl:0
	v_fmac_f32_dpp v157, v229, v225 row_shr:1 row_mask:0xf bank_mask:0xf bound_ctrl:0
	v_fmac_f32_dpp v158, v230, v226 row_shr:1 row_mask:0xf bank_mask:0xf bound_ctrl:0
	v_fmac_f32_dpp v159, v231, v227 row_shr:1 row_mask:0xf bank_mask:0xf bound_ctrl:0
	ds_read_b128 v[192:195], v9 offset:704
	ds_read_b128 v[224:227], v9 offset:960
	s_waitcnt lgkmcnt(2)
	v_mov_b32_e32 v228, v168
	v_mov_b32_e32 v229, v169
	v_mov_b32_e32 v230, v170
	v_mov_b32_e32 v231, v171
	v_fmac_f32_dpp v168, v168, v184 row_shr:1 row_mask:0xf bank_mask:0xf bound_ctrl:0
	v_fmac_f32_dpp v169, v169, v185 row_shr:1 row_mask:0xf bank_mask:0xf bound_ctrl:0
	v_fmac_f32_dpp v170, v170, v186 row_shr:1 row_mask:0xf bank_mask:0xf bound_ctrl:0
	v_fmac_f32_dpp v171, v171, v187 row_shr:1 row_mask:0xf bank_mask:0xf bound_ctrl:0
	v_fmac_f32_dpp v168, v172, -v188 row_shr:1 row_mask:0xf bank_mask:0xf bound_ctrl:0
	v_fmac_f32_dpp v169, v173, -v189 row_shr:1 row_mask:0xf bank_mask:0xf bound_ctrl:0
	v_fmac_f32_dpp v170, v174, -v190 row_shr:1 row_mask:0xf bank_mask:0xf bound_ctrl:0
	v_fmac_f32_dpp v171, v175, -v191 row_shr:1 row_mask:0xf bank_mask:0xf bound_ctrl:0
	v_fmac_f32_dpp v172, v172, v184 row_shr:1 row_mask:0xf bank_mask:0xf bound_ctrl:0
	v_fmac_f32_dpp v173, v173, v185 row_shr:1 row_mask:0xf bank_mask:0xf bound_ctrl:0
	v_fmac_f32_dpp v174, v174, v186 row_shr:1 row_mask:0xf bank_mask:0xf bound_ctrl:0
	v_fmac_f32_dpp v175, v175, v187 row_shr:1 row_mask:0xf bank_mask:0xf bound_ctrl:0
	v_fmac_f32_dpp v172, v228, v188 row_shr:1 row_mask:0xf bank_mask:0xf bound_ctrl:0
	v_fmac_f32_dpp v173, v229, v189 row_shr:1 row_mask:0xf bank_mask:0xf bound_ctrl:0
	v_fmac_f32_dpp v174, v230, v190 row_shr:1 row_mask:0xf bank_mask:0xf bound_ctrl:0
	v_fmac_f32_dpp v175, v231, v191 row_shr:1 row_mask:0xf bank_mask:0xf bound_ctrl:0
	ds_read_b128 v[184:187], v9 offset:1024
	ds_read_b128 v[188:191], v9 offset:1280
	s_waitcnt lgkmcnt(2)
	v_mov_b32_e32 v228, v176
	v_mov_b32_e32 v229, v177
	v_mov_b32_e32 v230, v178
	v_mov_b32_e32 v231, v179
	v_fmac_f32_dpp v176, v176, v192 row_shr:1 row_mask:0xf bank_mask:0xf bound_ctrl:0
	v_fmac_f32_dpp v177, v177, v193 row_shr:1 row_mask:0xf bank_mask:0xf bound_ctrl:0
	v_fmac_f32_dpp v178, v178, v194 row_shr:1 row_mask:0xf bank_mask:0xf bound_ctrl:0
	v_fmac_f32_dpp v179, v179, v195 row_shr:1 row_mask:0xf bank_mask:0xf bound_ctrl:0
	v_fmac_f32_dpp v176, v180, -v224 row_shr:1 row_mask:0xf bank_mask:0xf bound_ctrl:0
	v_fmac_f32_dpp v177, v181, -v225 row_shr:1 row_mask:0xf bank_mask:0xf bound_ctrl:0
	v_fmac_f32_dpp v178, v182, -v226 row_shr:1 row_mask:0xf bank_mask:0xf bound_ctrl:0
	v_fmac_f32_dpp v179, v183, -v227 row_shr:1 row_mask:0xf bank_mask:0xf bound_ctrl:0
	v_fmac_f32_dpp v180, v180, v192 row_shr:1 row_mask:0xf bank_mask:0xf bound_ctrl:0
	v_fmac_f32_dpp v181, v181, v193 row_shr:1 row_mask:0xf bank_mask:0xf bound_ctrl:0
	v_fmac_f32_dpp v182, v182, v194 row_shr:1 row_mask:0xf bank_mask:0xf bound_ctrl:0
	v_fmac_f32_dpp v183, v183, v195 row_shr:1 row_mask:0xf bank_mask:0xf bound_ctrl:0
	v_fmac_f32_dpp v180, v228, v224 row_shr:1 row_mask:0xf bank_mask:0xf bound_ctrl:0
	v_fmac_f32_dpp v181, v229, v225 row_shr:1 row_mask:0xf bank_mask:0xf bound_ctrl:0
	v_fmac_f32_dpp v182, v230, v226 row_shr:1 row_mask:0xf bank_mask:0xf bound_ctrl:0
	v_fmac_f32_dpp v183, v231, v227 row_shr:1 row_mask:0xf bank_mask:0xf bound_ctrl:0
	ds_read_b128 v[192:195], v9 offset:1088
	ds_read_b128 v[224:227], v9 offset:1344
	s_waitcnt lgkmcnt(2)
	v_mov_b32_e32 v228, v144
	v_mov_b32_e32 v229, v145
	v_mov_b32_e32 v230, v146
	v_mov_b32_e32 v231, v147
	v_fmac_f32_dpp v144, v144, v184 row_shr:2 row_mask:0xf bank_mask:0xf bound_ctrl:0
	v_fmac_f32_dpp v145, v145, v185 row_shr:2 row_mask:0xf bank_mask:0xf bound_ctrl:0
	v_fmac_f32_dpp v146, v146, v186 row_shr:2 row_mask:0xf bank_mask:0xf bound_ctrl:0
	v_fmac_f32_dpp v147, v147, v187 row_shr:2 row_mask:0xf bank_mask:0xf bound_ctrl:0
	v_fmac_f32_dpp v144, v148, -v188 row_shr:2 row_mask:0xf bank_mask:0xf bound_ctrl:0
	v_fmac_f32_dpp v145, v149, -v189 row_shr:2 row_mask:0xf bank_mask:0xf bound_ctrl:0
	v_fmac_f32_dpp v146, v150, -v190 row_shr:2 row_mask:0xf bank_mask:0xf bound_ctrl:0
	v_fmac_f32_dpp v147, v151, -v191 row_shr:2 row_mask:0xf bank_mask:0xf bound_ctrl:0
	v_fmac_f32_dpp v148, v148, v184 row_shr:2 row_mask:0xf bank_mask:0xf bound_ctrl:0
	v_fmac_f32_dpp v149, v149, v185 row_shr:2 row_mask:0xf bank_mask:0xf bound_ctrl:0
	v_fmac_f32_dpp v150, v150, v186 row_shr:2 row_mask:0xf bank_mask:0xf bound_ctrl:0
	v_fmac_f32_dpp v151, v151, v187 row_shr:2 row_mask:0xf bank_mask:0xf bound_ctrl:0
	v_fmac_f32_dpp v148, v228, v188 row_shr:2 row_mask:0xf bank_mask:0xf bound_ctrl:0
	v_fmac_f32_dpp v149, v229, v189 row_shr:2 row_mask:0xf bank_mask:0xf bound_ctrl:0
	v_fmac_f32_dpp v150, v230, v190 row_shr:2 row_mask:0xf bank_mask:0xf bound_ctrl:0
	v_fmac_f32_dpp v151, v231, v191 row_shr:2 row_mask:0xf bank_mask:0xf bound_ctrl:0
	ds_read_b128 v[184:187], v9 offset:1152
	ds_read_b128 v[188:191], v9 offset:1408
	s_waitcnt lgkmcnt(2)
	v_mov_b32_e32 v228, v152
	v_mov_b32_e32 v229, v153
	v_mov_b32_e32 v230, v154
	v_mov_b32_e32 v231, v155
	v_fmac_f32_dpp v152, v152, v192 row_shr:2 row_mask:0xf bank_mask:0xf bound_ctrl:0
	v_fmac_f32_dpp v153, v153, v193 row_shr:2 row_mask:0xf bank_mask:0xf bound_ctrl:0
	v_fmac_f32_dpp v154, v154, v194 row_shr:2 row_mask:0xf bank_mask:0xf bound_ctrl:0
	v_fmac_f32_dpp v155, v155, v195 row_shr:2 row_mask:0xf bank_mask:0xf bound_ctrl:0
	v_fmac_f32_dpp v152, v156, -v224 row_shr:2 row_mask:0xf bank_mask:0xf bound_ctrl:0
	v_fmac_f32_dpp v153, v157, -v225 row_shr:2 row_mask:0xf bank_mask:0xf bound_ctrl:0
	v_fmac_f32_dpp v154, v158, -v226 row_shr:2 row_mask:0xf bank_mask:0xf bound_ctrl:0
	v_fmac_f32_dpp v155, v159, -v227 row_shr:2 row_mask:0xf bank_mask:0xf bound_ctrl:0
	v_fmac_f32_dpp v156, v156, v192 row_shr:2 row_mask:0xf bank_mask:0xf bound_ctrl:0
	v_fmac_f32_dpp v157, v157, v193 row_shr:2 row_mask:0xf bank_mask:0xf bound_ctrl:0
	v_fmac_f32_dpp v158, v158, v194 row_shr:2 row_mask:0xf bank_mask:0xf bound_ctrl:0
	v_fmac_f32_dpp v159, v159, v195 row_shr:2 row_mask:0xf bank_mask:0xf bound_ctrl:0
	v_fmac_f32_dpp v156, v228, v224 row_shr:2 row_mask:0xf bank_mask:0xf bound_ctrl:0
	v_fmac_f32_dpp v157, v229, v225 row_shr:2 row_mask:0xf bank_mask:0xf bound_ctrl:0
	v_fmac_f32_dpp v158, v230, v226 row_shr:2 row_mask:0xf bank_mask:0xf bound_ctrl:0
	v_fmac_f32_dpp v159, v231, v227 row_shr:2 row_mask:0xf bank_mask:0xf bound_ctrl:0
	ds_read_b128 v[192:195], v9 offset:1216
	ds_read_b128 v[224:227], v9 offset:1472
	s_waitcnt lgkmcnt(2)
	v_mov_b32_e32 v228, v168
	v_mov_b32_e32 v229, v169
	v_mov_b32_e32 v230, v170
	v_mov_b32_e32 v231, v171
	v_fmac_f32_dpp v168, v168, v184 row_shr:2 row_mask:0xf bank_mask:0xf bound_ctrl:0
	v_fmac_f32_dpp v169, v169, v185 row_shr:2 row_mask:0xf bank_mask:0xf bound_ctrl:0
	v_fmac_f32_dpp v170, v170, v186 row_shr:2 row_mask:0xf bank_mask:0xf bound_ctrl:0
	v_fmac_f32_dpp v171, v171, v187 row_shr:2 row_mask:0xf bank_mask:0xf bound_ctrl:0
	v_fmac_f32_dpp v168, v172, -v188 row_shr:2 row_mask:0xf bank_mask:0xf bound_ctrl:0
	v_fmac_f32_dpp v169, v173, -v189 row_shr:2 row_mask:0xf bank_mask:0xf bound_ctrl:0
	v_fmac_f32_dpp v170, v174, -v190 row_shr:2 row_mask:0xf bank_mask:0xf bound_ctrl:0
	v_fmac_f32_dpp v171, v175, -v191 row_shr:2 row_mask:0xf bank_mask:0xf bound_ctrl:0
	v_fmac_f32_dpp v172, v172, v184 row_shr:2 row_mask:0xf bank_mask:0xf bound_ctrl:0
	v_fmac_f32_dpp v173, v173, v185 row_shr:2 row_mask:0xf bank_mask:0xf bound_ctrl:0
	v_fmac_f32_dpp v174, v174, v186 row_shr:2 row_mask:0xf bank_mask:0xf bound_ctrl:0
	v_fmac_f32_dpp v175, v175, v187 row_shr:2 row_mask:0xf bank_mask:0xf bound_ctrl:0
	v_fmac_f32_dpp v172, v228, v188 row_shr:2 row_mask:0xf bank_mask:0xf bound_ctrl:0
	v_fmac_f32_dpp v173, v229, v189 row_shr:2 row_mask:0xf bank_mask:0xf bound_ctrl:0
	v_fmac_f32_dpp v174, v230, v190 row_shr:2 row_mask:0xf bank_mask:0xf bound_ctrl:0
	v_fmac_f32_dpp v175, v231, v191 row_shr:2 row_mask:0xf bank_mask:0xf bound_ctrl:0
	ds_read_b128 v[184:187], v9 offset:1536
	ds_read_b128 v[188:191], v9 offset:1792
	s_waitcnt lgkmcnt(2)
	v_mov_b32_e32 v228, v176
	v_mov_b32_e32 v229, v177
	v_mov_b32_e32 v230, v178
	v_mov_b32_e32 v231, v179
	v_fmac_f32_dpp v176, v176, v192 row_shr:2 row_mask:0xf bank_mask:0xf bound_ctrl:0
	v_fmac_f32_dpp v177, v177, v193 row_shr:2 row_mask:0xf bank_mask:0xf bound_ctrl:0
	v_fmac_f32_dpp v178, v178, v194 row_shr:2 row_mask:0xf bank_mask:0xf bound_ctrl:0
	v_fmac_f32_dpp v179, v179, v195 row_shr:2 row_mask:0xf bank_mask:0xf bound_ctrl:0
	v_fmac_f32_dpp v176, v180, -v224 row_shr:2 row_mask:0xf bank_mask:0xf bound_ctrl:0
	v_fmac_f32_dpp v177, v181, -v225 row_shr:2 row_mask:0xf bank_mask:0xf bound_ctrl:0
	v_fmac_f32_dpp v178, v182, -v226 row_shr:2 row_mask:0xf bank_mask:0xf bound_ctrl:0
	v_fmac_f32_dpp v179, v183, -v227 row_shr:2 row_mask:0xf bank_mask:0xf bound_ctrl:0
	v_fmac_f32_dpp v180, v180, v192 row_shr:2 row_mask:0xf bank_mask:0xf bound_ctrl:0
	v_fmac_f32_dpp v181, v181, v193 row_shr:2 row_mask:0xf bank_mask:0xf bound_ctrl:0
	v_fmac_f32_dpp v182, v182, v194 row_shr:2 row_mask:0xf bank_mask:0xf bound_ctrl:0
	v_fmac_f32_dpp v183, v183, v195 row_shr:2 row_mask:0xf bank_mask:0xf bound_ctrl:0
	v_fmac_f32_dpp v180, v228, v224 row_shr:2 row_mask:0xf bank_mask:0xf bound_ctrl:0
	v_fmac_f32_dpp v181, v229, v225 row_shr:2 row_mask:0xf bank_mask:0xf bound_ctrl:0
	v_fmac_f32_dpp v182, v230, v226 row_shr:2 row_mask:0xf bank_mask:0xf bound_ctrl:0
	v_fmac_f32_dpp v183, v231, v227 row_shr:2 row_mask:0xf bank_mask:0xf bound_ctrl:0
	ds_read_b128 v[192:195], v9 offset:1600
	ds_read_b128 v[224:227], v9 offset:1856
	s_waitcnt lgkmcnt(2)
	v_mov_b32_e32 v228, v144
	v_mov_b32_e32 v229, v145
	v_mov_b32_e32 v230, v146
	v_mov_b32_e32 v231, v147
	v_fmac_f32_dpp v144, v144, v184 row_shr:4 row_mask:0xf bank_mask:0xf bound_ctrl:0
	v_fmac_f32_dpp v145, v145, v185 row_shr:4 row_mask:0xf bank_mask:0xf bound_ctrl:0
	v_fmac_f32_dpp v146, v146, v186 row_shr:4 row_mask:0xf bank_mask:0xf bound_ctrl:0
	v_fmac_f32_dpp v147, v147, v187 row_shr:4 row_mask:0xf bank_mask:0xf bound_ctrl:0
	v_fmac_f32_dpp v144, v148, -v188 row_shr:4 row_mask:0xf bank_mask:0xf bound_ctrl:0
	v_fmac_f32_dpp v145, v149, -v189 row_shr:4 row_mask:0xf bank_mask:0xf bound_ctrl:0
	v_fmac_f32_dpp v146, v150, -v190 row_shr:4 row_mask:0xf bank_mask:0xf bound_ctrl:0
	v_fmac_f32_dpp v147, v151, -v191 row_shr:4 row_mask:0xf bank_mask:0xf bound_ctrl:0
	v_fmac_f32_dpp v148, v148, v184 row_shr:4 row_mask:0xf bank_mask:0xf bound_ctrl:0
	v_fmac_f32_dpp v149, v149, v185 row_shr:4 row_mask:0xf bank_mask:0xf bound_ctrl:0
	v_fmac_f32_dpp v150, v150, v186 row_shr:4 row_mask:0xf bank_mask:0xf bound_ctrl:0
	v_fmac_f32_dpp v151, v151, v187 row_shr:4 row_mask:0xf bank_mask:0xf bound_ctrl:0
	v_fmac_f32_dpp v148, v228, v188 row_shr:4 row_mask:0xf bank_mask:0xf bound_ctrl:0
	v_fmac_f32_dpp v149, v229, v189 row_shr:4 row_mask:0xf bank_mask:0xf bound_ctrl:0
	v_fmac_f32_dpp v150, v230, v190 row_shr:4 row_mask:0xf bank_mask:0xf bound_ctrl:0
	v_fmac_f32_dpp v151, v231, v191 row_shr:4 row_mask:0xf bank_mask:0xf bound_ctrl:0
	ds_read_b128 v[184:187], v9 offset:1664
	ds_read_b128 v[188:191], v9 offset:1920
	s_waitcnt lgkmcnt(2)
	v_mov_b32_e32 v228, v152
	v_mov_b32_e32 v229, v153
	v_mov_b32_e32 v230, v154
	v_mov_b32_e32 v231, v155
	v_fmac_f32_dpp v152, v152, v192 row_shr:4 row_mask:0xf bank_mask:0xf bound_ctrl:0
	v_fmac_f32_dpp v153, v153, v193 row_shr:4 row_mask:0xf bank_mask:0xf bound_ctrl:0
	v_fmac_f32_dpp v154, v154, v194 row_shr:4 row_mask:0xf bank_mask:0xf bound_ctrl:0
	v_fmac_f32_dpp v155, v155, v195 row_shr:4 row_mask:0xf bank_mask:0xf bound_ctrl:0
	v_fmac_f32_dpp v152, v156, -v224 row_shr:4 row_mask:0xf bank_mask:0xf bound_ctrl:0
	v_fmac_f32_dpp v153, v157, -v225 row_shr:4 row_mask:0xf bank_mask:0xf bound_ctrl:0
	v_fmac_f32_dpp v154, v158, -v226 row_shr:4 row_mask:0xf bank_mask:0xf bound_ctrl:0
	v_fmac_f32_dpp v155, v159, -v227 row_shr:4 row_mask:0xf bank_mask:0xf bound_ctrl:0
	v_fmac_f32_dpp v156, v156, v192 row_shr:4 row_mask:0xf bank_mask:0xf bound_ctrl:0
	v_fmac_f32_dpp v157, v157, v193 row_shr:4 row_mask:0xf bank_mask:0xf bound_ctrl:0
	v_fmac_f32_dpp v158, v158, v194 row_shr:4 row_mask:0xf bank_mask:0xf bound_ctrl:0
	v_fmac_f32_dpp v159, v159, v195 row_shr:4 row_mask:0xf bank_mask:0xf bound_ctrl:0
	v_fmac_f32_dpp v156, v228, v224 row_shr:4 row_mask:0xf bank_mask:0xf bound_ctrl:0
	v_fmac_f32_dpp v157, v229, v225 row_shr:4 row_mask:0xf bank_mask:0xf bound_ctrl:0
	v_fmac_f32_dpp v158, v230, v226 row_shr:4 row_mask:0xf bank_mask:0xf bound_ctrl:0
	v_fmac_f32_dpp v159, v231, v227 row_shr:4 row_mask:0xf bank_mask:0xf bound_ctrl:0
	ds_read_b128 v[192:195], v9 offset:1728
	ds_read_b128 v[224:227], v9 offset:1984
	s_waitcnt lgkmcnt(2)
	v_mov_b32_e32 v228, v168
	v_mov_b32_e32 v229, v169
	v_mov_b32_e32 v230, v170
	v_mov_b32_e32 v231, v171
	v_fmac_f32_dpp v168, v168, v184 row_shr:4 row_mask:0xf bank_mask:0xf bound_ctrl:0
	v_fmac_f32_dpp v169, v169, v185 row_shr:4 row_mask:0xf bank_mask:0xf bound_ctrl:0
	v_fmac_f32_dpp v170, v170, v186 row_shr:4 row_mask:0xf bank_mask:0xf bound_ctrl:0
	v_fmac_f32_dpp v171, v171, v187 row_shr:4 row_mask:0xf bank_mask:0xf bound_ctrl:0
	v_fmac_f32_dpp v168, v172, -v188 row_shr:4 row_mask:0xf bank_mask:0xf bound_ctrl:0
	v_fmac_f32_dpp v169, v173, -v189 row_shr:4 row_mask:0xf bank_mask:0xf bound_ctrl:0
	v_fmac_f32_dpp v170, v174, -v190 row_shr:4 row_mask:0xf bank_mask:0xf bound_ctrl:0
	v_fmac_f32_dpp v171, v175, -v191 row_shr:4 row_mask:0xf bank_mask:0xf bound_ctrl:0
	v_fmac_f32_dpp v172, v172, v184 row_shr:4 row_mask:0xf bank_mask:0xf bound_ctrl:0
	v_fmac_f32_dpp v173, v173, v185 row_shr:4 row_mask:0xf bank_mask:0xf bound_ctrl:0
	v_fmac_f32_dpp v174, v174, v186 row_shr:4 row_mask:0xf bank_mask:0xf bound_ctrl:0
	v_fmac_f32_dpp v175, v175, v187 row_shr:4 row_mask:0xf bank_mask:0xf bound_ctrl:0
	v_fmac_f32_dpp v172, v228, v188 row_shr:4 row_mask:0xf bank_mask:0xf bound_ctrl:0
	v_fmac_f32_dpp v173, v229, v189 row_shr:4 row_mask:0xf bank_mask:0xf bound_ctrl:0
	v_fmac_f32_dpp v174, v230, v190 row_shr:4 row_mask:0xf bank_mask:0xf bound_ctrl:0
	v_fmac_f32_dpp v175, v231, v191 row_shr:4 row_mask:0xf bank_mask:0xf bound_ctrl:0
	ds_read_b128 v[184:187], v9 offset:2048
	ds_read_b128 v[188:191], v9 offset:2304
	s_waitcnt lgkmcnt(2)
	v_mov_b32_e32 v228, v176
	v_mov_b32_e32 v229, v177
	v_mov_b32_e32 v230, v178
	v_mov_b32_e32 v231, v179
	v_fmac_f32_dpp v176, v176, v192 row_shr:4 row_mask:0xf bank_mask:0xf bound_ctrl:0
	v_fmac_f32_dpp v177, v177, v193 row_shr:4 row_mask:0xf bank_mask:0xf bound_ctrl:0
	v_fmac_f32_dpp v178, v178, v194 row_shr:4 row_mask:0xf bank_mask:0xf bound_ctrl:0
	v_fmac_f32_dpp v179, v179, v195 row_shr:4 row_mask:0xf bank_mask:0xf bound_ctrl:0
	v_fmac_f32_dpp v176, v180, -v224 row_shr:4 row_mask:0xf bank_mask:0xf bound_ctrl:0
	v_fmac_f32_dpp v177, v181, -v225 row_shr:4 row_mask:0xf bank_mask:0xf bound_ctrl:0
	v_fmac_f32_dpp v178, v182, -v226 row_shr:4 row_mask:0xf bank_mask:0xf bound_ctrl:0
	v_fmac_f32_dpp v179, v183, -v227 row_shr:4 row_mask:0xf bank_mask:0xf bound_ctrl:0
	v_fmac_f32_dpp v180, v180, v192 row_shr:4 row_mask:0xf bank_mask:0xf bound_ctrl:0
	v_fmac_f32_dpp v181, v181, v193 row_shr:4 row_mask:0xf bank_mask:0xf bound_ctrl:0
	v_fmac_f32_dpp v182, v182, v194 row_shr:4 row_mask:0xf bank_mask:0xf bound_ctrl:0
	v_fmac_f32_dpp v183, v183, v195 row_shr:4 row_mask:0xf bank_mask:0xf bound_ctrl:0
	v_fmac_f32_dpp v180, v228, v224 row_shr:4 row_mask:0xf bank_mask:0xf bound_ctrl:0
	v_fmac_f32_dpp v181, v229, v225 row_shr:4 row_mask:0xf bank_mask:0xf bound_ctrl:0
	v_fmac_f32_dpp v182, v230, v226 row_shr:4 row_mask:0xf bank_mask:0xf bound_ctrl:0
	v_fmac_f32_dpp v183, v231, v227 row_shr:4 row_mask:0xf bank_mask:0xf bound_ctrl:0
	ds_read_b128 v[192:195], v9 offset:2112
	ds_read_b128 v[224:227], v9 offset:2368
	s_waitcnt lgkmcnt(2)
	v_mov_b32_e32 v228, v144
	v_mov_b32_e32 v229, v145
	v_mov_b32_e32 v230, v146
	v_mov_b32_e32 v231, v147
	v_fmac_f32_dpp v144, v144, v184 row_shr:8 row_mask:0xf bank_mask:0xf bound_ctrl:0
	v_fmac_f32_dpp v145, v145, v185 row_shr:8 row_mask:0xf bank_mask:0xf bound_ctrl:0
	v_fmac_f32_dpp v146, v146, v186 row_shr:8 row_mask:0xf bank_mask:0xf bound_ctrl:0
	v_fmac_f32_dpp v147, v147, v187 row_shr:8 row_mask:0xf bank_mask:0xf bound_ctrl:0
	v_fmac_f32_dpp v144, v148, -v188 row_shr:8 row_mask:0xf bank_mask:0xf bound_ctrl:0
	v_fmac_f32_dpp v145, v149, -v189 row_shr:8 row_mask:0xf bank_mask:0xf bound_ctrl:0
	v_fmac_f32_dpp v146, v150, -v190 row_shr:8 row_mask:0xf bank_mask:0xf bound_ctrl:0
	v_fmac_f32_dpp v147, v151, -v191 row_shr:8 row_mask:0xf bank_mask:0xf bound_ctrl:0
	v_fmac_f32_dpp v148, v148, v184 row_shr:8 row_mask:0xf bank_mask:0xf bound_ctrl:0
	v_fmac_f32_dpp v149, v149, v185 row_shr:8 row_mask:0xf bank_mask:0xf bound_ctrl:0
	v_fmac_f32_dpp v150, v150, v186 row_shr:8 row_mask:0xf bank_mask:0xf bound_ctrl:0
	v_fmac_f32_dpp v151, v151, v187 row_shr:8 row_mask:0xf bank_mask:0xf bound_ctrl:0
	v_fmac_f32_dpp v148, v228, v188 row_shr:8 row_mask:0xf bank_mask:0xf bound_ctrl:0
	v_fmac_f32_dpp v149, v229, v189 row_shr:8 row_mask:0xf bank_mask:0xf bound_ctrl:0
	v_fmac_f32_dpp v150, v230, v190 row_shr:8 row_mask:0xf bank_mask:0xf bound_ctrl:0
	v_fmac_f32_dpp v151, v231, v191 row_shr:8 row_mask:0xf bank_mask:0xf bound_ctrl:0
	ds_read_b128 v[184:187], v9 offset:2176
	ds_read_b128 v[188:191], v9 offset:2432
	s_waitcnt lgkmcnt(2)
	v_mov_b32_e32 v228, v152
	v_mov_b32_e32 v229, v153
	v_mov_b32_e32 v230, v154
	v_mov_b32_e32 v231, v155
	v_fmac_f32_dpp v152, v152, v192 row_shr:8 row_mask:0xf bank_mask:0xf bound_ctrl:0
	v_fmac_f32_dpp v153, v153, v193 row_shr:8 row_mask:0xf bank_mask:0xf bound_ctrl:0
	v_fmac_f32_dpp v154, v154, v194 row_shr:8 row_mask:0xf bank_mask:0xf bound_ctrl:0
	v_fmac_f32_dpp v155, v155, v195 row_shr:8 row_mask:0xf bank_mask:0xf bound_ctrl:0
	v_fmac_f32_dpp v152, v156, -v224 row_shr:8 row_mask:0xf bank_mask:0xf bound_ctrl:0
	v_fmac_f32_dpp v153, v157, -v225 row_shr:8 row_mask:0xf bank_mask:0xf bound_ctrl:0
	v_fmac_f32_dpp v154, v158, -v226 row_shr:8 row_mask:0xf bank_mask:0xf bound_ctrl:0
	v_fmac_f32_dpp v155, v159, -v227 row_shr:8 row_mask:0xf bank_mask:0xf bound_ctrl:0
	v_fmac_f32_dpp v156, v156, v192 row_shr:8 row_mask:0xf bank_mask:0xf bound_ctrl:0
	v_fmac_f32_dpp v157, v157, v193 row_shr:8 row_mask:0xf bank_mask:0xf bound_ctrl:0
	v_fmac_f32_dpp v158, v158, v194 row_shr:8 row_mask:0xf bank_mask:0xf bound_ctrl:0
	v_fmac_f32_dpp v159, v159, v195 row_shr:8 row_mask:0xf bank_mask:0xf bound_ctrl:0
	v_fmac_f32_dpp v156, v228, v224 row_shr:8 row_mask:0xf bank_mask:0xf bound_ctrl:0
	v_fmac_f32_dpp v157, v229, v225 row_shr:8 row_mask:0xf bank_mask:0xf bound_ctrl:0
	v_fmac_f32_dpp v158, v230, v226 row_shr:8 row_mask:0xf bank_mask:0xf bound_ctrl:0
	v_fmac_f32_dpp v159, v231, v227 row_shr:8 row_mask:0xf bank_mask:0xf bound_ctrl:0
	ds_read_b128 v[192:195], v9 offset:2240
	ds_read_b128 v[224:227], v9 offset:2496
	s_waitcnt lgkmcnt(2)
	v_mov_b32_e32 v228, v168
	v_mov_b32_e32 v229, v169
	v_mov_b32_e32 v230, v170
	v_mov_b32_e32 v231, v171
	v_fmac_f32_dpp v168, v168, v184 row_shr:8 row_mask:0xf bank_mask:0xf bound_ctrl:0
	v_fmac_f32_dpp v169, v169, v185 row_shr:8 row_mask:0xf bank_mask:0xf bound_ctrl:0
	v_fmac_f32_dpp v170, v170, v186 row_shr:8 row_mask:0xf bank_mask:0xf bound_ctrl:0
	v_fmac_f32_dpp v171, v171, v187 row_shr:8 row_mask:0xf bank_mask:0xf bound_ctrl:0
	v_fmac_f32_dpp v168, v172, -v188 row_shr:8 row_mask:0xf bank_mask:0xf bound_ctrl:0
	v_fmac_f32_dpp v169, v173, -v189 row_shr:8 row_mask:0xf bank_mask:0xf bound_ctrl:0
	v_fmac_f32_dpp v170, v174, -v190 row_shr:8 row_mask:0xf bank_mask:0xf bound_ctrl:0
	v_fmac_f32_dpp v171, v175, -v191 row_shr:8 row_mask:0xf bank_mask:0xf bound_ctrl:0
	v_fmac_f32_dpp v172, v172, v184 row_shr:8 row_mask:0xf bank_mask:0xf bound_ctrl:0
	v_fmac_f32_dpp v173, v173, v185 row_shr:8 row_mask:0xf bank_mask:0xf bound_ctrl:0
	v_fmac_f32_dpp v174, v174, v186 row_shr:8 row_mask:0xf bank_mask:0xf bound_ctrl:0
	v_fmac_f32_dpp v175, v175, v187 row_shr:8 row_mask:0xf bank_mask:0xf bound_ctrl:0
	v_fmac_f32_dpp v172, v228, v188 row_shr:8 row_mask:0xf bank_mask:0xf bound_ctrl:0
	v_fmac_f32_dpp v173, v229, v189 row_shr:8 row_mask:0xf bank_mask:0xf bound_ctrl:0
	v_fmac_f32_dpp v174, v230, v190 row_shr:8 row_mask:0xf bank_mask:0xf bound_ctrl:0
	v_fmac_f32_dpp v175, v231, v191 row_shr:8 row_mask:0xf bank_mask:0xf bound_ctrl:0
	s_waitcnt lgkmcnt(0)
	v_mov_b32_e32 v228, v176
	v_mov_b32_e32 v229, v177
	v_mov_b32_e32 v230, v178
	v_mov_b32_e32 v231, v179
	v_fmac_f32_dpp v176, v176, v192 row_shr:8 row_mask:0xf bank_mask:0xf bound_ctrl:0
	v_fmac_f32_dpp v177, v177, v193 row_shr:8 row_mask:0xf bank_mask:0xf bound_ctrl:0
	v_fmac_f32_dpp v178, v178, v194 row_shr:8 row_mask:0xf bank_mask:0xf bound_ctrl:0
	v_fmac_f32_dpp v179, v179, v195 row_shr:8 row_mask:0xf bank_mask:0xf bound_ctrl:0
	v_fmac_f32_dpp v176, v180, -v224 row_shr:8 row_mask:0xf bank_mask:0xf bound_ctrl:0
	v_fmac_f32_dpp v177, v181, -v225 row_shr:8 row_mask:0xf bank_mask:0xf bound_ctrl:0
	v_fmac_f32_dpp v178, v182, -v226 row_shr:8 row_mask:0xf bank_mask:0xf bound_ctrl:0
	v_fmac_f32_dpp v179, v183, -v227 row_shr:8 row_mask:0xf bank_mask:0xf bound_ctrl:0
	v_fmac_f32_dpp v180, v180, v192 row_shr:8 row_mask:0xf bank_mask:0xf bound_ctrl:0
	v_fmac_f32_dpp v181, v181, v193 row_shr:8 row_mask:0xf bank_mask:0xf bound_ctrl:0
	v_fmac_f32_dpp v182, v182, v194 row_shr:8 row_mask:0xf bank_mask:0xf bound_ctrl:0
	v_fmac_f32_dpp v183, v183, v195 row_shr:8 row_mask:0xf bank_mask:0xf bound_ctrl:0
	v_fmac_f32_dpp v180, v228, v224 row_shr:8 row_mask:0xf bank_mask:0xf bound_ctrl:0
	v_fmac_f32_dpp v181, v229, v225 row_shr:8 row_mask:0xf bank_mask:0xf bound_ctrl:0
	v_fmac_f32_dpp v182, v230, v226 row_shr:8 row_mask:0xf bank_mask:0xf bound_ctrl:0
	v_fmac_f32_dpp v183, v231, v227 row_shr:8 row_mask:0xf bank_mask:0xf bound_ctrl:0
	s_lshl_b32 s56, s0, 5
	s_add_i32 s55, s6, 0
	s_lshl_b32 s55, s55, 1
	s_add_i32 s56, s56, s55
	s_add_i32 s56, s56, 0
	s_lshl_b32 s56, s56, 9
	s_add_u32 s48, s94, 0x12dd6000
	s_addc_u32 s49, s95, 0
	s_add_u32 s48, s48, s56
	s_addc_u32 s49, s49, 0
	s_nop 1
	s_mov_b64 exec, s[10:11]
	global_store_dword v10, v144, s[48:49] offset:0
	global_store_dword v10, v148, s[48:49] offset:4
	global_store_dword v10, v145, s[48:49] offset:8
	global_store_dword v10, v149, s[48:49] offset:12
	global_store_dword v10, v146, s[48:49] offset:16
	global_store_dword v10, v150, s[48:49] offset:20
	global_store_dword v10, v147, s[48:49] offset:24
	global_store_dword v10, v151, s[48:49] offset:28
	global_store_dword v10, v152, s[48:49] offset:128
	global_store_dword v10, v156, s[48:49] offset:132
	global_store_dword v10, v153, s[48:49] offset:136
	global_store_dword v10, v157, s[48:49] offset:140
	global_store_dword v10, v154, s[48:49] offset:144
	global_store_dword v10, v158, s[48:49] offset:148
	global_store_dword v10, v155, s[48:49] offset:152
	global_store_dword v10, v159, s[48:49] offset:156
	global_store_dword v10, v168, s[48:49] offset:256
	global_store_dword v10, v172, s[48:49] offset:260
	global_store_dword v10, v169, s[48:49] offset:264
	global_store_dword v10, v173, s[48:49] offset:268
	global_store_dword v10, v170, s[48:49] offset:272
	global_store_dword v10, v174, s[48:49] offset:276
	global_store_dword v10, v171, s[48:49] offset:280
	global_store_dword v10, v175, s[48:49] offset:284
	global_store_dword v10, v176, s[48:49] offset:384
	global_store_dword v10, v180, s[48:49] offset:388
	global_store_dword v10, v177, s[48:49] offset:392
	global_store_dword v10, v181, s[48:49] offset:396
	global_store_dword v10, v178, s[48:49] offset:400
	global_store_dword v10, v182, s[48:49] offset:404
	global_store_dword v10, v179, s[48:49] offset:408
	global_store_dword v10, v183, s[48:49] offset:412
	s_mov_b64 exec, -1
	s_waitcnt vmcnt(32)
	v_mfma_f32_16x16x4_f32 v[80:83], v44, v232, 0
	v_mfma_f32_16x16x4_f32 v[84:87], v45, v232, 0
	v_mfma_f32_16x16x4_f32 v[144:147], v44, v236, 0
	v_mfma_f32_16x16x4_f32 v[148:151], v45, v236, 0
	v_mfma_f32_16x16x4_f32 v[112:115], v56, v232, 0
	v_mfma_f32_16x16x4_f32 v[116:119], v57, v232, 0
	v_mfma_f32_16x16x4_f32 v[152:155], v56, v236, 0
	v_mfma_f32_16x16x4_f32 v[156:159], v57, v236, 0
	v_mfma_f32_16x16x4_f32 v[120:123], v64, v232, 0
	v_mfma_f32_16x16x4_f32 v[124:127], v65, v232, 0
	v_mfma_f32_16x16x4_f32 v[168:171], v64, v236, 0
	v_mfma_f32_16x16x4_f32 v[172:175], v65, v236, 0
	v_mfma_f32_16x16x4_f32 v[128:131], v72, v232, 0
	v_mfma_f32_16x16x4_f32 v[140:143], v73, v232, 0
	v_mfma_f32_16x16x4_f32 v[176:179], v72, v236, 0
	v_mfma_f32_16x16x4_f32 v[180:183], v73, v236, 0
	v_mfma_f32_16x16x4_f32 v[80:83], v46, v233, v[80:83]
	v_mfma_f32_16x16x4_f32 v[84:87], v47, v233, v[84:87]
	v_mfma_f32_16x16x4_f32 v[144:147], v46, v237, v[144:147]
	v_mfma_f32_16x16x4_f32 v[148:151], v47, v237, v[148:151]
	v_mfma_f32_16x16x4_f32 v[112:115], v58, v233, v[112:115]
	v_mfma_f32_16x16x4_f32 v[116:119], v59, v233, v[116:119]
	v_mfma_f32_16x16x4_f32 v[152:155], v58, v237, v[152:155]
	v_mfma_f32_16x16x4_f32 v[156:159], v59, v237, v[156:159]
	v_mfma_f32_16x16x4_f32 v[120:123], v66, v233, v[120:123]
	v_mfma_f32_16x16x4_f32 v[124:127], v67, v233, v[124:127]
	v_mfma_f32_16x16x4_f32 v[168:171], v66, v237, v[168:171]
	v_mfma_f32_16x16x4_f32 v[172:175], v67, v237, v[172:175]
	v_mfma_f32_16x16x4_f32 v[128:131], v74, v233, v[128:131]
	v_mfma_f32_16x16x4_f32 v[140:143], v75, v233, v[140:143]
	v_mfma_f32_16x16x4_f32 v[176:179], v74, v237, v[176:179]
	v_mfma_f32_16x16x4_f32 v[180:183], v75, v237, v[180:183]
	v_mfma_f32_16x16x4_f32 v[80:83], v52, v234, v[80:83]
	v_mfma_f32_16x16x4_f32 v[84:87], v53, v234, v[84:87]
	v_mfma_f32_16x16x4_f32 v[144:147], v52, v238, v[144:147]
	v_mfma_f32_16x16x4_f32 v[148:151], v53, v238, v[148:151]
	v_mfma_f32_16x16x4_f32 v[112:115], v60, v234, v[112:115]
	v_mfma_f32_16x16x4_f32 v[116:119], v61, v234, v[116:119]
	v_mfma_f32_16x16x4_f32 v[152:155], v60, v238, v[152:155]
	v_mfma_f32_16x16x4_f32 v[156:159], v61, v238, v[156:159]
	v_mfma_f32_16x16x4_f32 v[120:123], v68, v234, v[120:123]
	v_mfma_f32_16x16x4_f32 v[124:127], v69, v234, v[124:127]
	v_mfma_f32_16x16x4_f32 v[168:171], v68, v238, v[168:171]
	v_mfma_f32_16x16x4_f32 v[172:175], v69, v238, v[172:175]
	v_mfma_f32_16x16x4_f32 v[128:131], v76, v234, v[128:131]
	v_mfma_f32_16x16x4_f32 v[140:143], v77, v234, v[140:143]
	v_mfma_f32_16x16x4_f32 v[176:179], v76, v238, v[176:179]
	v_mfma_f32_16x16x4_f32 v[180:183], v77, v238, v[180:183]
	v_mfma_f32_16x16x4_f32 v[80:83], v54, v235, v[80:83]
	v_mfma_f32_16x16x4_f32 v[84:87], v55, v235, v[84:87]
	v_mfma_f32_16x16x4_f32 v[144:147], v54, v239, v[144:147]
	v_mfma_f32_16x16x4_f32 v[148:151], v55, v239, v[148:151]
	v_mfma_f32_16x16x4_f32 v[112:115], v62, v235, v[112:115]
	v_mfma_f32_16x16x4_f32 v[116:119], v63, v235, v[116:119]
	v_mfma_f32_16x16x4_f32 v[152:155], v62, v239, v[152:155]
	v_mfma_f32_16x16x4_f32 v[156:159], v63, v239, v[156:159]
	v_mfma_f32_16x16x4_f32 v[120:123], v70, v235, v[120:123]
	v_mfma_f32_16x16x4_f32 v[124:127], v71, v235, v[124:127]
	v_mfma_f32_16x16x4_f32 v[168:171], v70, v239, v[168:171]
	v_mfma_f32_16x16x4_f32 v[172:175], v71, v239, v[172:175]
	v_mfma_f32_16x16x4_f32 v[128:131], v78, v235, v[128:131]
	v_mfma_f32_16x16x4_f32 v[140:143], v79, v235, v[140:143]
	v_mfma_f32_16x16x4_f32 v[176:179], v78, v239, v[176:179]
	v_mfma_f32_16x16x4_f32 v[180:183], v79, v239, v[180:183]
	s_nop 9
	ds_read_b128 v[184:187], v9 offset:2560
	ds_read_b128 v[188:191], v9 offset:2816
	ds_read_b128 v[192:195], v9 offset:2624
	ds_read_b128 v[224:227], v9 offset:2880
	s_waitcnt lgkmcnt(2)
	v_fmac_f32_e32 v80, v184, v144
	v_fmac_f32_e32 v81, v185, v145
	v_fmac_f32_e32 v82, v186, v146
	v_fmac_f32_e32 v83, v187, v147
	v_fma_f32 v80, -v188, v148, v80
	v_fma_f32 v81, -v189, v149, v81
	v_fma_f32 v82, -v190, v150, v82
	v_fma_f32 v83, -v191, v151, v83
	v_fmac_f32_e32 v84, v184, v148
	v_fmac_f32_e32 v85, v185, v149
	v_fmac_f32_e32 v86, v186, v150
	v_fmac_f32_e32 v87, v187, v151
	v_fmac_f32_e32 v84, v188, v144
	v_fmac_f32_e32 v85, v189, v145
	v_fmac_f32_e32 v86, v190, v146
	v_fmac_f32_e32 v87, v191, v147
	ds_read_b128 v[184:187], v9 offset:2688
	ds_read_b128 v[188:191], v9 offset:2944
	s_waitcnt lgkmcnt(2)
	v_fmac_f32_e32 v112, v192, v152
	v_fmac_f32_e32 v113, v193, v153
	v_fmac_f32_e32 v114, v194, v154
	v_fmac_f32_e32 v115, v195, v155
	v_fma_f32 v112, -v224, v156, v112
	v_fma_f32 v113, -v225, v157, v113
	v_fma_f32 v114, -v226, v158, v114
	v_fma_f32 v115, -v227, v159, v115
	v_fmac_f32_e32 v116, v192, v156
	v_fmac_f32_e32 v117, v193, v157
	v_fmac_f32_e32 v118, v194, v158
	v_fmac_f32_e32 v119, v195, v159
	v_fmac_f32_e32 v116, v224, v152
	v_fmac_f32_e32 v117, v225, v153
	v_fmac_f32_e32 v118, v226, v154
	v_fmac_f32_e32 v119, v227, v155
	ds_read_b128 v[192:195], v9 offset:2752
	ds_read_b128 v[224:227], v9 offset:3008
	s_waitcnt lgkmcnt(2)
	v_fmac_f32_e32 v120, v184, v168
	v_fmac_f32_e32 v121, v185, v169
	v_fmac_f32_e32 v122, v186, v170
	v_fmac_f32_e32 v123, v187, v171
	v_fma_f32 v120, -v188, v172, v120
	v_fma_f32 v121, -v189, v173, v121
	v_fma_f32 v122, -v190, v174, v122
	v_fma_f32 v123, -v191, v175, v123
	v_fmac_f32_e32 v124, v184, v172
	v_fmac_f32_e32 v125, v185, v173
	v_fmac_f32_e32 v126, v186, v174
	v_fmac_f32_e32 v127, v187, v175
	v_fmac_f32_e32 v124, v188, v168
	v_fmac_f32_e32 v125, v189, v169
	v_fmac_f32_e32 v126, v190, v170
	v_fmac_f32_e32 v127, v191, v171
	s_waitcnt lgkmcnt(0)
	v_fmac_f32_e32 v128, v192, v176
	v_fmac_f32_e32 v129, v193, v177
	v_fmac_f32_e32 v130, v194, v178
	v_fmac_f32_e32 v131, v195, v179
	v_fma_f32 v128, -v224, v180, v128
	v_fma_f32 v129, -v225, v181, v129
	v_fma_f32 v130, -v226, v182, v130
	v_fma_f32 v131, -v227, v183, v131
	v_fmac_f32_e32 v140, v192, v180
	v_fmac_f32_e32 v141, v193, v181
	v_fmac_f32_e32 v142, v194, v182
	v_fmac_f32_e32 v143, v195, v183
	v_fmac_f32_e32 v140, v224, v176
	v_fmac_f32_e32 v141, v225, v177
	v_fmac_f32_e32 v142, v226, v178
	v_fmac_f32_e32 v143, v227, v179
	global_load_dwordx4 v[12:15], v6, s[36:37] offset:0
	global_load_dwordx4 v[16:19], v6, s[36:37] offset:1024
	global_load_dwordx4 v[20:23], v6, s[36:37] offset:256
	global_load_dwordx4 v[24:27], v6, s[36:37] offset:1280
	global_load_dwordx4 v[28:31], v6, s[36:37] offset:512
	global_load_dwordx4 v[32:35], v6, s[36:37] offset:1536
	global_load_dwordx4 v[36:39], v6, s[36:37] offset:768
	global_load_dwordx4 v[40:43], v6, s[36:37] offset:1792
	ds_read_b128 v[184:187], v9 offset:3072
	ds_read_b128 v[188:191], v9 offset:3328
	ds_read_b128 v[192:195], v9 offset:3136
	ds_read_b128 v[224:227], v9 offset:3392
	s_waitcnt lgkmcnt(2)
	v_mov_b32_e32 v228, v80
	v_mov_b32_e32 v229, v81
	v_mov_b32_e32 v230, v82
	v_mov_b32_e32 v231, v83
	s_nop 1
	v_fmac_f32_dpp v80, v80, v184 row_shl:1 row_mask:0xf bank_mask:0xf bound_ctrl:0
	v_fmac_f32_dpp v81, v81, v185 row_shl:1 row_mask:0xf bank_mask:0xf bound_ctrl:0
	v_fmac_f32_dpp v82, v82, v186 row_shl:1 row_mask:0xf bank_mask:0xf bound_ctrl:0
	v_fmac_f32_dpp v83, v83, v187 row_shl:1 row_mask:0xf bank_mask:0xf bound_ctrl:0
	v_fmac_f32_dpp v80, v84, -v188 row_shl:1 row_mask:0xf bank_mask:0xf bound_ctrl:0
	v_fmac_f32_dpp v81, v85, -v189 row_shl:1 row_mask:0xf bank_mask:0xf bound_ctrl:0
	v_fmac_f32_dpp v82, v86, -v190 row_shl:1 row_mask:0xf bank_mask:0xf bound_ctrl:0
	v_fmac_f32_dpp v83, v87, -v191 row_shl:1 row_mask:0xf bank_mask:0xf bound_ctrl:0
	v_fmac_f32_dpp v84, v84, v184 row_shl:1 row_mask:0xf bank_mask:0xf bound_ctrl:0
	v_fmac_f32_dpp v85, v85, v185 row_shl:1 row_mask:0xf bank_mask:0xf bound_ctrl:0
	v_fmac_f32_dpp v86, v86, v186 row_shl:1 row_mask:0xf bank_mask:0xf bound_ctrl:0
	v_fmac_f32_dpp v87, v87, v187 row_shl:1 row_mask:0xf bank_mask:0xf bound_ctrl:0
	v_fmac_f32_dpp v84, v228, v188 row_shl:1 row_mask:0xf bank_mask:0xf bound_ctrl:0
	v_fmac_f32_dpp v85, v229, v189 row_shl:1 row_mask:0xf bank_mask:0xf bound_ctrl:0
	v_fmac_f32_dpp v86, v230, v190 row_shl:1 row_mask:0xf bank_mask:0xf bound_ctrl:0
	v_fmac_f32_dpp v87, v231, v191 row_shl:1 row_mask:0xf bank_mask:0xf bound_ctrl:0
	ds_read_b128 v[184:187], v9 offset:3200
	ds_read_b128 v[188:191], v9 offset:3456
	s_waitcnt lgkmcnt(2)
	v_mov_b32_e32 v228, v112
	v_mov_b32_e32 v229, v113
	v_mov_b32_e32 v230, v114
	v_mov_b32_e32 v231, v115
	v_fmac_f32_dpp v112, v112, v192 row_shl:1 row_mask:0xf bank_mask:0xf bound_ctrl:0
	v_fmac_f32_dpp v113, v113, v193 row_shl:1 row_mask:0xf bank_mask:0xf bound_ctrl:0
	v_fmac_f32_dpp v114, v114, v194 row_shl:1 row_mask:0xf bank_mask:0xf bound_ctrl:0
	v_fmac_f32_dpp v115, v115, v195 row_shl:1 row_mask:0xf bank_mask:0xf bound_ctrl:0
	v_fmac_f32_dpp v112, v116, -v224 row_shl:1 row_mask:0xf bank_mask:0xf bound_ctrl:0
	v_fmac_f32_dpp v113, v117, -v225 row_shl:1 row_mask:0xf bank_mask:0xf bound_ctrl:0
	v_fmac_f32_dpp v114, v118, -v226 row_shl:1 row_mask:0xf bank_mask:0xf bound_ctrl:0
	v_fmac_f32_dpp v115, v119, -v227 row_shl:1 row_mask:0xf bank_mask:0xf bound_ctrl:0
	v_fmac_f32_dpp v116, v116, v192 row_shl:1 row_mask:0xf bank_mask:0xf bound_ctrl:0
	v_fmac_f32_dpp v117, v117, v193 row_shl:1 row_mask:0xf bank_mask:0xf bound_ctrl:0
	v_fmac_f32_dpp v118, v118, v194 row_shl:1 row_mask:0xf bank_mask:0xf bound_ctrl:0
	v_fmac_f32_dpp v119, v119, v195 row_shl:1 row_mask:0xf bank_mask:0xf bound_ctrl:0
	v_fmac_f32_dpp v116, v228, v224 row_shl:1 row_mask:0xf bank_mask:0xf bound_ctrl:0
	v_fmac_f32_dpp v117, v229, v225 row_shl:1 row_mask:0xf bank_mask:0xf bound_ctrl:0
	v_fmac_f32_dpp v118, v230, v226 row_shl:1 row_mask:0xf bank_mask:0xf bound_ctrl:0
	v_fmac_f32_dpp v119, v231, v227 row_shl:1 row_mask:0xf bank_mask:0xf bound_ctrl:0
	ds_read_b128 v[192:195], v9 offset:3264
	ds_read_b128 v[224:227], v9 offset:3520
	s_waitcnt lgkmcnt(2)
	v_mov_b32_e32 v228, v120
	v_mov_b32_e32 v229, v121
	v_mov_b32_e32 v230, v122
	v_mov_b32_e32 v231, v123
	v_fmac_f32_dpp v120, v120, v184 row_shl:1 row_mask:0xf bank_mask:0xf bound_ctrl:0
	v_fmac_f32_dpp v121, v121, v185 row_shl:1 row_mask:0xf bank_mask:0xf bound_ctrl:0
	v_fmac_f32_dpp v122, v122, v186 row_shl:1 row_mask:0xf bank_mask:0xf bound_ctrl:0
	v_fmac_f32_dpp v123, v123, v187 row_shl:1 row_mask:0xf bank_mask:0xf bound_ctrl:0
	v_fmac_f32_dpp v120, v124, -v188 row_shl:1 row_mask:0xf bank_mask:0xf bound_ctrl:0
	v_fmac_f32_dpp v121, v125, -v189 row_shl:1 row_mask:0xf bank_mask:0xf bound_ctrl:0
	v_fmac_f32_dpp v122, v126, -v190 row_shl:1 row_mask:0xf bank_mask:0xf bound_ctrl:0
	v_fmac_f32_dpp v123, v127, -v191 row_shl:1 row_mask:0xf bank_mask:0xf bound_ctrl:0
	v_fmac_f32_dpp v124, v124, v184 row_shl:1 row_mask:0xf bank_mask:0xf bound_ctrl:0
	v_fmac_f32_dpp v125, v125, v185 row_shl:1 row_mask:0xf bank_mask:0xf bound_ctrl:0
	v_fmac_f32_dpp v126, v126, v186 row_shl:1 row_mask:0xf bank_mask:0xf bound_ctrl:0
	v_fmac_f32_dpp v127, v127, v187 row_shl:1 row_mask:0xf bank_mask:0xf bound_ctrl:0
	v_fmac_f32_dpp v124, v228, v188 row_shl:1 row_mask:0xf bank_mask:0xf bound_ctrl:0
	v_fmac_f32_dpp v125, v229, v189 row_shl:1 row_mask:0xf bank_mask:0xf bound_ctrl:0
	v_fmac_f32_dpp v126, v230, v190 row_shl:1 row_mask:0xf bank_mask:0xf bound_ctrl:0
	v_fmac_f32_dpp v127, v231, v191 row_shl:1 row_mask:0xf bank_mask:0xf bound_ctrl:0
	ds_read_b128 v[184:187], v9 offset:3584
	ds_read_b128 v[188:191], v9 offset:3840
	s_waitcnt lgkmcnt(2)
	v_mov_b32_e32 v228, v128
	v_mov_b32_e32 v229, v129
	v_mov_b32_e32 v230, v130
	v_mov_b32_e32 v231, v131
	v_fmac_f32_dpp v128, v128, v192 row_shl:1 row_mask:0xf bank_mask:0xf bound_ctrl:0
	v_fmac_f32_dpp v129, v129, v193 row_shl:1 row_mask:0xf bank_mask:0xf bound_ctrl:0
	v_fmac_f32_dpp v130, v130, v194 row_shl:1 row_mask:0xf bank_mask:0xf bound_ctrl:0
	v_fmac_f32_dpp v131, v131, v195 row_shl:1 row_mask:0xf bank_mask:0xf bound_ctrl:0
	v_fmac_f32_dpp v128, v140, -v224 row_shl:1 row_mask:0xf bank_mask:0xf bound_ctrl:0
	v_fmac_f32_dpp v129, v141, -v225 row_shl:1 row_mask:0xf bank_mask:0xf bound_ctrl:0
	v_fmac_f32_dpp v130, v142, -v226 row_shl:1 row_mask:0xf bank_mask:0xf bound_ctrl:0
	v_fmac_f32_dpp v131, v143, -v227 row_shl:1 row_mask:0xf bank_mask:0xf bound_ctrl:0
	v_fmac_f32_dpp v140, v140, v192 row_shl:1 row_mask:0xf bank_mask:0xf bound_ctrl:0
	v_fmac_f32_dpp v141, v141, v193 row_shl:1 row_mask:0xf bank_mask:0xf bound_ctrl:0
	v_fmac_f32_dpp v142, v142, v194 row_shl:1 row_mask:0xf bank_mask:0xf bound_ctrl:0
	v_fmac_f32_dpp v143, v143, v195 row_shl:1 row_mask:0xf bank_mask:0xf bound_ctrl:0
	v_fmac_f32_dpp v140, v228, v224 row_shl:1 row_mask:0xf bank_mask:0xf bound_ctrl:0
	v_fmac_f32_dpp v141, v229, v225 row_shl:1 row_mask:0xf bank_mask:0xf bound_ctrl:0
	v_fmac_f32_dpp v142, v230, v226 row_shl:1 row_mask:0xf bank_mask:0xf bound_ctrl:0
	v_fmac_f32_dpp v143, v231, v227 row_shl:1 row_mask:0xf bank_mask:0xf bound_ctrl:0
	ds_read_b128 v[192:195], v9 offset:3648
	ds_read_b128 v[224:227], v9 offset:3904
	s_waitcnt lgkmcnt(2)
	v_mov_b32_e32 v228, v80
	v_mov_b32_e32 v229, v81
	v_mov_b32_e32 v230, v82
	v_mov_b32_e32 v231, v83
	v_fmac_f32_dpp v80, v80, v184 row_shl:2 row_mask:0xf bank_mask:0xf bound_ctrl:0
	v_fmac_f32_dpp v81, v81, v185 row_shl:2 row_mask:0xf bank_mask:0xf bound_ctrl:0
	v_fmac_f32_dpp v82, v82, v186 row_shl:2 row_mask:0xf bank_mask:0xf bound_ctrl:0
	v_fmac_f32_dpp v83, v83, v187 row_shl:2 row_mask:0xf bank_mask:0xf bound_ctrl:0
	v_fmac_f32_dpp v80, v84, -v188 row_shl:2 row_mask:0xf bank_mask:0xf bound_ctrl:0
	v_fmac_f32_dpp v81, v85, -v189 row_shl:2 row_mask:0xf bank_mask:0xf bound_ctrl:0
	v_fmac_f32_dpp v82, v86, -v190 row_shl:2 row_mask:0xf bank_mask:0xf bound_ctrl:0
	v_fmac_f32_dpp v83, v87, -v191 row_shl:2 row_mask:0xf bank_mask:0xf bound_ctrl:0
	v_fmac_f32_dpp v84, v84, v184 row_shl:2 row_mask:0xf bank_mask:0xf bound_ctrl:0
	v_fmac_f32_dpp v85, v85, v185 row_shl:2 row_mask:0xf bank_mask:0xf bound_ctrl:0
	v_fmac_f32_dpp v86, v86, v186 row_shl:2 row_mask:0xf bank_mask:0xf bound_ctrl:0
	v_fmac_f32_dpp v87, v87, v187 row_shl:2 row_mask:0xf bank_mask:0xf bound_ctrl:0
	v_fmac_f32_dpp v84, v228, v188 row_shl:2 row_mask:0xf bank_mask:0xf bound_ctrl:0
	v_fmac_f32_dpp v85, v229, v189 row_shl:2 row_mask:0xf bank_mask:0xf bound_ctrl:0
	v_fmac_f32_dpp v86, v230, v190 row_shl:2 row_mask:0xf bank_mask:0xf bound_ctrl:0
	v_fmac_f32_dpp v87, v231, v191 row_shl:2 row_mask:0xf bank_mask:0xf bound_ctrl:0
	ds_read_b128 v[184:187], v9 offset:3712
	ds_read_b128 v[188:191], v9 offset:3968
	s_waitcnt lgkmcnt(2)
	v_mov_b32_e32 v228, v112
	v_mov_b32_e32 v229, v113
	v_mov_b32_e32 v230, v114
	v_mov_b32_e32 v231, v115
	v_fmac_f32_dpp v112, v112, v192 row_shl:2 row_mask:0xf bank_mask:0xf bound_ctrl:0
	v_fmac_f32_dpp v113, v113, v193 row_shl:2 row_mask:0xf bank_mask:0xf bound_ctrl:0
	v_fmac_f32_dpp v114, v114, v194 row_shl:2 row_mask:0xf bank_mask:0xf bound_ctrl:0
	v_fmac_f32_dpp v115, v115, v195 row_shl:2 row_mask:0xf bank_mask:0xf bound_ctrl:0
	v_fmac_f32_dpp v112, v116, -v224 row_shl:2 row_mask:0xf bank_mask:0xf bound_ctrl:0
	v_fmac_f32_dpp v113, v117, -v225 row_shl:2 row_mask:0xf bank_mask:0xf bound_ctrl:0
	v_fmac_f32_dpp v114, v118, -v226 row_shl:2 row_mask:0xf bank_mask:0xf bound_ctrl:0
	v_fmac_f32_dpp v115, v119, -v227 row_shl:2 row_mask:0xf bank_mask:0xf bound_ctrl:0
	v_fmac_f32_dpp v116, v116, v192 row_shl:2 row_mask:0xf bank_mask:0xf bound_ctrl:0
	v_fmac_f32_dpp v117, v117, v193 row_shl:2 row_mask:0xf bank_mask:0xf bound_ctrl:0
	v_fmac_f32_dpp v118, v118, v194 row_shl:2 row_mask:0xf bank_mask:0xf bound_ctrl:0
	v_fmac_f32_dpp v119, v119, v195 row_shl:2 row_mask:0xf bank_mask:0xf bound_ctrl:0
	v_fmac_f32_dpp v116, v228, v224 row_shl:2 row_mask:0xf bank_mask:0xf bound_ctrl:0
	v_fmac_f32_dpp v117, v229, v225 row_shl:2 row_mask:0xf bank_mask:0xf bound_ctrl:0
	v_fmac_f32_dpp v118, v230, v226 row_shl:2 row_mask:0xf bank_mask:0xf bound_ctrl:0
	v_fmac_f32_dpp v119, v231, v227 row_shl:2 row_mask:0xf bank_mask:0xf bound_ctrl:0
	ds_read_b128 v[192:195], v9 offset:3776
	ds_read_b128 v[224:227], v9 offset:4032
	s_waitcnt lgkmcnt(2)
	v_mov_b32_e32 v228, v120
	v_mov_b32_e32 v229, v121
	v_mov_b32_e32 v230, v122
	v_mov_b32_e32 v231, v123
	v_fmac_f32_dpp v120, v120, v184 row_shl:2 row_mask:0xf bank_mask:0xf bound_ctrl:0
	v_fmac_f32_dpp v121, v121, v185 row_shl:2 row_mask:0xf bank_mask:0xf bound_ctrl:0
	v_fmac_f32_dpp v122, v122, v186 row_shl:2 row_mask:0xf bank_mask:0xf bound_ctrl:0
	v_fmac_f32_dpp v123, v123, v187 row_shl:2 row_mask:0xf bank_mask:0xf bound_ctrl:0
	v_fmac_f32_dpp v120, v124, -v188 row_shl:2 row_mask:0xf bank_mask:0xf bound_ctrl:0
	v_fmac_f32_dpp v121, v125, -v189 row_shl:2 row_mask:0xf bank_mask:0xf bound_ctrl:0
	v_fmac_f32_dpp v122, v126, -v190 row_shl:2 row_mask:0xf bank_mask:0xf bound_ctrl:0
	v_fmac_f32_dpp v123, v127, -v191 row_shl:2 row_mask:0xf bank_mask:0xf bound_ctrl:0
	v_fmac_f32_dpp v124, v124, v184 row_shl:2 row_mask:0xf bank_mask:0xf bound_ctrl:0
	v_fmac_f32_dpp v125, v125, v185 row_shl:2 row_mask:0xf bank_mask:0xf bound_ctrl:0
	v_fmac_f32_dpp v126, v126, v186 row_shl:2 row_mask:0xf bank_mask:0xf bound_ctrl:0
	v_fmac_f32_dpp v127, v127, v187 row_shl:2 row_mask:0xf bank_mask:0xf bound_ctrl:0
	v_fmac_f32_dpp v124, v228, v188 row_shl:2 row_mask:0xf bank_mask:0xf bound_ctrl:0
	v_fmac_f32_dpp v125, v229, v189 row_shl:2 row_mask:0xf bank_mask:0xf bound_ctrl:0
	v_fmac_f32_dpp v126, v230, v190 row_shl:2 row_mask:0xf bank_mask:0xf bound_ctrl:0
	v_fmac_f32_dpp v127, v231, v191 row_shl:2 row_mask:0xf bank_mask:0xf bound_ctrl:0
	ds_read_b128 v[184:187], v9 offset:4096
	ds_read_b128 v[188:191], v9 offset:4352
	s_waitcnt lgkmcnt(2)
	v_mov_b32_e32 v228, v128
	v_mov_b32_e32 v229, v129
	v_mov_b32_e32 v230, v130
	v_mov_b32_e32 v231, v131
	v_fmac_f32_dpp v128, v128, v192 row_shl:2 row_mask:0xf bank_mask:0xf bound_ctrl:0
	v_fmac_f32_dpp v129, v129, v193 row_shl:2 row_mask:0xf bank_mask:0xf bound_ctrl:0
	v_fmac_f32_dpp v130, v130, v194 row_shl:2 row_mask:0xf bank_mask:0xf bound_ctrl:0
	v_fmac_f32_dpp v131, v131, v195 row_shl:2 row_mask:0xf bank_mask:0xf bound_ctrl:0
	v_fmac_f32_dpp v128, v140, -v224 row_shl:2 row_mask:0xf bank_mask:0xf bound_ctrl:0
	v_fmac_f32_dpp v129, v141, -v225 row_shl:2 row_mask:0xf bank_mask:0xf bound_ctrl:0
	v_fmac_f32_dpp v130, v142, -v226 row_shl:2 row_mask:0xf bank_mask:0xf bound_ctrl:0
	v_fmac_f32_dpp v131, v143, -v227 row_shl:2 row_mask:0xf bank_mask:0xf bound_ctrl:0
	v_fmac_f32_dpp v140, v140, v192 row_shl:2 row_mask:0xf bank_mask:0xf bound_ctrl:0
	v_fmac_f32_dpp v141, v141, v193 row_shl:2 row_mask:0xf bank_mask:0xf bound_ctrl:0
	v_fmac_f32_dpp v142, v142, v194 row_shl:2 row_mask:0xf bank_mask:0xf bound_ctrl:0
	v_fmac_f32_dpp v143, v143, v195 row_shl:2 row_mask:0xf bank_mask:0xf bound_ctrl:0
	v_fmac_f32_dpp v140, v228, v224 row_shl:2 row_mask:0xf bank_mask:0xf bound_ctrl:0
	v_fmac_f32_dpp v141, v229, v225 row_shl:2 row_mask:0xf bank_mask:0xf bound_ctrl:0
	v_fmac_f32_dpp v142, v230, v226 row_shl:2 row_mask:0xf bank_mask:0xf bound_ctrl:0
	v_fmac_f32_dpp v143, v231, v227 row_shl:2 row_mask:0xf bank_mask:0xf bound_ctrl:0
	ds_read_b128 v[192:195], v9 offset:4160
	ds_read_b128 v[224:227], v9 offset:4416
	s_waitcnt lgkmcnt(2)
	v_mov_b32_e32 v228, v80
	v_mov_b32_e32 v229, v81
	v_mov_b32_e32 v230, v82
	v_mov_b32_e32 v231, v83
	v_fmac_f32_dpp v80, v80, v184 row_shl:4 row_mask:0xf bank_mask:0xf bound_ctrl:0
	v_fmac_f32_dpp v81, v81, v185 row_shl:4 row_mask:0xf bank_mask:0xf bound_ctrl:0
	v_fmac_f32_dpp v82, v82, v186 row_shl:4 row_mask:0xf bank_mask:0xf bound_ctrl:0
	v_fmac_f32_dpp v83, v83, v187 row_shl:4 row_mask:0xf bank_mask:0xf bound_ctrl:0
	v_fmac_f32_dpp v80, v84, -v188 row_shl:4 row_mask:0xf bank_mask:0xf bound_ctrl:0
	v_fmac_f32_dpp v81, v85, -v189 row_shl:4 row_mask:0xf bank_mask:0xf bound_ctrl:0
	v_fmac_f32_dpp v82, v86, -v190 row_shl:4 row_mask:0xf bank_mask:0xf bound_ctrl:0
	v_fmac_f32_dpp v83, v87, -v191 row_shl:4 row_mask:0xf bank_mask:0xf bound_ctrl:0
	v_fmac_f32_dpp v84, v84, v184 row_shl:4 row_mask:0xf bank_mask:0xf bound_ctrl:0
	v_fmac_f32_dpp v85, v85, v185 row_shl:4 row_mask:0xf bank_mask:0xf bound_ctrl:0
	v_fmac_f32_dpp v86, v86, v186 row_shl:4 row_mask:0xf bank_mask:0xf bound_ctrl:0
	v_fmac_f32_dpp v87, v87, v187 row_shl:4 row_mask:0xf bank_mask:0xf bound_ctrl:0
	v_fmac_f32_dpp v84, v228, v188 row_shl:4 row_mask:0xf bank_mask:0xf bound_ctrl:0
	v_fmac_f32_dpp v85, v229, v189 row_shl:4 row_mask:0xf bank_mask:0xf bound_ctrl:0
	v_fmac_f32_dpp v86, v230, v190 row_shl:4 row_mask:0xf bank_mask:0xf bound_ctrl:0
	v_fmac_f32_dpp v87, v231, v191 row_shl:4 row_mask:0xf bank_mask:0xf bound_ctrl:0
	ds_read_b128 v[184:187], v9 offset:4224
	ds_read_b128 v[188:191], v9 offset:4480
	s_waitcnt lgkmcnt(2)
	v_mov_b32_e32 v228, v112
	v_mov_b32_e32 v229, v113
	v_mov_b32_e32 v230, v114
	v_mov_b32_e32 v231, v115
	v_fmac_f32_dpp v112, v112, v192 row_shl:4 row_mask:0xf bank_mask:0xf bound_ctrl:0
	v_fmac_f32_dpp v113, v113, v193 row_shl:4 row_mask:0xf bank_mask:0xf bound_ctrl:0
	v_fmac_f32_dpp v114, v114, v194 row_shl:4 row_mask:0xf bank_mask:0xf bound_ctrl:0
	v_fmac_f32_dpp v115, v115, v195 row_shl:4 row_mask:0xf bank_mask:0xf bound_ctrl:0
	v_fmac_f32_dpp v112, v116, -v224 row_shl:4 row_mask:0xf bank_mask:0xf bound_ctrl:0
	v_fmac_f32_dpp v113, v117, -v225 row_shl:4 row_mask:0xf bank_mask:0xf bound_ctrl:0
	v_fmac_f32_dpp v114, v118, -v226 row_shl:4 row_mask:0xf bank_mask:0xf bound_ctrl:0
	v_fmac_f32_dpp v115, v119, -v227 row_shl:4 row_mask:0xf bank_mask:0xf bound_ctrl:0
	v_fmac_f32_dpp v116, v116, v192 row_shl:4 row_mask:0xf bank_mask:0xf bound_ctrl:0
	v_fmac_f32_dpp v117, v117, v193 row_shl:4 row_mask:0xf bank_mask:0xf bound_ctrl:0
	v_fmac_f32_dpp v118, v118, v194 row_shl:4 row_mask:0xf bank_mask:0xf bound_ctrl:0
	v_fmac_f32_dpp v119, v119, v195 row_shl:4 row_mask:0xf bank_mask:0xf bound_ctrl:0
	v_fmac_f32_dpp v116, v228, v224 row_shl:4 row_mask:0xf bank_mask:0xf bound_ctrl:0
	v_fmac_f32_dpp v117, v229, v225 row_shl:4 row_mask:0xf bank_mask:0xf bound_ctrl:0
	v_fmac_f32_dpp v118, v230, v226 row_shl:4 row_mask:0xf bank_mask:0xf bound_ctrl:0
	v_fmac_f32_dpp v119, v231, v227 row_shl:4 row_mask:0xf bank_mask:0xf bound_ctrl:0
	ds_read_b128 v[192:195], v9 offset:4288
	ds_read_b128 v[224:227], v9 offset:4544
	s_waitcnt lgkmcnt(2)
	v_mov_b32_e32 v228, v120
	v_mov_b32_e32 v229, v121
	v_mov_b32_e32 v230, v122
	v_mov_b32_e32 v231, v123
	v_fmac_f32_dpp v120, v120, v184 row_shl:4 row_mask:0xf bank_mask:0xf bound_ctrl:0
	v_fmac_f32_dpp v121, v121, v185 row_shl:4 row_mask:0xf bank_mask:0xf bound_ctrl:0
	v_fmac_f32_dpp v122, v122, v186 row_shl:4 row_mask:0xf bank_mask:0xf bound_ctrl:0
	v_fmac_f32_dpp v123, v123, v187 row_shl:4 row_mask:0xf bank_mask:0xf bound_ctrl:0
	v_fmac_f32_dpp v120, v124, -v188 row_shl:4 row_mask:0xf bank_mask:0xf bound_ctrl:0
	v_fmac_f32_dpp v121, v125, -v189 row_shl:4 row_mask:0xf bank_mask:0xf bound_ctrl:0
	v_fmac_f32_dpp v122, v126, -v190 row_shl:4 row_mask:0xf bank_mask:0xf bound_ctrl:0
	v_fmac_f32_dpp v123, v127, -v191 row_shl:4 row_mask:0xf bank_mask:0xf bound_ctrl:0
	v_fmac_f32_dpp v124, v124, v184 row_shl:4 row_mask:0xf bank_mask:0xf bound_ctrl:0
	v_fmac_f32_dpp v125, v125, v185 row_shl:4 row_mask:0xf bank_mask:0xf bound_ctrl:0
	v_fmac_f32_dpp v126, v126, v186 row_shl:4 row_mask:0xf bank_mask:0xf bound_ctrl:0
	v_fmac_f32_dpp v127, v127, v187 row_shl:4 row_mask:0xf bank_mask:0xf bound_ctrl:0
	v_fmac_f32_dpp v124, v228, v188 row_shl:4 row_mask:0xf bank_mask:0xf bound_ctrl:0
	v_fmac_f32_dpp v125, v229, v189 row_shl:4 row_mask:0xf bank_mask:0xf bound_ctrl:0
	v_fmac_f32_dpp v126, v230, v190 row_shl:4 row_mask:0xf bank_mask:0xf bound_ctrl:0
	v_fmac_f32_dpp v127, v231, v191 row_shl:4 row_mask:0xf bank_mask:0xf bound_ctrl:0
	ds_read_b128 v[184:187], v9 offset:4608
	ds_read_b128 v[188:191], v9 offset:4864
	s_waitcnt lgkmcnt(2)
	v_mov_b32_e32 v228, v128
	v_mov_b32_e32 v229, v129
	v_mov_b32_e32 v230, v130
	v_mov_b32_e32 v231, v131
	v_fmac_f32_dpp v128, v128, v192 row_shl:4 row_mask:0xf bank_mask:0xf bound_ctrl:0
	v_fmac_f32_dpp v129, v129, v193 row_shl:4 row_mask:0xf bank_mask:0xf bound_ctrl:0
	v_fmac_f32_dpp v130, v130, v194 row_shl:4 row_mask:0xf bank_mask:0xf bound_ctrl:0
	v_fmac_f32_dpp v131, v131, v195 row_shl:4 row_mask:0xf bank_mask:0xf bound_ctrl:0
	v_fmac_f32_dpp v128, v140, -v224 row_shl:4 row_mask:0xf bank_mask:0xf bound_ctrl:0
	v_fmac_f32_dpp v129, v141, -v225 row_shl:4 row_mask:0xf bank_mask:0xf bound_ctrl:0
	v_fmac_f32_dpp v130, v142, -v226 row_shl:4 row_mask:0xf bank_mask:0xf bound_ctrl:0
	v_fmac_f32_dpp v131, v143, -v227 row_shl:4 row_mask:0xf bank_mask:0xf bound_ctrl:0
	v_fmac_f32_dpp v140, v140, v192 row_shl:4 row_mask:0xf bank_mask:0xf bound_ctrl:0
	v_fmac_f32_dpp v141, v141, v193 row_shl:4 row_mask:0xf bank_mask:0xf bound_ctrl:0
	v_fmac_f32_dpp v142, v142, v194 row_shl:4 row_mask:0xf bank_mask:0xf bound_ctrl:0
	v_fmac_f32_dpp v143, v143, v195 row_shl:4 row_mask:0xf bank_mask:0xf bound_ctrl:0
	v_fmac_f32_dpp v140, v228, v224 row_shl:4 row_mask:0xf bank_mask:0xf bound_ctrl:0
	v_fmac_f32_dpp v141, v229, v225 row_shl:4 row_mask:0xf bank_mask:0xf bound_ctrl:0
	v_fmac_f32_dpp v142, v230, v226 row_shl:4 row_mask:0xf bank_mask:0xf bound_ctrl:0
	v_fmac_f32_dpp v143, v231, v227 row_shl:4 row_mask:0xf bank_mask:0xf bound_ctrl:0
	ds_read_b128 v[192:195], v9 offset:4672
	ds_read_b128 v[224:227], v9 offset:4928
	s_waitcnt lgkmcnt(2)
	v_mov_b32_e32 v228, v80
	v_mov_b32_e32 v229, v81
	v_mov_b32_e32 v230, v82
	v_mov_b32_e32 v231, v83
	v_fmac_f32_dpp v80, v80, v184 row_shl:8 row_mask:0xf bank_mask:0xf bound_ctrl:0
	v_fmac_f32_dpp v81, v81, v185 row_shl:8 row_mask:0xf bank_mask:0xf bound_ctrl:0
	v_fmac_f32_dpp v82, v82, v186 row_shl:8 row_mask:0xf bank_mask:0xf bound_ctrl:0
	v_fmac_f32_dpp v83, v83, v187 row_shl:8 row_mask:0xf bank_mask:0xf bound_ctrl:0
	v_fmac_f32_dpp v80, v84, -v188 row_shl:8 row_mask:0xf bank_mask:0xf bound_ctrl:0
	v_fmac_f32_dpp v81, v85, -v189 row_shl:8 row_mask:0xf bank_mask:0xf bound_ctrl:0
	v_fmac_f32_dpp v82, v86, -v190 row_shl:8 row_mask:0xf bank_mask:0xf bound_ctrl:0
	v_fmac_f32_dpp v83, v87, -v191 row_shl:8 row_mask:0xf bank_mask:0xf bound_ctrl:0
	v_fmac_f32_dpp v84, v84, v184 row_shl:8 row_mask:0xf bank_mask:0xf bound_ctrl:0
	v_fmac_f32_dpp v85, v85, v185 row_shl:8 row_mask:0xf bank_mask:0xf bound_ctrl:0
	v_fmac_f32_dpp v86, v86, v186 row_shl:8 row_mask:0xf bank_mask:0xf bound_ctrl:0
	v_fmac_f32_dpp v87, v87, v187 row_shl:8 row_mask:0xf bank_mask:0xf bound_ctrl:0
	v_fmac_f32_dpp v84, v228, v188 row_shl:8 row_mask:0xf bank_mask:0xf bound_ctrl:0
	v_fmac_f32_dpp v85, v229, v189 row_shl:8 row_mask:0xf bank_mask:0xf bound_ctrl:0
	v_fmac_f32_dpp v86, v230, v190 row_shl:8 row_mask:0xf bank_mask:0xf bound_ctrl:0
	v_fmac_f32_dpp v87, v231, v191 row_shl:8 row_mask:0xf bank_mask:0xf bound_ctrl:0
	ds_read_b128 v[184:187], v9 offset:4736
	ds_read_b128 v[188:191], v9 offset:4992
	s_waitcnt lgkmcnt(2)
	v_mov_b32_e32 v228, v112
	v_mov_b32_e32 v229, v113
	v_mov_b32_e32 v230, v114
	v_mov_b32_e32 v231, v115
	v_fmac_f32_dpp v112, v112, v192 row_shl:8 row_mask:0xf bank_mask:0xf bound_ctrl:0
	v_fmac_f32_dpp v113, v113, v193 row_shl:8 row_mask:0xf bank_mask:0xf bound_ctrl:0
	v_fmac_f32_dpp v114, v114, v194 row_shl:8 row_mask:0xf bank_mask:0xf bound_ctrl:0
	v_fmac_f32_dpp v115, v115, v195 row_shl:8 row_mask:0xf bank_mask:0xf bound_ctrl:0
	v_fmac_f32_dpp v112, v116, -v224 row_shl:8 row_mask:0xf bank_mask:0xf bound_ctrl:0
	v_fmac_f32_dpp v113, v117, -v225 row_shl:8 row_mask:0xf bank_mask:0xf bound_ctrl:0
	v_fmac_f32_dpp v114, v118, -v226 row_shl:8 row_mask:0xf bank_mask:0xf bound_ctrl:0
	v_fmac_f32_dpp v115, v119, -v227 row_shl:8 row_mask:0xf bank_mask:0xf bound_ctrl:0
	v_fmac_f32_dpp v116, v116, v192 row_shl:8 row_mask:0xf bank_mask:0xf bound_ctrl:0
	v_fmac_f32_dpp v117, v117, v193 row_shl:8 row_mask:0xf bank_mask:0xf bound_ctrl:0
	v_fmac_f32_dpp v118, v118, v194 row_shl:8 row_mask:0xf bank_mask:0xf bound_ctrl:0
	v_fmac_f32_dpp v119, v119, v195 row_shl:8 row_mask:0xf bank_mask:0xf bound_ctrl:0
	v_fmac_f32_dpp v116, v228, v224 row_shl:8 row_mask:0xf bank_mask:0xf bound_ctrl:0
	v_fmac_f32_dpp v117, v229, v225 row_shl:8 row_mask:0xf bank_mask:0xf bound_ctrl:0
	v_fmac_f32_dpp v118, v230, v226 row_shl:8 row_mask:0xf bank_mask:0xf bound_ctrl:0
	v_fmac_f32_dpp v119, v231, v227 row_shl:8 row_mask:0xf bank_mask:0xf bound_ctrl:0
	ds_read_b128 v[192:195], v9 offset:4800
	ds_read_b128 v[224:227], v9 offset:5056
	s_waitcnt lgkmcnt(2)
	v_mov_b32_e32 v228, v120
	v_mov_b32_e32 v229, v121
	v_mov_b32_e32 v230, v122
	v_mov_b32_e32 v231, v123
	v_fmac_f32_dpp v120, v120, v184 row_shl:8 row_mask:0xf bank_mask:0xf bound_ctrl:0
	v_fmac_f32_dpp v121, v121, v185 row_shl:8 row_mask:0xf bank_mask:0xf bound_ctrl:0
	v_fmac_f32_dpp v122, v122, v186 row_shl:8 row_mask:0xf bank_mask:0xf bound_ctrl:0
	v_fmac_f32_dpp v123, v123, v187 row_shl:8 row_mask:0xf bank_mask:0xf bound_ctrl:0
	v_fmac_f32_dpp v120, v124, -v188 row_shl:8 row_mask:0xf bank_mask:0xf bound_ctrl:0
	v_fmac_f32_dpp v121, v125, -v189 row_shl:8 row_mask:0xf bank_mask:0xf bound_ctrl:0
	v_fmac_f32_dpp v122, v126, -v190 row_shl:8 row_mask:0xf bank_mask:0xf bound_ctrl:0
	v_fmac_f32_dpp v123, v127, -v191 row_shl:8 row_mask:0xf bank_mask:0xf bound_ctrl:0
	v_fmac_f32_dpp v124, v124, v184 row_shl:8 row_mask:0xf bank_mask:0xf bound_ctrl:0
	v_fmac_f32_dpp v125, v125, v185 row_shl:8 row_mask:0xf bank_mask:0xf bound_ctrl:0
	v_fmac_f32_dpp v126, v126, v186 row_shl:8 row_mask:0xf bank_mask:0xf bound_ctrl:0
	v_fmac_f32_dpp v127, v127, v187 row_shl:8 row_mask:0xf bank_mask:0xf bound_ctrl:0
	v_fmac_f32_dpp v124, v228, v188 row_shl:8 row_mask:0xf bank_mask:0xf bound_ctrl:0
	v_fmac_f32_dpp v125, v229, v189 row_shl:8 row_mask:0xf bank_mask:0xf bound_ctrl:0
	v_fmac_f32_dpp v126, v230, v190 row_shl:8 row_mask:0xf bank_mask:0xf bound_ctrl:0
	v_fmac_f32_dpp v127, v231, v191 row_shl:8 row_mask:0xf bank_mask:0xf bound_ctrl:0
	s_waitcnt lgkmcnt(0)
	v_mov_b32_e32 v228, v128
	v_mov_b32_e32 v229, v129
	v_mov_b32_e32 v230, v130
	v_mov_b32_e32 v231, v131
	v_fmac_f32_dpp v128, v128, v192 row_shl:8 row_mask:0xf bank_mask:0xf bound_ctrl:0
	v_fmac_f32_dpp v129, v129, v193 row_shl:8 row_mask:0xf bank_mask:0xf bound_ctrl:0
	v_fmac_f32_dpp v130, v130, v194 row_shl:8 row_mask:0xf bank_mask:0xf bound_ctrl:0
	v_fmac_f32_dpp v131, v131, v195 row_shl:8 row_mask:0xf bank_mask:0xf bound_ctrl:0
	v_fmac_f32_dpp v128, v140, -v224 row_shl:8 row_mask:0xf bank_mask:0xf bound_ctrl:0
	v_fmac_f32_dpp v129, v141, -v225 row_shl:8 row_mask:0xf bank_mask:0xf bound_ctrl:0
	v_fmac_f32_dpp v130, v142, -v226 row_shl:8 row_mask:0xf bank_mask:0xf bound_ctrl:0
	v_fmac_f32_dpp v131, v143, -v227 row_shl:8 row_mask:0xf bank_mask:0xf bound_ctrl:0
	v_fmac_f32_dpp v140, v140, v192 row_shl:8 row_mask:0xf bank_mask:0xf bound_ctrl:0
	v_fmac_f32_dpp v141, v141, v193 row_shl:8 row_mask:0xf bank_mask:0xf bound_ctrl:0
	v_fmac_f32_dpp v142, v142, v194 row_shl:8 row_mask:0xf bank_mask:0xf bound_ctrl:0
	v_fmac_f32_dpp v143, v143, v195 row_shl:8 row_mask:0xf bank_mask:0xf bound_ctrl:0
	v_fmac_f32_dpp v140, v228, v224 row_shl:8 row_mask:0xf bank_mask:0xf bound_ctrl:0
	v_fmac_f32_dpp v141, v229, v225 row_shl:8 row_mask:0xf bank_mask:0xf bound_ctrl:0
	v_fmac_f32_dpp v142, v230, v226 row_shl:8 row_mask:0xf bank_mask:0xf bound_ctrl:0
	v_fmac_f32_dpp v143, v231, v227 row_shl:8 row_mask:0xf bank_mask:0xf bound_ctrl:0
	s_lshl_b32 s56, s0, 5
	s_add_i32 s55, s6, 0
	s_lshl_b32 s55, s55, 1
	s_add_i32 s56, s56, s55
	s_add_i32 s56, s56, 1
	s_lshl_b32 s56, s56, 9
	s_add_u32 s48, s94, 0x12dd6000
	s_addc_u32 s49, s95, 0
	s_add_u32 s48, s48, s56
	s_addc_u32 s49, s49, 0
	s_nop 1
	s_mov_b64 exec, s[52:53]
	global_store_dword v10, v80, s[48:49] offset:0
	global_store_dword v10, v84, s[48:49] offset:4
	global_store_dword v10, v81, s[48:49] offset:8
	global_store_dword v10, v85, s[48:49] offset:12
	global_store_dword v10, v82, s[48:49] offset:16
	global_store_dword v10, v86, s[48:49] offset:20
	global_store_dword v10, v83, s[48:49] offset:24
	global_store_dword v10, v87, s[48:49] offset:28
	global_store_dword v10, v112, s[48:49] offset:128
	global_store_dword v10, v116, s[48:49] offset:132
	global_store_dword v10, v113, s[48:49] offset:136
	global_store_dword v10, v117, s[48:49] offset:140
	global_store_dword v10, v114, s[48:49] offset:144
	global_store_dword v10, v118, s[48:49] offset:148
	global_store_dword v10, v115, s[48:49] offset:152
	global_store_dword v10, v119, s[48:49] offset:156
	global_store_dword v10, v120, s[48:49] offset:256
	global_store_dword v10, v124, s[48:49] offset:260
	global_store_dword v10, v121, s[48:49] offset:264
	global_store_dword v10, v125, s[48:49] offset:268
	global_store_dword v10, v122, s[48:49] offset:272
	global_store_dword v10, v126, s[48:49] offset:276
	global_store_dword v10, v123, s[48:49] offset:280
	global_store_dword v10, v127, s[48:49] offset:284
	global_store_dword v10, v128, s[48:49] offset:384
	global_store_dword v10, v140, s[48:49] offset:388
	global_store_dword v10, v129, s[48:49] offset:392
	global_store_dword v10, v141, s[48:49] offset:396
	global_store_dword v10, v130, s[48:49] offset:400
	global_store_dword v10, v142, s[48:49] offset:404
	global_store_dword v10, v131, s[48:49] offset:408
	global_store_dword v10, v143, s[48:49] offset:412
	s_mov_b64 exec, -1
	s_waitcnt vmcnt(32)
	v_mfma_f32_16x16x4_f32 v[80:83], v12, v240, 0
	v_mfma_f32_16x16x4_f32 v[84:87], v13, v240, 0
	v_mfma_f32_16x16x4_f32 v[144:147], v12, v244, 0
	v_mfma_f32_16x16x4_f32 v[148:151], v13, v244, 0
	v_mfma_f32_16x16x4_f32 v[112:115], v20, v240, 0
	v_mfma_f32_16x16x4_f32 v[116:119], v21, v240, 0
	v_mfma_f32_16x16x4_f32 v[152:155], v20, v244, 0
	v_mfma_f32_16x16x4_f32 v[156:159], v21, v244, 0
	v_mfma_f32_16x16x4_f32 v[120:123], v28, v240, 0
	v_mfma_f32_16x16x4_f32 v[124:127], v29, v240, 0
	v_mfma_f32_16x16x4_f32 v[168:171], v28, v244, 0
	v_mfma_f32_16x16x4_f32 v[172:175], v29, v244, 0
	v_mfma_f32_16x16x4_f32 v[128:131], v36, v240, 0
	v_mfma_f32_16x16x4_f32 v[140:143], v37, v240, 0
	v_mfma_f32_16x16x4_f32 v[176:179], v36, v244, 0
	v_mfma_f32_16x16x4_f32 v[180:183], v37, v244, 0
	v_mfma_f32_16x16x4_f32 v[80:83], v14, v241, v[80:83]
	v_mfma_f32_16x16x4_f32 v[84:87], v15, v241, v[84:87]
	v_mfma_f32_16x16x4_f32 v[144:147], v14, v245, v[144:147]
	v_mfma_f32_16x16x4_f32 v[148:151], v15, v245, v[148:151]
	v_mfma_f32_16x16x4_f32 v[112:115], v22, v241, v[112:115]
	v_mfma_f32_16x16x4_f32 v[116:119], v23, v241, v[116:119]
	v_mfma_f32_16x16x4_f32 v[152:155], v22, v245, v[152:155]
	v_mfma_f32_16x16x4_f32 v[156:159], v23, v245, v[156:159]
	v_mfma_f32_16x16x4_f32 v[120:123], v30, v241, v[120:123]
	v_mfma_f32_16x16x4_f32 v[124:127], v31, v241, v[124:127]
	v_mfma_f32_16x16x4_f32 v[168:171], v30, v245, v[168:171]
	v_mfma_f32_16x16x4_f32 v[172:175], v31, v245, v[172:175]
	v_mfma_f32_16x16x4_f32 v[128:131], v38, v241, v[128:131]
	v_mfma_f32_16x16x4_f32 v[140:143], v39, v241, v[140:143]
	v_mfma_f32_16x16x4_f32 v[176:179], v38, v245, v[176:179]
	v_mfma_f32_16x16x4_f32 v[180:183], v39, v245, v[180:183]
	v_mfma_f32_16x16x4_f32 v[80:83], v16, v242, v[80:83]
	v_mfma_f32_16x16x4_f32 v[84:87], v17, v242, v[84:87]
	v_mfma_f32_16x16x4_f32 v[144:147], v16, v246, v[144:147]
	v_mfma_f32_16x16x4_f32 v[148:151], v17, v246, v[148:151]
	v_mfma_f32_16x16x4_f32 v[112:115], v24, v242, v[112:115]
	v_mfma_f32_16x16x4_f32 v[116:119], v25, v242, v[116:119]
	v_mfma_f32_16x16x4_f32 v[152:155], v24, v246, v[152:155]
	v_mfma_f32_16x16x4_f32 v[156:159], v25, v246, v[156:159]
	v_mfma_f32_16x16x4_f32 v[120:123], v32, v242, v[120:123]
	v_mfma_f32_16x16x4_f32 v[124:127], v33, v242, v[124:127]
	v_mfma_f32_16x16x4_f32 v[168:171], v32, v246, v[168:171]
	v_mfma_f32_16x16x4_f32 v[172:175], v33, v246, v[172:175]
	v_mfma_f32_16x16x4_f32 v[128:131], v40, v242, v[128:131]
	v_mfma_f32_16x16x4_f32 v[140:143], v41, v242, v[140:143]
	v_mfma_f32_16x16x4_f32 v[176:179], v40, v246, v[176:179]
	v_mfma_f32_16x16x4_f32 v[180:183], v41, v246, v[180:183]
	v_mfma_f32_16x16x4_f32 v[80:83], v18, v243, v[80:83]
	v_mfma_f32_16x16x4_f32 v[84:87], v19, v243, v[84:87]
	v_mfma_f32_16x16x4_f32 v[144:147], v18, v247, v[144:147]
	v_mfma_f32_16x16x4_f32 v[148:151], v19, v247, v[148:151]
	v_mfma_f32_16x16x4_f32 v[112:115], v26, v243, v[112:115]
	v_mfma_f32_16x16x4_f32 v[116:119], v27, v243, v[116:119]
	v_mfma_f32_16x16x4_f32 v[152:155], v26, v247, v[152:155]
	v_mfma_f32_16x16x4_f32 v[156:159], v27, v247, v[156:159]
	v_mfma_f32_16x16x4_f32 v[120:123], v34, v243, v[120:123]
	v_mfma_f32_16x16x4_f32 v[124:127], v35, v243, v[124:127]
	v_mfma_f32_16x16x4_f32 v[168:171], v34, v247, v[168:171]
	v_mfma_f32_16x16x4_f32 v[172:175], v35, v247, v[172:175]
	v_mfma_f32_16x16x4_f32 v[128:131], v42, v243, v[128:131]
	v_mfma_f32_16x16x4_f32 v[140:143], v43, v243, v[140:143]
	v_mfma_f32_16x16x4_f32 v[176:179], v42, v247, v[176:179]
	v_mfma_f32_16x16x4_f32 v[180:183], v43, v247, v[180:183]
	s_nop 9
	ds_read_b128 v[184:187], v9 offset:5120
	ds_read_b128 v[188:191], v9 offset:5376
	ds_read_b128 v[192:195], v9 offset:5184
	ds_read_b128 v[224:227], v9 offset:5440
	s_waitcnt lgkmcnt(2)
	v_fmac_f32_e32 v144, v184, v80
	v_fmac_f32_e32 v145, v185, v81
	v_fmac_f32_e32 v146, v186, v82
	v_fmac_f32_e32 v147, v187, v83
	v_fma_f32 v144, -v188, v84, v144
	v_fma_f32 v145, -v189, v85, v145
	v_fma_f32 v146, -v190, v86, v146
	v_fma_f32 v147, -v191, v87, v147
	v_fmac_f32_e32 v148, v184, v84
	v_fmac_f32_e32 v149, v185, v85
	v_fmac_f32_e32 v150, v186, v86
	v_fmac_f32_e32 v151, v187, v87
	v_fmac_f32_e32 v148, v188, v80
	v_fmac_f32_e32 v149, v189, v81
	v_fmac_f32_e32 v150, v190, v82
	v_fmac_f32_e32 v151, v191, v83
	ds_read_b128 v[184:187], v9 offset:5248
	ds_read_b128 v[188:191], v9 offset:5504
	s_waitcnt lgkmcnt(2)
	v_fmac_f32_e32 v152, v192, v112
	v_fmac_f32_e32 v153, v193, v113
	v_fmac_f32_e32 v154, v194, v114
	v_fmac_f32_e32 v155, v195, v115
	v_fma_f32 v152, -v224, v116, v152
	v_fma_f32 v153, -v225, v117, v153
	v_fma_f32 v154, -v226, v118, v154
	v_fma_f32 v155, -v227, v119, v155
	v_fmac_f32_e32 v156, v192, v116
	v_fmac_f32_e32 v157, v193, v117
	v_fmac_f32_e32 v158, v194, v118
	v_fmac_f32_e32 v159, v195, v119
	v_fmac_f32_e32 v156, v224, v112
	v_fmac_f32_e32 v157, v225, v113
	v_fmac_f32_e32 v158, v226, v114
	v_fmac_f32_e32 v159, v227, v115
	ds_read_b128 v[192:195], v9 offset:5312
	ds_read_b128 v[224:227], v9 offset:5568
	s_waitcnt lgkmcnt(2)
	v_fmac_f32_e32 v168, v184, v120
	v_fmac_f32_e32 v169, v185, v121
	v_fmac_f32_e32 v170, v186, v122
	v_fmac_f32_e32 v171, v187, v123
	v_fma_f32 v168, -v188, v124, v168
	v_fma_f32 v169, -v189, v125, v169
	v_fma_f32 v170, -v190, v126, v170
	v_fma_f32 v171, -v191, v127, v171
	v_fmac_f32_e32 v172, v184, v124
	v_fmac_f32_e32 v173, v185, v125
	v_fmac_f32_e32 v174, v186, v126
	v_fmac_f32_e32 v175, v187, v127
	v_fmac_f32_e32 v172, v188, v120
	v_fmac_f32_e32 v173, v189, v121
	v_fmac_f32_e32 v174, v190, v122
	v_fmac_f32_e32 v175, v191, v123
	s_waitcnt lgkmcnt(0)
	v_fmac_f32_e32 v176, v192, v128
	v_fmac_f32_e32 v177, v193, v129
	v_fmac_f32_e32 v178, v194, v130
	v_fmac_f32_e32 v179, v195, v131
	v_fma_f32 v176, -v224, v140, v176
	v_fma_f32 v177, -v225, v141, v177
	v_fma_f32 v178, -v226, v142, v178
	v_fma_f32 v179, -v227, v143, v179
	v_fmac_f32_e32 v180, v192, v140
	v_fmac_f32_e32 v181, v193, v141
	v_fmac_f32_e32 v182, v194, v142
	v_fmac_f32_e32 v183, v195, v143
	v_fmac_f32_e32 v180, v224, v128
	v_fmac_f32_e32 v181, v225, v129
	v_fmac_f32_e32 v182, v226, v130
	v_fmac_f32_e32 v183, v227, v131
	global_load_dwordx4 v[44:47], v6, s[38:39] offset:0
	global_load_dwordx4 v[52:55], v6, s[38:39] offset:1024
	global_load_dwordx4 v[56:59], v6, s[38:39] offset:256
	global_load_dwordx4 v[60:63], v6, s[38:39] offset:1280
	global_load_dwordx4 v[64:67], v6, s[38:39] offset:512
	global_load_dwordx4 v[68:71], v6, s[38:39] offset:1536
	global_load_dwordx4 v[72:75], v6, s[38:39] offset:768
	global_load_dwordx4 v[76:79], v6, s[38:39] offset:1792
	ds_read_b128 v[184:187], v9 offset:5632
	ds_read_b128 v[188:191], v9 offset:5888
	ds_read_b128 v[192:195], v9 offset:5696
	ds_read_b128 v[224:227], v9 offset:5952
	s_waitcnt lgkmcnt(2)
	v_mov_b32_e32 v228, v144
	v_mov_b32_e32 v229, v145
	v_mov_b32_e32 v230, v146
	v_mov_b32_e32 v231, v147
	s_nop 1
	v_fmac_f32_dpp v144, v144, v184 row_shr:1 row_mask:0xf bank_mask:0xf bound_ctrl:0
	v_fmac_f32_dpp v145, v145, v185 row_shr:1 row_mask:0xf bank_mask:0xf bound_ctrl:0
	v_fmac_f32_dpp v146, v146, v186 row_shr:1 row_mask:0xf bank_mask:0xf bound_ctrl:0
	v_fmac_f32_dpp v147, v147, v187 row_shr:1 row_mask:0xf bank_mask:0xf bound_ctrl:0
	v_fmac_f32_dpp v144, v148, -v188 row_shr:1 row_mask:0xf bank_mask:0xf bound_ctrl:0
	v_fmac_f32_dpp v145, v149, -v189 row_shr:1 row_mask:0xf bank_mask:0xf bound_ctrl:0
	v_fmac_f32_dpp v146, v150, -v190 row_shr:1 row_mask:0xf bank_mask:0xf bound_ctrl:0
	v_fmac_f32_dpp v147, v151, -v191 row_shr:1 row_mask:0xf bank_mask:0xf bound_ctrl:0
	v_fmac_f32_dpp v148, v148, v184 row_shr:1 row_mask:0xf bank_mask:0xf bound_ctrl:0
	v_fmac_f32_dpp v149, v149, v185 row_shr:1 row_mask:0xf bank_mask:0xf bound_ctrl:0
	v_fmac_f32_dpp v150, v150, v186 row_shr:1 row_mask:0xf bank_mask:0xf bound_ctrl:0
	v_fmac_f32_dpp v151, v151, v187 row_shr:1 row_mask:0xf bank_mask:0xf bound_ctrl:0
	v_fmac_f32_dpp v148, v228, v188 row_shr:1 row_mask:0xf bank_mask:0xf bound_ctrl:0
	v_fmac_f32_dpp v149, v229, v189 row_shr:1 row_mask:0xf bank_mask:0xf bound_ctrl:0
	v_fmac_f32_dpp v150, v230, v190 row_shr:1 row_mask:0xf bank_mask:0xf bound_ctrl:0
	v_fmac_f32_dpp v151, v231, v191 row_shr:1 row_mask:0xf bank_mask:0xf bound_ctrl:0
	ds_read_b128 v[184:187], v9 offset:5760
	ds_read_b128 v[188:191], v9 offset:6016
	s_waitcnt lgkmcnt(2)
	v_mov_b32_e32 v228, v152
	v_mov_b32_e32 v229, v153
	v_mov_b32_e32 v230, v154
	v_mov_b32_e32 v231, v155
	v_fmac_f32_dpp v152, v152, v192 row_shr:1 row_mask:0xf bank_mask:0xf bound_ctrl:0
	v_fmac_f32_dpp v153, v153, v193 row_shr:1 row_mask:0xf bank_mask:0xf bound_ctrl:0
	v_fmac_f32_dpp v154, v154, v194 row_shr:1 row_mask:0xf bank_mask:0xf bound_ctrl:0
	v_fmac_f32_dpp v155, v155, v195 row_shr:1 row_mask:0xf bank_mask:0xf bound_ctrl:0
	v_fmac_f32_dpp v152, v156, -v224 row_shr:1 row_mask:0xf bank_mask:0xf bound_ctrl:0
	v_fmac_f32_dpp v153, v157, -v225 row_shr:1 row_mask:0xf bank_mask:0xf bound_ctrl:0
	v_fmac_f32_dpp v154, v158, -v226 row_shr:1 row_mask:0xf bank_mask:0xf bound_ctrl:0
	v_fmac_f32_dpp v155, v159, -v227 row_shr:1 row_mask:0xf bank_mask:0xf bound_ctrl:0
	v_fmac_f32_dpp v156, v156, v192 row_shr:1 row_mask:0xf bank_mask:0xf bound_ctrl:0
	v_fmac_f32_dpp v157, v157, v193 row_shr:1 row_mask:0xf bank_mask:0xf bound_ctrl:0
	v_fmac_f32_dpp v158, v158, v194 row_shr:1 row_mask:0xf bank_mask:0xf bound_ctrl:0
	v_fmac_f32_dpp v159, v159, v195 row_shr:1 row_mask:0xf bank_mask:0xf bound_ctrl:0
	v_fmac_f32_dpp v156, v228, v224 row_shr:1 row_mask:0xf bank_mask:0xf bound_ctrl:0
	v_fmac_f32_dpp v157, v229, v225 row_shr:1 row_mask:0xf bank_mask:0xf bound_ctrl:0
	v_fmac_f32_dpp v158, v230, v226 row_shr:1 row_mask:0xf bank_mask:0xf bound_ctrl:0
	v_fmac_f32_dpp v159, v231, v227 row_shr:1 row_mask:0xf bank_mask:0xf bound_ctrl:0
	ds_read_b128 v[192:195], v9 offset:5824
	ds_read_b128 v[224:227], v9 offset:6080
	s_waitcnt lgkmcnt(2)
	v_mov_b32_e32 v228, v168
	v_mov_b32_e32 v229, v169
	v_mov_b32_e32 v230, v170
	v_mov_b32_e32 v231, v171
	v_fmac_f32_dpp v168, v168, v184 row_shr:1 row_mask:0xf bank_mask:0xf bound_ctrl:0
	v_fmac_f32_dpp v169, v169, v185 row_shr:1 row_mask:0xf bank_mask:0xf bound_ctrl:0
	v_fmac_f32_dpp v170, v170, v186 row_shr:1 row_mask:0xf bank_mask:0xf bound_ctrl:0
	v_fmac_f32_dpp v171, v171, v187 row_shr:1 row_mask:0xf bank_mask:0xf bound_ctrl:0
	v_fmac_f32_dpp v168, v172, -v188 row_shr:1 row_mask:0xf bank_mask:0xf bound_ctrl:0
	v_fmac_f32_dpp v169, v173, -v189 row_shr:1 row_mask:0xf bank_mask:0xf bound_ctrl:0
	v_fmac_f32_dpp v170, v174, -v190 row_shr:1 row_mask:0xf bank_mask:0xf bound_ctrl:0
	v_fmac_f32_dpp v171, v175, -v191 row_shr:1 row_mask:0xf bank_mask:0xf bound_ctrl:0
	v_fmac_f32_dpp v172, v172, v184 row_shr:1 row_mask:0xf bank_mask:0xf bound_ctrl:0
	v_fmac_f32_dpp v173, v173, v185 row_shr:1 row_mask:0xf bank_mask:0xf bound_ctrl:0
	v_fmac_f32_dpp v174, v174, v186 row_shr:1 row_mask:0xf bank_mask:0xf bound_ctrl:0
	v_fmac_f32_dpp v175, v175, v187 row_shr:1 row_mask:0xf bank_mask:0xf bound_ctrl:0
	v_fmac_f32_dpp v172, v228, v188 row_shr:1 row_mask:0xf bank_mask:0xf bound_ctrl:0
	v_fmac_f32_dpp v173, v229, v189 row_shr:1 row_mask:0xf bank_mask:0xf bound_ctrl:0
	v_fmac_f32_dpp v174, v230, v190 row_shr:1 row_mask:0xf bank_mask:0xf bound_ctrl:0
	v_fmac_f32_dpp v175, v231, v191 row_shr:1 row_mask:0xf bank_mask:0xf bound_ctrl:0
	ds_read_b128 v[184:187], v9 offset:6144
	ds_read_b128 v[188:191], v9 offset:6400
	s_waitcnt lgkmcnt(2)
	v_mov_b32_e32 v228, v176
	v_mov_b32_e32 v229, v177
	v_mov_b32_e32 v230, v178
	v_mov_b32_e32 v231, v179
	v_fmac_f32_dpp v176, v176, v192 row_shr:1 row_mask:0xf bank_mask:0xf bound_ctrl:0
	v_fmac_f32_dpp v177, v177, v193 row_shr:1 row_mask:0xf bank_mask:0xf bound_ctrl:0
	v_fmac_f32_dpp v178, v178, v194 row_shr:1 row_mask:0xf bank_mask:0xf bound_ctrl:0
	v_fmac_f32_dpp v179, v179, v195 row_shr:1 row_mask:0xf bank_mask:0xf bound_ctrl:0
	v_fmac_f32_dpp v176, v180, -v224 row_shr:1 row_mask:0xf bank_mask:0xf bound_ctrl:0
	v_fmac_f32_dpp v177, v181, -v225 row_shr:1 row_mask:0xf bank_mask:0xf bound_ctrl:0
	v_fmac_f32_dpp v178, v182, -v226 row_shr:1 row_mask:0xf bank_mask:0xf bound_ctrl:0
	v_fmac_f32_dpp v179, v183, -v227 row_shr:1 row_mask:0xf bank_mask:0xf bound_ctrl:0
	v_fmac_f32_dpp v180, v180, v192 row_shr:1 row_mask:0xf bank_mask:0xf bound_ctrl:0
	v_fmac_f32_dpp v181, v181, v193 row_shr:1 row_mask:0xf bank_mask:0xf bound_ctrl:0
	v_fmac_f32_dpp v182, v182, v194 row_shr:1 row_mask:0xf bank_mask:0xf bound_ctrl:0
	v_fmac_f32_dpp v183, v183, v195 row_shr:1 row_mask:0xf bank_mask:0xf bound_ctrl:0
	v_fmac_f32_dpp v180, v228, v224 row_shr:1 row_mask:0xf bank_mask:0xf bound_ctrl:0
	v_fmac_f32_dpp v181, v229, v225 row_shr:1 row_mask:0xf bank_mask:0xf bound_ctrl:0
	v_fmac_f32_dpp v182, v230, v226 row_shr:1 row_mask:0xf bank_mask:0xf bound_ctrl:0
	v_fmac_f32_dpp v183, v231, v227 row_shr:1 row_mask:0xf bank_mask:0xf bound_ctrl:0
	ds_read_b128 v[192:195], v9 offset:6208
	ds_read_b128 v[224:227], v9 offset:6464
	s_waitcnt lgkmcnt(2)
	v_mov_b32_e32 v228, v144
	v_mov_b32_e32 v229, v145
	v_mov_b32_e32 v230, v146
	v_mov_b32_e32 v231, v147
	v_fmac_f32_dpp v144, v144, v184 row_shr:2 row_mask:0xf bank_mask:0xf bound_ctrl:0
	v_fmac_f32_dpp v145, v145, v185 row_shr:2 row_mask:0xf bank_mask:0xf bound_ctrl:0
	v_fmac_f32_dpp v146, v146, v186 row_shr:2 row_mask:0xf bank_mask:0xf bound_ctrl:0
	v_fmac_f32_dpp v147, v147, v187 row_shr:2 row_mask:0xf bank_mask:0xf bound_ctrl:0
	v_fmac_f32_dpp v144, v148, -v188 row_shr:2 row_mask:0xf bank_mask:0xf bound_ctrl:0
	v_fmac_f32_dpp v145, v149, -v189 row_shr:2 row_mask:0xf bank_mask:0xf bound_ctrl:0
	v_fmac_f32_dpp v146, v150, -v190 row_shr:2 row_mask:0xf bank_mask:0xf bound_ctrl:0
	v_fmac_f32_dpp v147, v151, -v191 row_shr:2 row_mask:0xf bank_mask:0xf bound_ctrl:0
	v_fmac_f32_dpp v148, v148, v184 row_shr:2 row_mask:0xf bank_mask:0xf bound_ctrl:0
	v_fmac_f32_dpp v149, v149, v185 row_shr:2 row_mask:0xf bank_mask:0xf bound_ctrl:0
	v_fmac_f32_dpp v150, v150, v186 row_shr:2 row_mask:0xf bank_mask:0xf bound_ctrl:0
	v_fmac_f32_dpp v151, v151, v187 row_shr:2 row_mask:0xf bank_mask:0xf bound_ctrl:0
	v_fmac_f32_dpp v148, v228, v188 row_shr:2 row_mask:0xf bank_mask:0xf bound_ctrl:0
	v_fmac_f32_dpp v149, v229, v189 row_shr:2 row_mask:0xf bank_mask:0xf bound_ctrl:0
	v_fmac_f32_dpp v150, v230, v190 row_shr:2 row_mask:0xf bank_mask:0xf bound_ctrl:0
	v_fmac_f32_dpp v151, v231, v191 row_shr:2 row_mask:0xf bank_mask:0xf bound_ctrl:0
	ds_read_b128 v[184:187], v9 offset:6272
	ds_read_b128 v[188:191], v9 offset:6528
	s_waitcnt lgkmcnt(2)
	v_mov_b32_e32 v228, v152
	v_mov_b32_e32 v229, v153
	v_mov_b32_e32 v230, v154
	v_mov_b32_e32 v231, v155
	v_fmac_f32_dpp v152, v152, v192 row_shr:2 row_mask:0xf bank_mask:0xf bound_ctrl:0
	v_fmac_f32_dpp v153, v153, v193 row_shr:2 row_mask:0xf bank_mask:0xf bound_ctrl:0
	v_fmac_f32_dpp v154, v154, v194 row_shr:2 row_mask:0xf bank_mask:0xf bound_ctrl:0
	v_fmac_f32_dpp v155, v155, v195 row_shr:2 row_mask:0xf bank_mask:0xf bound_ctrl:0
	v_fmac_f32_dpp v152, v156, -v224 row_shr:2 row_mask:0xf bank_mask:0xf bound_ctrl:0
	v_fmac_f32_dpp v153, v157, -v225 row_shr:2 row_mask:0xf bank_mask:0xf bound_ctrl:0
	v_fmac_f32_dpp v154, v158, -v226 row_shr:2 row_mask:0xf bank_mask:0xf bound_ctrl:0
	v_fmac_f32_dpp v155, v159, -v227 row_shr:2 row_mask:0xf bank_mask:0xf bound_ctrl:0
	v_fmac_f32_dpp v156, v156, v192 row_shr:2 row_mask:0xf bank_mask:0xf bound_ctrl:0
	v_fmac_f32_dpp v157, v157, v193 row_shr:2 row_mask:0xf bank_mask:0xf bound_ctrl:0
	v_fmac_f32_dpp v158, v158, v194 row_shr:2 row_mask:0xf bank_mask:0xf bound_ctrl:0
	v_fmac_f32_dpp v159, v159, v195 row_shr:2 row_mask:0xf bank_mask:0xf bound_ctrl:0
	v_fmac_f32_dpp v156, v228, v224 row_shr:2 row_mask:0xf bank_mask:0xf bound_ctrl:0
	v_fmac_f32_dpp v157, v229, v225 row_shr:2 row_mask:0xf bank_mask:0xf bound_ctrl:0
	v_fmac_f32_dpp v158, v230, v226 row_shr:2 row_mask:0xf bank_mask:0xf bound_ctrl:0
	v_fmac_f32_dpp v159, v231, v227 row_shr:2 row_mask:0xf bank_mask:0xf bound_ctrl:0
	ds_read_b128 v[192:195], v9 offset:6336
	ds_read_b128 v[224:227], v9 offset:6592
	s_waitcnt lgkmcnt(2)
	v_mov_b32_e32 v228, v168
	v_mov_b32_e32 v229, v169
	v_mov_b32_e32 v230, v170
	v_mov_b32_e32 v231, v171
	v_fmac_f32_dpp v168, v168, v184 row_shr:2 row_mask:0xf bank_mask:0xf bound_ctrl:0
	v_fmac_f32_dpp v169, v169, v185 row_shr:2 row_mask:0xf bank_mask:0xf bound_ctrl:0
	v_fmac_f32_dpp v170, v170, v186 row_shr:2 row_mask:0xf bank_mask:0xf bound_ctrl:0
	v_fmac_f32_dpp v171, v171, v187 row_shr:2 row_mask:0xf bank_mask:0xf bound_ctrl:0
	v_fmac_f32_dpp v168, v172, -v188 row_shr:2 row_mask:0xf bank_mask:0xf bound_ctrl:0
	v_fmac_f32_dpp v169, v173, -v189 row_shr:2 row_mask:0xf bank_mask:0xf bound_ctrl:0
	v_fmac_f32_dpp v170, v174, -v190 row_shr:2 row_mask:0xf bank_mask:0xf bound_ctrl:0
	v_fmac_f32_dpp v171, v175, -v191 row_shr:2 row_mask:0xf bank_mask:0xf bound_ctrl:0
	v_fmac_f32_dpp v172, v172, v184 row_shr:2 row_mask:0xf bank_mask:0xf bound_ctrl:0
	v_fmac_f32_dpp v173, v173, v185 row_shr:2 row_mask:0xf bank_mask:0xf bound_ctrl:0
	v_fmac_f32_dpp v174, v174, v186 row_shr:2 row_mask:0xf bank_mask:0xf bound_ctrl:0
	v_fmac_f32_dpp v175, v175, v187 row_shr:2 row_mask:0xf bank_mask:0xf bound_ctrl:0
	v_fmac_f32_dpp v172, v228, v188 row_shr:2 row_mask:0xf bank_mask:0xf bound_ctrl:0
	v_fmac_f32_dpp v173, v229, v189 row_shr:2 row_mask:0xf bank_mask:0xf bound_ctrl:0
	v_fmac_f32_dpp v174, v230, v190 row_shr:2 row_mask:0xf bank_mask:0xf bound_ctrl:0
	v_fmac_f32_dpp v175, v231, v191 row_shr:2 row_mask:0xf bank_mask:0xf bound_ctrl:0
	ds_read_b128 v[184:187], v9 offset:6656
	ds_read_b128 v[188:191], v9 offset:6912
	s_waitcnt lgkmcnt(2)
	v_mov_b32_e32 v228, v176
	v_mov_b32_e32 v229, v177
	v_mov_b32_e32 v230, v178
	v_mov_b32_e32 v231, v179
	v_fmac_f32_dpp v176, v176, v192 row_shr:2 row_mask:0xf bank_mask:0xf bound_ctrl:0
	v_fmac_f32_dpp v177, v177, v193 row_shr:2 row_mask:0xf bank_mask:0xf bound_ctrl:0
	v_fmac_f32_dpp v178, v178, v194 row_shr:2 row_mask:0xf bank_mask:0xf bound_ctrl:0
	v_fmac_f32_dpp v179, v179, v195 row_shr:2 row_mask:0xf bank_mask:0xf bound_ctrl:0
	v_fmac_f32_dpp v176, v180, -v224 row_shr:2 row_mask:0xf bank_mask:0xf bound_ctrl:0
	v_fmac_f32_dpp v177, v181, -v225 row_shr:2 row_mask:0xf bank_mask:0xf bound_ctrl:0
	v_fmac_f32_dpp v178, v182, -v226 row_shr:2 row_mask:0xf bank_mask:0xf bound_ctrl:0
	v_fmac_f32_dpp v179, v183, -v227 row_shr:2 row_mask:0xf bank_mask:0xf bound_ctrl:0
	v_fmac_f32_dpp v180, v180, v192 row_shr:2 row_mask:0xf bank_mask:0xf bound_ctrl:0
	v_fmac_f32_dpp v181, v181, v193 row_shr:2 row_mask:0xf bank_mask:0xf bound_ctrl:0
	v_fmac_f32_dpp v182, v182, v194 row_shr:2 row_mask:0xf bank_mask:0xf bound_ctrl:0
	v_fmac_f32_dpp v183, v183, v195 row_shr:2 row_mask:0xf bank_mask:0xf bound_ctrl:0
	v_fmac_f32_dpp v180, v228, v224 row_shr:2 row_mask:0xf bank_mask:0xf bound_ctrl:0
	v_fmac_f32_dpp v181, v229, v225 row_shr:2 row_mask:0xf bank_mask:0xf bound_ctrl:0
	v_fmac_f32_dpp v182, v230, v226 row_shr:2 row_mask:0xf bank_mask:0xf bound_ctrl:0
	v_fmac_f32_dpp v183, v231, v227 row_shr:2 row_mask:0xf bank_mask:0xf bound_ctrl:0
	ds_read_b128 v[192:195], v9 offset:6720
	ds_read_b128 v[224:227], v9 offset:6976
	s_waitcnt lgkmcnt(2)
	v_mov_b32_e32 v228, v144
	v_mov_b32_e32 v229, v145
	v_mov_b32_e32 v230, v146
	v_mov_b32_e32 v231, v147
	v_fmac_f32_dpp v144, v144, v184 row_shr:4 row_mask:0xf bank_mask:0xf bound_ctrl:0
	v_fmac_f32_dpp v145, v145, v185 row_shr:4 row_mask:0xf bank_mask:0xf bound_ctrl:0
	v_fmac_f32_dpp v146, v146, v186 row_shr:4 row_mask:0xf bank_mask:0xf bound_ctrl:0
	v_fmac_f32_dpp v147, v147, v187 row_shr:4 row_mask:0xf bank_mask:0xf bound_ctrl:0
	v_fmac_f32_dpp v144, v148, -v188 row_shr:4 row_mask:0xf bank_mask:0xf bound_ctrl:0
	v_fmac_f32_dpp v145, v149, -v189 row_shr:4 row_mask:0xf bank_mask:0xf bound_ctrl:0
	v_fmac_f32_dpp v146, v150, -v190 row_shr:4 row_mask:0xf bank_mask:0xf bound_ctrl:0
	v_fmac_f32_dpp v147, v151, -v191 row_shr:4 row_mask:0xf bank_mask:0xf bound_ctrl:0
	v_fmac_f32_dpp v148, v148, v184 row_shr:4 row_mask:0xf bank_mask:0xf bound_ctrl:0
	v_fmac_f32_dpp v149, v149, v185 row_shr:4 row_mask:0xf bank_mask:0xf bound_ctrl:0
	v_fmac_f32_dpp v150, v150, v186 row_shr:4 row_mask:0xf bank_mask:0xf bound_ctrl:0
	v_fmac_f32_dpp v151, v151, v187 row_shr:4 row_mask:0xf bank_mask:0xf bound_ctrl:0
	v_fmac_f32_dpp v148, v228, v188 row_shr:4 row_mask:0xf bank_mask:0xf bound_ctrl:0
	v_fmac_f32_dpp v149, v229, v189 row_shr:4 row_mask:0xf bank_mask:0xf bound_ctrl:0
	v_fmac_f32_dpp v150, v230, v190 row_shr:4 row_mask:0xf bank_mask:0xf bound_ctrl:0
	v_fmac_f32_dpp v151, v231, v191 row_shr:4 row_mask:0xf bank_mask:0xf bound_ctrl:0
	ds_read_b128 v[184:187], v9 offset:6784
	ds_read_b128 v[188:191], v9 offset:7040
	s_waitcnt lgkmcnt(2)
	v_mov_b32_e32 v228, v152
	v_mov_b32_e32 v229, v153
	v_mov_b32_e32 v230, v154
	v_mov_b32_e32 v231, v155
	v_fmac_f32_dpp v152, v152, v192 row_shr:4 row_mask:0xf bank_mask:0xf bound_ctrl:0
	v_fmac_f32_dpp v153, v153, v193 row_shr:4 row_mask:0xf bank_mask:0xf bound_ctrl:0
	v_fmac_f32_dpp v154, v154, v194 row_shr:4 row_mask:0xf bank_mask:0xf bound_ctrl:0
	v_fmac_f32_dpp v155, v155, v195 row_shr:4 row_mask:0xf bank_mask:0xf bound_ctrl:0
	v_fmac_f32_dpp v152, v156, -v224 row_shr:4 row_mask:0xf bank_mask:0xf bound_ctrl:0
	v_fmac_f32_dpp v153, v157, -v225 row_shr:4 row_mask:0xf bank_mask:0xf bound_ctrl:0
	v_fmac_f32_dpp v154, v158, -v226 row_shr:4 row_mask:0xf bank_mask:0xf bound_ctrl:0
	v_fmac_f32_dpp v155, v159, -v227 row_shr:4 row_mask:0xf bank_mask:0xf bound_ctrl:0
	v_fmac_f32_dpp v156, v156, v192 row_shr:4 row_mask:0xf bank_mask:0xf bound_ctrl:0
	v_fmac_f32_dpp v157, v157, v193 row_shr:4 row_mask:0xf bank_mask:0xf bound_ctrl:0
	v_fmac_f32_dpp v158, v158, v194 row_shr:4 row_mask:0xf bank_mask:0xf bound_ctrl:0
	v_fmac_f32_dpp v159, v159, v195 row_shr:4 row_mask:0xf bank_mask:0xf bound_ctrl:0
	v_fmac_f32_dpp v156, v228, v224 row_shr:4 row_mask:0xf bank_mask:0xf bound_ctrl:0
	v_fmac_f32_dpp v157, v229, v225 row_shr:4 row_mask:0xf bank_mask:0xf bound_ctrl:0
	v_fmac_f32_dpp v158, v230, v226 row_shr:4 row_mask:0xf bank_mask:0xf bound_ctrl:0
	v_fmac_f32_dpp v159, v231, v227 row_shr:4 row_mask:0xf bank_mask:0xf bound_ctrl:0
	ds_read_b128 v[192:195], v9 offset:6848
	ds_read_b128 v[224:227], v9 offset:7104
	s_waitcnt lgkmcnt(2)
	v_mov_b32_e32 v228, v168
	v_mov_b32_e32 v229, v169
	v_mov_b32_e32 v230, v170
	v_mov_b32_e32 v231, v171
	v_fmac_f32_dpp v168, v168, v184 row_shr:4 row_mask:0xf bank_mask:0xf bound_ctrl:0
	v_fmac_f32_dpp v169, v169, v185 row_shr:4 row_mask:0xf bank_mask:0xf bound_ctrl:0
	v_fmac_f32_dpp v170, v170, v186 row_shr:4 row_mask:0xf bank_mask:0xf bound_ctrl:0
	v_fmac_f32_dpp v171, v171, v187 row_shr:4 row_mask:0xf bank_mask:0xf bound_ctrl:0
	v_fmac_f32_dpp v168, v172, -v188 row_shr:4 row_mask:0xf bank_mask:0xf bound_ctrl:0
	v_fmac_f32_dpp v169, v173, -v189 row_shr:4 row_mask:0xf bank_mask:0xf bound_ctrl:0
	v_fmac_f32_dpp v170, v174, -v190 row_shr:4 row_mask:0xf bank_mask:0xf bound_ctrl:0
	v_fmac_f32_dpp v171, v175, -v191 row_shr:4 row_mask:0xf bank_mask:0xf bound_ctrl:0
	v_fmac_f32_dpp v172, v172, v184 row_shr:4 row_mask:0xf bank_mask:0xf bound_ctrl:0
	v_fmac_f32_dpp v173, v173, v185 row_shr:4 row_mask:0xf bank_mask:0xf bound_ctrl:0
	v_fmac_f32_dpp v174, v174, v186 row_shr:4 row_mask:0xf bank_mask:0xf bound_ctrl:0
	v_fmac_f32_dpp v175, v175, v187 row_shr:4 row_mask:0xf bank_mask:0xf bound_ctrl:0
	v_fmac_f32_dpp v172, v228, v188 row_shr:4 row_mask:0xf bank_mask:0xf bound_ctrl:0
	v_fmac_f32_dpp v173, v229, v189 row_shr:4 row_mask:0xf bank_mask:0xf bound_ctrl:0
	v_fmac_f32_dpp v174, v230, v190 row_shr:4 row_mask:0xf bank_mask:0xf bound_ctrl:0
	v_fmac_f32_dpp v175, v231, v191 row_shr:4 row_mask:0xf bank_mask:0xf bound_ctrl:0
	ds_read_b128 v[184:187], v9 offset:7168
	ds_read_b128 v[188:191], v9 offset:7424
	s_waitcnt lgkmcnt(2)
	v_mov_b32_e32 v228, v176
	v_mov_b32_e32 v229, v177
	v_mov_b32_e32 v230, v178
	v_mov_b32_e32 v231, v179
	v_fmac_f32_dpp v176, v176, v192 row_shr:4 row_mask:0xf bank_mask:0xf bound_ctrl:0
	v_fmac_f32_dpp v177, v177, v193 row_shr:4 row_mask:0xf bank_mask:0xf bound_ctrl:0
	v_fmac_f32_dpp v178, v178, v194 row_shr:4 row_mask:0xf bank_mask:0xf bound_ctrl:0
	v_fmac_f32_dpp v179, v179, v195 row_shr:4 row_mask:0xf bank_mask:0xf bound_ctrl:0
	v_fmac_f32_dpp v176, v180, -v224 row_shr:4 row_mask:0xf bank_mask:0xf bound_ctrl:0
	v_fmac_f32_dpp v177, v181, -v225 row_shr:4 row_mask:0xf bank_mask:0xf bound_ctrl:0
	v_fmac_f32_dpp v178, v182, -v226 row_shr:4 row_mask:0xf bank_mask:0xf bound_ctrl:0
	v_fmac_f32_dpp v179, v183, -v227 row_shr:4 row_mask:0xf bank_mask:0xf bound_ctrl:0
	v_fmac_f32_dpp v180, v180, v192 row_shr:4 row_mask:0xf bank_mask:0xf bound_ctrl:0
	v_fmac_f32_dpp v181, v181, v193 row_shr:4 row_mask:0xf bank_mask:0xf bound_ctrl:0
	v_fmac_f32_dpp v182, v182, v194 row_shr:4 row_mask:0xf bank_mask:0xf bound_ctrl:0
	v_fmac_f32_dpp v183, v183, v195 row_shr:4 row_mask:0xf bank_mask:0xf bound_ctrl:0
	v_fmac_f32_dpp v180, v228, v224 row_shr:4 row_mask:0xf bank_mask:0xf bound_ctrl:0
	v_fmac_f32_dpp v181, v229, v225 row_shr:4 row_mask:0xf bank_mask:0xf bound_ctrl:0
	v_fmac_f32_dpp v182, v230, v226 row_shr:4 row_mask:0xf bank_mask:0xf bound_ctrl:0
	v_fmac_f32_dpp v183, v231, v227 row_shr:4 row_mask:0xf bank_mask:0xf bound_ctrl:0
	ds_read_b128 v[192:195], v9 offset:7232
	ds_read_b128 v[224:227], v9 offset:7488
	s_waitcnt lgkmcnt(2)
	v_mov_b32_e32 v228, v144
	v_mov_b32_e32 v229, v145
	v_mov_b32_e32 v230, v146
	v_mov_b32_e32 v231, v147
	v_fmac_f32_dpp v144, v144, v184 row_shr:8 row_mask:0xf bank_mask:0xf bound_ctrl:0
	v_fmac_f32_dpp v145, v145, v185 row_shr:8 row_mask:0xf bank_mask:0xf bound_ctrl:0
	v_fmac_f32_dpp v146, v146, v186 row_shr:8 row_mask:0xf bank_mask:0xf bound_ctrl:0
	v_fmac_f32_dpp v147, v147, v187 row_shr:8 row_mask:0xf bank_mask:0xf bound_ctrl:0
	v_fmac_f32_dpp v144, v148, -v188 row_shr:8 row_mask:0xf bank_mask:0xf bound_ctrl:0
	v_fmac_f32_dpp v145, v149, -v189 row_shr:8 row_mask:0xf bank_mask:0xf bound_ctrl:0
	v_fmac_f32_dpp v146, v150, -v190 row_shr:8 row_mask:0xf bank_mask:0xf bound_ctrl:0
	v_fmac_f32_dpp v147, v151, -v191 row_shr:8 row_mask:0xf bank_mask:0xf bound_ctrl:0
	v_fmac_f32_dpp v148, v148, v184 row_shr:8 row_mask:0xf bank_mask:0xf bound_ctrl:0
	v_fmac_f32_dpp v149, v149, v185 row_shr:8 row_mask:0xf bank_mask:0xf bound_ctrl:0
	v_fmac_f32_dpp v150, v150, v186 row_shr:8 row_mask:0xf bank_mask:0xf bound_ctrl:0
	v_fmac_f32_dpp v151, v151, v187 row_shr:8 row_mask:0xf bank_mask:0xf bound_ctrl:0
	v_fmac_f32_dpp v148, v228, v188 row_shr:8 row_mask:0xf bank_mask:0xf bound_ctrl:0
	v_fmac_f32_dpp v149, v229, v189 row_shr:8 row_mask:0xf bank_mask:0xf bound_ctrl:0
	v_fmac_f32_dpp v150, v230, v190 row_shr:8 row_mask:0xf bank_mask:0xf bound_ctrl:0
	v_fmac_f32_dpp v151, v231, v191 row_shr:8 row_mask:0xf bank_mask:0xf bound_ctrl:0
	ds_read_b128 v[184:187], v9 offset:7296
	ds_read_b128 v[188:191], v9 offset:7552
	s_waitcnt lgkmcnt(2)
	v_mov_b32_e32 v228, v152
	v_mov_b32_e32 v229, v153
	v_mov_b32_e32 v230, v154
	v_mov_b32_e32 v231, v155
	v_fmac_f32_dpp v152, v152, v192 row_shr:8 row_mask:0xf bank_mask:0xf bound_ctrl:0
	v_fmac_f32_dpp v153, v153, v193 row_shr:8 row_mask:0xf bank_mask:0xf bound_ctrl:0
	v_fmac_f32_dpp v154, v154, v194 row_shr:8 row_mask:0xf bank_mask:0xf bound_ctrl:0
	v_fmac_f32_dpp v155, v155, v195 row_shr:8 row_mask:0xf bank_mask:0xf bound_ctrl:0
	v_fmac_f32_dpp v152, v156, -v224 row_shr:8 row_mask:0xf bank_mask:0xf bound_ctrl:0
	v_fmac_f32_dpp v153, v157, -v225 row_shr:8 row_mask:0xf bank_mask:0xf bound_ctrl:0
	v_fmac_f32_dpp v154, v158, -v226 row_shr:8 row_mask:0xf bank_mask:0xf bound_ctrl:0
	v_fmac_f32_dpp v155, v159, -v227 row_shr:8 row_mask:0xf bank_mask:0xf bound_ctrl:0
	v_fmac_f32_dpp v156, v156, v192 row_shr:8 row_mask:0xf bank_mask:0xf bound_ctrl:0
	v_fmac_f32_dpp v157, v157, v193 row_shr:8 row_mask:0xf bank_mask:0xf bound_ctrl:0
	v_fmac_f32_dpp v158, v158, v194 row_shr:8 row_mask:0xf bank_mask:0xf bound_ctrl:0
	v_fmac_f32_dpp v159, v159, v195 row_shr:8 row_mask:0xf bank_mask:0xf bound_ctrl:0
	v_fmac_f32_dpp v156, v228, v224 row_shr:8 row_mask:0xf bank_mask:0xf bound_ctrl:0
	v_fmac_f32_dpp v157, v229, v225 row_shr:8 row_mask:0xf bank_mask:0xf bound_ctrl:0
	v_fmac_f32_dpp v158, v230, v226 row_shr:8 row_mask:0xf bank_mask:0xf bound_ctrl:0
	v_fmac_f32_dpp v159, v231, v227 row_shr:8 row_mask:0xf bank_mask:0xf bound_ctrl:0
	ds_read_b128 v[192:195], v9 offset:7360
	ds_read_b128 v[224:227], v9 offset:7616
	s_waitcnt lgkmcnt(2)
	v_mov_b32_e32 v228, v168
	v_mov_b32_e32 v229, v169
	v_mov_b32_e32 v230, v170
	v_mov_b32_e32 v231, v171
	v_fmac_f32_dpp v168, v168, v184 row_shr:8 row_mask:0xf bank_mask:0xf bound_ctrl:0
	v_fmac_f32_dpp v169, v169, v185 row_shr:8 row_mask:0xf bank_mask:0xf bound_ctrl:0
	v_fmac_f32_dpp v170, v170, v186 row_shr:8 row_mask:0xf bank_mask:0xf bound_ctrl:0
	v_fmac_f32_dpp v171, v171, v187 row_shr:8 row_mask:0xf bank_mask:0xf bound_ctrl:0
	v_fmac_f32_dpp v168, v172, -v188 row_shr:8 row_mask:0xf bank_mask:0xf bound_ctrl:0
	v_fmac_f32_dpp v169, v173, -v189 row_shr:8 row_mask:0xf bank_mask:0xf bound_ctrl:0
	v_fmac_f32_dpp v170, v174, -v190 row_shr:8 row_mask:0xf bank_mask:0xf bound_ctrl:0
	v_fmac_f32_dpp v171, v175, -v191 row_shr:8 row_mask:0xf bank_mask:0xf bound_ctrl:0
	v_fmac_f32_dpp v172, v172, v184 row_shr:8 row_mask:0xf bank_mask:0xf bound_ctrl:0
	v_fmac_f32_dpp v173, v173, v185 row_shr:8 row_mask:0xf bank_mask:0xf bound_ctrl:0
	v_fmac_f32_dpp v174, v174, v186 row_shr:8 row_mask:0xf bank_mask:0xf bound_ctrl:0
	v_fmac_f32_dpp v175, v175, v187 row_shr:8 row_mask:0xf bank_mask:0xf bound_ctrl:0
	v_fmac_f32_dpp v172, v228, v188 row_shr:8 row_mask:0xf bank_mask:0xf bound_ctrl:0
	v_fmac_f32_dpp v173, v229, v189 row_shr:8 row_mask:0xf bank_mask:0xf bound_ctrl:0
	v_fmac_f32_dpp v174, v230, v190 row_shr:8 row_mask:0xf bank_mask:0xf bound_ctrl:0
	v_fmac_f32_dpp v175, v231, v191 row_shr:8 row_mask:0xf bank_mask:0xf bound_ctrl:0
	s_waitcnt lgkmcnt(0)
	v_mov_b32_e32 v228, v176
	v_mov_b32_e32 v229, v177
	v_mov_b32_e32 v230, v178
	v_mov_b32_e32 v231, v179
	v_fmac_f32_dpp v176, v176, v192 row_shr:8 row_mask:0xf bank_mask:0xf bound_ctrl:0
	v_fmac_f32_dpp v177, v177, v193 row_shr:8 row_mask:0xf bank_mask:0xf bound_ctrl:0
	v_fmac_f32_dpp v178, v178, v194 row_shr:8 row_mask:0xf bank_mask:0xf bound_ctrl:0
	v_fmac_f32_dpp v179, v179, v195 row_shr:8 row_mask:0xf bank_mask:0xf bound_ctrl:0
	v_fmac_f32_dpp v176, v180, -v224 row_shr:8 row_mask:0xf bank_mask:0xf bound_ctrl:0
	v_fmac_f32_dpp v177, v181, -v225 row_shr:8 row_mask:0xf bank_mask:0xf bound_ctrl:0
	v_fmac_f32_dpp v178, v182, -v226 row_shr:8 row_mask:0xf bank_mask:0xf bound_ctrl:0
	v_fmac_f32_dpp v179, v183, -v227 row_shr:8 row_mask:0xf bank_mask:0xf bound_ctrl:0
	v_fmac_f32_dpp v180, v180, v192 row_shr:8 row_mask:0xf bank_mask:0xf bound_ctrl:0
	v_fmac_f32_dpp v181, v181, v193 row_shr:8 row_mask:0xf bank_mask:0xf bound_ctrl:0
	v_fmac_f32_dpp v182, v182, v194 row_shr:8 row_mask:0xf bank_mask:0xf bound_ctrl:0
	v_fmac_f32_dpp v183, v183, v195 row_shr:8 row_mask:0xf bank_mask:0xf bound_ctrl:0
	v_fmac_f32_dpp v180, v228, v224 row_shr:8 row_mask:0xf bank_mask:0xf bound_ctrl:0
	v_fmac_f32_dpp v181, v229, v225 row_shr:8 row_mask:0xf bank_mask:0xf bound_ctrl:0
	v_fmac_f32_dpp v182, v230, v226 row_shr:8 row_mask:0xf bank_mask:0xf bound_ctrl:0
	v_fmac_f32_dpp v183, v231, v227 row_shr:8 row_mask:0xf bank_mask:0xf bound_ctrl:0
	s_lshl_b32 s56, s0, 5
	s_add_i32 s55, s6, 1
	s_lshl_b32 s55, s55, 1
	s_add_i32 s56, s56, s55
	s_add_i32 s56, s56, 0
	s_lshl_b32 s56, s56, 9
	s_add_u32 s48, s94, 0x12dd6000
	s_addc_u32 s49, s95, 0
	s_add_u32 s48, s48, s56
	s_addc_u32 s49, s49, 0
	s_nop 1
	s_mov_b64 exec, s[10:11]
	global_store_dword v10, v144, s[48:49] offset:0
	global_store_dword v10, v148, s[48:49] offset:4
	global_store_dword v10, v145, s[48:49] offset:8
	global_store_dword v10, v149, s[48:49] offset:12
	global_store_dword v10, v146, s[48:49] offset:16
	global_store_dword v10, v150, s[48:49] offset:20
	global_store_dword v10, v147, s[48:49] offset:24
	global_store_dword v10, v151, s[48:49] offset:28
	global_store_dword v10, v152, s[48:49] offset:128
	global_store_dword v10, v156, s[48:49] offset:132
	global_store_dword v10, v153, s[48:49] offset:136
	global_store_dword v10, v157, s[48:49] offset:140
	global_store_dword v10, v154, s[48:49] offset:144
	global_store_dword v10, v158, s[48:49] offset:148
	global_store_dword v10, v155, s[48:49] offset:152
	global_store_dword v10, v159, s[48:49] offset:156
	global_store_dword v10, v168, s[48:49] offset:256
	global_store_dword v10, v172, s[48:49] offset:260
	global_store_dword v10, v169, s[48:49] offset:264
	global_store_dword v10, v173, s[48:49] offset:268
	global_store_dword v10, v170, s[48:49] offset:272
	global_store_dword v10, v174, s[48:49] offset:276
	global_store_dword v10, v171, s[48:49] offset:280
	global_store_dword v10, v175, s[48:49] offset:284
	global_store_dword v10, v176, s[48:49] offset:384
	global_store_dword v10, v180, s[48:49] offset:388
	global_store_dword v10, v177, s[48:49] offset:392
	global_store_dword v10, v181, s[48:49] offset:396
	global_store_dword v10, v178, s[48:49] offset:400
	global_store_dword v10, v182, s[48:49] offset:404
	global_store_dword v10, v179, s[48:49] offset:408
	global_store_dword v10, v183, s[48:49] offset:412
	s_mov_b64 exec, -1
	s_waitcnt vmcnt(32)
	v_mfma_f32_16x16x4_f32 v[80:83], v44, v240, 0
	v_mfma_f32_16x16x4_f32 v[84:87], v45, v240, 0
	v_mfma_f32_16x16x4_f32 v[144:147], v44, v244, 0
	v_mfma_f32_16x16x4_f32 v[148:151], v45, v244, 0
	v_mfma_f32_16x16x4_f32 v[112:115], v56, v240, 0
	v_mfma_f32_16x16x4_f32 v[116:119], v57, v240, 0
	v_mfma_f32_16x16x4_f32 v[152:155], v56, v244, 0
	v_mfma_f32_16x16x4_f32 v[156:159], v57, v244, 0
	v_mfma_f32_16x16x4_f32 v[120:123], v64, v240, 0
	v_mfma_f32_16x16x4_f32 v[124:127], v65, v240, 0
	v_mfma_f32_16x16x4_f32 v[168:171], v64, v244, 0
	v_mfma_f32_16x16x4_f32 v[172:175], v65, v244, 0
	v_mfma_f32_16x16x4_f32 v[128:131], v72, v240, 0
	v_mfma_f32_16x16x4_f32 v[140:143], v73, v240, 0
	v_mfma_f32_16x16x4_f32 v[176:179], v72, v244, 0
	v_mfma_f32_16x16x4_f32 v[180:183], v73, v244, 0
	v_mfma_f32_16x16x4_f32 v[80:83], v46, v241, v[80:83]
	v_mfma_f32_16x16x4_f32 v[84:87], v47, v241, v[84:87]
	v_mfma_f32_16x16x4_f32 v[144:147], v46, v245, v[144:147]
	v_mfma_f32_16x16x4_f32 v[148:151], v47, v245, v[148:151]
	v_mfma_f32_16x16x4_f32 v[112:115], v58, v241, v[112:115]
	v_mfma_f32_16x16x4_f32 v[116:119], v59, v241, v[116:119]
	v_mfma_f32_16x16x4_f32 v[152:155], v58, v245, v[152:155]
	v_mfma_f32_16x16x4_f32 v[156:159], v59, v245, v[156:159]
	v_mfma_f32_16x16x4_f32 v[120:123], v66, v241, v[120:123]
	v_mfma_f32_16x16x4_f32 v[124:127], v67, v241, v[124:127]
	v_mfma_f32_16x16x4_f32 v[168:171], v66, v245, v[168:171]
	v_mfma_f32_16x16x4_f32 v[172:175], v67, v245, v[172:175]
	v_mfma_f32_16x16x4_f32 v[128:131], v74, v241, v[128:131]
	v_mfma_f32_16x16x4_f32 v[140:143], v75, v241, v[140:143]
	v_mfma_f32_16x16x4_f32 v[176:179], v74, v245, v[176:179]
	v_mfma_f32_16x16x4_f32 v[180:183], v75, v245, v[180:183]
	v_mfma_f32_16x16x4_f32 v[80:83], v52, v242, v[80:83]
	v_mfma_f32_16x16x4_f32 v[84:87], v53, v242, v[84:87]
	v_mfma_f32_16x16x4_f32 v[144:147], v52, v246, v[144:147]
	v_mfma_f32_16x16x4_f32 v[148:151], v53, v246, v[148:151]
	v_mfma_f32_16x16x4_f32 v[112:115], v60, v242, v[112:115]
	v_mfma_f32_16x16x4_f32 v[116:119], v61, v242, v[116:119]
	v_mfma_f32_16x16x4_f32 v[152:155], v60, v246, v[152:155]
	v_mfma_f32_16x16x4_f32 v[156:159], v61, v246, v[156:159]
	v_mfma_f32_16x16x4_f32 v[120:123], v68, v242, v[120:123]
	v_mfma_f32_16x16x4_f32 v[124:127], v69, v242, v[124:127]
	v_mfma_f32_16x16x4_f32 v[168:171], v68, v246, v[168:171]
	v_mfma_f32_16x16x4_f32 v[172:175], v69, v246, v[172:175]
	v_mfma_f32_16x16x4_f32 v[128:131], v76, v242, v[128:131]
	v_mfma_f32_16x16x4_f32 v[140:143], v77, v242, v[140:143]
	v_mfma_f32_16x16x4_f32 v[176:179], v76, v246, v[176:179]
	v_mfma_f32_16x16x4_f32 v[180:183], v77, v246, v[180:183]
	v_mfma_f32_16x16x4_f32 v[80:83], v54, v243, v[80:83]
	v_mfma_f32_16x16x4_f32 v[84:87], v55, v243, v[84:87]
	v_mfma_f32_16x16x4_f32 v[144:147], v54, v247, v[144:147]
	v_mfma_f32_16x16x4_f32 v[148:151], v55, v247, v[148:151]
	v_mfma_f32_16x16x4_f32 v[112:115], v62, v243, v[112:115]
	v_mfma_f32_16x16x4_f32 v[116:119], v63, v243, v[116:119]
	v_mfma_f32_16x16x4_f32 v[152:155], v62, v247, v[152:155]
	v_mfma_f32_16x16x4_f32 v[156:159], v63, v247, v[156:159]
	v_mfma_f32_16x16x4_f32 v[120:123], v70, v243, v[120:123]
	v_mfma_f32_16x16x4_f32 v[124:127], v71, v243, v[124:127]
	v_mfma_f32_16x16x4_f32 v[168:171], v70, v247, v[168:171]
	v_mfma_f32_16x16x4_f32 v[172:175], v71, v247, v[172:175]
	v_mfma_f32_16x16x4_f32 v[128:131], v78, v243, v[128:131]
	v_mfma_f32_16x16x4_f32 v[140:143], v79, v243, v[140:143]
	v_mfma_f32_16x16x4_f32 v[176:179], v78, v247, v[176:179]
	v_mfma_f32_16x16x4_f32 v[180:183], v79, v247, v[180:183]
	s_nop 9
	ds_read_b128 v[184:187], v9 offset:7680
	ds_read_b128 v[188:191], v9 offset:7936
	ds_read_b128 v[192:195], v9 offset:7744
	ds_read_b128 v[224:227], v9 offset:8000
	s_waitcnt lgkmcnt(2)
	v_fmac_f32_e32 v80, v184, v144
	v_fmac_f32_e32 v81, v185, v145
	v_fmac_f32_e32 v82, v186, v146
	v_fmac_f32_e32 v83, v187, v147
	v_fma_f32 v80, -v188, v148, v80
	v_fma_f32 v81, -v189, v149, v81
	v_fma_f32 v82, -v190, v150, v82
	v_fma_f32 v83, -v191, v151, v83
	v_fmac_f32_e32 v84, v184, v148
	v_fmac_f32_e32 v85, v185, v149
	v_fmac_f32_e32 v86, v186, v150
	v_fmac_f32_e32 v87, v187, v151
	v_fmac_f32_e32 v84, v188, v144
	v_fmac_f32_e32 v85, v189, v145
	v_fmac_f32_e32 v86, v190, v146
	v_fmac_f32_e32 v87, v191, v147
	ds_read_b128 v[184:187], v9 offset:7808
	ds_read_b128 v[188:191], v9 offset:8064
	s_waitcnt lgkmcnt(2)
	v_fmac_f32_e32 v112, v192, v152
	v_fmac_f32_e32 v113, v193, v153
	v_fmac_f32_e32 v114, v194, v154
	v_fmac_f32_e32 v115, v195, v155
	v_fma_f32 v112, -v224, v156, v112
	v_fma_f32 v113, -v225, v157, v113
	v_fma_f32 v114, -v226, v158, v114
	v_fma_f32 v115, -v227, v159, v115
	v_fmac_f32_e32 v116, v192, v156
	v_fmac_f32_e32 v117, v193, v157
	v_fmac_f32_e32 v118, v194, v158
	v_fmac_f32_e32 v119, v195, v159
	v_fmac_f32_e32 v116, v224, v152
	v_fmac_f32_e32 v117, v225, v153
	v_fmac_f32_e32 v118, v226, v154
	v_fmac_f32_e32 v119, v227, v155
	ds_read_b128 v[192:195], v9 offset:7872
	ds_read_b128 v[224:227], v9 offset:8128
	s_waitcnt lgkmcnt(2)
	v_fmac_f32_e32 v120, v184, v168
	v_fmac_f32_e32 v121, v185, v169
	v_fmac_f32_e32 v122, v186, v170
	v_fmac_f32_e32 v123, v187, v171
	v_fma_f32 v120, -v188, v172, v120
	v_fma_f32 v121, -v189, v173, v121
	v_fma_f32 v122, -v190, v174, v122
	v_fma_f32 v123, -v191, v175, v123
	v_fmac_f32_e32 v124, v184, v172
	v_fmac_f32_e32 v125, v185, v173
	v_fmac_f32_e32 v126, v186, v174
	v_fmac_f32_e32 v127, v187, v175
	v_fmac_f32_e32 v124, v188, v168
	v_fmac_f32_e32 v125, v189, v169
	v_fmac_f32_e32 v126, v190, v170
	v_fmac_f32_e32 v127, v191, v171
	s_waitcnt lgkmcnt(0)
	v_fmac_f32_e32 v128, v192, v176
	v_fmac_f32_e32 v129, v193, v177
	v_fmac_f32_e32 v130, v194, v178
	v_fmac_f32_e32 v131, v195, v179
	v_fma_f32 v128, -v224, v180, v128
	v_fma_f32 v129, -v225, v181, v129
	v_fma_f32 v130, -v226, v182, v130
	v_fma_f32 v131, -v227, v183, v131
	v_fmac_f32_e32 v140, v192, v180
	v_fmac_f32_e32 v141, v193, v181
	v_fmac_f32_e32 v142, v194, v182
	v_fmac_f32_e32 v143, v195, v183
	v_fmac_f32_e32 v140, v224, v176
	v_fmac_f32_e32 v141, v225, v177
	v_fmac_f32_e32 v142, v226, v178
	v_fmac_f32_e32 v143, v227, v179
	global_load_dwordx4 v[12:15], v6, s[12:13] offset:0
	global_load_dwordx4 v[16:19], v6, s[12:13] offset:1024
	global_load_dwordx4 v[20:23], v6, s[12:13] offset:256
	global_load_dwordx4 v[24:27], v6, s[12:13] offset:1280
	global_load_dwordx4 v[28:31], v6, s[12:13] offset:512
	global_load_dwordx4 v[32:35], v6, s[12:13] offset:1536
	global_load_dwordx4 v[36:39], v6, s[12:13] offset:768
	global_load_dwordx4 v[40:43], v6, s[12:13] offset:1792
	s_lshl_b32 s55, s1, 15
	s_add_i32 s56, s6, 0
	s_lshl_b32 s56, s56, 6
	s_add_u32 s55, s55, s56
	s_add_u32 s50, s94, 0x8a40000
	s_addc_u32 s51, s95, 0
	s_add_u32 s50, s50, s55
	s_addc_u32 s51, s51, 0
	global_load_dwordx4 v[232:235], v5, s[50:51] offset:0
	global_load_dwordx4 v[236:239], v5, s[50:51] offset:1024
	s_lshl_b32 s55, s1, 15
	s_add_i32 s56, s6, 1
	s_lshl_b32 s56, s56, 6
	s_add_u32 s55, s55, s56
	s_add_u32 s50, s94, 0x8a40000
	s_addc_u32 s51, s95, 0
	s_add_u32 s50, s50, s55
	s_addc_u32 s51, s51, 0
	global_load_dwordx4 v[240:243], v5, s[50:51] offset:0
	global_load_dwordx4 v[244:247], v5, s[50:51] offset:1024
	ds_read_b128 v[184:187], v9 offset:8192
	ds_read_b128 v[188:191], v9 offset:8448
	ds_read_b128 v[192:195], v9 offset:8256
	ds_read_b128 v[224:227], v9 offset:8512
	s_waitcnt lgkmcnt(2)
	v_mov_b32_e32 v228, v80
	v_mov_b32_e32 v229, v81
	v_mov_b32_e32 v230, v82
	v_mov_b32_e32 v231, v83
	s_nop 1
	v_fmac_f32_dpp v80, v80, v184 row_shl:1 row_mask:0xf bank_mask:0xf bound_ctrl:0
	v_fmac_f32_dpp v81, v81, v185 row_shl:1 row_mask:0xf bank_mask:0xf bound_ctrl:0
	v_fmac_f32_dpp v82, v82, v186 row_shl:1 row_mask:0xf bank_mask:0xf bound_ctrl:0
	v_fmac_f32_dpp v83, v83, v187 row_shl:1 row_mask:0xf bank_mask:0xf bound_ctrl:0
	v_fmac_f32_dpp v80, v84, -v188 row_shl:1 row_mask:0xf bank_mask:0xf bound_ctrl:0
	v_fmac_f32_dpp v81, v85, -v189 row_shl:1 row_mask:0xf bank_mask:0xf bound_ctrl:0
	v_fmac_f32_dpp v82, v86, -v190 row_shl:1 row_mask:0xf bank_mask:0xf bound_ctrl:0
	v_fmac_f32_dpp v83, v87, -v191 row_shl:1 row_mask:0xf bank_mask:0xf bound_ctrl:0
	v_fmac_f32_dpp v84, v84, v184 row_shl:1 row_mask:0xf bank_mask:0xf bound_ctrl:0
	v_fmac_f32_dpp v85, v85, v185 row_shl:1 row_mask:0xf bank_mask:0xf bound_ctrl:0
	v_fmac_f32_dpp v86, v86, v186 row_shl:1 row_mask:0xf bank_mask:0xf bound_ctrl:0
	v_fmac_f32_dpp v87, v87, v187 row_shl:1 row_mask:0xf bank_mask:0xf bound_ctrl:0
	v_fmac_f32_dpp v84, v228, v188 row_shl:1 row_mask:0xf bank_mask:0xf bound_ctrl:0
	v_fmac_f32_dpp v85, v229, v189 row_shl:1 row_mask:0xf bank_mask:0xf bound_ctrl:0
	v_fmac_f32_dpp v86, v230, v190 row_shl:1 row_mask:0xf bank_mask:0xf bound_ctrl:0
	v_fmac_f32_dpp v87, v231, v191 row_shl:1 row_mask:0xf bank_mask:0xf bound_ctrl:0
	ds_read_b128 v[184:187], v9 offset:8320
	ds_read_b128 v[188:191], v9 offset:8576
	s_waitcnt lgkmcnt(2)
	v_mov_b32_e32 v228, v112
	v_mov_b32_e32 v229, v113
	v_mov_b32_e32 v230, v114
	v_mov_b32_e32 v231, v115
	v_fmac_f32_dpp v112, v112, v192 row_shl:1 row_mask:0xf bank_mask:0xf bound_ctrl:0
	v_fmac_f32_dpp v113, v113, v193 row_shl:1 row_mask:0xf bank_mask:0xf bound_ctrl:0
	v_fmac_f32_dpp v114, v114, v194 row_shl:1 row_mask:0xf bank_mask:0xf bound_ctrl:0
	v_fmac_f32_dpp v115, v115, v195 row_shl:1 row_mask:0xf bank_mask:0xf bound_ctrl:0
	v_fmac_f32_dpp v112, v116, -v224 row_shl:1 row_mask:0xf bank_mask:0xf bound_ctrl:0
	v_fmac_f32_dpp v113, v117, -v225 row_shl:1 row_mask:0xf bank_mask:0xf bound_ctrl:0
	v_fmac_f32_dpp v114, v118, -v226 row_shl:1 row_mask:0xf bank_mask:0xf bound_ctrl:0
	v_fmac_f32_dpp v115, v119, -v227 row_shl:1 row_mask:0xf bank_mask:0xf bound_ctrl:0
	v_fmac_f32_dpp v116, v116, v192 row_shl:1 row_mask:0xf bank_mask:0xf bound_ctrl:0
	v_fmac_f32_dpp v117, v117, v193 row_shl:1 row_mask:0xf bank_mask:0xf bound_ctrl:0
	v_fmac_f32_dpp v118, v118, v194 row_shl:1 row_mask:0xf bank_mask:0xf bound_ctrl:0
	v_fmac_f32_dpp v119, v119, v195 row_shl:1 row_mask:0xf bank_mask:0xf bound_ctrl:0
	v_fmac_f32_dpp v116, v228, v224 row_shl:1 row_mask:0xf bank_mask:0xf bound_ctrl:0
	v_fmac_f32_dpp v117, v229, v225 row_shl:1 row_mask:0xf bank_mask:0xf bound_ctrl:0
	v_fmac_f32_dpp v118, v230, v226 row_shl:1 row_mask:0xf bank_mask:0xf bound_ctrl:0
	v_fmac_f32_dpp v119, v231, v227 row_shl:1 row_mask:0xf bank_mask:0xf bound_ctrl:0
	ds_read_b128 v[192:195], v9 offset:8384
	ds_read_b128 v[224:227], v9 offset:8640
	s_waitcnt lgkmcnt(2)
	v_mov_b32_e32 v228, v120
	v_mov_b32_e32 v229, v121
	v_mov_b32_e32 v230, v122
	v_mov_b32_e32 v231, v123
	v_fmac_f32_dpp v120, v120, v184 row_shl:1 row_mask:0xf bank_mask:0xf bound_ctrl:0
	v_fmac_f32_dpp v121, v121, v185 row_shl:1 row_mask:0xf bank_mask:0xf bound_ctrl:0
	v_fmac_f32_dpp v122, v122, v186 row_shl:1 row_mask:0xf bank_mask:0xf bound_ctrl:0
	v_fmac_f32_dpp v123, v123, v187 row_shl:1 row_mask:0xf bank_mask:0xf bound_ctrl:0
	v_fmac_f32_dpp v120, v124, -v188 row_shl:1 row_mask:0xf bank_mask:0xf bound_ctrl:0
	v_fmac_f32_dpp v121, v125, -v189 row_shl:1 row_mask:0xf bank_mask:0xf bound_ctrl:0
	v_fmac_f32_dpp v122, v126, -v190 row_shl:1 row_mask:0xf bank_mask:0xf bound_ctrl:0
	v_fmac_f32_dpp v123, v127, -v191 row_shl:1 row_mask:0xf bank_mask:0xf bound_ctrl:0
	v_fmac_f32_dpp v124, v124, v184 row_shl:1 row_mask:0xf bank_mask:0xf bound_ctrl:0
	v_fmac_f32_dpp v125, v125, v185 row_shl:1 row_mask:0xf bank_mask:0xf bound_ctrl:0
	v_fmac_f32_dpp v126, v126, v186 row_shl:1 row_mask:0xf bank_mask:0xf bound_ctrl:0
	v_fmac_f32_dpp v127, v127, v187 row_shl:1 row_mask:0xf bank_mask:0xf bound_ctrl:0
	v_fmac_f32_dpp v124, v228, v188 row_shl:1 row_mask:0xf bank_mask:0xf bound_ctrl:0
	v_fmac_f32_dpp v125, v229, v189 row_shl:1 row_mask:0xf bank_mask:0xf bound_ctrl:0
	v_fmac_f32_dpp v126, v230, v190 row_shl:1 row_mask:0xf bank_mask:0xf bound_ctrl:0
	v_fmac_f32_dpp v127, v231, v191 row_shl:1 row_mask:0xf bank_mask:0xf bound_ctrl:0
	ds_read_b128 v[184:187], v9 offset:8704
	ds_read_b128 v[188:191], v9 offset:8960
	s_waitcnt lgkmcnt(2)
	v_mov_b32_e32 v228, v128
	v_mov_b32_e32 v229, v129
	v_mov_b32_e32 v230, v130
	v_mov_b32_e32 v231, v131
	v_fmac_f32_dpp v128, v128, v192 row_shl:1 row_mask:0xf bank_mask:0xf bound_ctrl:0
	v_fmac_f32_dpp v129, v129, v193 row_shl:1 row_mask:0xf bank_mask:0xf bound_ctrl:0
	v_fmac_f32_dpp v130, v130, v194 row_shl:1 row_mask:0xf bank_mask:0xf bound_ctrl:0
	v_fmac_f32_dpp v131, v131, v195 row_shl:1 row_mask:0xf bank_mask:0xf bound_ctrl:0
	v_fmac_f32_dpp v128, v140, -v224 row_shl:1 row_mask:0xf bank_mask:0xf bound_ctrl:0
	v_fmac_f32_dpp v129, v141, -v225 row_shl:1 row_mask:0xf bank_mask:0xf bound_ctrl:0
	v_fmac_f32_dpp v130, v142, -v226 row_shl:1 row_mask:0xf bank_mask:0xf bound_ctrl:0
	v_fmac_f32_dpp v131, v143, -v227 row_shl:1 row_mask:0xf bank_mask:0xf bound_ctrl:0
	v_fmac_f32_dpp v140, v140, v192 row_shl:1 row_mask:0xf bank_mask:0xf bound_ctrl:0
	v_fmac_f32_dpp v141, v141, v193 row_shl:1 row_mask:0xf bank_mask:0xf bound_ctrl:0
	v_fmac_f32_dpp v142, v142, v194 row_shl:1 row_mask:0xf bank_mask:0xf bound_ctrl:0
	v_fmac_f32_dpp v143, v143, v195 row_shl:1 row_mask:0xf bank_mask:0xf bound_ctrl:0
	v_fmac_f32_dpp v140, v228, v224 row_shl:1 row_mask:0xf bank_mask:0xf bound_ctrl:0
	v_fmac_f32_dpp v141, v229, v225 row_shl:1 row_mask:0xf bank_mask:0xf bound_ctrl:0
	v_fmac_f32_dpp v142, v230, v226 row_shl:1 row_mask:0xf bank_mask:0xf bound_ctrl:0
	v_fmac_f32_dpp v143, v231, v227 row_shl:1 row_mask:0xf bank_mask:0xf bound_ctrl:0
	ds_read_b128 v[192:195], v9 offset:8768
	ds_read_b128 v[224:227], v9 offset:9024
	s_waitcnt lgkmcnt(2)
	v_mov_b32_e32 v228, v80
	v_mov_b32_e32 v229, v81
	v_mov_b32_e32 v230, v82
	v_mov_b32_e32 v231, v83
	v_fmac_f32_dpp v80, v80, v184 row_shl:2 row_mask:0xf bank_mask:0xf bound_ctrl:0
	v_fmac_f32_dpp v81, v81, v185 row_shl:2 row_mask:0xf bank_mask:0xf bound_ctrl:0
	v_fmac_f32_dpp v82, v82, v186 row_shl:2 row_mask:0xf bank_mask:0xf bound_ctrl:0
	v_fmac_f32_dpp v83, v83, v187 row_shl:2 row_mask:0xf bank_mask:0xf bound_ctrl:0
	v_fmac_f32_dpp v80, v84, -v188 row_shl:2 row_mask:0xf bank_mask:0xf bound_ctrl:0
	v_fmac_f32_dpp v81, v85, -v189 row_shl:2 row_mask:0xf bank_mask:0xf bound_ctrl:0
	v_fmac_f32_dpp v82, v86, -v190 row_shl:2 row_mask:0xf bank_mask:0xf bound_ctrl:0
	v_fmac_f32_dpp v83, v87, -v191 row_shl:2 row_mask:0xf bank_mask:0xf bound_ctrl:0
	v_fmac_f32_dpp v84, v84, v184 row_shl:2 row_mask:0xf bank_mask:0xf bound_ctrl:0
	v_fmac_f32_dpp v85, v85, v185 row_shl:2 row_mask:0xf bank_mask:0xf bound_ctrl:0
	v_fmac_f32_dpp v86, v86, v186 row_shl:2 row_mask:0xf bank_mask:0xf bound_ctrl:0
	v_fmac_f32_dpp v87, v87, v187 row_shl:2 row_mask:0xf bank_mask:0xf bound_ctrl:0
	v_fmac_f32_dpp v84, v228, v188 row_shl:2 row_mask:0xf bank_mask:0xf bound_ctrl:0
	v_fmac_f32_dpp v85, v229, v189 row_shl:2 row_mask:0xf bank_mask:0xf bound_ctrl:0
	v_fmac_f32_dpp v86, v230, v190 row_shl:2 row_mask:0xf bank_mask:0xf bound_ctrl:0
	v_fmac_f32_dpp v87, v231, v191 row_shl:2 row_mask:0xf bank_mask:0xf bound_ctrl:0
	ds_read_b128 v[184:187], v9 offset:8832
	ds_read_b128 v[188:191], v9 offset:9088
	s_waitcnt lgkmcnt(2)
	v_mov_b32_e32 v228, v112
	v_mov_b32_e32 v229, v113
	v_mov_b32_e32 v230, v114
	v_mov_b32_e32 v231, v115
	v_fmac_f32_dpp v112, v112, v192 row_shl:2 row_mask:0xf bank_mask:0xf bound_ctrl:0
	v_fmac_f32_dpp v113, v113, v193 row_shl:2 row_mask:0xf bank_mask:0xf bound_ctrl:0
	v_fmac_f32_dpp v114, v114, v194 row_shl:2 row_mask:0xf bank_mask:0xf bound_ctrl:0
	v_fmac_f32_dpp v115, v115, v195 row_shl:2 row_mask:0xf bank_mask:0xf bound_ctrl:0
	v_fmac_f32_dpp v112, v116, -v224 row_shl:2 row_mask:0xf bank_mask:0xf bound_ctrl:0
	v_fmac_f32_dpp v113, v117, -v225 row_shl:2 row_mask:0xf bank_mask:0xf bound_ctrl:0
	v_fmac_f32_dpp v114, v118, -v226 row_shl:2 row_mask:0xf bank_mask:0xf bound_ctrl:0
	v_fmac_f32_dpp v115, v119, -v227 row_shl:2 row_mask:0xf bank_mask:0xf bound_ctrl:0
	v_fmac_f32_dpp v116, v116, v192 row_shl:2 row_mask:0xf bank_mask:0xf bound_ctrl:0
	v_fmac_f32_dpp v117, v117, v193 row_shl:2 row_mask:0xf bank_mask:0xf bound_ctrl:0
	v_fmac_f32_dpp v118, v118, v194 row_shl:2 row_mask:0xf bank_mask:0xf bound_ctrl:0
	v_fmac_f32_dpp v119, v119, v195 row_shl:2 row_mask:0xf bank_mask:0xf bound_ctrl:0
	v_fmac_f32_dpp v116, v228, v224 row_shl:2 row_mask:0xf bank_mask:0xf bound_ctrl:0
	v_fmac_f32_dpp v117, v229, v225 row_shl:2 row_mask:0xf bank_mask:0xf bound_ctrl:0
	v_fmac_f32_dpp v118, v230, v226 row_shl:2 row_mask:0xf bank_mask:0xf bound_ctrl:0
	v_fmac_f32_dpp v119, v231, v227 row_shl:2 row_mask:0xf bank_mask:0xf bound_ctrl:0
	ds_read_b128 v[192:195], v9 offset:8896
	ds_read_b128 v[224:227], v9 offset:9152
	s_waitcnt lgkmcnt(2)
	v_mov_b32_e32 v228, v120
	v_mov_b32_e32 v229, v121
	v_mov_b32_e32 v230, v122
	v_mov_b32_e32 v231, v123
	v_fmac_f32_dpp v120, v120, v184 row_shl:2 row_mask:0xf bank_mask:0xf bound_ctrl:0
	v_fmac_f32_dpp v121, v121, v185 row_shl:2 row_mask:0xf bank_mask:0xf bound_ctrl:0
	v_fmac_f32_dpp v122, v122, v186 row_shl:2 row_mask:0xf bank_mask:0xf bound_ctrl:0
	v_fmac_f32_dpp v123, v123, v187 row_shl:2 row_mask:0xf bank_mask:0xf bound_ctrl:0
	v_fmac_f32_dpp v120, v124, -v188 row_shl:2 row_mask:0xf bank_mask:0xf bound_ctrl:0
	v_fmac_f32_dpp v121, v125, -v189 row_shl:2 row_mask:0xf bank_mask:0xf bound_ctrl:0
	v_fmac_f32_dpp v122, v126, -v190 row_shl:2 row_mask:0xf bank_mask:0xf bound_ctrl:0
	v_fmac_f32_dpp v123, v127, -v191 row_shl:2 row_mask:0xf bank_mask:0xf bound_ctrl:0
	v_fmac_f32_dpp v124, v124, v184 row_shl:2 row_mask:0xf bank_mask:0xf bound_ctrl:0
	v_fmac_f32_dpp v125, v125, v185 row_shl:2 row_mask:0xf bank_mask:0xf bound_ctrl:0
	v_fmac_f32_dpp v126, v126, v186 row_shl:2 row_mask:0xf bank_mask:0xf bound_ctrl:0
	v_fmac_f32_dpp v127, v127, v187 row_shl:2 row_mask:0xf bank_mask:0xf bound_ctrl:0
	v_fmac_f32_dpp v124, v228, v188 row_shl:2 row_mask:0xf bank_mask:0xf bound_ctrl:0
	v_fmac_f32_dpp v125, v229, v189 row_shl:2 row_mask:0xf bank_mask:0xf bound_ctrl:0
	v_fmac_f32_dpp v126, v230, v190 row_shl:2 row_mask:0xf bank_mask:0xf bound_ctrl:0
	v_fmac_f32_dpp v127, v231, v191 row_shl:2 row_mask:0xf bank_mask:0xf bound_ctrl:0
	ds_read_b128 v[184:187], v9 offset:9216
	ds_read_b128 v[188:191], v9 offset:9472
	s_waitcnt lgkmcnt(2)
	v_mov_b32_e32 v228, v128
	v_mov_b32_e32 v229, v129
	v_mov_b32_e32 v230, v130
	v_mov_b32_e32 v231, v131
	v_fmac_f32_dpp v128, v128, v192 row_shl:2 row_mask:0xf bank_mask:0xf bound_ctrl:0
	v_fmac_f32_dpp v129, v129, v193 row_shl:2 row_mask:0xf bank_mask:0xf bound_ctrl:0
	v_fmac_f32_dpp v130, v130, v194 row_shl:2 row_mask:0xf bank_mask:0xf bound_ctrl:0
	v_fmac_f32_dpp v131, v131, v195 row_shl:2 row_mask:0xf bank_mask:0xf bound_ctrl:0
	v_fmac_f32_dpp v128, v140, -v224 row_shl:2 row_mask:0xf bank_mask:0xf bound_ctrl:0
	v_fmac_f32_dpp v129, v141, -v225 row_shl:2 row_mask:0xf bank_mask:0xf bound_ctrl:0
	v_fmac_f32_dpp v130, v142, -v226 row_shl:2 row_mask:0xf bank_mask:0xf bound_ctrl:0
	v_fmac_f32_dpp v131, v143, -v227 row_shl:2 row_mask:0xf bank_mask:0xf bound_ctrl:0
	v_fmac_f32_dpp v140, v140, v192 row_shl:2 row_mask:0xf bank_mask:0xf bound_ctrl:0
	v_fmac_f32_dpp v141, v141, v193 row_shl:2 row_mask:0xf bank_mask:0xf bound_ctrl:0
	v_fmac_f32_dpp v142, v142, v194 row_shl:2 row_mask:0xf bank_mask:0xf bound_ctrl:0
	v_fmac_f32_dpp v143, v143, v195 row_shl:2 row_mask:0xf bank_mask:0xf bound_ctrl:0
	v_fmac_f32_dpp v140, v228, v224 row_shl:2 row_mask:0xf bank_mask:0xf bound_ctrl:0
	v_fmac_f32_dpp v141, v229, v225 row_shl:2 row_mask:0xf bank_mask:0xf bound_ctrl:0
	v_fmac_f32_dpp v142, v230, v226 row_shl:2 row_mask:0xf bank_mask:0xf bound_ctrl:0
	v_fmac_f32_dpp v143, v231, v227 row_shl:2 row_mask:0xf bank_mask:0xf bound_ctrl:0
	ds_read_b128 v[192:195], v9 offset:9280
	ds_read_b128 v[224:227], v9 offset:9536
	s_waitcnt lgkmcnt(2)
	v_mov_b32_e32 v228, v80
	v_mov_b32_e32 v229, v81
	v_mov_b32_e32 v230, v82
	v_mov_b32_e32 v231, v83
	v_fmac_f32_dpp v80, v80, v184 row_shl:4 row_mask:0xf bank_mask:0xf bound_ctrl:0
	v_fmac_f32_dpp v81, v81, v185 row_shl:4 row_mask:0xf bank_mask:0xf bound_ctrl:0
	v_fmac_f32_dpp v82, v82, v186 row_shl:4 row_mask:0xf bank_mask:0xf bound_ctrl:0
	v_fmac_f32_dpp v83, v83, v187 row_shl:4 row_mask:0xf bank_mask:0xf bound_ctrl:0
	v_fmac_f32_dpp v80, v84, -v188 row_shl:4 row_mask:0xf bank_mask:0xf bound_ctrl:0
	v_fmac_f32_dpp v81, v85, -v189 row_shl:4 row_mask:0xf bank_mask:0xf bound_ctrl:0
	v_fmac_f32_dpp v82, v86, -v190 row_shl:4 row_mask:0xf bank_mask:0xf bound_ctrl:0
	v_fmac_f32_dpp v83, v87, -v191 row_shl:4 row_mask:0xf bank_mask:0xf bound_ctrl:0
	v_fmac_f32_dpp v84, v84, v184 row_shl:4 row_mask:0xf bank_mask:0xf bound_ctrl:0
	v_fmac_f32_dpp v85, v85, v185 row_shl:4 row_mask:0xf bank_mask:0xf bound_ctrl:0
	v_fmac_f32_dpp v86, v86, v186 row_shl:4 row_mask:0xf bank_mask:0xf bound_ctrl:0
	v_fmac_f32_dpp v87, v87, v187 row_shl:4 row_mask:0xf bank_mask:0xf bound_ctrl:0
	v_fmac_f32_dpp v84, v228, v188 row_shl:4 row_mask:0xf bank_mask:0xf bound_ctrl:0
	v_fmac_f32_dpp v85, v229, v189 row_shl:4 row_mask:0xf bank_mask:0xf bound_ctrl:0
	v_fmac_f32_dpp v86, v230, v190 row_shl:4 row_mask:0xf bank_mask:0xf bound_ctrl:0
	v_fmac_f32_dpp v87, v231, v191 row_shl:4 row_mask:0xf bank_mask:0xf bound_ctrl:0
	ds_read_b128 v[184:187], v9 offset:9344
	ds_read_b128 v[188:191], v9 offset:9600
	s_waitcnt lgkmcnt(2)
	v_mov_b32_e32 v228, v112
	v_mov_b32_e32 v229, v113
	v_mov_b32_e32 v230, v114
	v_mov_b32_e32 v231, v115
	v_fmac_f32_dpp v112, v112, v192 row_shl:4 row_mask:0xf bank_mask:0xf bound_ctrl:0
	v_fmac_f32_dpp v113, v113, v193 row_shl:4 row_mask:0xf bank_mask:0xf bound_ctrl:0
	v_fmac_f32_dpp v114, v114, v194 row_shl:4 row_mask:0xf bank_mask:0xf bound_ctrl:0
	v_fmac_f32_dpp v115, v115, v195 row_shl:4 row_mask:0xf bank_mask:0xf bound_ctrl:0
	v_fmac_f32_dpp v112, v116, -v224 row_shl:4 row_mask:0xf bank_mask:0xf bound_ctrl:0
	v_fmac_f32_dpp v113, v117, -v225 row_shl:4 row_mask:0xf bank_mask:0xf bound_ctrl:0
	v_fmac_f32_dpp v114, v118, -v226 row_shl:4 row_mask:0xf bank_mask:0xf bound_ctrl:0
	v_fmac_f32_dpp v115, v119, -v227 row_shl:4 row_mask:0xf bank_mask:0xf bound_ctrl:0
	v_fmac_f32_dpp v116, v116, v192 row_shl:4 row_mask:0xf bank_mask:0xf bound_ctrl:0
	v_fmac_f32_dpp v117, v117, v193 row_shl:4 row_mask:0xf bank_mask:0xf bound_ctrl:0
	v_fmac_f32_dpp v118, v118, v194 row_shl:4 row_mask:0xf bank_mask:0xf bound_ctrl:0
	v_fmac_f32_dpp v119, v119, v195 row_shl:4 row_mask:0xf bank_mask:0xf bound_ctrl:0
	v_fmac_f32_dpp v116, v228, v224 row_shl:4 row_mask:0xf bank_mask:0xf bound_ctrl:0
	v_fmac_f32_dpp v117, v229, v225 row_shl:4 row_mask:0xf bank_mask:0xf bound_ctrl:0
	v_fmac_f32_dpp v118, v230, v226 row_shl:4 row_mask:0xf bank_mask:0xf bound_ctrl:0
	v_fmac_f32_dpp v119, v231, v227 row_shl:4 row_mask:0xf bank_mask:0xf bound_ctrl:0
	ds_read_b128 v[192:195], v9 offset:9408
	ds_read_b128 v[224:227], v9 offset:9664
	s_waitcnt lgkmcnt(2)
	v_mov_b32_e32 v228, v120
	v_mov_b32_e32 v229, v121
	v_mov_b32_e32 v230, v122
	v_mov_b32_e32 v231, v123
	v_fmac_f32_dpp v120, v120, v184 row_shl:4 row_mask:0xf bank_mask:0xf bound_ctrl:0
	v_fmac_f32_dpp v121, v121, v185 row_shl:4 row_mask:0xf bank_mask:0xf bound_ctrl:0
	v_fmac_f32_dpp v122, v122, v186 row_shl:4 row_mask:0xf bank_mask:0xf bound_ctrl:0
	v_fmac_f32_dpp v123, v123, v187 row_shl:4 row_mask:0xf bank_mask:0xf bound_ctrl:0
	v_fmac_f32_dpp v120, v124, -v188 row_shl:4 row_mask:0xf bank_mask:0xf bound_ctrl:0
	v_fmac_f32_dpp v121, v125, -v189 row_shl:4 row_mask:0xf bank_mask:0xf bound_ctrl:0
	v_fmac_f32_dpp v122, v126, -v190 row_shl:4 row_mask:0xf bank_mask:0xf bound_ctrl:0
	v_fmac_f32_dpp v123, v127, -v191 row_shl:4 row_mask:0xf bank_mask:0xf bound_ctrl:0
	v_fmac_f32_dpp v124, v124, v184 row_shl:4 row_mask:0xf bank_mask:0xf bound_ctrl:0
	v_fmac_f32_dpp v125, v125, v185 row_shl:4 row_mask:0xf bank_mask:0xf bound_ctrl:0
	v_fmac_f32_dpp v126, v126, v186 row_shl:4 row_mask:0xf bank_mask:0xf bound_ctrl:0
	v_fmac_f32_dpp v127, v127, v187 row_shl:4 row_mask:0xf bank_mask:0xf bound_ctrl:0
	v_fmac_f32_dpp v124, v228, v188 row_shl:4 row_mask:0xf bank_mask:0xf bound_ctrl:0
	v_fmac_f32_dpp v125, v229, v189 row_shl:4 row_mask:0xf bank_mask:0xf bound_ctrl:0
	v_fmac_f32_dpp v126, v230, v190 row_shl:4 row_mask:0xf bank_mask:0xf bound_ctrl:0
	v_fmac_f32_dpp v127, v231, v191 row_shl:4 row_mask:0xf bank_mask:0xf bound_ctrl:0
	ds_read_b128 v[184:187], v9 offset:9728
	ds_read_b128 v[188:191], v9 offset:9984
	s_waitcnt lgkmcnt(2)
	v_mov_b32_e32 v228, v128
	v_mov_b32_e32 v229, v129
	v_mov_b32_e32 v230, v130
	v_mov_b32_e32 v231, v131
	v_fmac_f32_dpp v128, v128, v192 row_shl:4 row_mask:0xf bank_mask:0xf bound_ctrl:0
	v_fmac_f32_dpp v129, v129, v193 row_shl:4 row_mask:0xf bank_mask:0xf bound_ctrl:0
	v_fmac_f32_dpp v130, v130, v194 row_shl:4 row_mask:0xf bank_mask:0xf bound_ctrl:0
	v_fmac_f32_dpp v131, v131, v195 row_shl:4 row_mask:0xf bank_mask:0xf bound_ctrl:0
	v_fmac_f32_dpp v128, v140, -v224 row_shl:4 row_mask:0xf bank_mask:0xf bound_ctrl:0
	v_fmac_f32_dpp v129, v141, -v225 row_shl:4 row_mask:0xf bank_mask:0xf bound_ctrl:0
	v_fmac_f32_dpp v130, v142, -v226 row_shl:4 row_mask:0xf bank_mask:0xf bound_ctrl:0
	v_fmac_f32_dpp v131, v143, -v227 row_shl:4 row_mask:0xf bank_mask:0xf bound_ctrl:0
	v_fmac_f32_dpp v140, v140, v192 row_shl:4 row_mask:0xf bank_mask:0xf bound_ctrl:0
	v_fmac_f32_dpp v141, v141, v193 row_shl:4 row_mask:0xf bank_mask:0xf bound_ctrl:0
	v_fmac_f32_dpp v142, v142, v194 row_shl:4 row_mask:0xf bank_mask:0xf bound_ctrl:0
	v_fmac_f32_dpp v143, v143, v195 row_shl:4 row_mask:0xf bank_mask:0xf bound_ctrl:0
	v_fmac_f32_dpp v140, v228, v224 row_shl:4 row_mask:0xf bank_mask:0xf bound_ctrl:0
	v_fmac_f32_dpp v141, v229, v225 row_shl:4 row_mask:0xf bank_mask:0xf bound_ctrl:0
	v_fmac_f32_dpp v142, v230, v226 row_shl:4 row_mask:0xf bank_mask:0xf bound_ctrl:0
	v_fmac_f32_dpp v143, v231, v227 row_shl:4 row_mask:0xf bank_mask:0xf bound_ctrl:0
	ds_read_b128 v[192:195], v9 offset:9792
	ds_read_b128 v[224:227], v9 offset:10048
	s_waitcnt lgkmcnt(2)
	v_mov_b32_e32 v228, v80
	v_mov_b32_e32 v229, v81
	v_mov_b32_e32 v230, v82
	v_mov_b32_e32 v231, v83
	v_fmac_f32_dpp v80, v80, v184 row_shl:8 row_mask:0xf bank_mask:0xf bound_ctrl:0
	v_fmac_f32_dpp v81, v81, v185 row_shl:8 row_mask:0xf bank_mask:0xf bound_ctrl:0
	v_fmac_f32_dpp v82, v82, v186 row_shl:8 row_mask:0xf bank_mask:0xf bound_ctrl:0
	v_fmac_f32_dpp v83, v83, v187 row_shl:8 row_mask:0xf bank_mask:0xf bound_ctrl:0
	v_fmac_f32_dpp v80, v84, -v188 row_shl:8 row_mask:0xf bank_mask:0xf bound_ctrl:0
	v_fmac_f32_dpp v81, v85, -v189 row_shl:8 row_mask:0xf bank_mask:0xf bound_ctrl:0
	v_fmac_f32_dpp v82, v86, -v190 row_shl:8 row_mask:0xf bank_mask:0xf bound_ctrl:0
	v_fmac_f32_dpp v83, v87, -v191 row_shl:8 row_mask:0xf bank_mask:0xf bound_ctrl:0
	v_fmac_f32_dpp v84, v84, v184 row_shl:8 row_mask:0xf bank_mask:0xf bound_ctrl:0
	v_fmac_f32_dpp v85, v85, v185 row_shl:8 row_mask:0xf bank_mask:0xf bound_ctrl:0
	v_fmac_f32_dpp v86, v86, v186 row_shl:8 row_mask:0xf bank_mask:0xf bound_ctrl:0
	v_fmac_f32_dpp v87, v87, v187 row_shl:8 row_mask:0xf bank_mask:0xf bound_ctrl:0
	v_fmac_f32_dpp v84, v228, v188 row_shl:8 row_mask:0xf bank_mask:0xf bound_ctrl:0
	v_fmac_f32_dpp v85, v229, v189 row_shl:8 row_mask:0xf bank_mask:0xf bound_ctrl:0
	v_fmac_f32_dpp v86, v230, v190 row_shl:8 row_mask:0xf bank_mask:0xf bound_ctrl:0
	v_fmac_f32_dpp v87, v231, v191 row_shl:8 row_mask:0xf bank_mask:0xf bound_ctrl:0
	ds_read_b128 v[184:187], v9 offset:9856
	ds_read_b128 v[188:191], v9 offset:10112
	s_waitcnt lgkmcnt(2)
	v_mov_b32_e32 v228, v112
	v_mov_b32_e32 v229, v113
	v_mov_b32_e32 v230, v114
	v_mov_b32_e32 v231, v115
	v_fmac_f32_dpp v112, v112, v192 row_shl:8 row_mask:0xf bank_mask:0xf bound_ctrl:0
	v_fmac_f32_dpp v113, v113, v193 row_shl:8 row_mask:0xf bank_mask:0xf bound_ctrl:0
	v_fmac_f32_dpp v114, v114, v194 row_shl:8 row_mask:0xf bank_mask:0xf bound_ctrl:0
	v_fmac_f32_dpp v115, v115, v195 row_shl:8 row_mask:0xf bank_mask:0xf bound_ctrl:0
	v_fmac_f32_dpp v112, v116, -v224 row_shl:8 row_mask:0xf bank_mask:0xf bound_ctrl:0
	v_fmac_f32_dpp v113, v117, -v225 row_shl:8 row_mask:0xf bank_mask:0xf bound_ctrl:0
	v_fmac_f32_dpp v114, v118, -v226 row_shl:8 row_mask:0xf bank_mask:0xf bound_ctrl:0
	v_fmac_f32_dpp v115, v119, -v227 row_shl:8 row_mask:0xf bank_mask:0xf bound_ctrl:0
	v_fmac_f32_dpp v116, v116, v192 row_shl:8 row_mask:0xf bank_mask:0xf bound_ctrl:0
	v_fmac_f32_dpp v117, v117, v193 row_shl:8 row_mask:0xf bank_mask:0xf bound_ctrl:0
	v_fmac_f32_dpp v118, v118, v194 row_shl:8 row_mask:0xf bank_mask:0xf bound_ctrl:0
	v_fmac_f32_dpp v119, v119, v195 row_shl:8 row_mask:0xf bank_mask:0xf bound_ctrl:0
	v_fmac_f32_dpp v116, v228, v224 row_shl:8 row_mask:0xf bank_mask:0xf bound_ctrl:0
	v_fmac_f32_dpp v117, v229, v225 row_shl:8 row_mask:0xf bank_mask:0xf bound_ctrl:0
	v_fmac_f32_dpp v118, v230, v226 row_shl:8 row_mask:0xf bank_mask:0xf bound_ctrl:0
	v_fmac_f32_dpp v119, v231, v227 row_shl:8 row_mask:0xf bank_mask:0xf bound_ctrl:0
	ds_read_b128 v[192:195], v9 offset:9920
	ds_read_b128 v[224:227], v9 offset:10176
	s_waitcnt lgkmcnt(2)
	v_mov_b32_e32 v228, v120
	v_mov_b32_e32 v229, v121
	v_mov_b32_e32 v230, v122
	v_mov_b32_e32 v231, v123
	v_fmac_f32_dpp v120, v120, v184 row_shl:8 row_mask:0xf bank_mask:0xf bound_ctrl:0
	v_fmac_f32_dpp v121, v121, v185 row_shl:8 row_mask:0xf bank_mask:0xf bound_ctrl:0
	v_fmac_f32_dpp v122, v122, v186 row_shl:8 row_mask:0xf bank_mask:0xf bound_ctrl:0
	v_fmac_f32_dpp v123, v123, v187 row_shl:8 row_mask:0xf bank_mask:0xf bound_ctrl:0
	v_fmac_f32_dpp v120, v124, -v188 row_shl:8 row_mask:0xf bank_mask:0xf bound_ctrl:0
	v_fmac_f32_dpp v121, v125, -v189 row_shl:8 row_mask:0xf bank_mask:0xf bound_ctrl:0
	v_fmac_f32_dpp v122, v126, -v190 row_shl:8 row_mask:0xf bank_mask:0xf bound_ctrl:0
	v_fmac_f32_dpp v123, v127, -v191 row_shl:8 row_mask:0xf bank_mask:0xf bound_ctrl:0
	v_fmac_f32_dpp v124, v124, v184 row_shl:8 row_mask:0xf bank_mask:0xf bound_ctrl:0
	v_fmac_f32_dpp v125, v125, v185 row_shl:8 row_mask:0xf bank_mask:0xf bound_ctrl:0
	v_fmac_f32_dpp v126, v126, v186 row_shl:8 row_mask:0xf bank_mask:0xf bound_ctrl:0
	v_fmac_f32_dpp v127, v127, v187 row_shl:8 row_mask:0xf bank_mask:0xf bound_ctrl:0
	v_fmac_f32_dpp v124, v228, v188 row_shl:8 row_mask:0xf bank_mask:0xf bound_ctrl:0
	v_fmac_f32_dpp v125, v229, v189 row_shl:8 row_mask:0xf bank_mask:0xf bound_ctrl:0
	v_fmac_f32_dpp v126, v230, v190 row_shl:8 row_mask:0xf bank_mask:0xf bound_ctrl:0
	v_fmac_f32_dpp v127, v231, v191 row_shl:8 row_mask:0xf bank_mask:0xf bound_ctrl:0
	s_waitcnt lgkmcnt(0)
	v_mov_b32_e32 v228, v128
	v_mov_b32_e32 v229, v129
	v_mov_b32_e32 v230, v130
	v_mov_b32_e32 v231, v131
	v_fmac_f32_dpp v128, v128, v192 row_shl:8 row_mask:0xf bank_mask:0xf bound_ctrl:0
	v_fmac_f32_dpp v129, v129, v193 row_shl:8 row_mask:0xf bank_mask:0xf bound_ctrl:0
	v_fmac_f32_dpp v130, v130, v194 row_shl:8 row_mask:0xf bank_mask:0xf bound_ctrl:0
	v_fmac_f32_dpp v131, v131, v195 row_shl:8 row_mask:0xf bank_mask:0xf bound_ctrl:0
	v_fmac_f32_dpp v128, v140, -v224 row_shl:8 row_mask:0xf bank_mask:0xf bound_ctrl:0
	v_fmac_f32_dpp v129, v141, -v225 row_shl:8 row_mask:0xf bank_mask:0xf bound_ctrl:0
	v_fmac_f32_dpp v130, v142, -v226 row_shl:8 row_mask:0xf bank_mask:0xf bound_ctrl:0
	v_fmac_f32_dpp v131, v143, -v227 row_shl:8 row_mask:0xf bank_mask:0xf bound_ctrl:0
	v_fmac_f32_dpp v140, v140, v192 row_shl:8 row_mask:0xf bank_mask:0xf bound_ctrl:0
	v_fmac_f32_dpp v141, v141, v193 row_shl:8 row_mask:0xf bank_mask:0xf bound_ctrl:0
	v_fmac_f32_dpp v142, v142, v194 row_shl:8 row_mask:0xf bank_mask:0xf bound_ctrl:0
	v_fmac_f32_dpp v143, v143, v195 row_shl:8 row_mask:0xf bank_mask:0xf bound_ctrl:0
	v_fmac_f32_dpp v140, v228, v224 row_shl:8 row_mask:0xf bank_mask:0xf bound_ctrl:0
	v_fmac_f32_dpp v141, v229, v225 row_shl:8 row_mask:0xf bank_mask:0xf bound_ctrl:0
	v_fmac_f32_dpp v142, v230, v226 row_shl:8 row_mask:0xf bank_mask:0xf bound_ctrl:0
	v_fmac_f32_dpp v143, v231, v227 row_shl:8 row_mask:0xf bank_mask:0xf bound_ctrl:0
	s_lshl_b32 s56, s0, 5
	s_add_i32 s55, s6, 1
	s_lshl_b32 s55, s55, 1
	s_add_i32 s56, s56, s55
	s_add_i32 s56, s56, 1
	s_lshl_b32 s56, s56, 9
	s_add_u32 s48, s94, 0x12dd6000
	s_addc_u32 s49, s95, 0
	s_add_u32 s48, s48, s56
	s_addc_u32 s49, s49, 0
	s_nop 1
	s_mov_b64 exec, s[52:53]
	global_store_dword v10, v80, s[48:49] offset:0
	global_store_dword v10, v84, s[48:49] offset:4
	global_store_dword v10, v81, s[48:49] offset:8
	global_store_dword v10, v85, s[48:49] offset:12
	global_store_dword v10, v82, s[48:49] offset:16
	global_store_dword v10, v86, s[48:49] offset:20
	global_store_dword v10, v83, s[48:49] offset:24
	global_store_dword v10, v87, s[48:49] offset:28
	global_store_dword v10, v112, s[48:49] offset:128
	global_store_dword v10, v116, s[48:49] offset:132
	global_store_dword v10, v113, s[48:49] offset:136
	global_store_dword v10, v117, s[48:49] offset:140
	global_store_dword v10, v114, s[48:49] offset:144
	global_store_dword v10, v118, s[48:49] offset:148
	global_store_dword v10, v115, s[48:49] offset:152
	global_store_dword v10, v119, s[48:49] offset:156
	global_store_dword v10, v120, s[48:49] offset:256
	global_store_dword v10, v124, s[48:49] offset:260
	global_store_dword v10, v121, s[48:49] offset:264
	global_store_dword v10, v125, s[48:49] offset:268
	global_store_dword v10, v122, s[48:49] offset:272
	global_store_dword v10, v126, s[48:49] offset:276
	global_store_dword v10, v123, s[48:49] offset:280
	global_store_dword v10, v127, s[48:49] offset:284
	global_store_dword v10, v128, s[48:49] offset:384
	global_store_dword v10, v140, s[48:49] offset:388
	global_store_dword v10, v129, s[48:49] offset:392
	global_store_dword v10, v141, s[48:49] offset:396
	global_store_dword v10, v130, s[48:49] offset:400
	global_store_dword v10, v142, s[48:49] offset:404
	global_store_dword v10, v131, s[48:49] offset:408
	global_store_dword v10, v143, s[48:49] offset:412
	s_mov_b64 exec, -1
	s_waitcnt vmcnt(32)
	s_add_i32 s55, s86, s84
	s_cmp_lt_i32 s55, 640
	s_cbranch_scc0 .Ls5a_exit3
	s_mov_b32 s86, s55
	s_mov_b32 s0, s1
	s_branch .Ls5a_head1
.Ls5a_exit3:
	s_waitcnt vmcnt(0)
	s_branch .LBB0_618
